# on top of v16: the address and loop-control instructions after each compute interval's last MFMA moved into the MFMA run after the 12th MFMA (24 sites)
# speedup vs baseline: 1.0096x; 1.0078x over previous
; #define PG8_STAGE(bufoff, gbase) do { _Pragma("unroll") for (int _i = 0; _i < 2; ++_i) \
;         __builtin_amdgcn_global_load_lds((const unsigned*)((const char*)(gbase) + voff[_i]), (LAS unsigned*)(lds + (bufoff) + ldsw + _i * 8192), 16, 0, 0); } while (0)
; #define PG8_LDA(dst, b, h) do { _Pragma("unroll") for (int m = 0; m < 4; ++m) _Pragma("unroll") for (int k = 0; k < 2; ++k) dst[m][k] = *(const LAS bf16x8*)(lds + PG8_SA(b, h) + aoff + m * 2048 + k * 1024); } while (0)
; #define PG8_LDB(dst, b, h) do { _Pragma("unroll") for (int n = 0; n < 2; ++n) _Pragma("unroll") for (int k = 0; k < 2; ++k) dst[n][k] = *(const LAS bf16x8*)(lds + PG8_SB(b, h) + boff + n * 2048 + k * 1024); } while (0)
; #define PG8_MMA(ai, bj, At, Bt) do { __builtin_amdgcn_s_setprio(1); _Pragma("unroll") for (int m = 0; m < 4; ++m) _Pragma("unroll") for (int n = 0; n < 2; ++n) _Pragma("unroll") for (int k = 0; k < 2; ++k) \
;         acc[ai][bj][m][n] = __builtin_amdgcn_mfma_f32_16x16x32_bf16(Bt[n][k], At[m][k], acc[ai][bj][m][n], 0, 0, 0); __builtin_amdgcn_s_setprio(0); } while (0)
; #define PG8_WAIT_L(n) asm volatile("s_waitcnt lgkmcnt(" #n ")" ::: "memory")
; #define PG8_BAR __builtin_amdgcn_s_barrier()
; #define PG8_SCHED __builtin_amdgcn_sched_barrier(0)
; template <class Epi>
; DI void gemm_phase(LAS unsigned char* lds, const Gemm g, const StaticOrder& S, const Epi& E) {
;     ...
;         for (int t = 0; t < nt; t += 2) {
;             const bool last = (t == nt - 2);
;             const char* a1 = cA + (size_t)(t + 1) * kstep;
;             const char* a2 = last ? nA : cA + (size_t)(t + 2) * kstep; const char* b2 = last ? nB : cB + (size_t)(t + 2) * kstep;
;             const char* a3 = a2 + kstep; const char* b3 = b2 + kstep;
;             PG8_LDB(B0, 0, 0); PG8_SCHED; PG8_LDA(At, 0, 0); PG8_STAGE(PG8_SA(1, 1), a1 + hstep);
;             PG8_WAIT_L(8); PG8_BAR; PG8_WAIT_L(0); PG8_MMA(0, 0, At, B0); PG8_BAR; PG8_SCHED;
;             PG8_LDB(B1, 0, 1); PG8_STAGE(PG8_SB(0, 0), b2);
;             PG8_BAR; PG8_WAIT_L(0); PG8_MMA(0, 1, At, B1); PG8_BAR;
;             PG8_LDA(At, 0, 1); PG8_STAGE(PG8_SA(0, 0), a2);
;             PG8_BAR; PG8_WAIT_L(0); PG8_MMA(1, 0, At, B0); PG8_BAR; PG8_SCHED;
.LBB0_37:
	s_add_u32 s20, s18, 0xfff80080
	s_addc_u32 s21, s19, -1
	s_add_i32 s39, 0, 0x10000
	v_add_u32_e32 v150, s39, v135
	ds_read_b128 v[138:141], v150
	ds_read_b128 v[142:145], v150 offset:1024
	ds_read_b128 v[146:149], v150 offset:2048
	ds_read_b128 v[150:153], v150 offset:3072
	s_cmp_eq_u32 s38, 28
	s_cselect_b32 s23, s4, s21
	s_cselect_b32 s22, s5, s20
	s_cselect_b32 s21, s9, s37
	s_cselect_b32 s20, s11, s33
	v_lshl_add_u64 v[154:155], s[18:19], 0, v[130:131]
	s_add_i32 m0, s28, 0xc000
	ds_read_b128 v[186:189], v137
	ds_read_b128 v[190:193], v137 offset:1024
	ds_read_b128 v[194:197], v137 offset:2048
	ds_read_b128 v[198:201], v137 offset:3072
	ds_read_b128 v[202:205], v137 offset:4096
	ds_read_b128 v[206:209], v137 offset:5120
	ds_read_b128 v[210:213], v137 offset:6144
	ds_read_b128 v[214:217], v137 offset:7168
	global_load_lds_dwordx4 v[154:155], off
	v_lshl_add_u64 v[154:155], s[18:19], 0, v[132:133]
	s_add_i32 m0, s28, 0xe000
	s_nop 0
	global_load_lds_dwordx4 v[154:155], off
	s_waitcnt lgkmcnt(8)
	s_setprio 1
	s_barrier
	s_waitcnt lgkmcnt(0)
	v_mfma_f32_16x16x32_bf16 v[124:127], v[138:141], v[186:189], v[124:127]
	v_mfma_f32_16x16x32_bf16 v[120:123], v[146:149], v[186:189], v[120:123]
	v_mfma_f32_16x16x32_bf16 v[108:111], v[138:141], v[194:197], v[108:111]
	v_mfma_f32_16x16x32_bf16 v[104:107], v[146:149], v[194:197], v[104:107]
	v_mfma_f32_16x16x32_bf16 v[92:95], v[138:141], v[202:205], v[92:95]
	v_mfma_f32_16x16x32_bf16 v[88:91], v[146:149], v[202:205], v[88:91]
	v_mfma_f32_16x16x32_bf16 v[76:79], v[138:141], v[210:213], v[76:79]
	v_mfma_f32_16x16x32_bf16 v[72:75], v[146:149], v[210:213], v[72:75]
	v_mfma_f32_16x16x32_bf16 v[124:127], v[142:145], v[190:193], v[124:127]
	v_mfma_f32_16x16x32_bf16 v[120:123], v[150:153], v[190:193], v[120:123]
	v_mfma_f32_16x16x32_bf16 v[108:111], v[142:145], v[198:201], v[108:111]
	v_mfma_f32_16x16x32_bf16 v[104:107], v[150:153], v[198:201], v[104:107]
	v_mfma_f32_16x16x32_bf16 v[92:95], v[142:145], v[206:209], v[92:95]
	v_mfma_f32_16x16x32_bf16 v[88:91], v[150:153], v[206:209], v[88:91]
	v_mfma_f32_16x16x32_bf16 v[76:79], v[142:145], v[214:217], v[76:79]
	v_mfma_f32_16x16x32_bf16 v[72:75], v[150:153], v[214:217], v[72:75]
	s_setprio 0
	s_barrier
	s_add_i32 s42, 0, 0x14000
	v_add_u32_e32 v154, s42, v135
	s_add_i32 s39, s39, s27
	ds_read_b128 v[226:229], v154
	ds_read_b128 v[230:233], v154 offset:1024
	ds_read_b128 v[234:237], v154 offset:2048
	ds_read_b128 v[238:241], v154 offset:3072
	v_lshl_add_u64 v[154:155], s[20:21], 0, v[158:159]
	s_mov_b32 m0, s39
	v_lshl_add_u64 v[218:219], s[20:21], 0, v[128:129]
	global_load_lds_dwordx4 v[154:155], off
	s_add_i32 m0, s39, 0x2000
	s_nop 0
	global_load_lds_dwordx4 v[218:219], off
	s_waitcnt lgkmcnt(0)
	s_setprio 1
	s_barrier
	v_mfma_f32_16x16x32_bf16 v[116:119], v[226:229], v[186:189], v[116:119]
	v_mfma_f32_16x16x32_bf16 v[112:115], v[234:237], v[186:189], v[112:115]
	v_mfma_f32_16x16x32_bf16 v[100:103], v[226:229], v[194:197], v[100:103]
	v_mfma_f32_16x16x32_bf16 v[96:99], v[234:237], v[194:197], v[96:99]
	v_mfma_f32_16x16x32_bf16 v[84:87], v[226:229], v[202:205], v[84:87]
	v_mfma_f32_16x16x32_bf16 v[80:83], v[234:237], v[202:205], v[80:83]
	v_mfma_f32_16x16x32_bf16 v[68:71], v[226:229], v[210:213], v[68:71]
	v_mfma_f32_16x16x32_bf16 v[64:67], v[234:237], v[210:213], v[64:67]
	v_mfma_f32_16x16x32_bf16 v[116:119], v[230:233], v[190:193], v[116:119]
	v_mfma_f32_16x16x32_bf16 v[112:115], v[238:241], v[190:193], v[112:115]
	v_mfma_f32_16x16x32_bf16 v[100:103], v[230:233], v[198:201], v[100:103]
	v_mfma_f32_16x16x32_bf16 v[96:99], v[238:241], v[198:201], v[96:99]
	s_mov_b32 m0, s28
	v_lshl_add_u64 v[220:221], s[22:23], 0, v[158:159]
	v_mfma_f32_16x16x32_bf16 v[84:87], v[230:233], v[206:209], v[84:87]
	v_mfma_f32_16x16x32_bf16 v[80:83], v[238:241], v[206:209], v[80:83]
	v_mfma_f32_16x16x32_bf16 v[68:71], v[230:233], v[214:217], v[68:71]
	v_mfma_f32_16x16x32_bf16 v[64:67], v[238:241], v[214:217], v[64:67]
	s_setprio 0
	s_barrier
	ds_read_b128 v[186:189], v137 offset:16384
	ds_read_b128 v[190:193], v137 offset:17408
	ds_read_b128 v[194:197], v137 offset:18432
	ds_read_b128 v[198:201], v137 offset:19456
	ds_read_b128 v[202:205], v137 offset:20480
	ds_read_b128 v[206:209], v137 offset:21504
	ds_read_b128 v[210:213], v137 offset:22528
	ds_read_b128 v[214:217], v137 offset:23552
	global_load_lds_dwordx4 v[220:221], off
	v_lshl_add_u64 v[242:243], s[22:23], 0, v[128:129]
	s_mov_b32 m0, s29
	s_nop 0
	global_load_lds_dwordx4 v[242:243], off
	s_waitcnt lgkmcnt(0)
	s_setprio 1
	s_barrier
	v_mfma_f32_16x16x32_bf16 v[60:63], v[138:141], v[186:189], v[60:63]
	v_mfma_f32_16x16x32_bf16 v[56:59], v[146:149], v[186:189], v[56:59]
	v_mfma_f32_16x16x32_bf16 v[44:47], v[138:141], v[194:197], v[44:47]
	v_mfma_f32_16x16x32_bf16 v[40:43], v[146:149], v[194:197], v[40:43]
	v_mfma_f32_16x16x32_bf16 v[28:31], v[138:141], v[202:205], v[28:31]
	v_mfma_f32_16x16x32_bf16 v[24:27], v[146:149], v[202:205], v[24:27]
	v_mfma_f32_16x16x32_bf16 v[12:15], v[138:141], v[210:213], v[12:15]
	v_mfma_f32_16x16x32_bf16 v[8:11], v[146:149], v[210:213], v[8:11]
	v_mfma_f32_16x16x32_bf16 v[60:63], v[142:145], v[190:193], v[60:63]
	v_mfma_f32_16x16x32_bf16 v[56:59], v[150:153], v[190:193], v[56:59]
	v_mfma_f32_16x16x32_bf16 v[44:47], v[142:145], v[198:201], v[44:47]
	v_mfma_f32_16x16x32_bf16 v[40:43], v[150:153], v[198:201], v[40:43]
	v_mfma_f32_16x16x32_bf16 v[28:31], v[142:145], v[206:209], v[28:31]
	v_mfma_f32_16x16x32_bf16 v[24:27], v[150:153], v[206:209], v[24:27]
	v_mfma_f32_16x16x32_bf16 v[12:15], v[142:145], v[214:217], v[12:15]
	v_mfma_f32_16x16x32_bf16 v[8:11], v[150:153], v[214:217], v[8:11]
	s_setprio 0
	s_barrier
; #define PG8_STAGE(bufoff, gbase) do { _Pragma("unroll") for (int _i = 0; _i < 2; ++_i) \
;         __builtin_amdgcn_global_load_lds((const unsigned*)((const char*)(gbase) + voff[_i]), (LAS unsigned*)(lds + (bufoff) + ldsw + _i * 8192), 16, 0, 0); } while (0)
; #define PG8_LDA(dst, b, h) do { _Pragma("unroll") for (int m = 0; m < 4; ++m) _Pragma("unroll") for (int k = 0; k < 2; ++k) dst[m][k] = *(const LAS bf16x8*)(lds + PG8_SA(b, h) + aoff + m * 2048 + k * 1024); } while (0)
; #define PG8_LDB(dst, b, h) do { _Pragma("unroll") for (int n = 0; n < 2; ++n) _Pragma("unroll") for (int k = 0; k < 2; ++k) dst[n][k] = *(const LAS bf16x8*)(lds + PG8_SB(b, h) + boff + n * 2048 + k * 1024); } while (0)
; #define PG8_MMA(ai, bj, At, Bt) do { __builtin_amdgcn_s_setprio(1); _Pragma("unroll") for (int m = 0; m < 4; ++m) _Pragma("unroll") for (int n = 0; n < 2; ++n) _Pragma("unroll") for (int k = 0; k < 2; ++k) \
;         acc[ai][bj][m][n] = __builtin_amdgcn_mfma_f32_16x16x32_bf16(Bt[n][k], At[m][k], acc[ai][bj][m][n], 0, 0, 0); __builtin_amdgcn_s_setprio(0); } while (0)
; #define PG8_WAIT_V(n) asm volatile("s_waitcnt vmcnt(" #n ")" ::: "memory")
; #define PG8_WAIT_L(n) asm volatile("s_waitcnt lgkmcnt(" #n ")" ::: "memory")
; #define PG8_BAR __builtin_amdgcn_s_barrier()
; #define PG8_SCHED __builtin_amdgcn_sched_barrier(0)
; template <class Epi>
; DI void gemm_phase(LAS unsigned char* lds, const Gemm g, const StaticOrder& S, const Epi& E) {
;     ...
;             PG8_BAR; PG8_WAIT_L(0); PG8_MMA(1, 0, At, B0); PG8_BAR; PG8_SCHED;
;             PG8_STAGE(PG8_SB(0, 1), b2 + hstep);
;             PG8_WAIT_V(6); PG8_BAR; PG8_MMA(1, 1, At, B1); PG8_BAR;
;             PG8_LDB(B0, 1, 0); PG8_SCHED; PG8_LDA(At, 1, 0); PG8_STAGE(PG8_SA(0, 1), a2 + hstep);
;             PG8_WAIT_L(8); PG8_BAR; PG8_WAIT_L(0); PG8_MMA(0, 0, At, B0); PG8_BAR; PG8_SCHED;
;             PG8_LDB(B1, 1, 1); PG8_STAGE(PG8_SB(1, 0), b3);
;             PG8_BAR; PG8_WAIT_L(0); PG8_MMA(0, 1, At, B1); PG8_BAR;
;             PG8_LDA(At, 1, 1); PG8_STAGE(PG8_SA(1, 0), a3);
;             PG8_BAR; PG8_WAIT_L(0); PG8_MMA(1, 0, At, B0); PG8_BAR; PG8_SCHED;
	s_add_u32 s40, s20, 0x80000
	s_addc_u32 s41, s21, 0
	s_add_i32 s39, s42, s27
	v_lshl_add_u64 v[138:139], s[40:41], 0, v[158:159]
	s_mov_b32 m0, s39
	s_nop 0
	global_load_lds_dwordx4 v[138:139], off
	v_lshl_add_u64 v[138:139], s[40:41], 0, v[128:129]
	s_add_i32 m0, s39, 0x2000
	s_nop 0
	global_load_lds_dwordx4 v[138:139], off
	s_waitcnt vmcnt(6)
	s_setprio 1
	s_barrier
	v_mfma_f32_16x16x32_bf16 v[52:55], v[226:229], v[186:189], v[52:55]
	v_mfma_f32_16x16x32_bf16 v[48:51], v[234:237], v[186:189], v[48:51]
	v_mfma_f32_16x16x32_bf16 v[36:39], v[226:229], v[194:197], v[36:39]
	v_mfma_f32_16x16x32_bf16 v[32:35], v[234:237], v[194:197], v[32:35]
	v_mfma_f32_16x16x32_bf16 v[20:23], v[226:229], v[202:205], v[20:23]
	v_mfma_f32_16x16x32_bf16 v[16:19], v[234:237], v[202:205], v[16:19]
	v_mfma_f32_16x16x32_bf16 v[4:7], v[226:229], v[210:213], v[4:7]
	v_mfma_f32_16x16x32_bf16 v[0:3], v[234:237], v[210:213], v[0:3]
	v_mfma_f32_16x16x32_bf16 v[52:55], v[230:233], v[190:193], v[52:55]
	v_mfma_f32_16x16x32_bf16 v[48:51], v[238:241], v[190:193], v[48:51]
	v_mfma_f32_16x16x32_bf16 v[36:39], v[230:233], v[198:201], v[36:39]
	v_mfma_f32_16x16x32_bf16 v[32:35], v[238:241], v[198:201], v[32:35]
	s_add_i32 s39, 0, 0x18000
	v_add_u32_e32 v150, s39, v135
	v_mfma_f32_16x16x32_bf16 v[20:23], v[230:233], v[206:209], v[20:23]
	v_mfma_f32_16x16x32_bf16 v[16:19], v[238:241], v[206:209], v[16:19]
	v_mfma_f32_16x16x32_bf16 v[4:7], v[230:233], v[214:217], v[4:7]
	v_mfma_f32_16x16x32_bf16 v[0:3], v[238:241], v[214:217], v[0:3]
	s_setprio 0
	s_barrier
	ds_read_b128 v[138:141], v150
	ds_read_b128 v[142:145], v150 offset:1024
	ds_read_b128 v[146:149], v150 offset:2048
	ds_read_b128 v[150:153], v150 offset:3072
	s_add_u32 s22, s22, 0x80000
	s_addc_u32 s23, s23, 0
	s_mov_b32 m0, s30
	v_lshl_add_u64 v[226:227], s[22:23], 0, v[158:159]
	ds_read_b128 v[186:189], v137 offset:32768
	ds_read_b128 v[190:193], v137 offset:33792
	ds_read_b128 v[194:197], v137 offset:34816
	ds_read_b128 v[198:201], v137 offset:35840
	ds_read_b128 v[202:205], v137 offset:36864
	ds_read_b128 v[206:209], v137 offset:37888
	ds_read_b128 v[210:213], v137 offset:38912
	ds_read_b128 v[214:217], v137 offset:39936
	global_load_lds_dwordx4 v[226:227], off
	v_lshl_add_u64 v[226:227], s[22:23], 0, v[128:129]
	s_mov_b32 m0, s31
	s_nop 0
	global_load_lds_dwordx4 v[226:227], off
	s_waitcnt lgkmcnt(8)
	s_setprio 1
	s_barrier
	s_waitcnt lgkmcnt(0)
	v_mfma_f32_16x16x32_bf16 v[124:127], v[138:141], v[186:189], v[124:127]
	v_mfma_f32_16x16x32_bf16 v[120:123], v[146:149], v[186:189], v[120:123]
	v_mfma_f32_16x16x32_bf16 v[108:111], v[138:141], v[194:197], v[108:111]
	v_mfma_f32_16x16x32_bf16 v[104:107], v[146:149], v[194:197], v[104:107]
	v_mfma_f32_16x16x32_bf16 v[92:95], v[138:141], v[202:205], v[92:95]
	v_mfma_f32_16x16x32_bf16 v[88:91], v[146:149], v[202:205], v[88:91]
	v_mfma_f32_16x16x32_bf16 v[76:79], v[138:141], v[210:213], v[76:79]
	v_mfma_f32_16x16x32_bf16 v[72:75], v[146:149], v[210:213], v[72:75]
	v_mfma_f32_16x16x32_bf16 v[124:127], v[142:145], v[190:193], v[124:127]
	v_mfma_f32_16x16x32_bf16 v[120:123], v[150:153], v[190:193], v[120:123]
	v_mfma_f32_16x16x32_bf16 v[108:111], v[142:145], v[198:201], v[108:111]
	v_mfma_f32_16x16x32_bf16 v[104:107], v[150:153], v[198:201], v[104:107]
	v_mfma_f32_16x16x32_bf16 v[92:95], v[142:145], v[206:209], v[92:95]
	v_mfma_f32_16x16x32_bf16 v[88:91], v[150:153], v[206:209], v[88:91]
	v_mfma_f32_16x16x32_bf16 v[76:79], v[142:145], v[214:217], v[76:79]
	v_mfma_f32_16x16x32_bf16 v[72:75], v[150:153], v[214:217], v[72:75]
	s_setprio 0
	s_barrier
	s_add_i32 s22, 0, 0x1c000
	s_add_i32 s23, s39, s27
	v_add_u32_e32 v225, s22, v135
	v_lshl_add_u64 v[154:155], v[154:155], 0, s[94:95]
	s_mov_b32 m0, s23
	ds_read_b128 v[226:229], v225
	ds_read_b128 v[230:233], v225 offset:1024
	ds_read_b128 v[234:237], v225 offset:2048
	ds_read_b128 v[238:241], v225 offset:3072
	global_load_lds_dwordx4 v[154:155], off
	v_lshl_add_u64 v[154:155], v[218:219], 0, s[94:95]
	s_add_i32 m0, s23, 0x2000
	s_nop 0
	global_load_lds_dwordx4 v[154:155], off
	s_waitcnt lgkmcnt(0)
	s_setprio 1
	s_barrier
	v_mfma_f32_16x16x32_bf16 v[116:119], v[226:229], v[186:189], v[116:119]
	v_mfma_f32_16x16x32_bf16 v[112:115], v[234:237], v[186:189], v[112:115]
	v_mfma_f32_16x16x32_bf16 v[100:103], v[226:229], v[194:197], v[100:103]
	v_mfma_f32_16x16x32_bf16 v[96:99], v[234:237], v[194:197], v[96:99]
	v_mfma_f32_16x16x32_bf16 v[84:87], v[226:229], v[202:205], v[84:87]
	v_mfma_f32_16x16x32_bf16 v[80:83], v[234:237], v[202:205], v[80:83]
	v_mfma_f32_16x16x32_bf16 v[68:71], v[226:229], v[210:213], v[68:71]
	v_mfma_f32_16x16x32_bf16 v[64:67], v[234:237], v[210:213], v[64:67]
	v_mfma_f32_16x16x32_bf16 v[116:119], v[230:233], v[190:193], v[116:119]
	v_mfma_f32_16x16x32_bf16 v[112:115], v[238:241], v[190:193], v[112:115]
	v_mfma_f32_16x16x32_bf16 v[100:103], v[230:233], v[198:201], v[100:103]
	v_mfma_f32_16x16x32_bf16 v[96:99], v[238:241], v[198:201], v[96:99]
	s_mov_b32 m0, s34
	v_lshl_add_u64 v[154:155], v[220:221], 0, s[94:95]
	v_mfma_f32_16x16x32_bf16 v[84:87], v[230:233], v[206:209], v[84:87]
	v_mfma_f32_16x16x32_bf16 v[80:83], v[238:241], v[206:209], v[80:83]
	v_mfma_f32_16x16x32_bf16 v[68:71], v[230:233], v[214:217], v[68:71]
	v_mfma_f32_16x16x32_bf16 v[64:67], v[238:241], v[214:217], v[64:67]
	s_setprio 0
	s_barrier
	ds_read_b128 v[186:189], v137 offset:49152
	ds_read_b128 v[190:193], v137 offset:50176
	ds_read_b128 v[194:197], v137 offset:51200
	ds_read_b128 v[198:201], v137 offset:52224
	ds_read_b128 v[202:205], v137 offset:53248
	ds_read_b128 v[206:209], v137 offset:54272
	ds_read_b128 v[210:213], v137 offset:55296
	ds_read_b128 v[214:217], v137 offset:56320
	global_load_lds_dwordx4 v[154:155], off
	v_lshl_add_u64 v[154:155], v[242:243], 0, s[94:95]
	s_mov_b32 m0, s35
	s_nop 0
	global_load_lds_dwordx4 v[154:155], off
	s_waitcnt lgkmcnt(0)
	s_setprio 1
	s_barrier
; #define PG8_STAGE(bufoff, gbase) do { _Pragma("unroll") for (int _i = 0; _i < 2; ++_i) \
;         __builtin_amdgcn_global_load_lds((const unsigned*)((const char*)(gbase) + voff[_i]), (LAS unsigned*)(lds + (bufoff) + ldsw + _i * 8192), 16, 0, 0); } while (0)
; #define PG8_MMA(ai, bj, At, Bt) do { __builtin_amdgcn_s_setprio(1); _Pragma("unroll") for (int m = 0; m < 4; ++m) _Pragma("unroll") for (int n = 0; n < 2; ++n) _Pragma("unroll") for (int k = 0; k < 2; ++k) \
;         acc[ai][bj][m][n] = __builtin_amdgcn_mfma_f32_16x16x32_bf16(Bt[n][k], At[m][k], acc[ai][bj][m][n], 0, 0, 0); __builtin_amdgcn_s_setprio(0); } while (0)
; #define PG8_WAIT_V(n) asm volatile("s_waitcnt vmcnt(" #n ")" ::: "memory")
; #define PG8_WAIT_L(n) asm volatile("s_waitcnt lgkmcnt(" #n ")" ::: "memory")
; #define PG8_BAR __builtin_amdgcn_s_barrier()
; #define PG8_SCHED __builtin_amdgcn_sched_barrier(0)
; template <class Epi>
; DI void gemm_phase(LAS unsigned char* lds, const Gemm g, const StaticOrder& S, const Epi& E) {
;     ...
;             PG8_BAR; PG8_WAIT_L(0); PG8_MMA(1, 0, At, B0); PG8_BAR; PG8_SCHED;
;             PG8_STAGE(PG8_SB(1, 1), b3 + hstep);
;             PG8_WAIT_V(6); PG8_BAR; PG8_MMA(1, 1, At, B1); PG8_BAR;
;     DI void operator()(const f32x4 (&acc)[2][2][4][2], const Unit& u, int wr, int wc, int fr, int fq) const {
;         const int row0 = u.pm * BM + wr * 64 + fr, col0 = u.pn * HALF + wc * 32 + 8 * fq;
; #pragma unroll
;         for (int ai = 0; ai < 2; ++ai)
; #pragma unroll
;             for (int m = 0; m < 4; ++m) { float hv[8];
; #pragma unroll
;                 for (int n = 0; n < 2; ++n)
; #pragma unroll
;                     for (int e = 0; e < 4; ++e) { const float gt = acc[ai][0][m][n][e], up = acc[ai][1][m][n][e];
;                         hv[n * 4 + e] = gt * __builtin_amdgcn_rcpf(1.f + __builtin_amdgcn_exp2f(-1.4426950408889634f * gt)) * up; }
;                 *(u32x4*)(H + (size_t)(row0 + ai * HALF + m * 16) * DFF + col0) = (u32x4){pk(hv[0], hv[1]), pk(hv[2], hv[3]), pk(hv[4], hv[5]), pk(hv[6], hv[7])}; }
	v_mfma_f32_16x16x32_bf16 v[60:63], v[138:141], v[186:189], v[60:63]
	v_mfma_f32_16x16x32_bf16 v[56:59], v[146:149], v[186:189], v[56:59]
	v_mfma_f32_16x16x32_bf16 v[44:47], v[138:141], v[194:197], v[44:47]
	v_mfma_f32_16x16x32_bf16 v[40:43], v[146:149], v[194:197], v[40:43]
	v_mfma_f32_16x16x32_bf16 v[28:31], v[138:141], v[202:205], v[28:31]
	v_mfma_f32_16x16x32_bf16 v[24:27], v[146:149], v[202:205], v[24:27]
	v_mfma_f32_16x16x32_bf16 v[12:15], v[138:141], v[210:213], v[12:15]
	v_mfma_f32_16x16x32_bf16 v[8:11], v[146:149], v[210:213], v[8:11]
	v_mfma_f32_16x16x32_bf16 v[60:63], v[142:145], v[190:193], v[60:63]
	v_mfma_f32_16x16x32_bf16 v[56:59], v[150:153], v[190:193], v[56:59]
	v_mfma_f32_16x16x32_bf16 v[44:47], v[142:145], v[198:201], v[44:47]
	v_mfma_f32_16x16x32_bf16 v[40:43], v[150:153], v[198:201], v[40:43]
	v_mfma_f32_16x16x32_bf16 v[28:31], v[142:145], v[206:209], v[28:31]
	v_mfma_f32_16x16x32_bf16 v[24:27], v[150:153], v[206:209], v[24:27]
	v_mfma_f32_16x16x32_bf16 v[12:15], v[142:145], v[214:217], v[12:15]
	v_mfma_f32_16x16x32_bf16 v[8:11], v[150:153], v[214:217], v[8:11]
	s_setprio 0
	s_barrier
	s_add_u32 s20, s20, 0x80080
	s_addc_u32 s21, s21, 0
	s_add_i32 s22, s22, s27
	v_lshl_add_u64 v[138:139], s[20:21], 0, v[158:159]
	s_mov_b32 m0, s22
	s_nop 0
	global_load_lds_dwordx4 v[138:139], off
	v_lshl_add_u64 v[138:139], s[20:21], 0, v[128:129]
	s_add_i32 m0, s22, 0x2000
	s_nop 0
	global_load_lds_dwordx4 v[138:139], off
	s_waitcnt vmcnt(6)
	s_setprio 1
	s_barrier
	v_mfma_f32_16x16x32_bf16 v[52:55], v[226:229], v[186:189], v[52:55]
	v_mfma_f32_16x16x32_bf16 v[48:51], v[234:237], v[186:189], v[48:51]
	v_mfma_f32_16x16x32_bf16 v[36:39], v[226:229], v[194:197], v[36:39]
	v_mfma_f32_16x16x32_bf16 v[32:35], v[234:237], v[194:197], v[32:35]
	v_mfma_f32_16x16x32_bf16 v[20:23], v[226:229], v[202:205], v[20:23]
	v_mfma_f32_16x16x32_bf16 v[16:19], v[234:237], v[202:205], v[16:19]
	v_mfma_f32_16x16x32_bf16 v[4:7], v[226:229], v[210:213], v[4:7]
	v_mfma_f32_16x16x32_bf16 v[0:3], v[234:237], v[210:213], v[0:3]
	v_mfma_f32_16x16x32_bf16 v[52:55], v[230:233], v[190:193], v[52:55]
	v_mfma_f32_16x16x32_bf16 v[48:51], v[238:241], v[190:193], v[48:51]
	v_mfma_f32_16x16x32_bf16 v[36:39], v[230:233], v[198:201], v[36:39]
	v_mfma_f32_16x16x32_bf16 v[32:35], v[238:241], v[198:201], v[32:35]
	s_add_i32 s38, s38, 2
	s_add_u32 s18, s18, 0x100
	s_addc_u32 s19, s19, 0
	s_add_u32 s33, s33, 0x100
	s_addc_u32 s37, s37, 0
	s_cmp_gt_u32 s38, 29
	v_mfma_f32_16x16x32_bf16 v[20:23], v[230:233], v[206:209], v[20:23]
	v_mfma_f32_16x16x32_bf16 v[16:19], v[238:241], v[206:209], v[16:19]
	v_mfma_f32_16x16x32_bf16 v[4:7], v[230:233], v[214:217], v[4:7]
	v_mfma_f32_16x16x32_bf16 v[0:3], v[238:241], v[214:217], v[0:3]
	s_setprio 0
	s_barrier
	s_cbranch_scc0 .LBB0_37
	v_mul_f32_e32 v139, 0xbfb8aa3b, v124
	v_exp_f32_e32 v139, v139
	v_lshl_or_b32 v140, s2, 7, v136
	v_lshl_add_u32 v138, s3, 8, v134
	v_ashrrev_i32_e32 v141, 31, v140
	v_add_f32_e32 v139, 1.0, v139
	v_rcp_f32_e32 v142, v139
	v_mul_f32_e32 v139, 0xbfb8aa3b, v125
	v_exp_f32_e32 v139, v139
	s_movk_i32 s4, 0x2c00
	s_and_b64 vcc, exec, s[6:7]
	s_mov_b64 s[20:21], s[16:17]
	v_add_f32_e32 v139, 1.0, v139
	v_rcp_f32_e32 v143, v139
	v_mul_f32_e32 v139, 0xbfb8aa3b, v126
	v_exp_f32_e32 v139, v139
	s_mov_b64 s[18:19], s[14:15]
	v_pk_mul_f32 v[124:125], v[124:125], v[142:143]
	v_add_f32_e32 v139, 1.0, v139
	v_rcp_f32_e32 v144, v139
	v_mul_f32_e32 v139, 0xbfb8aa3b, v127
	v_exp_f32_e32 v139, v139
	v_pk_mul_f32 v[116:117], v[124:125], v[116:117]
	v_add_f32_e32 v139, 1.0, v139
	v_rcp_f32_e32 v145, v139
	v_mul_f32_e32 v139, 0xbfb8aa3b, v120
	v_exp_f32_e32 v139, v139
	v_cvt_pk_bf16_f32 v116, v116, v117
	v_pk_mul_f32 v[124:125], v[126:127], v[144:145]
	v_add_f32_e32 v139, 1.0, v139
	v_rcp_f32_e32 v146, v139
	v_mul_f32_e32 v139, 0xbfb8aa3b, v121
	v_exp_f32_e32 v139, v139
	v_pk_mul_f32 v[118:119], v[124:125], v[118:119]
	v_add_f32_e32 v139, 1.0, v139
	v_rcp_f32_e32 v147, v139
	v_mul_f32_e32 v139, 0xbfb8aa3b, v122
	v_exp_f32_e32 v139, v139
	v_cvt_pk_bf16_f32 v117, v118, v119
	v_pk_mul_f32 v[118:119], v[120:121], v[146:147]
	v_add_f32_e32 v139, 1.0, v139
	v_rcp_f32_e32 v148, v139
	v_mul_f32_e32 v139, 0xbfb8aa3b, v123
	v_exp_f32_e32 v139, v139
	v_pk_mul_f32 v[112:113], v[118:119], v[112:113]
	v_add_f32_e32 v139, 1.0, v139
	v_rcp_f32_e32 v149, v139
	v_cvt_pk_bf16_f32 v118, v112, v113
	v_pk_mul_f32 v[112:113], v[122:123], v[148:149]
	s_nop 0
	v_pk_mul_f32 v[112:113], v[112:113], v[114:115]
	v_lshlrev_b64 v[114:115], 1, v[140:141]
	v_cvt_pk_bf16_f32 v119, v112, v113
	v_mov_b64_e32 v[112:113], s[54:55]
	v_mad_i64_i32 v[120:121], s[2:3], v138, s4, v[112:113]
	v_lshl_add_u64 v[120:121], v[120:121], 0, v[114:115]
	global_store_dwordx4 v[120:121], v[116:119], off
	v_mul_f32_e32 v120, 0xbfb8aa3b, v104
	v_mul_f32_e32 v121, 0xbfb8aa3b, v105
	v_mul_f32_e32 v116, 0xbfb8aa3b, v108
	v_mul_f32_e32 v117, 0xbfb8aa3b, v109
	v_exp_f32_e32 v116, v116
	v_exp_f32_e32 v117, v117
	v_mul_f32_e32 v118, 0xbfb8aa3b, v110
	v_mul_f32_e32 v119, 0xbfb8aa3b, v111
	v_exp_f32_e32 v118, v118
	v_exp_f32_e32 v119, v119
	v_exp_f32_e32 v120, v120
	v_exp_f32_e32 v121, v121
	v_add_f32_e32 v116, 1.0, v116
	v_add_f32_e32 v117, 1.0, v117
	v_mul_f32_e32 v122, 0xbfb8aa3b, v106
	v_mul_f32_e32 v123, 0xbfb8aa3b, v107
	v_rcp_f32_e32 v116, v116
	v_rcp_f32_e32 v117, v117
	v_add_f32_e32 v118, 1.0, v118
	v_add_f32_e32 v119, 1.0, v119
	v_exp_f32_e32 v122, v122
	v_exp_f32_e32 v123, v123
	v_rcp_f32_e32 v118, v118
	v_rcp_f32_e32 v119, v119
	v_add_f32_e32 v120, 1.0, v120
	v_add_f32_e32 v121, 1.0, v121
	v_rcp_f32_e32 v120, v120
	v_rcp_f32_e32 v121, v121
	v_add_f32_e32 v122, 1.0, v122
;     DI void operator()(const f32x4 (&acc)[2][2][4][2], const Unit& u, int wr, int wc, int fr, int fq) const {
;     ...
;             for (int m = 0; m < 4; ++m) { float hv[8];
; #pragma unroll
;                 for (int n = 0; n < 2; ++n)
; #pragma unroll
;                     for (int e = 0; e < 4; ++e) { const float gt = acc[ai][0][m][n][e], up = acc[ai][1][m][n][e];
;                         hv[n * 4 + e] = gt * __builtin_amdgcn_rcpf(1.f + __builtin_amdgcn_exp2f(-1.4426950408889634f * gt)) * up; }
;                 *(u32x4*)(H + (size_t)(row0 + ai * HALF + m * 16) * DFF + col0) = (u32x4){pk(hv[0], hv[1]), pk(hv[2], hv[3]), pk(hv[4], hv[5]), pk(hv[6], hv[7])}; }
	v_add_f32_e32 v123, 1.0, v123
	v_pk_mul_f32 v[108:109], v[108:109], v[116:117]
	v_rcp_f32_e32 v122, v122
	v_rcp_f32_e32 v123, v123
	v_pk_mul_f32 v[100:101], v[108:109], v[100:101]
	v_pk_mul_f32 v[108:109], v[110:111], v[118:119]
	v_cvt_pk_bf16_f32 v100, v100, v101
	v_pk_mul_f32 v[102:103], v[108:109], v[102:103]
	s_nop 0
	v_cvt_pk_bf16_f32 v101, v102, v103
	v_pk_mul_f32 v[102:103], v[104:105], v[120:121]
	s_nop 0
	v_pk_mul_f32 v[96:97], v[102:103], v[96:97]
	s_nop 0
	v_cvt_pk_bf16_f32 v102, v96, v97
	v_pk_mul_f32 v[96:97], v[106:107], v[122:123]
	s_nop 0
	v_pk_mul_f32 v[96:97], v[96:97], v[98:99]
	v_mul_f32_e32 v98, 0xbfb8aa3b, v94
	v_cvt_pk_bf16_f32 v103, v96, v97
	v_or_b32_e32 v96, 16, v138
	v_mad_i64_i32 v[96:97], s[2:3], v96, s4, v[112:113]
	v_lshl_add_u64 v[96:97], v[96:97], 0, v[114:115]
	global_store_dwordx4 v[96:97], v[100:103], off
	v_mul_f32_e32 v96, 0xbfb8aa3b, v92
	v_mul_f32_e32 v97, 0xbfb8aa3b, v93
	v_exp_f32_e32 v96, v96
	v_exp_f32_e32 v97, v97
	v_mul_f32_e32 v99, 0xbfb8aa3b, v95
	v_exp_f32_e32 v98, v98
	v_exp_f32_e32 v99, v99
	v_mul_f32_e32 v100, 0xbfb8aa3b, v88
	v_mul_f32_e32 v101, 0xbfb8aa3b, v89
	v_exp_f32_e32 v100, v100
	v_exp_f32_e32 v101, v101
	v_add_f32_e32 v96, 1.0, v96
	v_add_f32_e32 v97, 1.0, v97
	v_mul_f32_e32 v102, 0xbfb8aa3b, v90
	v_mul_f32_e32 v103, 0xbfb8aa3b, v91
	v_rcp_f32_e32 v96, v96
	v_rcp_f32_e32 v97, v97
	v_add_f32_e32 v98, 1.0, v98
	v_add_f32_e32 v99, 1.0, v99
	v_exp_f32_e32 v102, v102
	v_exp_f32_e32 v103, v103
	v_rcp_f32_e32 v98, v98
	v_rcp_f32_e32 v99, v99
	v_add_f32_e32 v100, 1.0, v100
	v_add_f32_e32 v101, 1.0, v101
	v_rcp_f32_e32 v100, v100
	v_rcp_f32_e32 v101, v101
	v_add_f32_e32 v102, 1.0, v102
	v_add_f32_e32 v103, 1.0, v103
	v_pk_mul_f32 v[92:93], v[92:93], v[96:97]
	v_rcp_f32_e32 v102, v102
	v_rcp_f32_e32 v103, v103
	v_pk_mul_f32 v[84:85], v[92:93], v[84:85]
	v_pk_mul_f32 v[92:93], v[94:95], v[98:99]
	v_cvt_pk_bf16_f32 v84, v84, v85
	v_pk_mul_f32 v[86:87], v[92:93], v[86:87]
	s_nop 0
	v_cvt_pk_bf16_f32 v85, v86, v87
	v_pk_mul_f32 v[86:87], v[88:89], v[100:101]
	s_nop 0
	v_pk_mul_f32 v[80:81], v[86:87], v[80:81]
	s_nop 0
	v_cvt_pk_bf16_f32 v86, v80, v81
	v_pk_mul_f32 v[80:81], v[90:91], v[102:103]
	s_nop 0
	v_pk_mul_f32 v[80:81], v[80:81], v[82:83]
	v_mul_f32_e32 v82, 0xbfb8aa3b, v78
	v_cvt_pk_bf16_f32 v87, v80, v81
	v_or_b32_e32 v80, 32, v138
	v_mad_i64_i32 v[80:81], s[2:3], v80, s4, v[112:113]
	v_lshl_add_u64 v[80:81], v[80:81], 0, v[114:115]
	global_store_dwordx4 v[80:81], v[84:87], off
	v_mul_f32_e32 v80, 0xbfb8aa3b, v76
	v_mul_f32_e32 v81, 0xbfb8aa3b, v77
	v_exp_f32_e32 v80, v80
	v_exp_f32_e32 v81, v81
	v_mul_f32_e32 v83, 0xbfb8aa3b, v79
	v_exp_f32_e32 v82, v82
	v_exp_f32_e32 v83, v83
	v_mul_f32_e32 v84, 0xbfb8aa3b, v72
	v_mul_f32_e32 v85, 0xbfb8aa3b, v73
	v_exp_f32_e32 v84, v84
	v_exp_f32_e32 v85, v85
	v_add_f32_e32 v80, 1.0, v80
	v_add_f32_e32 v81, 1.0, v81
	v_mul_f32_e32 v86, 0xbfb8aa3b, v74
	v_mul_f32_e32 v87, 0xbfb8aa3b, v75
	v_rcp_f32_e32 v80, v80
	v_rcp_f32_e32 v81, v81
	v_add_f32_e32 v82, 1.0, v82
	v_add_f32_e32 v83, 1.0, v83
	v_exp_f32_e32 v86, v86
	v_exp_f32_e32 v87, v87
	v_rcp_f32_e32 v82, v82
	v_rcp_f32_e32 v83, v83
	v_add_f32_e32 v84, 1.0, v84
	v_add_f32_e32 v85, 1.0, v85
	v_rcp_f32_e32 v84, v84
	v_rcp_f32_e32 v85, v85
	v_add_f32_e32 v86, 1.0, v86
	v_add_f32_e32 v87, 1.0, v87
	v_pk_mul_f32 v[76:77], v[76:77], v[80:81]
	v_rcp_f32_e32 v86, v86
	v_rcp_f32_e32 v87, v87
	v_pk_mul_f32 v[68:69], v[76:77], v[68:69]
	v_pk_mul_f32 v[76:77], v[78:79], v[82:83]
	v_cvt_pk_bf16_f32 v68, v68, v69
	v_pk_mul_f32 v[70:71], v[76:77], v[70:71]
	s_nop 0
	v_cvt_pk_bf16_f32 v69, v70, v71
	v_pk_mul_f32 v[70:71], v[72:73], v[84:85]
	v_add_u32_e32 v72, 0x80, v138
	v_pk_mul_f32 v[64:65], v[70:71], v[64:65]
	s_nop 0
	v_cvt_pk_bf16_f32 v70, v64, v65
	v_pk_mul_f32 v[64:65], v[74:75], v[86:87]
	s_nop 0
	v_pk_mul_f32 v[64:65], v[64:65], v[66:67]
	v_mul_f32_e32 v66, 0xbfb8aa3b, v62
	v_cvt_pk_bf16_f32 v71, v64, v65
	v_or_b32_e32 v64, 48, v138
	v_mad_i64_i32 v[64:65], s[2:3], v64, s4, v[112:113]
	v_lshl_add_u64 v[64:65], v[64:65], 0, v[114:115]
	global_store_dwordx4 v[64:65], v[68:71], off
	v_mul_f32_e32 v64, 0xbfb8aa3b, v60
	v_mul_f32_e32 v65, 0xbfb8aa3b, v61
	v_exp_f32_e32 v64, v64
	v_exp_f32_e32 v65, v65
	v_mul_f32_e32 v67, 0xbfb8aa3b, v63
	v_exp_f32_e32 v66, v66
	v_exp_f32_e32 v67, v67
	v_mul_f32_e32 v68, 0xbfb8aa3b, v56
	v_mul_f32_e32 v69, 0xbfb8aa3b, v57
	v_exp_f32_e32 v68, v68
	v_exp_f32_e32 v69, v69
	v_add_f32_e32 v64, 1.0, v64
	v_add_f32_e32 v65, 1.0, v65
	v_mul_f32_e32 v70, 0xbfb8aa3b, v58
	v_mul_f32_e32 v71, 0xbfb8aa3b, v59
	v_rcp_f32_e32 v64, v64
	v_rcp_f32_e32 v65, v65
	v_add_f32_e32 v66, 1.0, v66
	v_add_f32_e32 v67, 1.0, v67
	v_exp_f32_e32 v70, v70
	v_exp_f32_e32 v71, v71
	v_rcp_f32_e32 v66, v66
	v_rcp_f32_e32 v67, v67
	v_add_f32_e32 v68, 1.0, v68
	v_add_f32_e32 v69, 1.0, v69
	v_rcp_f32_e32 v68, v68
	v_rcp_f32_e32 v69, v69
	v_add_f32_e32 v70, 1.0, v70
	v_add_f32_e32 v71, 1.0, v71
	v_pk_mul_f32 v[60:61], v[60:61], v[64:65]
	v_rcp_f32_e32 v70, v70
	v_rcp_f32_e32 v71, v71
	v_pk_mul_f32 v[52:53], v[60:61], v[52:53]
	v_pk_mul_f32 v[60:61], v[62:63], v[66:67]
	v_cvt_pk_bf16_f32 v52, v52, v53
	v_pk_mul_f32 v[54:55], v[60:61], v[54:55]
	s_nop 0
	v_cvt_pk_bf16_f32 v53, v54, v55
	v_pk_mul_f32 v[54:55], v[56:57], v[68:69]
; #define PG8_WAIT_V(n) asm volatile("s_waitcnt vmcnt(" #n ")" ::: "memory")
; #define PG8_BAR __builtin_amdgcn_s_barrier()
; template <class Epi>
; DI void gemm_phase(LAS unsigned char* lds, const Gemm g, const StaticOrder& S, const Epi& E) {
;     ...
;         if (!has_next) break;
; #pragma unroll
;         for (int a = 0; a < 2; ++a)
; #pragma unroll
;             for (int b = 0; b < 2; ++b)
; #pragma unroll
;                 for (int m = 0; m < 4; ++m)
; #pragma unroll
;                     for (int n = 0; n < 2; ++n) acc[a][b][m][n] = (f32x4){0.f, 0.f, 0.f, 0.f};
;         cur = nxt; cA = nA; cB = nB; ++ui;
;     }
;     PG8_WAIT_V(0);
;     if (wr == 0) PG8_BAR;
;     PG8_BAR;
;     DI void operator()(const f32x4 (&acc)[2][2][4][2], const Unit& u, int wr, int wc, int fr, int fq) const {
;     ...
;             for (int m = 0; m < 4; ++m) { float hv[8];
; #pragma unroll
;                 for (int n = 0; n < 2; ++n)
; #pragma unroll
;                     for (int e = 0; e < 4; ++e) { const float gt = acc[ai][0][m][n][e], up = acc[ai][1][m][n][e];
;                         hv[n * 4 + e] = gt * __builtin_amdgcn_rcpf(1.f + __builtin_amdgcn_exp2f(-1.4426950408889634f * gt)) * up; }
;                 *(u32x4*)(H + (size_t)(row0 + ai * HALF + m * 16) * DFF + col0) = (u32x4){pk(hv[0], hv[1]), pk(hv[2], hv[3]), pk(hv[4], hv[5]), pk(hv[6], hv[7])}; }
	s_nop 0
	v_pk_mul_f32 v[48:49], v[54:55], v[48:49]
	s_nop 0
	v_cvt_pk_bf16_f32 v54, v48, v49
	v_pk_mul_f32 v[48:49], v[58:59], v[70:71]
	s_nop 0
	v_pk_mul_f32 v[48:49], v[48:49], v[50:51]
	v_mul_f32_e32 v50, 0xbfb8aa3b, v46
	v_cvt_pk_bf16_f32 v55, v48, v49
	v_mad_i64_i32 v[48:49], s[2:3], v72, s4, v[112:113]
	v_lshl_add_u64 v[48:49], v[48:49], 0, v[114:115]
	global_store_dwordx4 v[48:49], v[52:55], off
	v_mul_f32_e32 v48, 0xbfb8aa3b, v44
	v_mul_f32_e32 v49, 0xbfb8aa3b, v45
	v_exp_f32_e32 v48, v48
	v_exp_f32_e32 v49, v49
	v_mul_f32_e32 v51, 0xbfb8aa3b, v47
	v_exp_f32_e32 v50, v50
	v_exp_f32_e32 v51, v51
	v_mul_f32_e32 v52, 0xbfb8aa3b, v40
	v_mul_f32_e32 v53, 0xbfb8aa3b, v41
	v_exp_f32_e32 v52, v52
	v_exp_f32_e32 v53, v53
	v_add_f32_e32 v48, 1.0, v48
	v_add_f32_e32 v49, 1.0, v49
	v_mul_f32_e32 v54, 0xbfb8aa3b, v42
	v_mul_f32_e32 v55, 0xbfb8aa3b, v43
	v_rcp_f32_e32 v48, v48
	v_rcp_f32_e32 v49, v49
	v_add_f32_e32 v50, 1.0, v50
	v_add_f32_e32 v51, 1.0, v51
	v_exp_f32_e32 v54, v54
	v_exp_f32_e32 v55, v55
	v_rcp_f32_e32 v50, v50
	v_rcp_f32_e32 v51, v51
	v_add_f32_e32 v52, 1.0, v52
	v_add_f32_e32 v53, 1.0, v53
	v_rcp_f32_e32 v52, v52
	v_rcp_f32_e32 v53, v53
	v_add_f32_e32 v54, 1.0, v54
	v_add_f32_e32 v55, 1.0, v55
	v_pk_mul_f32 v[44:45], v[44:45], v[48:49]
	v_rcp_f32_e32 v54, v54
	v_rcp_f32_e32 v55, v55
	v_pk_mul_f32 v[36:37], v[44:45], v[36:37]
	v_pk_mul_f32 v[44:45], v[46:47], v[50:51]
	v_cvt_pk_bf16_f32 v36, v36, v37
	v_pk_mul_f32 v[38:39], v[44:45], v[38:39]
	s_nop 0
	v_cvt_pk_bf16_f32 v37, v38, v39
	v_pk_mul_f32 v[38:39], v[40:41], v[52:53]
	s_nop 0
	v_pk_mul_f32 v[32:33], v[38:39], v[32:33]
	s_nop 0
	v_cvt_pk_bf16_f32 v38, v32, v33
	v_pk_mul_f32 v[32:33], v[42:43], v[54:55]
	s_nop 0
	v_pk_mul_f32 v[32:33], v[32:33], v[34:35]
	v_mul_f32_e32 v34, 0xbfb8aa3b, v30
	v_cvt_pk_bf16_f32 v39, v32, v33
	v_add_u32_e32 v32, 0x90, v138
	v_mad_i64_i32 v[32:33], s[2:3], v32, s4, v[112:113]
	v_lshl_add_u64 v[32:33], v[32:33], 0, v[114:115]
	global_store_dwordx4 v[32:33], v[36:39], off
	v_mul_f32_e32 v32, 0xbfb8aa3b, v28
	v_mul_f32_e32 v33, 0xbfb8aa3b, v29
	v_exp_f32_e32 v32, v32
	v_exp_f32_e32 v33, v33
	v_mul_f32_e32 v35, 0xbfb8aa3b, v31
	v_exp_f32_e32 v34, v34
	v_exp_f32_e32 v35, v35
	v_mul_f32_e32 v36, 0xbfb8aa3b, v24
	v_mul_f32_e32 v37, 0xbfb8aa3b, v25
	v_exp_f32_e32 v36, v36
	v_exp_f32_e32 v37, v37
	v_add_f32_e32 v32, 1.0, v32
	v_add_f32_e32 v33, 1.0, v33
	v_mul_f32_e32 v38, 0xbfb8aa3b, v26
	v_mul_f32_e32 v39, 0xbfb8aa3b, v27
	v_rcp_f32_e32 v32, v32
	v_rcp_f32_e32 v33, v33
	v_add_f32_e32 v34, 1.0, v34
	v_add_f32_e32 v35, 1.0, v35
	v_exp_f32_e32 v38, v38
	v_exp_f32_e32 v39, v39
	v_rcp_f32_e32 v34, v34
	v_rcp_f32_e32 v35, v35
	v_add_f32_e32 v36, 1.0, v36
	v_add_f32_e32 v37, 1.0, v37
	v_rcp_f32_e32 v36, v36
	v_rcp_f32_e32 v37, v37
	v_add_f32_e32 v38, 1.0, v38
	v_add_f32_e32 v39, 1.0, v39
	v_pk_mul_f32 v[28:29], v[28:29], v[32:33]
	v_rcp_f32_e32 v38, v38
	v_rcp_f32_e32 v39, v39
	v_pk_mul_f32 v[20:21], v[28:29], v[20:21]
	v_pk_mul_f32 v[28:29], v[30:31], v[34:35]
	v_cvt_pk_bf16_f32 v20, v20, v21
	v_pk_mul_f32 v[22:23], v[28:29], v[22:23]
	s_nop 0
	v_cvt_pk_bf16_f32 v21, v22, v23
	v_pk_mul_f32 v[22:23], v[24:25], v[36:37]
	s_nop 0
	v_pk_mul_f32 v[16:17], v[22:23], v[16:17]
	s_nop 0
	v_cvt_pk_bf16_f32 v22, v16, v17
	v_pk_mul_f32 v[16:17], v[26:27], v[38:39]
	s_nop 0
	v_pk_mul_f32 v[16:17], v[16:17], v[18:19]
	v_mul_f32_e32 v18, 0xbfb8aa3b, v14
	v_cvt_pk_bf16_f32 v23, v16, v17
	v_add_u32_e32 v16, 0xa0, v138
	v_mad_i64_i32 v[16:17], s[2:3], v16, s4, v[112:113]
	v_lshl_add_u64 v[16:17], v[16:17], 0, v[114:115]
	global_store_dwordx4 v[16:17], v[20:23], off
	v_mul_f32_e32 v16, 0xbfb8aa3b, v12
	v_mul_f32_e32 v17, 0xbfb8aa3b, v13
	v_exp_f32_e32 v16, v16
	v_exp_f32_e32 v17, v17
	v_mul_f32_e32 v19, 0xbfb8aa3b, v15
	v_exp_f32_e32 v18, v18
	v_exp_f32_e32 v19, v19
	v_mul_f32_e32 v20, 0xbfb8aa3b, v8
	v_mul_f32_e32 v21, 0xbfb8aa3b, v9
	v_exp_f32_e32 v20, v20
	v_exp_f32_e32 v21, v21
	v_add_f32_e32 v16, 1.0, v16
	v_add_f32_e32 v17, 1.0, v17
	v_mul_f32_e32 v22, 0xbfb8aa3b, v10
	v_mul_f32_e32 v23, 0xbfb8aa3b, v11
	v_rcp_f32_e32 v16, v16
	v_rcp_f32_e32 v17, v17
	v_add_f32_e32 v18, 1.0, v18
	v_add_f32_e32 v19, 1.0, v19
	v_exp_f32_e32 v22, v22
	v_exp_f32_e32 v23, v23
	v_rcp_f32_e32 v18, v18
	v_rcp_f32_e32 v19, v19
	v_add_f32_e32 v20, 1.0, v20
	v_add_f32_e32 v21, 1.0, v21
	v_rcp_f32_e32 v20, v20
	v_rcp_f32_e32 v21, v21
	v_add_f32_e32 v22, 1.0, v22
	v_add_f32_e32 v23, 1.0, v23
	v_pk_mul_f32 v[12:13], v[12:13], v[16:17]
	v_rcp_f32_e32 v22, v22
	v_rcp_f32_e32 v23, v23
	v_pk_mul_f32 v[4:5], v[12:13], v[4:5]
	v_pk_mul_f32 v[12:13], v[14:15], v[18:19]
	v_cvt_pk_bf16_f32 v4, v4, v5
	v_pk_mul_f32 v[6:7], v[12:13], v[6:7]
	s_nop 0
	v_cvt_pk_bf16_f32 v5, v6, v7
	v_pk_mul_f32 v[6:7], v[8:9], v[20:21]
	s_nop 0
	v_pk_mul_f32 v[0:1], v[6:7], v[0:1]
	s_nop 0
	v_cvt_pk_bf16_f32 v6, v0, v1
	v_pk_mul_f32 v[0:1], v[10:11], v[22:23]
	s_nop 0
	v_pk_mul_f32 v[0:1], v[0:1], v[2:3]
	s_nop 0
	v_cvt_pk_bf16_f32 v7, v0, v1
	v_add_u32_e32 v0, 0xb0, v138
	v_mad_i64_i32 v[0:1], s[2:3], v0, s4, v[112:113]
	v_lshl_add_u64 v[0:1], v[0:1], 0, v[114:115]
	s_mov_b32 s2, s8
	s_mov_b32 s3, s10
	global_store_dwordx4 v[0:1], v[4:7], off
	s_cbranch_vccz .LBB0_34
	s_waitcnt vmcnt(0)
	s_cmpk_gt_u32 s24, 0xff
	s_cbranch_scc1 .LBB0_41
	s_barrier

; #define PG8_STAGE(bufoff, gbase) do { _Pragma("unroll") for (int _i = 0; _i < 2; ++_i) \
;         __builtin_amdgcn_global_load_lds((const unsigned*)((const char*)(gbase) + voff[_i]), (LAS unsigned*)(lds + (bufoff) + ldsw + _i * 8192), 16, 0, 0); } while (0)
; #define PG8_LDA(dst, b, h) do { _Pragma("unroll") for (int m = 0; m < 4; ++m) _Pragma("unroll") for (int k = 0; k < 2; ++k) dst[m][k] = *(const LAS bf16x8*)(lds + PG8_SA(b, h) + aoff + m * 2048 + k * 1024); } while (0)
; #define PG8_LDB(dst, b, h) do { _Pragma("unroll") for (int n = 0; n < 2; ++n) _Pragma("unroll") for (int k = 0; k < 2; ++k) dst[n][k] = *(const LAS bf16x8*)(lds + PG8_SB(b, h) + boff + n * 2048 + k * 1024); } while (0)
; #define PG8_MMA(ai, bj, At, Bt) do { __builtin_amdgcn_s_setprio(1); _Pragma("unroll") for (int m = 0; m < 4; ++m) _Pragma("unroll") for (int n = 0; n < 2; ++n) _Pragma("unroll") for (int k = 0; k < 2; ++k) \
;         acc[ai][bj][m][n] = __builtin_amdgcn_mfma_f32_16x16x32_bf16(Bt[n][k], At[m][k], acc[ai][bj][m][n], 0, 0, 0); __builtin_amdgcn_s_setprio(0); } while (0)
; #define PG8_WAIT_L(n) asm volatile("s_waitcnt lgkmcnt(" #n ")" ::: "memory")
; #define PG8_BAR __builtin_amdgcn_s_barrier()
; #define PG8_SCHED __builtin_amdgcn_sched_barrier(0)
; template <class Epi>
; DI void gemm_phase(LAS unsigned char* lds, const Gemm g, const StaticOrder& S, const Epi& E) {
;     ...
;         for (int t = 0; t < nt; t += 2) {
;             const bool last = (t == nt - 2);
;             const char* a1 = cA + (size_t)(t + 1) * kstep;
;             const char* a2 = last ? nA : cA + (size_t)(t + 2) * kstep; const char* b2 = last ? nB : cB + (size_t)(t + 2) * kstep;
;             const char* a3 = a2 + kstep; const char* b3 = b2 + kstep;
;             PG8_LDB(B0, 0, 0); PG8_SCHED; PG8_LDA(At, 0, 0); PG8_STAGE(PG8_SA(1, 1), a1 + hstep);
;             PG8_WAIT_L(8); PG8_BAR; PG8_WAIT_L(0); PG8_MMA(0, 0, At, B0); PG8_BAR; PG8_SCHED;
;             PG8_LDB(B1, 0, 1); PG8_STAGE(PG8_SB(0, 0), b2);
;             PG8_BAR; PG8_WAIT_L(0); PG8_MMA(0, 1, At, B1); PG8_BAR;
;             PG8_LDA(At, 0, 1); PG8_STAGE(PG8_SA(0, 0), a2);
;             PG8_BAR; PG8_WAIT_L(0); PG8_MMA(1, 0, At, B0); PG8_BAR; PG8_SCHED;
.LBB0_77:
	s_add_u32 s22, s20, 0x100
	s_addc_u32 s23, s21, 0
	s_add_i32 s43, 0, 0x10000
	v_add_u32_e32 v140, s43, v226
	ds_read_b128 v[128:131], v140
	ds_read_b128 v[132:135], v140 offset:1024
	ds_read_b128 v[136:139], v140 offset:2048
	ds_read_b128 v[140:143], v140 offset:3072
	s_cmp_eq_u32 s33, 32
	s_cselect_b32 s27, s9, s23
	s_cselect_b32 s26, s8, s22
	s_cselect_b32 s25, s11, s5
	s_cselect_b32 s24, s10, s4
	v_lshl_add_u64 v[214:215], s[20:21], 0, v[190:191]
	s_add_i32 m0, s34, 0xc000
	ds_read_b128 v[144:147], v228
	ds_read_b128 v[148:151], v228 offset:1024
	ds_read_b128 v[152:155], v228 offset:2048
	ds_read_b128 v[194:197], v228 offset:3072
	ds_read_b128 v[198:201], v228 offset:4096
	ds_read_b128 v[202:205], v228 offset:5120
	ds_read_b128 v[206:209], v228 offset:6144
	ds_read_b128 v[210:213], v228 offset:7168
	global_load_lds_dwordx4 v[214:215], off
	v_lshl_add_u64 v[214:215], s[20:21], 0, v[192:193]
	s_add_i32 m0, s34, 0xe000
	s_nop 0
	global_load_lds_dwordx4 v[214:215], off
	s_waitcnt lgkmcnt(8)
	s_setprio 1
	s_barrier
	s_waitcnt lgkmcnt(0)
	v_mfma_f32_16x16x32_bf16 v[124:127], v[128:131], v[144:147], v[124:127]
	v_mfma_f32_16x16x32_bf16 v[120:123], v[136:139], v[144:147], v[120:123]
	v_mfma_f32_16x16x32_bf16 v[116:119], v[128:131], v[152:155], v[116:119]
	v_mfma_f32_16x16x32_bf16 v[112:115], v[136:139], v[152:155], v[112:115]
	v_mfma_f32_16x16x32_bf16 v[108:111], v[128:131], v[198:201], v[108:111]
	v_mfma_f32_16x16x32_bf16 v[104:107], v[136:139], v[198:201], v[104:107]
	v_mfma_f32_16x16x32_bf16 v[100:103], v[128:131], v[206:209], v[100:103]
	v_mfma_f32_16x16x32_bf16 v[96:99], v[136:139], v[206:209], v[96:99]
	v_mfma_f32_16x16x32_bf16 v[124:127], v[132:135], v[148:151], v[124:127]
	v_mfma_f32_16x16x32_bf16 v[120:123], v[140:143], v[148:151], v[120:123]
	v_mfma_f32_16x16x32_bf16 v[116:119], v[132:135], v[194:197], v[116:119]
	v_mfma_f32_16x16x32_bf16 v[112:115], v[140:143], v[194:197], v[112:115]
	v_mfma_f32_16x16x32_bf16 v[108:111], v[132:135], v[202:205], v[108:111]
	v_mfma_f32_16x16x32_bf16 v[104:107], v[140:143], v[202:205], v[104:107]
	v_mfma_f32_16x16x32_bf16 v[100:103], v[132:135], v[210:213], v[100:103]
	v_mfma_f32_16x16x32_bf16 v[96:99], v[140:143], v[210:213], v[96:99]
	s_setprio 0
	s_barrier
	s_add_i32 s44, 0, 0x14000
	s_add_i32 s20, s43, s31
	v_add_u32_e32 v158, s44, v226
	v_lshl_add_u64 v[218:219], s[24:25], 0, v[188:189]
	s_mov_b32 m0, s20
	ds_read_b128 v[214:217], v158
	ds_read_b128 v[230:233], v158 offset:1024
	ds_read_b128 v[234:237], v158 offset:2048
	ds_read_b128 v[238:241], v158 offset:3072
	global_load_lds_dwordx4 v[218:219], off
	v_lshl_add_u64 v[220:221], s[24:25], 0, v[186:187]
	s_add_i32 m0, s20, 0x2000
	s_nop 0
	global_load_lds_dwordx4 v[220:221], off
	s_waitcnt lgkmcnt(0)
	s_setprio 1
	s_barrier
	v_mfma_f32_16x16x32_bf16 v[60:63], v[214:217], v[144:147], v[60:63]
	v_mfma_f32_16x16x32_bf16 v[56:59], v[234:237], v[144:147], v[56:59]
	v_mfma_f32_16x16x32_bf16 v[52:55], v[214:217], v[152:155], v[52:55]
	v_mfma_f32_16x16x32_bf16 v[48:51], v[234:237], v[152:155], v[48:51]
	v_mfma_f32_16x16x32_bf16 v[44:47], v[214:217], v[198:201], v[44:47]
	v_mfma_f32_16x16x32_bf16 v[40:43], v[234:237], v[198:201], v[40:43]
	v_mfma_f32_16x16x32_bf16 v[36:39], v[214:217], v[206:209], v[36:39]
	v_mfma_f32_16x16x32_bf16 v[32:35], v[234:237], v[206:209], v[32:35]
	v_mfma_f32_16x16x32_bf16 v[60:63], v[230:233], v[148:151], v[60:63]
	v_mfma_f32_16x16x32_bf16 v[56:59], v[238:241], v[148:151], v[56:59]
	v_mfma_f32_16x16x32_bf16 v[52:55], v[230:233], v[194:197], v[52:55]
	v_mfma_f32_16x16x32_bf16 v[48:51], v[238:241], v[194:197], v[48:51]
	s_mov_b32 m0, s34
	v_lshl_add_u64 v[242:243], s[26:27], 0, v[188:189]
	v_mfma_f32_16x16x32_bf16 v[44:47], v[230:233], v[202:205], v[44:47]
	v_mfma_f32_16x16x32_bf16 v[40:43], v[238:241], v[202:205], v[40:43]
	v_mfma_f32_16x16x32_bf16 v[36:39], v[230:233], v[210:213], v[36:39]
	v_mfma_f32_16x16x32_bf16 v[32:35], v[238:241], v[210:213], v[32:35]
	s_setprio 0
	s_barrier
	ds_read_b128 v[144:147], v228 offset:16384
	ds_read_b128 v[148:151], v228 offset:17408
	ds_read_b128 v[152:155], v228 offset:18432
	ds_read_b128 v[194:197], v228 offset:19456
	ds_read_b128 v[198:201], v228 offset:20480
	ds_read_b128 v[202:205], v228 offset:21504
	ds_read_b128 v[206:209], v228 offset:22528
	ds_read_b128 v[210:213], v228 offset:23552
	global_load_lds_dwordx4 v[242:243], off
	v_lshl_add_u64 v[244:245], s[26:27], 0, v[186:187]
	s_mov_b32 m0, s35
	s_nop 0
	global_load_lds_dwordx4 v[244:245], off
	s_waitcnt lgkmcnt(0)
	s_setprio 1
	s_barrier
	v_mfma_f32_16x16x32_bf16 v[92:95], v[128:131], v[144:147], v[92:95]
	v_mfma_f32_16x16x32_bf16 v[88:91], v[136:139], v[144:147], v[88:91]
	v_mfma_f32_16x16x32_bf16 v[84:87], v[128:131], v[152:155], v[84:87]
	v_mfma_f32_16x16x32_bf16 v[80:83], v[136:139], v[152:155], v[80:83]
	v_mfma_f32_16x16x32_bf16 v[76:79], v[128:131], v[198:201], v[76:79]
	v_mfma_f32_16x16x32_bf16 v[72:75], v[136:139], v[198:201], v[72:75]
	v_mfma_f32_16x16x32_bf16 v[68:71], v[128:131], v[206:209], v[68:71]
	v_mfma_f32_16x16x32_bf16 v[64:67], v[136:139], v[206:209], v[64:67]
	v_mfma_f32_16x16x32_bf16 v[92:95], v[132:135], v[148:151], v[92:95]
	v_mfma_f32_16x16x32_bf16 v[88:91], v[140:143], v[148:151], v[88:91]
	v_mfma_f32_16x16x32_bf16 v[84:87], v[132:135], v[194:197], v[84:87]
	v_mfma_f32_16x16x32_bf16 v[80:83], v[140:143], v[194:197], v[80:83]
	v_mfma_f32_16x16x32_bf16 v[76:79], v[132:135], v[202:205], v[76:79]
	v_mfma_f32_16x16x32_bf16 v[72:75], v[140:143], v[202:205], v[72:75]
	v_mfma_f32_16x16x32_bf16 v[68:71], v[132:135], v[210:213], v[68:71]
	v_mfma_f32_16x16x32_bf16 v[64:67], v[140:143], v[210:213], v[64:67]
	s_setprio 0
	s_barrier
; #define PG8_STAGE(bufoff, gbase) do { _Pragma("unroll") for (int _i = 0; _i < 2; ++_i) \
;         __builtin_amdgcn_global_load_lds((const unsigned*)((const char*)(gbase) + voff[_i]), (LAS unsigned*)(lds + (bufoff) + ldsw + _i * 8192), 16, 0, 0); } while (0)
; #define PG8_LDA(dst, b, h) do { _Pragma("unroll") for (int m = 0; m < 4; ++m) _Pragma("unroll") for (int k = 0; k < 2; ++k) dst[m][k] = *(const LAS bf16x8*)(lds + PG8_SA(b, h) + aoff + m * 2048 + k * 1024); } while (0)
; #define PG8_LDB(dst, b, h) do { _Pragma("unroll") for (int n = 0; n < 2; ++n) _Pragma("unroll") for (int k = 0; k < 2; ++k) dst[n][k] = *(const LAS bf16x8*)(lds + PG8_SB(b, h) + boff + n * 2048 + k * 1024); } while (0)
; #define PG8_MMA(ai, bj, At, Bt) do { __builtin_amdgcn_s_setprio(1); _Pragma("unroll") for (int m = 0; m < 4; ++m) _Pragma("unroll") for (int n = 0; n < 2; ++n) _Pragma("unroll") for (int k = 0; k < 2; ++k) \
;         acc[ai][bj][m][n] = __builtin_amdgcn_mfma_f32_16x16x32_bf16(Bt[n][k], At[m][k], acc[ai][bj][m][n], 0, 0, 0); __builtin_amdgcn_s_setprio(0); } while (0)
; #define PG8_WAIT_V(n) asm volatile("s_waitcnt vmcnt(" #n ")" ::: "memory")
; #define PG8_WAIT_L(n) asm volatile("s_waitcnt lgkmcnt(" #n ")" ::: "memory")
; #define PG8_BAR __builtin_amdgcn_s_barrier()
; #define PG8_SCHED __builtin_amdgcn_sched_barrier(0)
; template <class Epi>
; DI void gemm_phase(LAS unsigned char* lds, const Gemm g, const StaticOrder& S, const Epi& E) {
;     ...
;             PG8_STAGE(PG8_SB(0, 1), b2 + hstep);
;             PG8_WAIT_V(6); PG8_BAR; PG8_MMA(1, 1, At, B1); PG8_BAR;
;             PG8_LDB(B0, 1, 0); PG8_SCHED; PG8_LDA(At, 1, 0); PG8_STAGE(PG8_SA(0, 1), a2 + hstep);
;             PG8_WAIT_L(8); PG8_BAR; PG8_WAIT_L(0); PG8_MMA(0, 0, At, B0); PG8_BAR; PG8_SCHED;
;             PG8_LDB(B1, 1, 1); PG8_STAGE(PG8_SB(1, 0), b3);
;             PG8_BAR; PG8_WAIT_L(0); PG8_MMA(0, 1, At, B1); PG8_BAR;
;             PG8_LDA(At, 1, 1); PG8_STAGE(PG8_SA(1, 0), a3);
;             PG8_BAR; PG8_WAIT_L(0); PG8_MMA(1, 0, At, B0); PG8_BAR; PG8_SCHED;
	s_add_u32 s20, s24, 0x90000
	s_addc_u32 s21, s25, 0
	s_add_i32 s43, s44, s31
	v_lshl_add_u64 v[128:129], s[20:21], 0, v[188:189]
	s_mov_b32 m0, s43
	s_nop 0
	global_load_lds_dwordx4 v[128:129], off
	v_lshl_add_u64 v[128:129], s[20:21], 0, v[186:187]
	s_add_i32 m0, s43, 0x2000
	s_nop 0
	global_load_lds_dwordx4 v[128:129], off
	s_waitcnt vmcnt(6)
	s_setprio 1
	s_barrier
	v_mfma_f32_16x16x32_bf16 v[28:31], v[214:217], v[144:147], v[28:31]
	v_mfma_f32_16x16x32_bf16 v[24:27], v[234:237], v[144:147], v[24:27]
	v_mfma_f32_16x16x32_bf16 v[20:23], v[214:217], v[152:155], v[20:23]
	v_mfma_f32_16x16x32_bf16 v[16:19], v[234:237], v[152:155], v[16:19]
	v_mfma_f32_16x16x32_bf16 v[12:15], v[214:217], v[198:201], v[12:15]
	v_mfma_f32_16x16x32_bf16 v[8:11], v[234:237], v[198:201], v[8:11]
	v_mfma_f32_16x16x32_bf16 v[4:7], v[214:217], v[206:209], v[4:7]
	v_mfma_f32_16x16x32_bf16 v[0:3], v[234:237], v[206:209], v[0:3]
	v_mfma_f32_16x16x32_bf16 v[28:31], v[230:233], v[148:151], v[28:31]
	v_mfma_f32_16x16x32_bf16 v[24:27], v[238:241], v[148:151], v[24:27]
	v_mfma_f32_16x16x32_bf16 v[20:23], v[230:233], v[194:197], v[20:23]
	v_mfma_f32_16x16x32_bf16 v[16:19], v[238:241], v[194:197], v[16:19]
	s_add_i32 s43, 0, 0x18000
	v_add_u32_e32 v140, s43, v226
	v_mfma_f32_16x16x32_bf16 v[12:15], v[230:233], v[202:205], v[12:15]
	v_mfma_f32_16x16x32_bf16 v[8:11], v[238:241], v[202:205], v[8:11]
	v_mfma_f32_16x16x32_bf16 v[4:7], v[230:233], v[210:213], v[4:7]
	v_mfma_f32_16x16x32_bf16 v[0:3], v[238:241], v[210:213], v[0:3]
	s_setprio 0
	s_barrier
	ds_read_b128 v[128:131], v140
	ds_read_b128 v[132:135], v140 offset:1024
	ds_read_b128 v[136:139], v140 offset:2048
	ds_read_b128 v[140:143], v140 offset:3072
	s_add_u32 s20, s26, 0x90000
	s_addc_u32 s21, s27, 0
	s_mov_b32 m0, s36
	v_lshl_add_u64 v[214:215], s[20:21], 0, v[188:189]
	ds_read_b128 v[144:147], v228 offset:32768
	ds_read_b128 v[148:151], v228 offset:33792
	ds_read_b128 v[152:155], v228 offset:34816
	ds_read_b128 v[194:197], v228 offset:35840
	ds_read_b128 v[198:201], v228 offset:36864
	ds_read_b128 v[202:205], v228 offset:37888
	ds_read_b128 v[206:209], v228 offset:38912
	ds_read_b128 v[210:213], v228 offset:39936
	global_load_lds_dwordx4 v[214:215], off
	v_lshl_add_u64 v[214:215], s[20:21], 0, v[186:187]
	s_mov_b32 m0, s37
	s_nop 0
	global_load_lds_dwordx4 v[214:215], off
	s_waitcnt lgkmcnt(8)
	s_setprio 1
	s_barrier
	s_waitcnt lgkmcnt(0)
	v_mfma_f32_16x16x32_bf16 v[124:127], v[128:131], v[144:147], v[124:127]
	v_mfma_f32_16x16x32_bf16 v[120:123], v[136:139], v[144:147], v[120:123]
	v_mfma_f32_16x16x32_bf16 v[116:119], v[128:131], v[152:155], v[116:119]
	v_mfma_f32_16x16x32_bf16 v[112:115], v[136:139], v[152:155], v[112:115]
	v_mfma_f32_16x16x32_bf16 v[108:111], v[128:131], v[198:201], v[108:111]
	v_mfma_f32_16x16x32_bf16 v[104:107], v[136:139], v[198:201], v[104:107]
	v_mfma_f32_16x16x32_bf16 v[100:103], v[128:131], v[206:209], v[100:103]
	v_mfma_f32_16x16x32_bf16 v[96:99], v[136:139], v[206:209], v[96:99]
	v_mfma_f32_16x16x32_bf16 v[124:127], v[132:135], v[148:151], v[124:127]
	v_mfma_f32_16x16x32_bf16 v[120:123], v[140:143], v[148:151], v[120:123]
	v_mfma_f32_16x16x32_bf16 v[116:119], v[132:135], v[194:197], v[116:119]
	v_mfma_f32_16x16x32_bf16 v[112:115], v[140:143], v[194:197], v[112:115]
	v_mfma_f32_16x16x32_bf16 v[108:111], v[132:135], v[202:205], v[108:111]
	v_mfma_f32_16x16x32_bf16 v[104:107], v[140:143], v[202:205], v[104:107]
	v_mfma_f32_16x16x32_bf16 v[100:103], v[132:135], v[210:213], v[100:103]
	v_mfma_f32_16x16x32_bf16 v[96:99], v[140:143], v[210:213], v[96:99]
	s_setprio 0
	s_barrier
	s_add_i32 s26, 0, 0x1c000
	s_add_i32 s20, s43, s31
	v_add_u32_e32 v158, s26, v226
	v_lshl_add_u64 v[218:219], v[218:219], 0, s[94:95]
	s_mov_b32 m0, s20
	ds_read_b128 v[214:217], v158
	ds_read_b128 v[230:233], v158 offset:1024
	ds_read_b128 v[234:237], v158 offset:2048
	ds_read_b128 v[238:241], v158 offset:3072
	global_load_lds_dwordx4 v[218:219], off
	v_lshl_add_u64 v[218:219], v[220:221], 0, s[94:95]
	s_add_i32 m0, s20, 0x2000
	s_nop 0
	global_load_lds_dwordx4 v[218:219], off
	s_waitcnt lgkmcnt(0)
	s_setprio 1
	s_barrier
	v_mfma_f32_16x16x32_bf16 v[60:63], v[214:217], v[144:147], v[60:63]
	v_mfma_f32_16x16x32_bf16 v[56:59], v[234:237], v[144:147], v[56:59]
	v_mfma_f32_16x16x32_bf16 v[52:55], v[214:217], v[152:155], v[52:55]
	v_mfma_f32_16x16x32_bf16 v[48:51], v[234:237], v[152:155], v[48:51]
	v_mfma_f32_16x16x32_bf16 v[44:47], v[214:217], v[198:201], v[44:47]
	v_mfma_f32_16x16x32_bf16 v[40:43], v[234:237], v[198:201], v[40:43]
	v_mfma_f32_16x16x32_bf16 v[36:39], v[214:217], v[206:209], v[36:39]
	v_mfma_f32_16x16x32_bf16 v[32:35], v[234:237], v[206:209], v[32:35]
	v_mfma_f32_16x16x32_bf16 v[60:63], v[230:233], v[148:151], v[60:63]
	v_mfma_f32_16x16x32_bf16 v[56:59], v[238:241], v[148:151], v[56:59]
	v_mfma_f32_16x16x32_bf16 v[52:55], v[230:233], v[194:197], v[52:55]
	v_mfma_f32_16x16x32_bf16 v[48:51], v[238:241], v[194:197], v[48:51]
	s_mov_b32 m0, s38
	v_lshl_add_u64 v[218:219], v[242:243], 0, s[94:95]
	v_mfma_f32_16x16x32_bf16 v[44:47], v[230:233], v[202:205], v[44:47]
	v_mfma_f32_16x16x32_bf16 v[40:43], v[238:241], v[202:205], v[40:43]
	v_mfma_f32_16x16x32_bf16 v[36:39], v[230:233], v[210:213], v[36:39]
	v_mfma_f32_16x16x32_bf16 v[32:35], v[238:241], v[210:213], v[32:35]
	s_setprio 0
	s_barrier
	ds_read_b128 v[144:147], v228 offset:49152
	ds_read_b128 v[148:151], v228 offset:50176
	ds_read_b128 v[152:155], v228 offset:51200
	ds_read_b128 v[194:197], v228 offset:52224
	ds_read_b128 v[198:201], v228 offset:53248
	ds_read_b128 v[202:205], v228 offset:54272
	ds_read_b128 v[206:209], v228 offset:55296
	ds_read_b128 v[210:213], v228 offset:56320
	global_load_lds_dwordx4 v[218:219], off
	v_lshl_add_u64 v[218:219], v[244:245], 0, s[94:95]
	s_mov_b32 m0, s39
	s_nop 0
	global_load_lds_dwordx4 v[218:219], off
	s_waitcnt lgkmcnt(0)
	s_setprio 1
	s_barrier
; template <class Epi>
; DI void gemm_phase(LAS unsigned char* lds, const Gemm g, const StaticOrder& S, const Epi& E) {
;     ...
;             PG8_BAR; PG8_WAIT_L(0); PG8_MMA(1, 0, At, B0); PG8_BAR; PG8_SCHED;
;             PG8_STAGE(PG8_SB(1, 1), b3 + hstep);
;             PG8_WAIT_V(6); PG8_BAR; PG8_MMA(1, 1, At, B1); PG8_BAR;
;         }
;         E(acc, cur, wr, wc, fr, fq);
;     template <bool LN, int BJ, int LO, int HI> DI void batch(const f32x4 (&acc)[2][2][4][2], unsigned row0, unsigned col0, const f32x4 (&gv)[2], const f32x4 (&bv)[2]) const {
;         f32x4 r[HI - LO]; float mean[(HI - LO) / 2], rstd[(HI - LO) / 2];
; #pragma unroll
;         for (int i = LO; i < HI; ++i) { const int ai = i >> 3, m = (i >> 1) & 3, n = i & 1; const unsigned row = row0 + ai * HALF + m * 16;
;             if (n == 0) { mean[(i - LO) >> 1] = 0.f; rstd[(i - LO) >> 1] = 1.f;
;                 if (LN) { const float2 st = *(const float2*)(stats + row * 2u); mean[(i - LO) >> 1] = st.x; rstd[(i - LO) >> 1] = st.y; } }
;             r[i - LO] = *(const f32x4*)(src + (row * (unsigned)DM + col0 + BJ * HALF + n * 16)); }
; #pragma unroll
;         for (int i = LO; i < HI; ++i) { const int ai = i >> 3, m = (i >> 1) & 3, n = i & 1; const unsigned row = row0 + ai * HALF + m * 16;
;             *(f32x4*)(Y + (row * (unsigned)DM + col0 + BJ * HALF + n * 16)) = acc[ai][BJ][m][n] + ((r[i - LO] - mean[(i - LO) >> 1]) * rstd[(i - LO) >> 1]) * gv[n] + bv[n]; }
;         __builtin_amdgcn_sched_barrier(0);
;     }
;     template <bool LN, int BJ> DI void load_gb(unsigned col0, f32x4 (&gv)[2], f32x4 (&bv)[2]) const {
; #pragma unroll
;         for (int n = 0; n < 2; ++n) {
;             if (LN) { gv[n] = *(const f32x4*)(gam + col0 + BJ * HALF + n * 16) * ALPHA; bv[n] = *(const f32x4*)(bet + col0 + BJ * HALF + n * 16) * ALPHA; }
;             else { gv[n] = (f32x4){ALPHA, ALPHA, ALPHA, ALPHA}; bv[n] = (f32x4){0.f, 0.f, 0.f, 0.f}; }
;         }
;     }
;     template <bool LN> DI void run(const f32x4 (&acc)[2][2][4][2], const Unit& u, int wr, int wc, int fr, int fq) const {
;         const unsigned row0 = u.pm * BM + wr * 64 + fr, col0 = u.pn * BM + wc * 32 + 4 * fq;
;         f32x4 gv[2], bv[2];
;         load_gb<LN, 0>(col0, gv, bv);
;         batch<LN, 0, 0, 4>(acc, row0, col0, gv, bv);
;         batch<LN, 0, 4, 8>(acc, row0, col0, gv, bv);
;         batch<LN, 0, 8, 12>(acc, row0, col0, gv, bv);
	v_mfma_f32_16x16x32_bf16 v[92:95], v[128:131], v[144:147], v[92:95]
	v_mfma_f32_16x16x32_bf16 v[88:91], v[136:139], v[144:147], v[88:91]
	v_mfma_f32_16x16x32_bf16 v[84:87], v[128:131], v[152:155], v[84:87]
	v_mfma_f32_16x16x32_bf16 v[80:83], v[136:139], v[152:155], v[80:83]
	v_mfma_f32_16x16x32_bf16 v[76:79], v[128:131], v[198:201], v[76:79]
	v_mfma_f32_16x16x32_bf16 v[72:75], v[136:139], v[198:201], v[72:75]
	v_mfma_f32_16x16x32_bf16 v[68:71], v[128:131], v[206:209], v[68:71]
	v_mfma_f32_16x16x32_bf16 v[64:67], v[136:139], v[206:209], v[64:67]
	v_mfma_f32_16x16x32_bf16 v[92:95], v[132:135], v[148:151], v[92:95]
	v_mfma_f32_16x16x32_bf16 v[88:91], v[140:143], v[148:151], v[88:91]
	v_mfma_f32_16x16x32_bf16 v[84:87], v[132:135], v[194:197], v[84:87]
	v_mfma_f32_16x16x32_bf16 v[80:83], v[140:143], v[194:197], v[80:83]
	v_mfma_f32_16x16x32_bf16 v[76:79], v[132:135], v[202:205], v[76:79]
	v_mfma_f32_16x16x32_bf16 v[72:75], v[140:143], v[202:205], v[72:75]
	v_mfma_f32_16x16x32_bf16 v[68:71], v[132:135], v[210:213], v[68:71]
	v_mfma_f32_16x16x32_bf16 v[64:67], v[140:143], v[210:213], v[64:67]
	s_setprio 0
	s_barrier
	s_add_u32 s20, s24, 0x90080
	s_addc_u32 s21, s25, 0
	s_add_i32 s24, s26, s31
	v_lshl_add_u64 v[128:129], s[20:21], 0, v[188:189]
	s_mov_b32 m0, s24
	s_nop 0
	global_load_lds_dwordx4 v[128:129], off
	v_lshl_add_u64 v[128:129], s[20:21], 0, v[186:187]
	s_add_i32 m0, s24, 0x2000
	s_nop 0
	global_load_lds_dwordx4 v[128:129], off
	s_waitcnt vmcnt(6)
	s_setprio 1
	s_barrier
	v_mfma_f32_16x16x32_bf16 v[28:31], v[214:217], v[144:147], v[28:31]
	v_mfma_f32_16x16x32_bf16 v[24:27], v[234:237], v[144:147], v[24:27]
	v_mfma_f32_16x16x32_bf16 v[20:23], v[214:217], v[152:155], v[20:23]
	v_mfma_f32_16x16x32_bf16 v[16:19], v[234:237], v[152:155], v[16:19]
	v_mfma_f32_16x16x32_bf16 v[12:15], v[214:217], v[198:201], v[12:15]
	v_mfma_f32_16x16x32_bf16 v[8:11], v[234:237], v[198:201], v[8:11]
	v_mfma_f32_16x16x32_bf16 v[4:7], v[214:217], v[206:209], v[4:7]
	v_mfma_f32_16x16x32_bf16 v[0:3], v[234:237], v[206:209], v[0:3]
	v_mfma_f32_16x16x32_bf16 v[28:31], v[230:233], v[148:151], v[28:31]
	v_mfma_f32_16x16x32_bf16 v[24:27], v[238:241], v[148:151], v[24:27]
	v_mfma_f32_16x16x32_bf16 v[20:23], v[230:233], v[194:197], v[20:23]
	v_mfma_f32_16x16x32_bf16 v[16:19], v[238:241], v[194:197], v[16:19]
	s_add_i32 s33, s33, 2
	s_add_u32 s4, s4, 0x100
	s_addc_u32 s5, s5, 0
	s_cmp_gt_u32 s33, 33
	s_mov_b64 s[20:21], s[22:23]
	v_mfma_f32_16x16x32_bf16 v[12:15], v[230:233], v[202:205], v[12:15]
	v_mfma_f32_16x16x32_bf16 v[8:11], v[238:241], v[202:205], v[8:11]
	v_mfma_f32_16x16x32_bf16 v[4:7], v[230:233], v[210:213], v[4:7]
	v_mfma_f32_16x16x32_bf16 v[0:3], v[238:241], v[210:213], v[0:3]
	s_setprio 0
	s_barrier
	s_cbranch_scc0 .LBB0_77
	v_lshl_add_u32 v206, s3, 8, v225
	v_lshl_or_b32 v158, s2, 8, v227
	v_lshlrev_b32_e32 v232, 11, v206
	s_andn2_b64 vcc, exec, s[14:15]
	v_or_b32_e32 v231, 16, v158
	v_add_u32_e32 v194, v232, v158
	v_or_b32_e32 v230, 0x80, v158
	v_or_b32_e32 v229, 0x90, v158
	s_cbranch_vccnz .LBB0_80
	v_lshlrev_b64 v[132:133], 2, v[158:159]
	v_lshl_add_u64 v[140:141], s[16:17], 0, v[132:133]
	global_load_dwordx4 v[128:131], v[140:141], off
	v_lshl_add_u64 v[142:143], s[18:19], 0, v[132:133]
	v_readlane_b32 s2, v253, 8
	v_mov_b32_e32 v195, v159
	v_lshlrev_b32_e32 v136, 1, v206
	v_mov_b32_e32 v137, v159
	v_readlane_b32 s3, v253, 9
	v_lshlrev_b64 v[212:213], 2, v[194:195]
	v_add_u32_e32 v146, v232, v231
	v_lshl_add_u64 v[144:145], v[136:137], 2, s[2:3]
	v_lshl_add_u64 v[136:137], s[88:89], 0, v[212:213]
	v_mov_b32_e32 v147, v159
	v_lshl_add_u64 v[146:147], v[146:147], 2, s[88:89]
	v_or_b32_e32 v195, 16, v206
	v_mov_b32_e32 v201, v159
	v_mov_b32_e32 v209, v159
	v_lshl_add_u64 v[212:213], s[90:91], 0, v[212:213]
	s_waitcnt vmcnt(0)
	v_pk_mul_f32 v[152:153], v[130:131], s[78:79] op_sel_hi:[1,0]
	v_pk_mul_f32 v[154:155], v[128:129], s[78:79] op_sel_hi:[1,0]
	global_load_dwordx4 v[132:135], v[142:143], off
	global_load_dwordx4 v[128:131], v[140:141], off offset:64
	global_load_dwordx2 v[204:205], v[144:145], off
	global_load_dwordx4 v[196:199], v[146:147], off
	v_lshlrev_b32_e32 v146, 1, v195
	global_load_dwordx4 v[136:139], v[136:137], off
	v_lshlrev_b32_e32 v195, 11, v195
	v_mov_b32_e32 v147, v159
	v_add_u32_e32 v200, v195, v158
	v_lshl_add_u64 v[146:147], v[146:147], 2, s[2:3]
	v_lshl_add_u64 v[200:201], v[200:201], 2, s[88:89]
	global_load_dwordx2 v[214:215], v[146:147], off
	v_add_u32_e32 v208, v195, v231
	global_load_dwordx4 v[200:203], v[200:201], off
	v_lshl_add_u64 v[208:209], v[208:209], 2, s[88:89]
	global_load_dwordx4 v[208:211], v[208:209], off
	s_waitcnt vmcnt(0)
	v_pk_mul_f32 v[148:149], v[130:131], s[78:79] op_sel_hi:[1,0]
	v_pk_mul_f32 v[150:151], v[128:129], s[78:79] op_sel_hi:[1,0]
	global_load_dwordx4 v[128:131], v[142:143], off offset:64
	v_sub_f32_e32 v137, v137, v204
	v_sub_f32_e32 v136, v136, v204
	v_sub_f32_e32 v139, v139, v204
	v_sub_f32_e32 v138, v138, v204
	v_pk_mul_f32 v[138:139], v[204:205], v[138:139] op_sel:[1,0]
	v_pk_mul_f32 v[136:137], v[204:205], v[136:137] op_sel:[1,0]
	v_pk_fma_f32 v[138:139], v[152:153], v[138:139], v[126:127]
	v_pk_fma_f32 v[136:137], v[154:155], v[136:137], v[124:125]
	v_pk_fma_f32 v[138:139], v[134:135], s[78:79], v[138:139] op_sel_hi:[1,0,1]
	v_pk_fma_f32 v[136:137], v[132:133], s[78:79], v[136:137] op_sel_hi:[1,0,1]
	global_store_dwordx4 v[212:213], v[136:139], off
	s_nop 1
	v_sub_f32_e32 v137, v197, v204
	v_sub_f32_e32 v136, v196, v204
	v_sub_f32_e32 v139, v199, v204
	v_sub_f32_e32 v138, v198, v204
	v_pk_mul_f32 v[138:139], v[204:205], v[138:139] op_sel:[1,0]
	v_pk_mul_f32 v[136:137], v[204:205], v[136:137] op_sel:[1,0]
	v_pk_fma_f32 v[138:139], v[148:149], v[138:139], v[122:123]
	v_pk_fma_f32 v[136:137], v[150:151], v[136:137], v[120:121]
	v_or_b32_e32 v196, 16, v194
	v_mov_b32_e32 v197, v159
	v_lshl_add_u64 v[196:197], v[196:197], 2, s[90:91]
	s_waitcnt vmcnt(0)
;     template <bool LN, int BJ, int LO, int HI> DI void batch(const f32x4 (&acc)[2][2][4][2], unsigned row0, unsigned col0, const f32x4 (&gv)[2], const f32x4 (&bv)[2]) const {
;         f32x4 r[HI - LO]; float mean[(HI - LO) / 2], rstd[(HI - LO) / 2];
; #pragma unroll
;         for (int i = LO; i < HI; ++i) { const int ai = i >> 3, m = (i >> 1) & 3, n = i & 1; const unsigned row = row0 + ai * HALF + m * 16;
;             if (n == 0) { mean[(i - LO) >> 1] = 0.f; rstd[(i - LO) >> 1] = 1.f;
;                 if (LN) { const float2 st = *(const float2*)(stats + row * 2u); mean[(i - LO) >> 1] = st.x; rstd[(i - LO) >> 1] = st.y; } }
;             r[i - LO] = *(const f32x4*)(src + (row * (unsigned)DM + col0 + BJ * HALF + n * 16)); }
; #pragma unroll
;         for (int i = LO; i < HI; ++i) { const int ai = i >> 3, m = (i >> 1) & 3, n = i & 1; const unsigned row = row0 + ai * HALF + m * 16;
;             *(f32x4*)(Y + (row * (unsigned)DM + col0 + BJ * HALF + n * 16)) = acc[ai][BJ][m][n] + ((r[i - LO] - mean[(i - LO) >> 1]) * rstd[(i - LO) >> 1]) * gv[n] + bv[n]; }
;         __builtin_amdgcn_sched_barrier(0);
;     }
;     template <bool LN, int BJ> DI void load_gb(unsigned col0, f32x4 (&gv)[2], f32x4 (&bv)[2]) const {
; #pragma unroll
;         for (int n = 0; n < 2; ++n) {
;             if (LN) { gv[n] = *(const f32x4*)(gam + col0 + BJ * HALF + n * 16) * ALPHA; bv[n] = *(const f32x4*)(bet + col0 + BJ * HALF + n * 16) * ALPHA; }
;             else { gv[n] = (f32x4){ALPHA, ALPHA, ALPHA, ALPHA}; bv[n] = (f32x4){0.f, 0.f, 0.f, 0.f}; }
;         }
;     }
;     template <bool LN> DI void run(const f32x4 (&acc)[2][2][4][2], const Unit& u, int wr, int wc, int fr, int fq) const {
;         const unsigned row0 = u.pm * BM + wr * 64 + fr, col0 = u.pn * BM + wc * 32 + 4 * fq;
;         f32x4 gv[2], bv[2];
;         load_gb<LN, 0>(col0, gv, bv);
;         batch<LN, 0, 0, 4>(acc, row0, col0, gv, bv);
;         batch<LN, 0, 4, 8>(acc, row0, col0, gv, bv);
;         batch<LN, 0, 8, 12>(acc, row0, col0, gv, bv);
;         batch<LN, 0, 12, 16>(acc, row0, col0, gv, bv);
	v_pk_fma_f32 v[138:139], v[130:131], s[78:79], v[138:139] op_sel_hi:[1,0,1]
	v_pk_fma_f32 v[136:137], v[128:129], s[78:79], v[136:137] op_sel_hi:[1,0,1]
	global_store_dwordx4 v[196:197], v[136:139], off
	v_add_u32_e32 v196, 0x8000, v194
	v_mov_b32_e32 v197, v159
	v_sub_f32_e32 v137, v201, v214
	v_sub_f32_e32 v136, v200, v214
	v_sub_f32_e32 v139, v203, v214
	v_sub_f32_e32 v138, v202, v214
	v_pk_mul_f32 v[138:139], v[214:215], v[138:139] op_sel:[1,0]
	v_pk_mul_f32 v[136:137], v[214:215], v[136:137] op_sel:[1,0]
	v_pk_fma_f32 v[138:139], v[152:153], v[138:139], v[118:119]
	v_pk_fma_f32 v[136:137], v[154:155], v[136:137], v[116:117]
	v_pk_fma_f32 v[138:139], v[134:135], s[78:79], v[138:139] op_sel_hi:[1,0,1]
	v_pk_fma_f32 v[136:137], v[132:133], s[78:79], v[136:137] op_sel_hi:[1,0,1]
	v_lshl_add_u64 v[196:197], v[196:197], 2, s[90:91]
	global_store_dwordx4 v[196:197], v[136:139], off
	v_add_u32_e32 v196, 0x8010, v194
	v_mov_b32_e32 v197, v159
	v_sub_f32_e32 v137, v209, v214
	v_sub_f32_e32 v136, v208, v214
	v_sub_f32_e32 v139, v211, v214
	v_sub_f32_e32 v138, v210, v214
	v_pk_mul_f32 v[138:139], v[214:215], v[138:139] op_sel:[1,0]
	v_pk_mul_f32 v[136:137], v[214:215], v[136:137] op_sel:[1,0]
	v_pk_fma_f32 v[138:139], v[148:149], v[138:139], v[114:115]
	v_pk_fma_f32 v[136:137], v[150:151], v[136:137], v[112:113]
	v_pk_fma_f32 v[138:139], v[130:131], s[78:79], v[138:139] op_sel_hi:[1,0,1]
	v_pk_fma_f32 v[136:137], v[128:129], s[78:79], v[136:137] op_sel_hi:[1,0,1]
	v_lshl_add_u64 v[196:197], v[196:197], 2, s[90:91]
	global_store_dwordx4 v[196:197], v[136:139], off
	s_nop 1
	v_or_b32_e32 v138, 32, v206
	v_lshlrev_b32_e32 v136, 1, v138
	v_mov_b32_e32 v137, v159
	v_lshlrev_b32_e32 v236, 11, v138
	v_lshl_add_u64 v[200:201], v[136:137], 2, s[2:3]
	v_add_u32_e32 v136, v236, v158
	v_lshl_add_u64 v[136:137], v[136:137], 2, s[88:89]
	global_load_dwordx2 v[204:205], v[200:201], off
	v_add_u32_e32 v196, v236, v231
	global_load_dwordx4 v[136:139], v[136:137], off
	v_mov_b32_e32 v197, v159
	v_lshl_add_u64 v[196:197], v[196:197], 2, s[88:89]
	global_load_dwordx4 v[196:199], v[196:197], off
	v_or_b32_e32 v207, 48, v206
	v_lshlrev_b32_e32 v235, 11, v207
	v_lshlrev_b32_e32 v202, 1, v207
	v_mov_b32_e32 v203, v159
	v_add_u32_e32 v208, v235, v158
	v_mov_b32_e32 v209, v159
	v_lshl_add_u64 v[202:203], v[202:203], 2, s[2:3]
	v_lshl_add_u64 v[208:209], v[208:209], 2, s[88:89]
	global_load_dwordx2 v[216:217], v[202:203], off
	v_add_u32_e32 v212, v235, v231
	global_load_dwordx4 v[208:211], v[208:209], off
	v_mov_b32_e32 v213, v159
	v_lshl_add_u64 v[212:213], v[212:213], 2, s[88:89]
	global_load_dwordx4 v[212:215], v[212:213], off
	v_add_u32_e32 v218, 0x10000, v194
	v_mov_b32_e32 v219, v159
	v_lshl_add_u64 v[218:219], v[218:219], 2, s[90:91]
	s_waitcnt vmcnt(0)
	v_sub_f32_e32 v137, v137, v204
	v_sub_f32_e32 v136, v136, v204
	v_sub_f32_e32 v139, v139, v204
	v_sub_f32_e32 v138, v138, v204
	v_pk_mul_f32 v[138:139], v[204:205], v[138:139] op_sel:[1,0]
	v_pk_mul_f32 v[136:137], v[204:205], v[136:137] op_sel:[1,0]
	v_pk_fma_f32 v[138:139], v[152:153], v[138:139], v[110:111]
	v_pk_fma_f32 v[136:137], v[154:155], v[136:137], v[108:109]
	v_pk_fma_f32 v[138:139], v[134:135], s[78:79], v[138:139] op_sel_hi:[1,0,1]
	v_pk_fma_f32 v[136:137], v[132:133], s[78:79], v[136:137] op_sel_hi:[1,0,1]
	global_store_dwordx4 v[218:219], v[136:139], off
	s_nop 1
	v_sub_f32_e32 v137, v197, v204
	v_sub_f32_e32 v136, v196, v204
	v_sub_f32_e32 v139, v199, v204
	v_sub_f32_e32 v138, v198, v204
	v_pk_mul_f32 v[138:139], v[204:205], v[138:139] op_sel:[1,0]
	v_pk_mul_f32 v[136:137], v[204:205], v[136:137] op_sel:[1,0]
	v_pk_fma_f32 v[138:139], v[148:149], v[138:139], v[106:107]
	v_pk_fma_f32 v[136:137], v[150:151], v[136:137], v[104:105]
	v_add_u32_e32 v196, 0x10010, v194
	v_mov_b32_e32 v197, v159
	v_pk_fma_f32 v[138:139], v[130:131], s[78:79], v[138:139] op_sel_hi:[1,0,1]
	v_pk_fma_f32 v[136:137], v[128:129], s[78:79], v[136:137] op_sel_hi:[1,0,1]
	v_lshl_add_u64 v[196:197], v[196:197], 2, s[90:91]
	global_store_dwordx4 v[196:197], v[136:139], off
	v_add_u32_e32 v196, 0x18000, v194
	v_mov_b32_e32 v197, v159
	v_sub_f32_e32 v137, v209, v216
	v_sub_f32_e32 v136, v208, v216
	v_sub_f32_e32 v139, v211, v216
	v_sub_f32_e32 v138, v210, v216
	v_pk_mul_f32 v[138:139], v[216:217], v[138:139] op_sel:[1,0]
	v_pk_mul_f32 v[136:137], v[216:217], v[136:137] op_sel:[1,0]
	v_pk_fma_f32 v[138:139], v[152:153], v[138:139], v[102:103]
	v_pk_fma_f32 v[136:137], v[154:155], v[136:137], v[100:101]
	v_pk_fma_f32 v[138:139], v[134:135], s[78:79], v[138:139] op_sel_hi:[1,0,1]
	v_pk_fma_f32 v[136:137], v[132:133], s[78:79], v[136:137] op_sel_hi:[1,0,1]
	v_lshl_add_u64 v[196:197], v[196:197], 2, s[90:91]
	global_store_dwordx4 v[196:197], v[136:139], off
	v_add_u32_e32 v196, 0x18010, v194
	v_mov_b32_e32 v197, v159
	v_sub_f32_e32 v137, v213, v216
	v_sub_f32_e32 v136, v212, v216
	v_sub_f32_e32 v139, v215, v216
	v_sub_f32_e32 v138, v214, v216
	v_pk_mul_f32 v[138:139], v[216:217], v[138:139] op_sel:[1,0]
	v_pk_mul_f32 v[136:137], v[216:217], v[136:137] op_sel:[1,0]
	v_pk_fma_f32 v[138:139], v[148:149], v[138:139], v[98:99]
	v_pk_fma_f32 v[136:137], v[150:151], v[136:137], v[96:97]
	v_pk_fma_f32 v[138:139], v[130:131], s[78:79], v[138:139] op_sel_hi:[1,0,1]
	v_pk_fma_f32 v[136:137], v[128:129], s[78:79], v[136:137] op_sel_hi:[1,0,1]
	v_lshl_add_u64 v[196:197], v[196:197], 2, s[90:91]
	global_store_dwordx4 v[196:197], v[136:139], off
	s_nop 1
	v_add_u32_e32 v138, 0x80, v206
	v_lshlrev_b32_e32 v136, 1, v138
	v_mov_b32_e32 v137, v159
	v_lshlrev_b32_e32 v233, 11, v138
	v_lshl_add_u64 v[196:197], v[136:137], 2, s[2:3]
	v_add_u32_e32 v136, v233, v158
	v_lshl_add_u64 v[136:137], v[136:137], 2, s[88:89]
	global_load_dwordx2 v[204:205], v[196:197], off
	v_add_u32_e32 v198, v233, v231
	global_load_dwordx4 v[136:139], v[136:137], off
	v_mov_b32_e32 v199, v159
	v_add_u32_e32 v207, 0x90, v206
	v_lshl_add_u64 v[198:199], v[198:199], 2, s[88:89]
	v_lshlrev_b32_e32 v234, 11, v207
	global_load_dwordx4 v[208:211], v[198:199], off
	v_add_u32_e32 v212, v234, v158
	v_mov_b32_e32 v213, v159
	v_lshl_add_u64 v[212:213], v[212:213], 2, s[88:89]
	global_load_dwordx4 v[212:215], v[212:213], off
	v_lshlrev_b32_e32 v198, 1, v207
	v_mov_b32_e32 v199, v159
	v_lshl_add_u64 v[198:199], v[198:199], 2, s[2:3]
	global_load_dwordx2 v[220:221], v[198:199], off
	v_add_u32_e32 v216, v234, v231
	v_mov_b32_e32 v217, v159
	v_lshl_add_u64 v[216:217], v[216:217], 2, s[88:89]
	global_load_dwordx4 v[216:219], v[216:217], off
	v_add_u32_e32 v238, 0x40000, v194
	v_mov_b32_e32 v239, v159
	v_lshl_add_u64 v[238:239], v[238:239], 2, s[90:91]
	s_waitcnt vmcnt(0)
;     template <bool LN, int BJ, int LO, int HI> DI void batch(const f32x4 (&acc)[2][2][4][2], unsigned row0, unsigned col0, const f32x4 (&gv)[2], const f32x4 (&bv)[2]) const {
;         f32x4 r[HI - LO]; float mean[(HI - LO) / 2], rstd[(HI - LO) / 2];
; #pragma unroll
;         for (int i = LO; i < HI; ++i) { const int ai = i >> 3, m = (i >> 1) & 3, n = i & 1; const unsigned row = row0 + ai * HALF + m * 16;
;             if (n == 0) { mean[(i - LO) >> 1] = 0.f; rstd[(i - LO) >> 1] = 1.f;
;                 if (LN) { const float2 st = *(const float2*)(stats + row * 2u); mean[(i - LO) >> 1] = st.x; rstd[(i - LO) >> 1] = st.y; } }
;             r[i - LO] = *(const f32x4*)(src + (row * (unsigned)DM + col0 + BJ * HALF + n * 16)); }
; #pragma unroll
;         for (int i = LO; i < HI; ++i) { const int ai = i >> 3, m = (i >> 1) & 3, n = i & 1; const unsigned row = row0 + ai * HALF + m * 16;
;             *(f32x4*)(Y + (row * (unsigned)DM + col0 + BJ * HALF + n * 16)) = acc[ai][BJ][m][n] + ((r[i - LO] - mean[(i - LO) >> 1]) * rstd[(i - LO) >> 1]) * gv[n] + bv[n]; }
;         __builtin_amdgcn_sched_barrier(0);
;     }
;     template <bool LN, int BJ> DI void load_gb(unsigned col0, f32x4 (&gv)[2], f32x4 (&bv)[2]) const {
; #pragma unroll
;         for (int n = 0; n < 2; ++n) {
;             if (LN) { gv[n] = *(const f32x4*)(gam + col0 + BJ * HALF + n * 16) * ALPHA; bv[n] = *(const f32x4*)(bet + col0 + BJ * HALF + n * 16) * ALPHA; }
;             else { gv[n] = (f32x4){ALPHA, ALPHA, ALPHA, ALPHA}; bv[n] = (f32x4){0.f, 0.f, 0.f, 0.f}; }
;         }
;     }
;     template <bool LN> DI void run(const f32x4 (&acc)[2][2][4][2], const Unit& u, int wr, int wc, int fr, int fq) const {
;         const unsigned row0 = u.pm * BM + wr * 64 + fr, col0 = u.pn * BM + wc * 32 + 4 * fq;
;         f32x4 gv[2], bv[2];
;         load_gb<LN, 0>(col0, gv, bv);
;         batch<LN, 0, 0, 4>(acc, row0, col0, gv, bv);
;         batch<LN, 0, 4, 8>(acc, row0, col0, gv, bv);
;         batch<LN, 0, 8, 12>(acc, row0, col0, gv, bv);
;         batch<LN, 0, 12, 16>(acc, row0, col0, gv, bv);
	v_sub_f32_e32 v137, v137, v204
	v_sub_f32_e32 v136, v136, v204
	v_sub_f32_e32 v139, v139, v204
	v_sub_f32_e32 v138, v138, v204
	v_pk_mul_f32 v[138:139], v[204:205], v[138:139] op_sel:[1,0]
	v_pk_mul_f32 v[136:137], v[204:205], v[136:137] op_sel:[1,0]
	v_pk_fma_f32 v[138:139], v[152:153], v[138:139], v[94:95]
	v_pk_fma_f32 v[136:137], v[154:155], v[136:137], v[92:93]
	v_pk_fma_f32 v[138:139], v[134:135], s[78:79], v[138:139] op_sel_hi:[1,0,1]
	v_pk_fma_f32 v[136:137], v[132:133], s[78:79], v[136:137] op_sel_hi:[1,0,1]
	global_store_dwordx4 v[238:239], v[136:139], off
	s_nop 1
	v_sub_f32_e32 v137, v209, v204
	v_sub_f32_e32 v136, v208, v204
	v_sub_f32_e32 v139, v211, v204
	v_sub_f32_e32 v138, v210, v204
	v_pk_mul_f32 v[138:139], v[204:205], v[138:139] op_sel:[1,0]
	v_pk_mul_f32 v[136:137], v[204:205], v[136:137] op_sel:[1,0]
	v_pk_fma_f32 v[138:139], v[148:149], v[138:139], v[90:91]
	v_pk_fma_f32 v[136:137], v[150:151], v[136:137], v[88:89]
	v_add_u32_e32 v204, 0x40010, v194
	v_mov_b32_e32 v205, v159
	v_pk_fma_f32 v[138:139], v[130:131], s[78:79], v[138:139] op_sel_hi:[1,0,1]
	v_pk_fma_f32 v[136:137], v[128:129], s[78:79], v[136:137] op_sel_hi:[1,0,1]
	v_lshl_add_u64 v[204:205], v[204:205], 2, s[90:91]
	global_store_dwordx4 v[204:205], v[136:139], off
	v_add_u32_e32 v204, 0x48000, v194
	v_mov_b32_e32 v205, v159
	v_sub_f32_e32 v137, v213, v220
	v_sub_f32_e32 v136, v212, v220
	v_sub_f32_e32 v139, v215, v220
	v_sub_f32_e32 v138, v214, v220
	v_pk_mul_f32 v[138:139], v[220:221], v[138:139] op_sel:[1,0]
	v_pk_mul_f32 v[136:137], v[220:221], v[136:137] op_sel:[1,0]
	v_pk_fma_f32 v[138:139], v[152:153], v[138:139], v[86:87]
	v_pk_fma_f32 v[136:137], v[154:155], v[136:137], v[84:85]
	v_pk_fma_f32 v[138:139], v[134:135], s[78:79], v[138:139] op_sel_hi:[1,0,1]
	v_pk_fma_f32 v[136:137], v[132:133], s[78:79], v[136:137] op_sel_hi:[1,0,1]
	v_lshl_add_u64 v[204:205], v[204:205], 2, s[90:91]
	global_store_dwordx4 v[204:205], v[136:139], off
	v_add_u32_e32 v204, 0x48010, v194
	v_mov_b32_e32 v205, v159
	v_sub_f32_e32 v137, v217, v220
	v_sub_f32_e32 v136, v216, v220
	v_sub_f32_e32 v139, v219, v220
	v_sub_f32_e32 v138, v218, v220
	v_pk_mul_f32 v[138:139], v[220:221], v[138:139] op_sel:[1,0]
	v_pk_mul_f32 v[136:137], v[220:221], v[136:137] op_sel:[1,0]
	v_pk_fma_f32 v[138:139], v[148:149], v[138:139], v[82:83]
	v_pk_fma_f32 v[136:137], v[150:151], v[136:137], v[80:81]
	v_pk_fma_f32 v[138:139], v[130:131], s[78:79], v[138:139] op_sel_hi:[1,0,1]
	v_pk_fma_f32 v[136:137], v[128:129], s[78:79], v[136:137] op_sel_hi:[1,0,1]
	v_lshl_add_u64 v[204:205], v[204:205], 2, s[90:91]
	global_store_dwordx4 v[204:205], v[136:139], off
	s_nop 1
	v_add_u32_e32 v138, 0xa0, v206
	v_lshlrev_b32_e32 v136, 1, v138
	v_mov_b32_e32 v137, v159
	v_lshlrev_b32_e32 v237, 11, v138
	v_lshl_add_u64 v[204:205], v[136:137], 2, s[2:3]
	v_add_u32_e32 v136, v237, v158
	v_lshl_add_u64 v[136:137], v[136:137], 2, s[88:89]
	global_load_dwordx2 v[220:221], v[204:205], off
	v_add_u32_e32 v208, v237, v231
	global_load_dwordx4 v[136:139], v[136:137], off
	v_mov_b32_e32 v209, v159
	v_lshl_add_u64 v[208:209], v[208:209], 2, s[88:89]
	global_load_dwordx4 v[212:215], v[208:209], off
	v_add_u32_e32 v208, 0xb0, v206
	v_lshlrev_b32_e32 v206, 1, v208
	v_mov_b32_e32 v207, v159
	v_lshlrev_b32_e32 v238, 11, v208
	v_lshl_add_u64 v[210:211], v[206:207], 2, s[2:3]
	v_add_u32_e32 v206, v238, v158
	v_lshl_add_u64 v[206:207], v[206:207], 2, s[88:89]
	global_load_dwordx2 v[240:241], v[210:211], off
	v_add_u32_e32 v216, v238, v231
	global_load_dwordx4 v[206:209], v[206:207], off
	v_mov_b32_e32 v217, v159
	v_lshl_add_u64 v[216:217], v[216:217], 2, s[88:89]
	global_load_dwordx4 v[216:219], v[216:217], off
	v_add_u32_e32 v242, 0x50000, v194
	v_mov_b32_e32 v243, v159
	v_lshl_add_u64 v[242:243], v[242:243], 2, s[90:91]
	s_waitcnt vmcnt(0)
	v_sub_f32_e32 v137, v137, v220
	v_sub_f32_e32 v136, v136, v220
	v_sub_f32_e32 v139, v139, v220
	v_sub_f32_e32 v138, v138, v220
	v_pk_mul_f32 v[138:139], v[220:221], v[138:139] op_sel:[1,0]
	v_pk_mul_f32 v[136:137], v[220:221], v[136:137] op_sel:[1,0]
	v_pk_fma_f32 v[138:139], v[152:153], v[138:139], v[78:79]
	v_pk_fma_f32 v[136:137], v[154:155], v[136:137], v[76:77]
	v_pk_fma_f32 v[138:139], v[134:135], s[78:79], v[138:139] op_sel_hi:[1,0,1]
	v_pk_fma_f32 v[136:137], v[132:133], s[78:79], v[136:137] op_sel_hi:[1,0,1]
	global_store_dwordx4 v[242:243], v[136:139], off
	s_nop 1
	v_sub_f32_e32 v137, v213, v220
	v_sub_f32_e32 v136, v212, v220
	v_sub_f32_e32 v139, v215, v220
	v_sub_f32_e32 v138, v214, v220
	v_pk_mul_f32 v[138:139], v[220:221], v[138:139] op_sel:[1,0]
	v_pk_mul_f32 v[136:137], v[220:221], v[136:137] op_sel:[1,0]
	v_pk_fma_f32 v[138:139], v[148:149], v[138:139], v[74:75]
	v_pk_fma_f32 v[136:137], v[150:151], v[136:137], v[72:73]
	v_add_u32_e32 v212, 0x50010, v194
	v_mov_b32_e32 v213, v159
	v_pk_fma_f32 v[138:139], v[130:131], s[78:79], v[138:139] op_sel_hi:[1,0,1]
	v_pk_fma_f32 v[136:137], v[128:129], s[78:79], v[136:137] op_sel_hi:[1,0,1]
	v_lshl_add_u64 v[212:213], v[212:213], 2, s[90:91]
	global_store_dwordx4 v[212:213], v[136:139], off
	s_nop 1
	v_sub_f32_e32 v137, v207, v240
	v_sub_f32_e32 v136, v206, v240
	v_sub_f32_e32 v139, v209, v240
	v_sub_f32_e32 v138, v208, v240
	v_pk_mul_f32 v[136:137], v[240:241], v[136:137] op_sel:[1,0]
	v_pk_mul_f32 v[138:139], v[240:241], v[138:139] op_sel:[1,0]
	v_pk_fma_f32 v[136:137], v[154:155], v[136:137], v[68:69]
	v_pk_fma_f32 v[138:139], v[152:153], v[138:139], v[70:71]
	v_pk_fma_f32 v[132:133], v[132:133], s[78:79], v[136:137] op_sel_hi:[1,0,1]
	v_add_u32_e32 v136, 0x58000, v194
	v_mov_b32_e32 v137, v159
	v_pk_fma_f32 v[134:135], v[134:135], s[78:79], v[138:139] op_sel_hi:[1,0,1]
	v_lshl_add_u64 v[136:137], v[136:137], 2, s[90:91]
	global_store_dwordx4 v[136:137], v[132:135], off
	s_nop 1
	v_sub_f32_e32 v133, v217, v240
	v_sub_f32_e32 v132, v216, v240
	v_sub_f32_e32 v135, v219, v240
	v_sub_f32_e32 v134, v218, v240
	v_pk_mul_f32 v[132:133], v[240:241], v[132:133] op_sel:[1,0]
	v_pk_mul_f32 v[134:135], v[240:241], v[134:135] op_sel:[1,0]
	v_pk_fma_f32 v[132:133], v[150:151], v[132:133], v[64:65]
	v_pk_fma_f32 v[134:135], v[148:149], v[134:135], v[66:67]
	v_pk_fma_f32 v[128:129], v[128:129], s[78:79], v[132:133] op_sel_hi:[1,0,1]
	v_add_u32_e32 v132, 0x58010, v194
	v_mov_b32_e32 v133, v159
	v_pk_fma_f32 v[130:131], v[130:131], s[78:79], v[134:135] op_sel_hi:[1,0,1]
	v_lshl_add_u64 v[132:133], v[132:133], 2, s[90:91]
	global_store_dwordx4 v[132:133], v[128:131], off
	global_load_dwordx4 v[128:131], v[140:141], off offset:512
	v_add_u32_e32 v136, v232, v230
	v_mov_b32_e32 v137, v159
	v_lshl_add_u64 v[136:137], v[136:137], 2, s[88:89]
	s_waitcnt vmcnt(0)
;     template <bool LN, int BJ, int LO, int HI> DI void batch(const f32x4 (&acc)[2][2][4][2], unsigned row0, unsigned col0, const f32x4 (&gv)[2], const f32x4 (&bv)[2]) const {
;         f32x4 r[HI - LO]; float mean[(HI - LO) / 2], rstd[(HI - LO) / 2];
; #pragma unroll
;         for (int i = LO; i < HI; ++i) { const int ai = i >> 3, m = (i >> 1) & 3, n = i & 1; const unsigned row = row0 + ai * HALF + m * 16;
;             if (n == 0) { mean[(i - LO) >> 1] = 0.f; rstd[(i - LO) >> 1] = 1.f;
;                 if (LN) { const float2 st = *(const float2*)(stats + row * 2u); mean[(i - LO) >> 1] = st.x; rstd[(i - LO) >> 1] = st.y; } }
;             r[i - LO] = *(const f32x4*)(src + (row * (unsigned)DM + col0 + BJ * HALF + n * 16)); }
; #pragma unroll
;         for (int i = LO; i < HI; ++i) { const int ai = i >> 3, m = (i >> 1) & 3, n = i & 1; const unsigned row = row0 + ai * HALF + m * 16;
;             *(f32x4*)(Y + (row * (unsigned)DM + col0 + BJ * HALF + n * 16)) = acc[ai][BJ][m][n] + ((r[i - LO] - mean[(i - LO) >> 1]) * rstd[(i - LO) >> 1]) * gv[n] + bv[n]; }
;         __builtin_amdgcn_sched_barrier(0);
;     }
;     template <bool LN, int BJ> DI void load_gb(unsigned col0, f32x4 (&gv)[2], f32x4 (&bv)[2]) const {
; #pragma unroll
;         for (int n = 0; n < 2; ++n) {
;             if (LN) { gv[n] = *(const f32x4*)(gam + col0 + BJ * HALF + n * 16) * ALPHA; bv[n] = *(const f32x4*)(bet + col0 + BJ * HALF + n * 16) * ALPHA; }
;             else { gv[n] = (f32x4){ALPHA, ALPHA, ALPHA, ALPHA}; bv[n] = (f32x4){0.f, 0.f, 0.f, 0.f}; }
;         }
;     }
;     template <bool LN> DI void run(const f32x4 (&acc)[2][2][4][2], const Unit& u, int wr, int wc, int fr, int fq) const {
;         const unsigned row0 = u.pm * BM + wr * 64 + fr, col0 = u.pn * BM + wc * 32 + 4 * fq;
;         f32x4 gv[2], bv[2];
;         load_gb<LN, 0>(col0, gv, bv);
;         batch<LN, 0, 0, 4>(acc, row0, col0, gv, bv);
;         batch<LN, 0, 4, 8>(acc, row0, col0, gv, bv);
;         batch<LN, 0, 8, 12>(acc, row0, col0, gv, bv);
;         batch<LN, 0, 12, 16>(acc, row0, col0, gv, bv);
;         load_gb<LN, 1>(col0, gv, bv);
;         batch<LN, 1, 0, 8>(acc, row0, col0, gv, bv);
;         batch<LN, 1, 8, 16>(acc, row0, col0, gv, bv);
	v_pk_mul_f32 v[212:213], v[130:131], s[78:79] op_sel_hi:[1,0]
	v_pk_mul_f32 v[214:215], v[128:129], s[78:79] op_sel_hi:[1,0]
	global_load_dwordx4 v[132:135], v[142:143], off offset:512
	global_load_dwordx4 v[128:131], v[140:141], off offset:576
	s_waitcnt vmcnt(0)
	v_pk_mul_f32 v[206:207], v[130:131], s[78:79] op_sel_hi:[1,0]
	v_pk_mul_f32 v[208:209], v[128:129], s[78:79] op_sel_hi:[1,0]
	global_load_dwordx4 v[128:131], v[142:143], off offset:576
	global_load_dwordx2 v[220:221], v[144:145], off
	global_load_dwordx4 v[240:243], v[136:137], off
	v_add_u32_e32 v136, v232, v229
	v_mov_b32_e32 v137, v159
	v_lshl_add_u64 v[136:137], v[136:137], 2, s[88:89]
	global_load_dwordx4 v[244:247], v[136:137], off
	global_load_dwordx2 v[218:219], v[146:147], off
	v_add_u32_e32 v136, v195, v230
	v_mov_b32_e32 v137, v159
	v_lshl_add_u64 v[136:137], v[136:137], 2, s[88:89]
	global_load_dwordx4 v[248:251], v[136:137], off
	v_add_u32_e32 v136, v195, v229
	v_mov_b32_e32 v137, v159
	v_lshl_add_u64 v[136:137], v[136:137], 2, s[88:89]
	global_load_dwordx4 v[152:155], v[136:137], off
	global_load_dwordx2 v[216:217], v[200:201], off
	v_add_u32_e32 v136, v236, v230
	v_mov_b32_e32 v137, v159
	v_lshl_add_u64 v[136:137], v[136:137], 2, s[88:89]
	global_load_dwordx4 v[148:151], v[136:137], off
	v_add_u32_e32 v136, v236, v229
	v_mov_b32_e32 v137, v159
	v_lshl_add_u64 v[136:137], v[136:137], 2, s[88:89]
	global_load_dwordx4 v[144:147], v[136:137], off
	global_load_dwordx2 v[200:201], v[202:203], off
	v_add_u32_e32 v136, v235, v230
	v_mov_b32_e32 v137, v159
	v_lshl_add_u64 v[136:137], v[136:137], 2, s[88:89]
	global_load_dwordx4 v[140:143], v[136:137], off
	v_add_u32_e32 v136, v235, v229
	v_mov_b32_e32 v137, v159
	v_lshl_add_u64 v[136:137], v[136:137], 2, s[88:89]
	global_load_dwordx4 v[136:139], v[136:137], off
	v_add_u32_e32 v202, 0x80, v194
	v_mov_b32_e32 v203, v159
	v_lshl_add_u64 v[202:203], v[202:203], 2, s[90:91]
	s_waitcnt vmcnt(0)
	v_sub_f32_e32 v241, v241, v220
	v_sub_f32_e32 v240, v240, v220
	v_sub_f32_e32 v243, v243, v220
	v_sub_f32_e32 v242, v242, v220
	v_pk_mul_f32 v[242:243], v[220:221], v[242:243] op_sel:[1,0]
	v_pk_mul_f32 v[240:241], v[220:221], v[240:241] op_sel:[1,0]
	v_pk_fma_f32 v[242:243], v[212:213], v[242:243], v[62:63]
	v_pk_fma_f32 v[240:241], v[214:215], v[240:241], v[60:61]
	v_pk_fma_f32 v[242:243], v[134:135], s[78:79], v[242:243] op_sel_hi:[1,0,1]
	v_pk_fma_f32 v[240:241], v[132:133], s[78:79], v[240:241] op_sel_hi:[1,0,1]
	global_store_dwordx4 v[202:203], v[240:243], off
	v_sub_f32_e32 v203, v245, v220
	v_sub_f32_e32 v202, v244, v220
	v_sub_f32_e32 v241, v247, v220
	v_sub_f32_e32 v240, v246, v220
	v_pk_mul_f32 v[202:203], v[220:221], v[202:203] op_sel:[1,0]
	v_pk_mul_f32 v[240:241], v[220:221], v[240:241] op_sel:[1,0]
	v_pk_fma_f32 v[202:203], v[208:209], v[202:203], v[56:57]
	v_pk_fma_f32 v[220:221], v[206:207], v[240:241], v[58:59]
	v_pk_fma_f32 v[240:241], v[128:129], s[78:79], v[202:203] op_sel_hi:[1,0,1]
	v_add_u32_e32 v202, 0x90, v194
	v_mov_b32_e32 v203, v159
	v_pk_fma_f32 v[242:243], v[130:131], s[78:79], v[220:221] op_sel_hi:[1,0,1]
	v_lshl_add_u64 v[202:203], v[202:203], 2, s[90:91]
	global_store_dwordx4 v[202:203], v[240:243], off
	v_sub_f32_e32 v203, v249, v218
	v_sub_f32_e32 v202, v248, v218
	v_sub_f32_e32 v221, v251, v218
	v_sub_f32_e32 v220, v250, v218
	v_pk_mul_f32 v[202:203], v[218:219], v[202:203] op_sel:[1,0]
	v_pk_mul_f32 v[220:221], v[218:219], v[220:221] op_sel:[1,0]
	v_pk_fma_f32 v[202:203], v[214:215], v[202:203], v[52:53]
	v_pk_fma_f32 v[220:221], v[212:213], v[220:221], v[54:55]
	v_pk_fma_f32 v[240:241], v[132:133], s[78:79], v[202:203] op_sel_hi:[1,0,1]
	v_add_u32_e32 v202, 0x8080, v194
	v_mov_b32_e32 v203, v159
	v_sub_f32_e32 v153, v153, v218
	v_sub_f32_e32 v152, v152, v218
	v_sub_f32_e32 v155, v155, v218
	v_sub_f32_e32 v154, v154, v218
	v_pk_fma_f32 v[242:243], v[134:135], s[78:79], v[220:221] op_sel_hi:[1,0,1]
	v_lshl_add_u64 v[202:203], v[202:203], 2, s[90:91]
	v_pk_mul_f32 v[154:155], v[218:219], v[154:155] op_sel:[1,0]
	v_pk_mul_f32 v[152:153], v[218:219], v[152:153] op_sel:[1,0]
	global_store_dwordx4 v[202:203], v[240:243], off
	v_pk_fma_f32 v[152:153], v[208:209], v[152:153], v[48:49]
	v_pk_fma_f32 v[154:155], v[206:207], v[154:155], v[50:51]
	v_add_u32_e32 v202, 0x8090, v194
	v_mov_b32_e32 v203, v159
	v_sub_f32_e32 v149, v149, v216
	v_sub_f32_e32 v148, v148, v216
	v_sub_f32_e32 v151, v151, v216
	v_sub_f32_e32 v150, v150, v216
	v_pk_fma_f32 v[154:155], v[130:131], s[78:79], v[154:155] op_sel_hi:[1,0,1]
	v_pk_fma_f32 v[152:153], v[128:129], s[78:79], v[152:153] op_sel_hi:[1,0,1]
	v_lshl_add_u64 v[202:203], v[202:203], 2, s[90:91]
	v_pk_mul_f32 v[150:151], v[216:217], v[150:151] op_sel:[1,0]
	v_pk_mul_f32 v[148:149], v[216:217], v[148:149] op_sel:[1,0]
	global_store_dwordx4 v[202:203], v[152:155], off
	v_pk_fma_f32 v[148:149], v[214:215], v[148:149], v[44:45]
	v_pk_fma_f32 v[150:151], v[212:213], v[150:151], v[46:47]
	v_add_u32_e32 v152, 0x10080, v194
	v_mov_b32_e32 v153, v159
	v_sub_f32_e32 v145, v145, v216
	v_sub_f32_e32 v144, v144, v216
	v_sub_f32_e32 v147, v147, v216
	v_sub_f32_e32 v146, v146, v216
	v_pk_fma_f32 v[150:151], v[134:135], s[78:79], v[150:151] op_sel_hi:[1,0,1]
	v_pk_fma_f32 v[148:149], v[132:133], s[78:79], v[148:149] op_sel_hi:[1,0,1]
	v_lshl_add_u64 v[152:153], v[152:153], 2, s[90:91]
	v_pk_mul_f32 v[146:147], v[216:217], v[146:147] op_sel:[1,0]
	v_pk_mul_f32 v[144:145], v[216:217], v[144:145] op_sel:[1,0]
	global_store_dwordx4 v[152:153], v[148:151], off
	v_pk_fma_f32 v[144:145], v[208:209], v[144:145], v[40:41]
	v_pk_fma_f32 v[146:147], v[206:207], v[146:147], v[42:43]
;     template <bool LN, int BJ, int LO, int HI> DI void batch(const f32x4 (&acc)[2][2][4][2], unsigned row0, unsigned col0, const f32x4 (&gv)[2], const f32x4 (&bv)[2]) const {
;         f32x4 r[HI - LO]; float mean[(HI - LO) / 2], rstd[(HI - LO) / 2];
; #pragma unroll
;         for (int i = LO; i < HI; ++i) { const int ai = i >> 3, m = (i >> 1) & 3, n = i & 1; const unsigned row = row0 + ai * HALF + m * 16;
;             if (n == 0) { mean[(i - LO) >> 1] = 0.f; rstd[(i - LO) >> 1] = 1.f;
;                 if (LN) { const float2 st = *(const float2*)(stats + row * 2u); mean[(i - LO) >> 1] = st.x; rstd[(i - LO) >> 1] = st.y; } }
;             r[i - LO] = *(const f32x4*)(src + (row * (unsigned)DM + col0 + BJ * HALF + n * 16)); }
; #pragma unroll
;         for (int i = LO; i < HI; ++i) { const int ai = i >> 3, m = (i >> 1) & 3, n = i & 1; const unsigned row = row0 + ai * HALF + m * 16;
;             *(f32x4*)(Y + (row * (unsigned)DM + col0 + BJ * HALF + n * 16)) = acc[ai][BJ][m][n] + ((r[i - LO] - mean[(i - LO) >> 1]) * rstd[(i - LO) >> 1]) * gv[n] + bv[n]; }
;         __builtin_amdgcn_sched_barrier(0);
;     }
;     template <bool LN, int BJ> DI void load_gb(unsigned col0, f32x4 (&gv)[2], f32x4 (&bv)[2]) const {
; #pragma unroll
;         for (int n = 0; n < 2; ++n) {
;             if (LN) { gv[n] = *(const f32x4*)(gam + col0 + BJ * HALF + n * 16) * ALPHA; bv[n] = *(const f32x4*)(bet + col0 + BJ * HALF + n * 16) * ALPHA; }
;             else { gv[n] = (f32x4){ALPHA, ALPHA, ALPHA, ALPHA}; bv[n] = (f32x4){0.f, 0.f, 0.f, 0.f}; }
;         }
;     }
;     template <bool LN> DI void run(const f32x4 (&acc)[2][2][4][2], const Unit& u, int wr, int wc, int fr, int fq) const {
;         const unsigned row0 = u.pm * BM + wr * 64 + fr, col0 = u.pn * BM + wc * 32 + 4 * fq;
;         f32x4 gv[2], bv[2];
;         load_gb<LN, 0>(col0, gv, bv);
;         batch<LN, 0, 0, 4>(acc, row0, col0, gv, bv);
;         batch<LN, 0, 4, 8>(acc, row0, col0, gv, bv);
;         batch<LN, 0, 8, 12>(acc, row0, col0, gv, bv);
;         batch<LN, 0, 12, 16>(acc, row0, col0, gv, bv);
;         load_gb<LN, 1>(col0, gv, bv);
;         batch<LN, 1, 0, 8>(acc, row0, col0, gv, bv);
;         batch<LN, 1, 8, 16>(acc, row0, col0, gv, bv);
	v_add_u32_e32 v148, 0x10090, v194
	v_mov_b32_e32 v149, v159
	v_sub_f32_e32 v141, v141, v200
	v_sub_f32_e32 v140, v140, v200
	v_sub_f32_e32 v143, v143, v200
	v_sub_f32_e32 v142, v142, v200
	v_pk_fma_f32 v[146:147], v[130:131], s[78:79], v[146:147] op_sel_hi:[1,0,1]
	v_pk_fma_f32 v[144:145], v[128:129], s[78:79], v[144:145] op_sel_hi:[1,0,1]
	v_lshl_add_u64 v[148:149], v[148:149], 2, s[90:91]
	v_pk_mul_f32 v[142:143], v[200:201], v[142:143] op_sel:[1,0]
	v_pk_mul_f32 v[140:141], v[200:201], v[140:141] op_sel:[1,0]
	global_store_dwordx4 v[148:149], v[144:147], off
	v_pk_fma_f32 v[140:141], v[214:215], v[140:141], v[36:37]
	v_pk_fma_f32 v[142:143], v[212:213], v[142:143], v[38:39]
	v_add_u32_e32 v144, 0x18080, v194
	v_mov_b32_e32 v145, v159
	v_sub_f32_e32 v137, v137, v200
	v_sub_f32_e32 v136, v136, v200
	v_sub_f32_e32 v139, v139, v200
	v_sub_f32_e32 v138, v138, v200
	v_pk_fma_f32 v[142:143], v[134:135], s[78:79], v[142:143] op_sel_hi:[1,0,1]
	v_pk_fma_f32 v[140:141], v[132:133], s[78:79], v[140:141] op_sel_hi:[1,0,1]
	v_lshl_add_u64 v[144:145], v[144:145], 2, s[90:91]
	v_pk_mul_f32 v[138:139], v[200:201], v[138:139] op_sel:[1,0]
	v_pk_mul_f32 v[136:137], v[200:201], v[136:137] op_sel:[1,0]
	global_store_dwordx4 v[144:145], v[140:143], off
	v_pk_fma_f32 v[136:137], v[208:209], v[136:137], v[32:33]
	v_pk_fma_f32 v[138:139], v[206:207], v[138:139], v[34:35]
	v_add_u32_e32 v140, 0x18090, v194
	v_mov_b32_e32 v141, v159
	v_pk_fma_f32 v[138:139], v[130:131], s[78:79], v[138:139] op_sel_hi:[1,0,1]
	v_pk_fma_f32 v[136:137], v[128:129], s[78:79], v[136:137] op_sel_hi:[1,0,1]
	v_lshl_add_u64 v[140:141], v[140:141], 2, s[90:91]
	global_store_dwordx4 v[140:141], v[136:139], off
	s_nop 1
	v_add_u32_e32 v136, v233, v230
	v_mov_b32_e32 v137, v159
	v_lshl_add_u64 v[136:137], v[136:137], 2, s[88:89]
	global_load_dwordx2 v[220:221], v[196:197], off
	global_load_dwordx4 v[216:219], v[136:137], off
	v_add_u32_e32 v136, v233, v229
	v_mov_b32_e32 v137, v159
	v_lshl_add_u64 v[136:137], v[136:137], 2, s[88:89]
	global_load_dwordx4 v[240:243], v[136:137], off
	global_load_dwordx2 v[200:201], v[198:199], off
	v_add_u32_e32 v136, v234, v230
	v_mov_b32_e32 v137, v159
	v_lshl_add_u64 v[136:137], v[136:137], 2, s[88:89]
	global_load_dwordx4 v[244:247], v[136:137], off
	v_add_u32_e32 v136, v234, v229
	v_mov_b32_e32 v137, v159
	v_lshl_add_u64 v[136:137], v[136:137], 2, s[88:89]
	global_load_dwordx4 v[152:155], v[136:137], off
	global_load_dwordx2 v[198:199], v[204:205], off
	v_add_u32_e32 v136, v237, v230
	v_mov_b32_e32 v137, v159
	v_lshl_add_u64 v[136:137], v[136:137], 2, s[88:89]
	global_load_dwordx4 v[148:151], v[136:137], off
	v_add_u32_e32 v136, v237, v229
	v_mov_b32_e32 v137, v159
	v_lshl_add_u64 v[136:137], v[136:137], 2, s[88:89]
	global_load_dwordx4 v[144:147], v[136:137], off
	global_load_dwordx2 v[196:197], v[210:211], off
	v_add_u32_e32 v136, v238, v230
	v_mov_b32_e32 v137, v159
	v_lshl_add_u64 v[136:137], v[136:137], 2, s[88:89]
	global_load_dwordx4 v[140:143], v[136:137], off
	v_add_u32_e32 v136, v238, v229
	v_mov_b32_e32 v137, v159
	v_lshl_add_u64 v[136:137], v[136:137], 2, s[88:89]
	global_load_dwordx4 v[136:139], v[136:137], off
	v_add_u32_e32 v210, 0x40080, v194
	v_mov_b32_e32 v211, v159
	v_lshl_add_u64 v[210:211], v[210:211], 2, s[90:91]
	s_waitcnt vmcnt(0)
;     template <bool LN, int BJ, int LO, int HI> DI void batch(const f32x4 (&acc)[2][2][4][2], unsigned row0, unsigned col0, const f32x4 (&gv)[2], const f32x4 (&bv)[2]) const {
;         f32x4 r[HI - LO]; float mean[(HI - LO) / 2], rstd[(HI - LO) / 2];
; #pragma unroll
;         for (int i = LO; i < HI; ++i) { const int ai = i >> 3, m = (i >> 1) & 3, n = i & 1; const unsigned row = row0 + ai * HALF + m * 16;
;             if (n == 0) { mean[(i - LO) >> 1] = 0.f; rstd[(i - LO) >> 1] = 1.f;
;                 if (LN) { const float2 st = *(const float2*)(stats + row * 2u); mean[(i - LO) >> 1] = st.x; rstd[(i - LO) >> 1] = st.y; } }
;             r[i - LO] = *(const f32x4*)(src + (row * (unsigned)DM + col0 + BJ * HALF + n * 16)); }
; #pragma unroll
;         for (int i = LO; i < HI; ++i) { const int ai = i >> 3, m = (i >> 1) & 3, n = i & 1; const unsigned row = row0 + ai * HALF + m * 16;
;             *(f32x4*)(Y + (row * (unsigned)DM + col0 + BJ * HALF + n * 16)) = acc[ai][BJ][m][n] + ((r[i - LO] - mean[(i - LO) >> 1]) * rstd[(i - LO) >> 1]) * gv[n] + bv[n]; }
;         __builtin_amdgcn_sched_barrier(0);
;     }
;     template <bool LN, int BJ> DI void load_gb(unsigned col0, f32x4 (&gv)[2], f32x4 (&bv)[2]) const {
; #pragma unroll
;         for (int n = 0; n < 2; ++n) {
;             if (LN) { gv[n] = *(const f32x4*)(gam + col0 + BJ * HALF + n * 16) * ALPHA; bv[n] = *(const f32x4*)(bet + col0 + BJ * HALF + n * 16) * ALPHA; }
;             else { gv[n] = (f32x4){ALPHA, ALPHA, ALPHA, ALPHA}; bv[n] = (f32x4){0.f, 0.f, 0.f, 0.f}; }
;         }
;     }
;     template <bool LN> DI void run(const f32x4 (&acc)[2][2][4][2], const Unit& u, int wr, int wc, int fr, int fq) const {
;         const unsigned row0 = u.pm * BM + wr * 64 + fr, col0 = u.pn * BM + wc * 32 + 4 * fq;
;         f32x4 gv[2], bv[2];
;         load_gb<LN, 0>(col0, gv, bv);
;         batch<LN, 0, 0, 4>(acc, row0, col0, gv, bv);
;         batch<LN, 0, 4, 8>(acc, row0, col0, gv, bv);
;         batch<LN, 0, 8, 12>(acc, row0, col0, gv, bv);
;         batch<LN, 0, 12, 16>(acc, row0, col0, gv, bv);
;         load_gb<LN, 1>(col0, gv, bv);
;         batch<LN, 1, 0, 8>(acc, row0, col0, gv, bv);
;         batch<LN, 1, 8, 16>(acc, row0, col0, gv, bv);
	v_sub_f32_e32 v203, v217, v220
	v_sub_f32_e32 v202, v216, v220
	v_sub_f32_e32 v205, v219, v220
	v_sub_f32_e32 v204, v218, v220
	v_pk_mul_f32 v[204:205], v[220:221], v[204:205] op_sel:[1,0]
	v_pk_mul_f32 v[202:203], v[220:221], v[202:203] op_sel:[1,0]
	v_pk_fma_f32 v[204:205], v[212:213], v[204:205], v[30:31]
	v_pk_fma_f32 v[202:203], v[214:215], v[202:203], v[28:29]
	v_pk_fma_f32 v[204:205], v[134:135], s[78:79], v[204:205] op_sel_hi:[1,0,1]
	v_pk_fma_f32 v[202:203], v[132:133], s[78:79], v[202:203] op_sel_hi:[1,0,1]
	global_store_dwordx4 v[210:211], v[202:205], off
	v_add_u32_e32 v210, 0x40090, v194
	v_mov_b32_e32 v211, v159
	v_sub_f32_e32 v203, v241, v220
	v_sub_f32_e32 v202, v240, v220
	v_sub_f32_e32 v205, v243, v220
	v_sub_f32_e32 v204, v242, v220
	v_pk_mul_f32 v[204:205], v[220:221], v[204:205] op_sel:[1,0]
	v_pk_mul_f32 v[202:203], v[220:221], v[202:203] op_sel:[1,0]
	v_pk_fma_f32 v[204:205], v[206:207], v[204:205], v[26:27]
	v_pk_fma_f32 v[202:203], v[208:209], v[202:203], v[24:25]
	v_pk_fma_f32 v[204:205], v[130:131], s[78:79], v[204:205] op_sel_hi:[1,0,1]
	v_pk_fma_f32 v[202:203], v[128:129], s[78:79], v[202:203] op_sel_hi:[1,0,1]
	v_lshl_add_u64 v[210:211], v[210:211], 2, s[90:91]
	global_store_dwordx4 v[210:211], v[202:205], off
	v_sub_f32_e32 v149, v149, v198
	v_sub_f32_e32 v148, v148, v198
	v_sub_f32_e32 v203, v245, v200
	v_sub_f32_e32 v202, v244, v200
	v_sub_f32_e32 v141, v141, v196
	v_sub_f32_e32 v140, v140, v196
	v_sub_f32_e32 v205, v247, v200
	v_sub_f32_e32 v204, v246, v200
	v_pk_mul_f32 v[202:203], v[200:201], v[202:203] op_sel:[1,0]
	v_sub_f32_e32 v151, v151, v198
	v_sub_f32_e32 v150, v150, v198
	v_pk_mul_f32 v[148:149], v[198:199], v[148:149] op_sel:[1,0]
	v_sub_f32_e32 v143, v143, v196
	v_sub_f32_e32 v142, v142, v196
	v_pk_mul_f32 v[140:141], v[196:197], v[140:141] op_sel:[1,0]
	v_pk_mul_f32 v[204:205], v[200:201], v[204:205] op_sel:[1,0]
	v_pk_fma_f32 v[202:203], v[214:215], v[202:203], v[20:21]
	v_sub_f32_e32 v153, v153, v200
	v_sub_f32_e32 v152, v152, v200
	v_sub_f32_e32 v155, v155, v200
	v_sub_f32_e32 v154, v154, v200
	v_pk_mul_f32 v[150:151], v[198:199], v[150:151] op_sel:[1,0]
	v_pk_fma_f32 v[148:149], v[214:215], v[148:149], v[12:13]
	v_pk_mul_f32 v[142:143], v[196:197], v[142:143] op_sel:[1,0]
	v_pk_fma_f32 v[140:141], v[214:215], v[140:141], v[4:5]
	v_pk_fma_f32 v[204:205], v[212:213], v[204:205], v[22:23]
	v_pk_fma_f32 v[202:203], v[132:133], s[78:79], v[202:203] op_sel_hi:[1,0,1]
	v_pk_mul_f32 v[154:155], v[200:201], v[154:155] op_sel:[1,0]
	v_pk_mul_f32 v[152:153], v[200:201], v[152:153] op_sel:[1,0]
	v_pk_fma_f32 v[150:151], v[212:213], v[150:151], v[14:15]
	v_pk_fma_f32 v[148:149], v[132:133], s[78:79], v[148:149] op_sel_hi:[1,0,1]
	v_pk_fma_f32 v[142:143], v[212:213], v[142:143], v[6:7]
	v_pk_fma_f32 v[132:133], v[132:133], s[78:79], v[140:141] op_sel_hi:[1,0,1]
	v_add_u32_e32 v140, 0x58080, v194
	v_mov_b32_e32 v141, v159
	v_pk_fma_f32 v[204:205], v[134:135], s[78:79], v[204:205] op_sel_hi:[1,0,1]
	v_pk_fma_f32 v[152:153], v[208:209], v[152:153], v[16:17]
	v_pk_fma_f32 v[154:155], v[206:207], v[154:155], v[18:19]
	v_add_u32_e32 v200, 0x48090, v194
	v_mov_b32_e32 v201, v159
	v_pk_fma_f32 v[150:151], v[134:135], s[78:79], v[150:151] op_sel_hi:[1,0,1]
	v_pk_fma_f32 v[134:135], v[134:135], s[78:79], v[142:143] op_sel_hi:[1,0,1]
	v_lshl_add_u64 v[140:141], v[140:141], 2, s[90:91]
	v_pk_fma_f32 v[154:155], v[130:131], s[78:79], v[154:155] op_sel_hi:[1,0,1]
	v_pk_fma_f32 v[152:153], v[128:129], s[78:79], v[152:153] op_sel_hi:[1,0,1]
	v_lshl_add_u64 v[200:201], v[200:201], 2, s[90:91]
	v_sub_f32_e32 v145, v145, v198
	v_sub_f32_e32 v144, v144, v198
	global_store_dwordx4 v[140:141], v[132:135], off
	global_store_dwordx4 v[200:201], v[152:155], off
	v_sub_f32_e32 v147, v147, v198
	v_sub_f32_e32 v133, v137, v196
	v_sub_f32_e32 v132, v136, v196
	v_add_u32_e32 v152, 0x50080, v194
	v_mov_b32_e32 v153, v159
	v_sub_f32_e32 v146, v146, v198
	v_pk_mul_f32 v[144:145], v[198:199], v[144:145] op_sel:[1,0]
	v_sub_f32_e32 v135, v139, v196
	v_sub_f32_e32 v134, v138, v196
	v_pk_mul_f32 v[132:133], v[196:197], v[132:133] op_sel:[1,0]
	v_lshl_add_u64 v[152:153], v[152:153], 2, s[90:91]
	v_pk_mul_f32 v[146:147], v[198:199], v[146:147] op_sel:[1,0]
	v_pk_fma_f32 v[144:145], v[208:209], v[144:145], v[8:9]
	v_pk_mul_f32 v[134:135], v[196:197], v[134:135] op_sel:[1,0]
	v_pk_fma_f32 v[132:133], v[208:209], v[132:133], v[0:1]
	v_add_u32_e32 v210, 0x48080, v194
	v_mov_b32_e32 v211, v159
	global_store_dwordx4 v[152:153], v[148:151], off
	v_pk_fma_f32 v[146:147], v[206:207], v[146:147], v[10:11]
	v_pk_fma_f32 v[144:145], v[128:129], s[78:79], v[144:145] op_sel_hi:[1,0,1]
	v_add_u32_e32 v148, 0x50090, v194
	v_mov_b32_e32 v149, v159
	v_pk_fma_f32 v[134:135], v[206:207], v[134:135], v[2:3]
	v_pk_fma_f32 v[128:129], v[128:129], s[78:79], v[132:133] op_sel_hi:[1,0,1]
	v_add_u32_e32 v132, 0x58090, v194
	v_mov_b32_e32 v133, v159
	v_lshl_add_u64 v[210:211], v[210:211], 2, s[90:91]
	v_pk_fma_f32 v[146:147], v[130:131], s[78:79], v[146:147] op_sel_hi:[1,0,1]
	v_lshl_add_u64 v[148:149], v[148:149], 2, s[90:91]
	v_pk_fma_f32 v[130:131], v[130:131], s[78:79], v[134:135] op_sel_hi:[1,0,1]
	v_lshl_add_u64 v[132:133], v[132:133], 2, s[90:91]
	global_store_dwordx4 v[210:211], v[202:205], off
	global_store_dwordx4 v[148:149], v[144:147], off
	global_store_dwordx4 v[132:133], v[128:131], off
	s_mov_b64 s[20:21], 0
	s_branch .LBB0_81

; #define PG8_STAGE(bufoff, gbase) do { _Pragma("unroll") for (int _i = 0; _i < 2; ++_i) \
;         __builtin_amdgcn_global_load_lds((const unsigned*)((const char*)(gbase) + voff[_i]), (LAS unsigned*)(lds + (bufoff) + ldsw + _i * 8192), 16, 0, 0); } while (0)
; #define PG8_LDA(dst, b, h) do { _Pragma("unroll") for (int m = 0; m < 4; ++m) _Pragma("unroll") for (int k = 0; k < 2; ++k) dst[m][k] = *(const LAS bf16x8*)(lds + PG8_SA(b, h) + aoff + m * 2048 + k * 1024); } while (0)
; #define PG8_LDB(dst, b, h) do { _Pragma("unroll") for (int n = 0; n < 2; ++n) _Pragma("unroll") for (int k = 0; k < 2; ++k) dst[n][k] = *(const LAS bf16x8*)(lds + PG8_SB(b, h) + boff + n * 2048 + k * 1024); } while (0)
; #define PG8_MMA(ai, bj, At, Bt) do { __builtin_amdgcn_s_setprio(1); _Pragma("unroll") for (int m = 0; m < 4; ++m) _Pragma("unroll") for (int n = 0; n < 2; ++n) _Pragma("unroll") for (int k = 0; k < 2; ++k) \
;         acc[ai][bj][m][n] = __builtin_amdgcn_mfma_f32_16x16x32_bf16(Bt[n][k], At[m][k], acc[ai][bj][m][n], 0, 0, 0); __builtin_amdgcn_s_setprio(0); } while (0)
; #define PG8_WAIT_L(n) asm volatile("s_waitcnt lgkmcnt(" #n ")" ::: "memory")
; #define PG8_BAR __builtin_amdgcn_s_barrier()
; #define PG8_SCHED __builtin_amdgcn_sched_barrier(0)
; template <class Epi>
; DI void gemm_phase(LAS unsigned char* lds, const Gemm g, const StaticOrder& S, const Epi& E) {
;     ...
;         for (int t = 0; t < nt; t += 2) {
;             const bool last = (t == nt - 2);
;             const char* a1 = cA + (size_t)(t + 1) * kstep;
;             const char* a2 = last ? nA : cA + (size_t)(t + 2) * kstep; const char* b2 = last ? nB : cB + (size_t)(t + 2) * kstep;
;             const char* a3 = a2 + kstep; const char* b3 = b2 + kstep;
;             PG8_LDB(B0, 0, 0); PG8_SCHED; PG8_LDA(At, 0, 0); PG8_STAGE(PG8_SA(1, 1), a1 + hstep);
;             PG8_WAIT_L(8); PG8_BAR; PG8_WAIT_L(0); PG8_MMA(0, 0, At, B0); PG8_BAR; PG8_SCHED;
;             PG8_LDB(B1, 0, 1); PG8_STAGE(PG8_SB(0, 0), b2);
;             PG8_BAR; PG8_WAIT_L(0); PG8_MMA(0, 1, At, B1); PG8_BAR;
;             PG8_LDA(At, 0, 1); PG8_STAGE(PG8_SA(0, 0), a2);
;             PG8_BAR; PG8_WAIT_L(0); PG8_MMA(1, 0, At, B0); PG8_BAR; PG8_SCHED;
.LBB0_134:
	s_add_u32 s18, s16, 0x100
	s_addc_u32 s19, s17, 0
	s_add_i32 s39, 0, 0x10000
	v_add_u32_e32 v148, s39, v199
	ds_read_b128 v[96:99], v148
	ds_read_b128 v[100:103], v148 offset:1024
	ds_read_b128 v[136:139], v148 offset:2048
	ds_read_b128 v[148:151], v148 offset:3072
	s_cmpk_eq_i32 s33, 0x54
	s_cselect_b32 s23, s9, s19
	s_cselect_b32 s22, s8, s18
	s_cselect_b32 s21, s11, s5
	s_cselect_b32 s20, s10, s4
	v_lshl_add_u64 v[218:219], s[16:17], 0, v[144:145]
	s_add_i32 m0, s28, 0xc000
	ds_read_b128 v[152:155], v201
	ds_read_b128 v[186:189], v201 offset:1024
	ds_read_b128 v[190:193], v201 offset:2048
	ds_read_b128 v[194:197], v201 offset:3072
	ds_read_b128 v[202:205], v201 offset:4096
	ds_read_b128 v[206:209], v201 offset:5120
	ds_read_b128 v[210:213], v201 offset:6144
	ds_read_b128 v[214:217], v201 offset:7168
	global_load_lds_dwordx4 v[218:219], off
	v_lshl_add_u64 v[218:219], s[16:17], 0, v[146:147]
	s_add_i32 m0, s28, 0xe000
	s_nop 0
	global_load_lds_dwordx4 v[218:219], off
	s_waitcnt lgkmcnt(8)
	s_setprio 1
	s_barrier
	s_waitcnt lgkmcnt(0)
	v_mfma_f32_16x16x32_bf16 v[132:135], v[96:99], v[152:155], v[132:135]
	v_mfma_f32_16x16x32_bf16 v[128:131], v[136:139], v[152:155], v[128:131]
	v_mfma_f32_16x16x32_bf16 v[124:127], v[96:99], v[190:193], v[124:127]
	v_mfma_f32_16x16x32_bf16 v[120:123], v[136:139], v[190:193], v[120:123]
	v_mfma_f32_16x16x32_bf16 v[116:119], v[96:99], v[202:205], v[116:119]
	v_mfma_f32_16x16x32_bf16 v[112:115], v[136:139], v[202:205], v[112:115]
	v_mfma_f32_16x16x32_bf16 v[108:111], v[96:99], v[210:213], v[108:111]
	v_mfma_f32_16x16x32_bf16 v[104:107], v[136:139], v[210:213], v[104:107]
	v_mfma_f32_16x16x32_bf16 v[132:135], v[100:103], v[186:189], v[132:135]
	v_mfma_f32_16x16x32_bf16 v[128:131], v[148:151], v[186:189], v[128:131]
	v_mfma_f32_16x16x32_bf16 v[124:127], v[100:103], v[194:197], v[124:127]
	v_mfma_f32_16x16x32_bf16 v[120:123], v[148:151], v[194:197], v[120:123]
	v_mfma_f32_16x16x32_bf16 v[116:119], v[100:103], v[206:209], v[116:119]
	v_mfma_f32_16x16x32_bf16 v[112:115], v[148:151], v[206:209], v[112:115]
	v_mfma_f32_16x16x32_bf16 v[108:111], v[100:103], v[214:217], v[108:111]
	v_mfma_f32_16x16x32_bf16 v[104:107], v[148:151], v[214:217], v[104:107]
	s_setprio 0
	s_barrier
	s_add_i32 s40, 0, 0x14000
	s_add_i32 s16, s39, s27
	v_add_u32_e32 v158, s40, v199
	v_lshl_add_u64 v[218:219], s[20:21], 0, v[142:143]
	s_mov_b32 m0, s16
	ds_read_b128 v[226:229], v158
	ds_read_b128 v[230:233], v158 offset:1024
	ds_read_b128 v[234:237], v158 offset:2048
	ds_read_b128 v[238:241], v158 offset:3072
	global_load_lds_dwordx4 v[218:219], off
	v_lshl_add_u64 v[220:221], s[20:21], 0, v[140:141]
	s_add_i32 m0, s16, 0x2000
	s_nop 0
	global_load_lds_dwordx4 v[220:221], off
	s_waitcnt lgkmcnt(0)
	s_setprio 1
	s_barrier
	v_mfma_f32_16x16x32_bf16 v[60:63], v[226:229], v[152:155], v[60:63]
	v_mfma_f32_16x16x32_bf16 v[56:59], v[234:237], v[152:155], v[56:59]
	v_mfma_f32_16x16x32_bf16 v[52:55], v[226:229], v[190:193], v[52:55]
	v_mfma_f32_16x16x32_bf16 v[48:51], v[234:237], v[190:193], v[48:51]
	v_mfma_f32_16x16x32_bf16 v[44:47], v[226:229], v[202:205], v[44:47]
	v_mfma_f32_16x16x32_bf16 v[40:43], v[234:237], v[202:205], v[40:43]
	v_mfma_f32_16x16x32_bf16 v[36:39], v[226:229], v[210:213], v[36:39]
	v_mfma_f32_16x16x32_bf16 v[32:35], v[234:237], v[210:213], v[32:35]
	v_mfma_f32_16x16x32_bf16 v[60:63], v[230:233], v[186:189], v[60:63]
	v_mfma_f32_16x16x32_bf16 v[56:59], v[238:241], v[186:189], v[56:59]
	v_mfma_f32_16x16x32_bf16 v[52:55], v[230:233], v[194:197], v[52:55]
	v_mfma_f32_16x16x32_bf16 v[48:51], v[238:241], v[194:197], v[48:51]
	s_mov_b32 m0, s28
	v_lshl_add_u64 v[242:243], s[22:23], 0, v[142:143]
	v_mfma_f32_16x16x32_bf16 v[44:47], v[230:233], v[206:209], v[44:47]
	v_mfma_f32_16x16x32_bf16 v[40:43], v[238:241], v[206:209], v[40:43]
	v_mfma_f32_16x16x32_bf16 v[36:39], v[230:233], v[214:217], v[36:39]
	v_mfma_f32_16x16x32_bf16 v[32:35], v[238:241], v[214:217], v[32:35]
	s_setprio 0
	s_barrier
	ds_read_b128 v[152:155], v201 offset:16384
	ds_read_b128 v[186:189], v201 offset:17408
	ds_read_b128 v[190:193], v201 offset:18432
	ds_read_b128 v[194:197], v201 offset:19456
	ds_read_b128 v[202:205], v201 offset:20480
	ds_read_b128 v[206:209], v201 offset:21504
	ds_read_b128 v[210:213], v201 offset:22528
	ds_read_b128 v[214:217], v201 offset:23552
	global_load_lds_dwordx4 v[242:243], off
	v_lshl_add_u64 v[244:245], s[22:23], 0, v[140:141]
	s_mov_b32 m0, s29
	s_nop 0
	global_load_lds_dwordx4 v[244:245], off
	s_waitcnt lgkmcnt(0)
	s_setprio 1
	s_barrier
	v_mfma_f32_16x16x32_bf16 v[92:95], v[96:99], v[152:155], v[92:95]
	v_mfma_f32_16x16x32_bf16 v[88:91], v[136:139], v[152:155], v[88:91]
	v_mfma_f32_16x16x32_bf16 v[84:87], v[96:99], v[190:193], v[84:87]
	v_mfma_f32_16x16x32_bf16 v[80:83], v[136:139], v[190:193], v[80:83]
	v_mfma_f32_16x16x32_bf16 v[76:79], v[96:99], v[202:205], v[76:79]
	v_mfma_f32_16x16x32_bf16 v[72:75], v[136:139], v[202:205], v[72:75]
	v_mfma_f32_16x16x32_bf16 v[68:71], v[96:99], v[210:213], v[68:71]
	v_mfma_f32_16x16x32_bf16 v[64:67], v[136:139], v[210:213], v[64:67]
	v_mfma_f32_16x16x32_bf16 v[92:95], v[100:103], v[186:189], v[92:95]
	v_mfma_f32_16x16x32_bf16 v[88:91], v[148:151], v[186:189], v[88:91]
	v_mfma_f32_16x16x32_bf16 v[84:87], v[100:103], v[194:197], v[84:87]
	v_mfma_f32_16x16x32_bf16 v[80:83], v[148:151], v[194:197], v[80:83]
	v_mfma_f32_16x16x32_bf16 v[76:79], v[100:103], v[206:209], v[76:79]
	v_mfma_f32_16x16x32_bf16 v[72:75], v[148:151], v[206:209], v[72:75]
	v_mfma_f32_16x16x32_bf16 v[68:71], v[100:103], v[214:217], v[68:71]
	v_mfma_f32_16x16x32_bf16 v[64:67], v[148:151], v[214:217], v[64:67]
	s_setprio 0
	s_barrier
; #define PG8_STAGE(bufoff, gbase) do { _Pragma("unroll") for (int _i = 0; _i < 2; ++_i) \
;         __builtin_amdgcn_global_load_lds((const unsigned*)((const char*)(gbase) + voff[_i]), (LAS unsigned*)(lds + (bufoff) + ldsw + _i * 8192), 16, 0, 0); } while (0)
; #define PG8_LDA(dst, b, h) do { _Pragma("unroll") for (int m = 0; m < 4; ++m) _Pragma("unroll") for (int k = 0; k < 2; ++k) dst[m][k] = *(const LAS bf16x8*)(lds + PG8_SA(b, h) + aoff + m * 2048 + k * 1024); } while (0)
; #define PG8_LDB(dst, b, h) do { _Pragma("unroll") for (int n = 0; n < 2; ++n) _Pragma("unroll") for (int k = 0; k < 2; ++k) dst[n][k] = *(const LAS bf16x8*)(lds + PG8_SB(b, h) + boff + n * 2048 + k * 1024); } while (0)
; #define PG8_MMA(ai, bj, At, Bt) do { __builtin_amdgcn_s_setprio(1); _Pragma("unroll") for (int m = 0; m < 4; ++m) _Pragma("unroll") for (int n = 0; n < 2; ++n) _Pragma("unroll") for (int k = 0; k < 2; ++k) \
;         acc[ai][bj][m][n] = __builtin_amdgcn_mfma_f32_16x16x32_bf16(Bt[n][k], At[m][k], acc[ai][bj][m][n], 0, 0, 0); __builtin_amdgcn_s_setprio(0); } while (0)
; #define PG8_WAIT_V(n) asm volatile("s_waitcnt vmcnt(" #n ")" ::: "memory")
; #define PG8_WAIT_L(n) asm volatile("s_waitcnt lgkmcnt(" #n ")" ::: "memory")
; #define PG8_BAR __builtin_amdgcn_s_barrier()
; #define PG8_SCHED __builtin_amdgcn_sched_barrier(0)
; template <class Epi>
; DI void gemm_phase(LAS unsigned char* lds, const Gemm g, const StaticOrder& S, const Epi& E) {
;     ...
;             PG8_STAGE(PG8_SB(0, 1), b2 + hstep);
;             PG8_WAIT_V(6); PG8_BAR; PG8_MMA(1, 1, At, B1); PG8_BAR;
;             PG8_LDB(B0, 1, 0); PG8_SCHED; PG8_LDA(At, 1, 0); PG8_STAGE(PG8_SA(0, 1), a2 + hstep);
;             PG8_WAIT_L(8); PG8_BAR; PG8_WAIT_L(0); PG8_MMA(0, 0, At, B0); PG8_BAR; PG8_SCHED;
;             PG8_LDB(B1, 1, 1); PG8_STAGE(PG8_SB(1, 0), b3);
;             PG8_BAR; PG8_WAIT_L(0); PG8_MMA(0, 1, At, B1); PG8_BAR;
;             PG8_LDA(At, 1, 1); PG8_STAGE(PG8_SA(1, 0), a3);
;             PG8_BAR; PG8_WAIT_L(0); PG8_MMA(1, 0, At, B0); PG8_BAR; PG8_SCHED;
	s_add_u32 s16, s20, 0x160000
	s_addc_u32 s17, s21, 0
	s_add_i32 s39, s40, s27
	v_lshl_add_u64 v[96:97], s[16:17], 0, v[142:143]
	s_mov_b32 m0, s39
	s_nop 0
	global_load_lds_dwordx4 v[96:97], off
	v_lshl_add_u64 v[96:97], s[16:17], 0, v[140:141]
	s_add_i32 m0, s39, 0x2000
	s_nop 0
	global_load_lds_dwordx4 v[96:97], off
	s_waitcnt vmcnt(6)
	s_setprio 1
	s_barrier
	v_mfma_f32_16x16x32_bf16 v[28:31], v[226:229], v[152:155], v[28:31]
	v_mfma_f32_16x16x32_bf16 v[24:27], v[234:237], v[152:155], v[24:27]
	v_mfma_f32_16x16x32_bf16 v[20:23], v[226:229], v[190:193], v[20:23]
	v_mfma_f32_16x16x32_bf16 v[16:19], v[234:237], v[190:193], v[16:19]
	v_mfma_f32_16x16x32_bf16 v[12:15], v[226:229], v[202:205], v[12:15]
	v_mfma_f32_16x16x32_bf16 v[8:11], v[234:237], v[202:205], v[8:11]
	v_mfma_f32_16x16x32_bf16 v[4:7], v[226:229], v[210:213], v[4:7]
	v_mfma_f32_16x16x32_bf16 v[0:3], v[234:237], v[210:213], v[0:3]
	v_mfma_f32_16x16x32_bf16 v[28:31], v[230:233], v[186:189], v[28:31]
	v_mfma_f32_16x16x32_bf16 v[24:27], v[238:241], v[186:189], v[24:27]
	v_mfma_f32_16x16x32_bf16 v[20:23], v[230:233], v[194:197], v[20:23]
	v_mfma_f32_16x16x32_bf16 v[16:19], v[238:241], v[194:197], v[16:19]
	s_add_i32 s39, 0, 0x18000
	v_add_u32_e32 v148, s39, v199
	v_mfma_f32_16x16x32_bf16 v[12:15], v[230:233], v[206:209], v[12:15]
	v_mfma_f32_16x16x32_bf16 v[8:11], v[238:241], v[206:209], v[8:11]
	v_mfma_f32_16x16x32_bf16 v[4:7], v[230:233], v[214:217], v[4:7]
	v_mfma_f32_16x16x32_bf16 v[0:3], v[238:241], v[214:217], v[0:3]
	s_setprio 0
	s_barrier
	ds_read_b128 v[96:99], v148
	ds_read_b128 v[100:103], v148 offset:1024
	ds_read_b128 v[136:139], v148 offset:2048
	ds_read_b128 v[148:151], v148 offset:3072
	s_add_u32 s16, s22, 0x160000
	s_addc_u32 s17, s23, 0
	s_mov_b32 m0, s30
	v_lshl_add_u64 v[226:227], s[16:17], 0, v[142:143]
	ds_read_b128 v[152:155], v201 offset:32768
	ds_read_b128 v[186:189], v201 offset:33792
	ds_read_b128 v[190:193], v201 offset:34816
	ds_read_b128 v[194:197], v201 offset:35840
	ds_read_b128 v[202:205], v201 offset:36864
	ds_read_b128 v[206:209], v201 offset:37888
	ds_read_b128 v[210:213], v201 offset:38912
	ds_read_b128 v[214:217], v201 offset:39936
	global_load_lds_dwordx4 v[226:227], off
	v_lshl_add_u64 v[226:227], s[16:17], 0, v[140:141]
	s_mov_b32 m0, s31
	s_nop 0
	global_load_lds_dwordx4 v[226:227], off
	s_waitcnt lgkmcnt(8)
	s_setprio 1
	s_barrier
	s_waitcnt lgkmcnt(0)
	v_mfma_f32_16x16x32_bf16 v[132:135], v[96:99], v[152:155], v[132:135]
	v_mfma_f32_16x16x32_bf16 v[128:131], v[136:139], v[152:155], v[128:131]
	v_mfma_f32_16x16x32_bf16 v[124:127], v[96:99], v[190:193], v[124:127]
	v_mfma_f32_16x16x32_bf16 v[120:123], v[136:139], v[190:193], v[120:123]
	v_mfma_f32_16x16x32_bf16 v[116:119], v[96:99], v[202:205], v[116:119]
	v_mfma_f32_16x16x32_bf16 v[112:115], v[136:139], v[202:205], v[112:115]
	v_mfma_f32_16x16x32_bf16 v[108:111], v[96:99], v[210:213], v[108:111]
	v_mfma_f32_16x16x32_bf16 v[104:107], v[136:139], v[210:213], v[104:107]
	v_mfma_f32_16x16x32_bf16 v[132:135], v[100:103], v[186:189], v[132:135]
	v_mfma_f32_16x16x32_bf16 v[128:131], v[148:151], v[186:189], v[128:131]
	v_mfma_f32_16x16x32_bf16 v[124:127], v[100:103], v[194:197], v[124:127]
	v_mfma_f32_16x16x32_bf16 v[120:123], v[148:151], v[194:197], v[120:123]
	v_mfma_f32_16x16x32_bf16 v[116:119], v[100:103], v[206:209], v[116:119]
	v_mfma_f32_16x16x32_bf16 v[112:115], v[148:151], v[206:209], v[112:115]
	v_mfma_f32_16x16x32_bf16 v[108:111], v[100:103], v[214:217], v[108:111]
	v_mfma_f32_16x16x32_bf16 v[104:107], v[148:151], v[214:217], v[104:107]
	s_setprio 0
	s_barrier
	s_add_i32 s22, 0, 0x1c000
	s_add_i32 s16, s39, s27
	v_add_u32_e32 v158, s22, v199
	v_lshl_add_u64 v[218:219], v[218:219], 0, s[94:95]
	s_mov_b32 m0, s16
	ds_read_b128 v[226:229], v158
	ds_read_b128 v[230:233], v158 offset:1024
	ds_read_b128 v[234:237], v158 offset:2048
	ds_read_b128 v[238:241], v158 offset:3072
	global_load_lds_dwordx4 v[218:219], off
	v_lshl_add_u64 v[218:219], v[220:221], 0, s[94:95]
	s_add_i32 m0, s16, 0x2000
	s_nop 0
	global_load_lds_dwordx4 v[218:219], off
	s_waitcnt lgkmcnt(0)
	s_setprio 1
	s_barrier
	v_mfma_f32_16x16x32_bf16 v[60:63], v[226:229], v[152:155], v[60:63]
	v_mfma_f32_16x16x32_bf16 v[56:59], v[234:237], v[152:155], v[56:59]
	v_mfma_f32_16x16x32_bf16 v[52:55], v[226:229], v[190:193], v[52:55]
	v_mfma_f32_16x16x32_bf16 v[48:51], v[234:237], v[190:193], v[48:51]
	v_mfma_f32_16x16x32_bf16 v[44:47], v[226:229], v[202:205], v[44:47]
	v_mfma_f32_16x16x32_bf16 v[40:43], v[234:237], v[202:205], v[40:43]
	v_mfma_f32_16x16x32_bf16 v[36:39], v[226:229], v[210:213], v[36:39]
	v_mfma_f32_16x16x32_bf16 v[32:35], v[234:237], v[210:213], v[32:35]
	v_mfma_f32_16x16x32_bf16 v[60:63], v[230:233], v[186:189], v[60:63]
	v_mfma_f32_16x16x32_bf16 v[56:59], v[238:241], v[186:189], v[56:59]
	v_mfma_f32_16x16x32_bf16 v[52:55], v[230:233], v[194:197], v[52:55]
	v_mfma_f32_16x16x32_bf16 v[48:51], v[238:241], v[194:197], v[48:51]
	s_mov_b32 m0, s34
	v_lshl_add_u64 v[218:219], v[242:243], 0, s[94:95]
	v_mfma_f32_16x16x32_bf16 v[44:47], v[230:233], v[206:209], v[44:47]
	v_mfma_f32_16x16x32_bf16 v[40:43], v[238:241], v[206:209], v[40:43]
	v_mfma_f32_16x16x32_bf16 v[36:39], v[230:233], v[214:217], v[36:39]
	v_mfma_f32_16x16x32_bf16 v[32:35], v[238:241], v[214:217], v[32:35]
	s_setprio 0
	s_barrier
	ds_read_b128 v[152:155], v201 offset:49152
	ds_read_b128 v[186:189], v201 offset:50176
	ds_read_b128 v[190:193], v201 offset:51200
	ds_read_b128 v[194:197], v201 offset:52224
	ds_read_b128 v[202:205], v201 offset:53248
	ds_read_b128 v[206:209], v201 offset:54272
	ds_read_b128 v[210:213], v201 offset:55296
	ds_read_b128 v[214:217], v201 offset:56320
	global_load_lds_dwordx4 v[218:219], off
	v_lshl_add_u64 v[218:219], v[244:245], 0, s[94:95]
	s_mov_b32 m0, s35
	s_nop 0
	global_load_lds_dwordx4 v[218:219], off
	s_waitcnt lgkmcnt(0)
	s_setprio 1
	s_barrier
; template <class Epi>
; DI void gemm_phase(LAS unsigned char* lds, const Gemm g, const StaticOrder& S, const Epi& E) {
;     ...
;             PG8_BAR; PG8_WAIT_L(0); PG8_MMA(1, 0, At, B0); PG8_BAR; PG8_SCHED;
;             PG8_STAGE(PG8_SB(1, 1), b3 + hstep);
;             PG8_WAIT_V(6); PG8_BAR; PG8_MMA(1, 1, At, B1); PG8_BAR;
;         }
;         E(acc, cur, wr, wc, fr, fq);
;     template <bool LN, int BJ, int LO, int HI> DI void batch(const f32x4 (&acc)[2][2][4][2], unsigned row0, unsigned col0, const f32x4 (&gv)[2], const f32x4 (&bv)[2]) const {
;         f32x4 r[HI - LO]; float mean[(HI - LO) / 2], rstd[(HI - LO) / 2];
; #pragma unroll
;         for (int i = LO; i < HI; ++i) { const int ai = i >> 3, m = (i >> 1) & 3, n = i & 1; const unsigned row = row0 + ai * HALF + m * 16;
;             if (n == 0) { mean[(i - LO) >> 1] = 0.f; rstd[(i - LO) >> 1] = 1.f;
;                 if (LN) { const float2 st = *(const float2*)(stats + row * 2u); mean[(i - LO) >> 1] = st.x; rstd[(i - LO) >> 1] = st.y; } }
;             r[i - LO] = *(const f32x4*)(src + (row * (unsigned)DM + col0 + BJ * HALF + n * 16)); }
; #pragma unroll
;         for (int i = LO; i < HI; ++i) { const int ai = i >> 3, m = (i >> 1) & 3, n = i & 1; const unsigned row = row0 + ai * HALF + m * 16;
;             *(f32x4*)(Y + (row * (unsigned)DM + col0 + BJ * HALF + n * 16)) = acc[ai][BJ][m][n] + ((r[i - LO] - mean[(i - LO) >> 1]) * rstd[(i - LO) >> 1]) * gv[n] + bv[n]; }
;         __builtin_amdgcn_sched_barrier(0);
;     }
;     template <bool LN, int BJ> DI void load_gb(unsigned col0, f32x4 (&gv)[2], f32x4 (&bv)[2]) const {
; #pragma unroll
;         for (int n = 0; n < 2; ++n) {
;             if (LN) { gv[n] = *(const f32x4*)(gam + col0 + BJ * HALF + n * 16) * ALPHA; bv[n] = *(const f32x4*)(bet + col0 + BJ * HALF + n * 16) * ALPHA; }
;             else { gv[n] = (f32x4){ALPHA, ALPHA, ALPHA, ALPHA}; bv[n] = (f32x4){0.f, 0.f, 0.f, 0.f}; }
;         }
;     }
;     template <bool LN> DI void run(const f32x4 (&acc)[2][2][4][2], const Unit& u, int wr, int wc, int fr, int fq) const {
;         const unsigned row0 = u.pm * BM + wr * 64 + fr, col0 = u.pn * BM + wc * 32 + 4 * fq;
;         f32x4 gv[2], bv[2];
;         load_gb<LN, 0>(col0, gv, bv);
;         batch<LN, 0, 0, 4>(acc, row0, col0, gv, bv);
;         batch<LN, 0, 4, 8>(acc, row0, col0, gv, bv);
;         batch<LN, 0, 8, 12>(acc, row0, col0, gv, bv);
	v_mfma_f32_16x16x32_bf16 v[92:95], v[96:99], v[152:155], v[92:95]
	v_mfma_f32_16x16x32_bf16 v[88:91], v[136:139], v[152:155], v[88:91]
	v_mfma_f32_16x16x32_bf16 v[84:87], v[96:99], v[190:193], v[84:87]
	v_mfma_f32_16x16x32_bf16 v[80:83], v[136:139], v[190:193], v[80:83]
	v_mfma_f32_16x16x32_bf16 v[76:79], v[96:99], v[202:205], v[76:79]
	v_mfma_f32_16x16x32_bf16 v[72:75], v[136:139], v[202:205], v[72:75]
	v_mfma_f32_16x16x32_bf16 v[68:71], v[96:99], v[210:213], v[68:71]
	v_mfma_f32_16x16x32_bf16 v[64:67], v[136:139], v[210:213], v[64:67]
	v_mfma_f32_16x16x32_bf16 v[92:95], v[100:103], v[186:189], v[92:95]
	v_mfma_f32_16x16x32_bf16 v[88:91], v[148:151], v[186:189], v[88:91]
	v_mfma_f32_16x16x32_bf16 v[84:87], v[100:103], v[194:197], v[84:87]
	v_mfma_f32_16x16x32_bf16 v[80:83], v[148:151], v[194:197], v[80:83]
	v_mfma_f32_16x16x32_bf16 v[76:79], v[100:103], v[206:209], v[76:79]
	v_mfma_f32_16x16x32_bf16 v[72:75], v[148:151], v[206:209], v[72:75]
	v_mfma_f32_16x16x32_bf16 v[68:71], v[100:103], v[214:217], v[68:71]
	v_mfma_f32_16x16x32_bf16 v[64:67], v[148:151], v[214:217], v[64:67]
	s_setprio 0
	s_barrier
	s_add_u32 s16, s20, 0x160080
	s_addc_u32 s17, s21, 0
	s_add_i32 s20, s22, s27
	v_lshl_add_u64 v[96:97], s[16:17], 0, v[142:143]
	s_mov_b32 m0, s20
	s_nop 0
	global_load_lds_dwordx4 v[96:97], off
	v_lshl_add_u64 v[96:97], s[16:17], 0, v[140:141]
	s_add_i32 m0, s20, 0x2000
	s_nop 0
	global_load_lds_dwordx4 v[96:97], off
	s_waitcnt vmcnt(6)
	s_setprio 1
	s_barrier
	v_mfma_f32_16x16x32_bf16 v[28:31], v[226:229], v[152:155], v[28:31]
	v_mfma_f32_16x16x32_bf16 v[24:27], v[234:237], v[152:155], v[24:27]
	v_mfma_f32_16x16x32_bf16 v[20:23], v[226:229], v[190:193], v[20:23]
	v_mfma_f32_16x16x32_bf16 v[16:19], v[234:237], v[190:193], v[16:19]
	v_mfma_f32_16x16x32_bf16 v[12:15], v[226:229], v[202:205], v[12:15]
	v_mfma_f32_16x16x32_bf16 v[8:11], v[234:237], v[202:205], v[8:11]
	v_mfma_f32_16x16x32_bf16 v[4:7], v[226:229], v[210:213], v[4:7]
	v_mfma_f32_16x16x32_bf16 v[0:3], v[234:237], v[210:213], v[0:3]
	v_mfma_f32_16x16x32_bf16 v[28:31], v[230:233], v[186:189], v[28:31]
	v_mfma_f32_16x16x32_bf16 v[24:27], v[238:241], v[186:189], v[24:27]
	v_mfma_f32_16x16x32_bf16 v[20:23], v[230:233], v[194:197], v[20:23]
	v_mfma_f32_16x16x32_bf16 v[16:19], v[238:241], v[194:197], v[16:19]
	s_add_i32 s33, s33, 2
	s_add_u32 s4, s4, 0x100
	s_addc_u32 s5, s5, 0
	s_cmpk_gt_u32 s33, 0x55
	s_mov_b64 s[16:17], s[18:19]
	v_mfma_f32_16x16x32_bf16 v[12:15], v[230:233], v[206:209], v[12:15]
	v_mfma_f32_16x16x32_bf16 v[8:11], v[238:241], v[206:209], v[8:11]
	v_mfma_f32_16x16x32_bf16 v[4:7], v[230:233], v[214:217], v[4:7]
	v_mfma_f32_16x16x32_bf16 v[0:3], v[238:241], v[214:217], v[0:3]
	s_setprio 0
	s_barrier
	s_cbranch_scc0 .LBB0_134
	v_lshl_or_b32 v158, s2, 8, v200
	v_lshlrev_b64 v[100:101], 2, v[158:159]
	v_lshl_add_u64 v[150:151], s[12:13], 0, v[100:101]
	global_load_dwordx4 v[96:99], v[150:151], off
	v_lshl_add_u64 v[152:153], s[14:15], 0, v[100:101]
	v_lshl_add_u32 v203, s3, 8, v198
	v_lshlrev_b32_e32 v202, 11, v203
	v_add_u32_e32 v148, v202, v158
	v_mov_b32_e32 v149, v159
	v_lshlrev_b32_e32 v136, 1, v203
	v_mov_b32_e32 v137, v159
	v_lshlrev_b64 v[220:221], 2, v[148:149]
	v_lshl_add_u64 v[154:155], v[136:137], 2, s[96:97]
	v_lshl_add_u64 v[136:137], s[90:91], 0, v[220:221]
	v_or_b32_e32 v204, 16, v158
	v_or_b32_e32 v138, 16, v203
	v_lshlrev_b32_e32 v149, 11, v138
	s_waitcnt vmcnt(0)
	v_pk_mul_f32 v[192:193], v[98:99], s[78:79] op_sel_hi:[1,0]
	v_pk_mul_f32 v[194:195], v[96:97], s[78:79] op_sel_hi:[1,0]
	global_load_dwordx4 v[100:103], v[152:153], off
	global_load_dwordx4 v[96:99], v[150:151], off offset:64
	global_load_dwordx2 v[218:219], v[154:155], off
	global_load_dwordx4 v[206:209], v[136:137], off
	v_add_u32_e32 v136, v202, v204
	v_mov_b32_e32 v137, v159
	v_lshl_add_u64 v[136:137], v[136:137], 2, s[90:91]
	global_load_dwordx4 v[210:213], v[136:137], off
	v_lshlrev_b32_e32 v136, 1, v138
	v_mov_b32_e32 v137, v159
	v_lshl_add_u64 v[186:187], v[136:137], 2, s[96:97]
	v_add_u32_e32 v136, v149, v158
	v_lshl_add_u64 v[136:137], v[136:137], 2, s[90:91]
	global_load_dwordx2 v[196:197], v[186:187], off
	global_load_dwordx4 v[214:217], v[136:137], off
	v_add_u32_e32 v136, v149, v204
	v_mov_b32_e32 v137, v159
	v_lshl_add_u64 v[136:137], v[136:137], 2, s[90:91]
	global_load_dwordx4 v[136:139], v[136:137], off
	s_waitcnt vmcnt(0)
	v_pk_mul_f32 v[188:189], v[98:99], s[78:79] op_sel_hi:[1,0]
	v_pk_mul_f32 v[190:191], v[96:97], s[78:79] op_sel_hi:[1,0]
	global_load_dwordx4 v[96:99], v[152:153], off offset:64
	v_sub_f32_e32 v207, v207, v218
	v_sub_f32_e32 v206, v206, v218
	v_sub_f32_e32 v209, v209, v218
	v_sub_f32_e32 v208, v208, v218
	v_pk_mul_f32 v[208:209], v[218:219], v[208:209] op_sel:[1,0]
	v_pk_mul_f32 v[206:207], v[218:219], v[206:207] op_sel:[1,0]
	v_pk_fma_f32 v[134:135], v[192:193], v[208:209], v[134:135]
	v_pk_fma_f32 v[132:133], v[194:195], v[206:207], v[132:133]
	v_pk_fma_f32 v[134:135], v[102:103], s[78:79], v[134:135] op_sel_hi:[1,0,1]
	v_pk_fma_f32 v[132:133], v[100:101], s[78:79], v[132:133] op_sel_hi:[1,0,1]
	v_lshl_add_u64 v[206:207], s[88:89], 0, v[220:221]
	global_store_dwordx4 v[206:207], v[132:135], off
	s_nop 1
	v_sub_f32_e32 v133, v211, v218
	v_sub_f32_e32 v132, v210, v218
	v_sub_f32_e32 v135, v213, v218
	v_sub_f32_e32 v134, v212, v218
	v_pk_mul_f32 v[134:135], v[218:219], v[134:135] op_sel:[1,0]
	v_pk_mul_f32 v[132:133], v[218:219], v[132:133] op_sel:[1,0]
	v_pk_fma_f32 v[130:131], v[188:189], v[134:135], v[130:131]
	v_pk_fma_f32 v[128:129], v[190:191], v[132:133], v[128:129]
	v_or_b32_e32 v132, 16, v148
	v_mov_b32_e32 v133, v159
	v_lshl_add_u64 v[132:133], v[132:133], 2, s[88:89]
	s_waitcnt vmcnt(0)
;     template <bool LN, int BJ, int LO, int HI> DI void batch(const f32x4 (&acc)[2][2][4][2], unsigned row0, unsigned col0, const f32x4 (&gv)[2], const f32x4 (&bv)[2]) const {
;         f32x4 r[HI - LO]; float mean[(HI - LO) / 2], rstd[(HI - LO) / 2];
; #pragma unroll
;         for (int i = LO; i < HI; ++i) { const int ai = i >> 3, m = (i >> 1) & 3, n = i & 1; const unsigned row = row0 + ai * HALF + m * 16;
;             if (n == 0) { mean[(i - LO) >> 1] = 0.f; rstd[(i - LO) >> 1] = 1.f;
;                 if (LN) { const float2 st = *(const float2*)(stats + row * 2u); mean[(i - LO) >> 1] = st.x; rstd[(i - LO) >> 1] = st.y; } }
;             r[i - LO] = *(const f32x4*)(src + (row * (unsigned)DM + col0 + BJ * HALF + n * 16)); }
; #pragma unroll
;         for (int i = LO; i < HI; ++i) { const int ai = i >> 3, m = (i >> 1) & 3, n = i & 1; const unsigned row = row0 + ai * HALF + m * 16;
;             *(f32x4*)(Y + (row * (unsigned)DM + col0 + BJ * HALF + n * 16)) = acc[ai][BJ][m][n] + ((r[i - LO] - mean[(i - LO) >> 1]) * rstd[(i - LO) >> 1]) * gv[n] + bv[n]; }
;         __builtin_amdgcn_sched_barrier(0);
;     }
;     template <bool LN, int BJ> DI void load_gb(unsigned col0, f32x4 (&gv)[2], f32x4 (&bv)[2]) const {
; #pragma unroll
;         for (int n = 0; n < 2; ++n) {
;             if (LN) { gv[n] = *(const f32x4*)(gam + col0 + BJ * HALF + n * 16) * ALPHA; bv[n] = *(const f32x4*)(bet + col0 + BJ * HALF + n * 16) * ALPHA; }
;             else { gv[n] = (f32x4){ALPHA, ALPHA, ALPHA, ALPHA}; bv[n] = (f32x4){0.f, 0.f, 0.f, 0.f}; }
;         }
;     }
;     template <bool LN> DI void run(const f32x4 (&acc)[2][2][4][2], const Unit& u, int wr, int wc, int fr, int fq) const {
;         const unsigned row0 = u.pm * BM + wr * 64 + fr, col0 = u.pn * BM + wc * 32 + 4 * fq;
;         f32x4 gv[2], bv[2];
;         load_gb<LN, 0>(col0, gv, bv);
;         batch<LN, 0, 0, 4>(acc, row0, col0, gv, bv);
;         batch<LN, 0, 4, 8>(acc, row0, col0, gv, bv);
;         batch<LN, 0, 8, 12>(acc, row0, col0, gv, bv);
;         batch<LN, 0, 12, 16>(acc, row0, col0, gv, bv);
;         load_gb<LN, 1>(col0, gv, bv);
;         batch<LN, 1, 0, 8>(acc, row0, col0, gv, bv);
;         batch<LN, 1, 8, 16>(acc, row0, col0, gv, bv);
	v_pk_fma_f32 v[130:131], v[98:99], s[78:79], v[130:131] op_sel_hi:[1,0,1]
	v_pk_fma_f32 v[128:129], v[96:97], s[78:79], v[128:129] op_sel_hi:[1,0,1]
	global_store_dwordx4 v[132:133], v[128:131], off
	s_nop 1
	v_sub_f32_e32 v129, v215, v196
	v_sub_f32_e32 v128, v214, v196
	v_sub_f32_e32 v131, v217, v196
	v_sub_f32_e32 v130, v216, v196
	v_pk_mul_f32 v[130:131], v[196:197], v[130:131] op_sel:[1,0]
	v_pk_mul_f32 v[128:129], v[196:197], v[128:129] op_sel:[1,0]
	v_pk_fma_f32 v[126:127], v[192:193], v[130:131], v[126:127]
	v_pk_fma_f32 v[124:125], v[194:195], v[128:129], v[124:125]
	v_add_u32_e32 v128, 0x8000, v148
	v_mov_b32_e32 v129, v159
	v_pk_fma_f32 v[126:127], v[102:103], s[78:79], v[126:127] op_sel_hi:[1,0,1]
	v_pk_fma_f32 v[124:125], v[100:101], s[78:79], v[124:125] op_sel_hi:[1,0,1]
	v_lshl_add_u64 v[128:129], v[128:129], 2, s[88:89]
	global_store_dwordx4 v[128:129], v[124:127], off
	s_nop 1
	v_sub_f32_e32 v125, v137, v196
	v_sub_f32_e32 v124, v136, v196
	v_sub_f32_e32 v127, v139, v196
	v_sub_f32_e32 v126, v138, v196
	v_pk_mul_f32 v[126:127], v[196:197], v[126:127] op_sel:[1,0]
	v_pk_mul_f32 v[124:125], v[196:197], v[124:125] op_sel:[1,0]
	v_pk_fma_f32 v[122:123], v[188:189], v[126:127], v[122:123]
	v_pk_fma_f32 v[120:121], v[190:191], v[124:125], v[120:121]
	v_add_u32_e32 v124, 0x8010, v148
	v_mov_b32_e32 v125, v159
	v_pk_fma_f32 v[122:123], v[98:99], s[78:79], v[122:123] op_sel_hi:[1,0,1]
	v_pk_fma_f32 v[120:121], v[96:97], s[78:79], v[120:121] op_sel_hi:[1,0,1]
	v_lshl_add_u64 v[124:125], v[124:125], 2, s[88:89]
	global_store_dwordx4 v[124:125], v[120:123], off
	s_nop 1
	v_or_b32_e32 v122, 32, v203
	v_lshlrev_b32_e32 v124, 11, v122
	v_lshlrev_b32_e32 v120, 1, v122
	v_mov_b32_e32 v121, v159
	v_add_u32_e32 v122, v124, v158
	v_mov_b32_e32 v123, v159
	v_lshl_add_u64 v[120:121], v[120:121], 2, s[96:97]
	v_lshl_add_u64 v[122:123], v[122:123], 2, s[90:91]
	global_load_dwordx2 v[138:139], v[120:121], off
	global_load_dwordx4 v[126:129], v[122:123], off
	v_add_u32_e32 v122, v124, v204
	v_mov_b32_e32 v123, v159
	v_lshl_add_u64 v[122:123], v[122:123], 2, s[90:91]
	global_load_dwordx4 v[130:133], v[122:123], off
	v_or_b32_e32 v125, 48, v203
	v_lshlrev_b32_e32 v122, 1, v125
	v_lshlrev_b32_e32 v125, 11, v125
	v_mov_b32_e32 v123, v159
	v_add_u32_e32 v134, v125, v158
	v_mov_b32_e32 v135, v159
	v_lshl_add_u64 v[122:123], v[122:123], 2, s[96:97]
	v_lshl_add_u64 v[134:135], v[134:135], 2, s[90:91]
	global_load_dwordx2 v[196:197], v[122:123], off
	v_add_u32_e32 v206, v125, v204
	global_load_dwordx4 v[134:137], v[134:135], off
	v_mov_b32_e32 v207, v159
	v_lshl_add_u64 v[206:207], v[206:207], 2, s[90:91]
	global_load_dwordx4 v[206:209], v[206:207], off
	s_waitcnt vmcnt(0)
	v_sub_f32_e32 v127, v127, v138
	v_sub_f32_e32 v126, v126, v138
	v_sub_f32_e32 v129, v129, v138
	v_sub_f32_e32 v128, v128, v138
	v_pk_mul_f32 v[128:129], v[138:139], v[128:129] op_sel:[1,0]
	v_pk_mul_f32 v[126:127], v[138:139], v[126:127] op_sel:[1,0]
	v_pk_fma_f32 v[118:119], v[192:193], v[128:129], v[118:119]
	v_pk_fma_f32 v[116:117], v[194:195], v[126:127], v[116:117]
	v_add_u32_e32 v126, 0x10000, v148
	v_mov_b32_e32 v127, v159
	v_pk_fma_f32 v[118:119], v[102:103], s[78:79], v[118:119] op_sel_hi:[1,0,1]
	v_pk_fma_f32 v[116:117], v[100:101], s[78:79], v[116:117] op_sel_hi:[1,0,1]
	v_lshl_add_u64 v[126:127], v[126:127], 2, s[88:89]
	global_store_dwordx4 v[126:127], v[116:119], off
	s_nop 1
	v_sub_f32_e32 v117, v131, v138
	v_sub_f32_e32 v116, v130, v138
	v_sub_f32_e32 v119, v133, v138
	v_sub_f32_e32 v118, v132, v138
	v_pk_mul_f32 v[118:119], v[138:139], v[118:119] op_sel:[1,0]
	v_pk_mul_f32 v[116:117], v[138:139], v[116:117] op_sel:[1,0]
	v_pk_fma_f32 v[114:115], v[188:189], v[118:119], v[114:115]
	v_pk_fma_f32 v[112:113], v[190:191], v[116:117], v[112:113]
	v_add_u32_e32 v116, 0x10010, v148
	v_mov_b32_e32 v117, v159
	v_pk_fma_f32 v[114:115], v[98:99], s[78:79], v[114:115] op_sel_hi:[1,0,1]
	v_pk_fma_f32 v[112:113], v[96:97], s[78:79], v[112:113] op_sel_hi:[1,0,1]
	v_lshl_add_u64 v[116:117], v[116:117], 2, s[88:89]
	global_store_dwordx4 v[116:117], v[112:115], off
	s_nop 1
	v_sub_f32_e32 v113, v135, v196
	v_sub_f32_e32 v112, v134, v196
	v_sub_f32_e32 v115, v137, v196
	v_sub_f32_e32 v114, v136, v196
	v_pk_mul_f32 v[114:115], v[196:197], v[114:115] op_sel:[1,0]
	v_pk_mul_f32 v[112:113], v[196:197], v[112:113] op_sel:[1,0]
	v_pk_fma_f32 v[110:111], v[192:193], v[114:115], v[110:111]
	v_pk_fma_f32 v[108:109], v[194:195], v[112:113], v[108:109]
	v_add_u32_e32 v112, 0x18000, v148
	v_mov_b32_e32 v113, v159
	v_pk_fma_f32 v[110:111], v[102:103], s[78:79], v[110:111] op_sel_hi:[1,0,1]
	v_pk_fma_f32 v[108:109], v[100:101], s[78:79], v[108:109] op_sel_hi:[1,0,1]
	v_lshl_add_u64 v[112:113], v[112:113], 2, s[88:89]
	global_store_dwordx4 v[112:113], v[108:111], off
	s_nop 1
	v_sub_f32_e32 v109, v207, v196
	v_sub_f32_e32 v108, v206, v196
	v_sub_f32_e32 v111, v209, v196
	v_sub_f32_e32 v110, v208, v196
	v_pk_mul_f32 v[110:111], v[196:197], v[110:111] op_sel:[1,0]
	v_pk_mul_f32 v[108:109], v[196:197], v[108:109] op_sel:[1,0]
	v_pk_fma_f32 v[106:107], v[188:189], v[110:111], v[106:107]
	v_pk_fma_f32 v[104:105], v[190:191], v[108:109], v[104:105]
	v_add_u32_e32 v108, 0x18010, v148
	v_mov_b32_e32 v109, v159
	v_pk_fma_f32 v[106:107], v[98:99], s[78:79], v[106:107] op_sel_hi:[1,0,1]
	v_pk_fma_f32 v[104:105], v[96:97], s[78:79], v[104:105] op_sel_hi:[1,0,1]
	v_lshl_add_u64 v[108:109], v[108:109], 2, s[88:89]
	global_store_dwordx4 v[108:109], v[104:107], off
	s_nop 1
	v_add_u32_e32 v106, 0x80, v203
	v_lshlrev_b32_e32 v114, 11, v106
	v_lshlrev_b32_e32 v104, 1, v106
	v_mov_b32_e32 v105, v159
	v_add_u32_e32 v106, v114, v158
	v_mov_b32_e32 v107, v159
	v_lshl_add_u64 v[104:105], v[104:105], 2, s[96:97]
	v_lshl_add_u64 v[106:107], v[106:107], 2, s[90:91]
	global_load_dwordx2 v[112:113], v[104:105], off
	global_load_dwordx4 v[108:111], v[106:107], off
	v_add_u32_e32 v106, v114, v204
	v_mov_b32_e32 v107, v159
	v_lshl_add_u64 v[106:107], v[106:107], 2, s[90:91]
	global_load_dwordx4 v[116:119], v[106:107], off
	v_add_u32_e32 v115, 0x90, v203
	v_lshlrev_b32_e32 v106, 1, v115
	v_lshlrev_b32_e32 v115, 11, v115
	v_mov_b32_e32 v107, v159
	v_add_u32_e32 v126, v115, v158
	v_mov_b32_e32 v127, v159
	v_lshl_add_u64 v[106:107], v[106:107], 2, s[96:97]
	v_lshl_add_u64 v[126:127], v[126:127], 2, s[90:91]
	global_load_dwordx2 v[134:135], v[106:107], off
	v_add_u32_e32 v130, v115, v204
	global_load_dwordx4 v[126:129], v[126:127], off
	v_mov_b32_e32 v131, v159
	v_lshl_add_u64 v[130:131], v[130:131], 2, s[90:91]
	global_load_dwordx4 v[130:133], v[130:131], off
	s_waitcnt vmcnt(0)
;     template <bool LN, int BJ, int LO, int HI> DI void batch(const f32x4 (&acc)[2][2][4][2], unsigned row0, unsigned col0, const f32x4 (&gv)[2], const f32x4 (&bv)[2]) const {
;         f32x4 r[HI - LO]; float mean[(HI - LO) / 2], rstd[(HI - LO) / 2];
; #pragma unroll
;         for (int i = LO; i < HI; ++i) { const int ai = i >> 3, m = (i >> 1) & 3, n = i & 1; const unsigned row = row0 + ai * HALF + m * 16;
;             if (n == 0) { mean[(i - LO) >> 1] = 0.f; rstd[(i - LO) >> 1] = 1.f;
;                 if (LN) { const float2 st = *(const float2*)(stats + row * 2u); mean[(i - LO) >> 1] = st.x; rstd[(i - LO) >> 1] = st.y; } }
;             r[i - LO] = *(const f32x4*)(src + (row * (unsigned)DM + col0 + BJ * HALF + n * 16)); }
; #pragma unroll
;         for (int i = LO; i < HI; ++i) { const int ai = i >> 3, m = (i >> 1) & 3, n = i & 1; const unsigned row = row0 + ai * HALF + m * 16;
;             *(f32x4*)(Y + (row * (unsigned)DM + col0 + BJ * HALF + n * 16)) = acc[ai][BJ][m][n] + ((r[i - LO] - mean[(i - LO) >> 1]) * rstd[(i - LO) >> 1]) * gv[n] + bv[n]; }
;         __builtin_amdgcn_sched_barrier(0);
;     }
;     template <bool LN, int BJ> DI void load_gb(unsigned col0, f32x4 (&gv)[2], f32x4 (&bv)[2]) const {
; #pragma unroll
;         for (int n = 0; n < 2; ++n) {
;             if (LN) { gv[n] = *(const f32x4*)(gam + col0 + BJ * HALF + n * 16) * ALPHA; bv[n] = *(const f32x4*)(bet + col0 + BJ * HALF + n * 16) * ALPHA; }
;             else { gv[n] = (f32x4){ALPHA, ALPHA, ALPHA, ALPHA}; bv[n] = (f32x4){0.f, 0.f, 0.f, 0.f}; }
;         }
;     }
;     template <bool LN> DI void run(const f32x4 (&acc)[2][2][4][2], const Unit& u, int wr, int wc, int fr, int fq) const {
;         const unsigned row0 = u.pm * BM + wr * 64 + fr, col0 = u.pn * BM + wc * 32 + 4 * fq;
;         f32x4 gv[2], bv[2];
;         load_gb<LN, 0>(col0, gv, bv);
;         batch<LN, 0, 0, 4>(acc, row0, col0, gv, bv);
;         batch<LN, 0, 4, 8>(acc, row0, col0, gv, bv);
;         batch<LN, 0, 8, 12>(acc, row0, col0, gv, bv);
;         batch<LN, 0, 12, 16>(acc, row0, col0, gv, bv);
;         load_gb<LN, 1>(col0, gv, bv);
;         batch<LN, 1, 0, 8>(acc, row0, col0, gv, bv);
;         batch<LN, 1, 8, 16>(acc, row0, col0, gv, bv);
	v_sub_f32_e32 v109, v109, v112
	v_sub_f32_e32 v108, v108, v112
	v_sub_f32_e32 v111, v111, v112
	v_sub_f32_e32 v110, v110, v112
	v_pk_mul_f32 v[110:111], v[112:113], v[110:111] op_sel:[1,0]
	v_pk_mul_f32 v[108:109], v[112:113], v[108:109] op_sel:[1,0]
	v_pk_fma_f32 v[94:95], v[192:193], v[110:111], v[94:95]
	v_pk_fma_f32 v[92:93], v[194:195], v[108:109], v[92:93]
	v_add_u32_e32 v108, 0x40000, v148
	v_mov_b32_e32 v109, v159
	v_pk_fma_f32 v[94:95], v[102:103], s[78:79], v[94:95] op_sel_hi:[1,0,1]
	v_pk_fma_f32 v[92:93], v[100:101], s[78:79], v[92:93] op_sel_hi:[1,0,1]
	v_lshl_add_u64 v[108:109], v[108:109], 2, s[88:89]
	global_store_dwordx4 v[108:109], v[92:95], off
	s_nop 1
	v_sub_f32_e32 v93, v117, v112
	v_sub_f32_e32 v92, v116, v112
	v_sub_f32_e32 v95, v119, v112
	v_sub_f32_e32 v94, v118, v112
	v_pk_mul_f32 v[94:95], v[112:113], v[94:95] op_sel:[1,0]
	v_pk_mul_f32 v[92:93], v[112:113], v[92:93] op_sel:[1,0]
	v_pk_fma_f32 v[90:91], v[188:189], v[94:95], v[90:91]
	v_pk_fma_f32 v[88:89], v[190:191], v[92:93], v[88:89]
	v_add_u32_e32 v92, 0x40010, v148
	v_mov_b32_e32 v93, v159
	v_pk_fma_f32 v[90:91], v[98:99], s[78:79], v[90:91] op_sel_hi:[1,0,1]
	v_pk_fma_f32 v[88:89], v[96:97], s[78:79], v[88:89] op_sel_hi:[1,0,1]
	v_lshl_add_u64 v[92:93], v[92:93], 2, s[88:89]
	global_store_dwordx4 v[92:93], v[88:91], off
	s_nop 1
	v_sub_f32_e32 v89, v127, v134
	v_sub_f32_e32 v88, v126, v134
	v_sub_f32_e32 v91, v129, v134
	v_sub_f32_e32 v90, v128, v134
	v_pk_mul_f32 v[90:91], v[134:135], v[90:91] op_sel:[1,0]
	v_pk_mul_f32 v[88:89], v[134:135], v[88:89] op_sel:[1,0]
	v_pk_fma_f32 v[86:87], v[192:193], v[90:91], v[86:87]
	v_pk_fma_f32 v[84:85], v[194:195], v[88:89], v[84:85]
	v_add_u32_e32 v88, 0x48000, v148
	v_mov_b32_e32 v89, v159
	v_pk_fma_f32 v[86:87], v[102:103], s[78:79], v[86:87] op_sel_hi:[1,0,1]
	v_pk_fma_f32 v[84:85], v[100:101], s[78:79], v[84:85] op_sel_hi:[1,0,1]
	v_lshl_add_u64 v[88:89], v[88:89], 2, s[88:89]
	global_store_dwordx4 v[88:89], v[84:87], off
	s_nop 1
	v_sub_f32_e32 v85, v131, v134
	v_sub_f32_e32 v84, v130, v134
	v_sub_f32_e32 v87, v133, v134
	v_sub_f32_e32 v86, v132, v134
	v_pk_mul_f32 v[86:87], v[134:135], v[86:87] op_sel:[1,0]
	v_pk_mul_f32 v[84:85], v[134:135], v[84:85] op_sel:[1,0]
	v_pk_fma_f32 v[82:83], v[188:189], v[86:87], v[82:83]
	v_pk_fma_f32 v[80:81], v[190:191], v[84:85], v[80:81]
	v_add_u32_e32 v84, 0x48010, v148
	v_mov_b32_e32 v85, v159
	v_pk_fma_f32 v[82:83], v[98:99], s[78:79], v[82:83] op_sel_hi:[1,0,1]
	v_pk_fma_f32 v[80:81], v[96:97], s[78:79], v[80:81] op_sel_hi:[1,0,1]
	v_lshl_add_u64 v[84:85], v[84:85], 2, s[88:89]
	global_store_dwordx4 v[84:85], v[80:83], off
	s_nop 1
	v_add_u32_e32 v82, 0xa0, v203
	v_lshlrev_b32_e32 v80, 1, v82
	v_mov_b32_e32 v81, v159
	v_lshlrev_b32_e32 v116, 11, v82
	v_lshl_add_u64 v[108:109], v[80:81], 2, s[96:97]
	v_add_u32_e32 v80, v116, v158
	v_lshl_add_u64 v[80:81], v[80:81], 2, s[90:91]
	global_load_dwordx2 v[112:113], v[108:109], off
	v_add_u32_e32 v84, v116, v204
	global_load_dwordx4 v[80:83], v[80:81], off
	v_mov_b32_e32 v85, v159
	v_lshl_add_u64 v[84:85], v[84:85], 2, s[90:91]
	global_load_dwordx4 v[84:87], v[84:85], off
	v_add_u32_e32 v90, 0xb0, v203
	v_lshlrev_b32_e32 v88, 1, v90
	v_mov_b32_e32 v89, v159
	v_lshlrev_b32_e32 v117, 11, v90
	v_lshl_add_u64 v[110:111], v[88:89], 2, s[96:97]
	v_add_u32_e32 v88, v117, v158
	v_lshl_add_u64 v[88:89], v[88:89], 2, s[90:91]
	global_load_dwordx2 v[118:119], v[110:111], off
	v_add_u32_e32 v92, v117, v204
	global_load_dwordx4 v[88:91], v[88:89], off
	v_mov_b32_e32 v93, v159
	v_lshl_add_u64 v[92:93], v[92:93], 2, s[90:91]
	global_load_dwordx4 v[92:95], v[92:93], off
	s_waitcnt vmcnt(0)
	v_sub_f32_e32 v81, v81, v112
	v_sub_f32_e32 v80, v80, v112
	v_sub_f32_e32 v83, v83, v112
	v_sub_f32_e32 v82, v82, v112
	v_pk_mul_f32 v[82:83], v[112:113], v[82:83] op_sel:[1,0]
	v_pk_mul_f32 v[80:81], v[112:113], v[80:81] op_sel:[1,0]
	v_pk_fma_f32 v[78:79], v[192:193], v[82:83], v[78:79]
	v_pk_fma_f32 v[76:77], v[194:195], v[80:81], v[76:77]
	v_add_u32_e32 v80, 0x50000, v148
	v_mov_b32_e32 v81, v159
	v_pk_fma_f32 v[78:79], v[102:103], s[78:79], v[78:79] op_sel_hi:[1,0,1]
	v_pk_fma_f32 v[76:77], v[100:101], s[78:79], v[76:77] op_sel_hi:[1,0,1]
	v_lshl_add_u64 v[80:81], v[80:81], 2, s[88:89]
	global_store_dwordx4 v[80:81], v[76:79], off
	s_nop 1
	v_sub_f32_e32 v77, v85, v112
	v_sub_f32_e32 v76, v84, v112
	v_sub_f32_e32 v79, v87, v112
	v_sub_f32_e32 v78, v86, v112
	v_pk_mul_f32 v[78:79], v[112:113], v[78:79] op_sel:[1,0]
	v_pk_mul_f32 v[76:77], v[112:113], v[76:77] op_sel:[1,0]
	v_pk_fma_f32 v[74:75], v[188:189], v[78:79], v[74:75]
	v_pk_fma_f32 v[72:73], v[190:191], v[76:77], v[72:73]
	v_add_u32_e32 v76, 0x50010, v148
	v_mov_b32_e32 v77, v159
	v_pk_fma_f32 v[74:75], v[98:99], s[78:79], v[74:75] op_sel_hi:[1,0,1]
	v_pk_fma_f32 v[72:73], v[96:97], s[78:79], v[72:73] op_sel_hi:[1,0,1]
	v_lshl_add_u64 v[76:77], v[76:77], 2, s[88:89]
	global_store_dwordx4 v[76:77], v[72:75], off
	s_nop 1
	v_sub_f32_e32 v73, v89, v118
	v_sub_f32_e32 v72, v88, v118
	v_sub_f32_e32 v75, v91, v118
	v_sub_f32_e32 v74, v90, v118
	v_pk_mul_f32 v[74:75], v[118:119], v[74:75] op_sel:[1,0]
	v_pk_mul_f32 v[72:73], v[118:119], v[72:73] op_sel:[1,0]
	v_pk_fma_f32 v[70:71], v[192:193], v[74:75], v[70:71]
	v_pk_fma_f32 v[68:69], v[194:195], v[72:73], v[68:69]
	v_add_u32_e32 v72, 0x58000, v148
	v_mov_b32_e32 v73, v159
	v_pk_fma_f32 v[70:71], v[102:103], s[78:79], v[70:71] op_sel_hi:[1,0,1]
	v_pk_fma_f32 v[68:69], v[100:101], s[78:79], v[68:69] op_sel_hi:[1,0,1]
	v_lshl_add_u64 v[72:73], v[72:73], 2, s[88:89]
	global_store_dwordx4 v[72:73], v[68:71], off
	s_nop 1
	v_sub_f32_e32 v69, v93, v118
	v_sub_f32_e32 v68, v92, v118
	v_sub_f32_e32 v71, v95, v118
	v_sub_f32_e32 v70, v94, v118
	v_pk_mul_f32 v[70:71], v[118:119], v[70:71] op_sel:[1,0]
	v_pk_mul_f32 v[68:69], v[118:119], v[68:69] op_sel:[1,0]
	v_pk_fma_f32 v[66:67], v[188:189], v[70:71], v[66:67]
	v_pk_fma_f32 v[64:65], v[190:191], v[68:69], v[64:65]
	v_add_u32_e32 v68, 0x58010, v148
	v_mov_b32_e32 v69, v159
	v_pk_fma_f32 v[66:67], v[98:99], s[78:79], v[66:67] op_sel_hi:[1,0,1]
	v_pk_fma_f32 v[64:65], v[96:97], s[78:79], v[64:65] op_sel_hi:[1,0,1]
	v_lshl_add_u64 v[68:69], v[68:69], 2, s[88:89]
	global_store_dwordx4 v[68:69], v[64:67], off
	global_load_dwordx4 v[64:67], v[150:151], off offset:512
	v_or_b32_e32 v119, 0x80, v158
	v_add_u32_e32 v72, v202, v119
	v_mov_b32_e32 v73, v159
	v_lshl_add_u64 v[72:73], v[72:73], 2, s[90:91]
	v_or_b32_e32 v118, 0x90, v158
	v_add_u32_e32 v158, v202, v118
	s_waitcnt vmcnt(0)
;     template <bool LN, int BJ, int LO, int HI> DI void batch(const f32x4 (&acc)[2][2][4][2], unsigned row0, unsigned col0, const f32x4 (&gv)[2], const f32x4 (&bv)[2]) const {
;         f32x4 r[HI - LO]; float mean[(HI - LO) / 2], rstd[(HI - LO) / 2];
; #pragma unroll
;         for (int i = LO; i < HI; ++i) { const int ai = i >> 3, m = (i >> 1) & 3, n = i & 1; const unsigned row = row0 + ai * HALF + m * 16;
;             if (n == 0) { mean[(i - LO) >> 1] = 0.f; rstd[(i - LO) >> 1] = 1.f;
;                 if (LN) { const float2 st = *(const float2*)(stats + row * 2u); mean[(i - LO) >> 1] = st.x; rstd[(i - LO) >> 1] = st.y; } }
;             r[i - LO] = *(const f32x4*)(src + (row * (unsigned)DM + col0 + BJ * HALF + n * 16)); }
; #pragma unroll
;         for (int i = LO; i < HI; ++i) { const int ai = i >> 3, m = (i >> 1) & 3, n = i & 1; const unsigned row = row0 + ai * HALF + m * 16;
;             *(f32x4*)(Y + (row * (unsigned)DM + col0 + BJ * HALF + n * 16)) = acc[ai][BJ][m][n] + ((r[i - LO] - mean[(i - LO) >> 1]) * rstd[(i - LO) >> 1]) * gv[n] + bv[n]; }
;         __builtin_amdgcn_sched_barrier(0);
;     }
;     template <bool LN, int BJ> DI void load_gb(unsigned col0, f32x4 (&gv)[2], f32x4 (&bv)[2]) const {
; #pragma unroll
;         for (int n = 0; n < 2; ++n) {
;             if (LN) { gv[n] = *(const f32x4*)(gam + col0 + BJ * HALF + n * 16) * ALPHA; bv[n] = *(const f32x4*)(bet + col0 + BJ * HALF + n * 16) * ALPHA; }
;             else { gv[n] = (f32x4){ALPHA, ALPHA, ALPHA, ALPHA}; bv[n] = (f32x4){0.f, 0.f, 0.f, 0.f}; }
;         }
;     }
;     template <bool LN> DI void run(const f32x4 (&acc)[2][2][4][2], const Unit& u, int wr, int wc, int fr, int fq) const {
;         const unsigned row0 = u.pm * BM + wr * 64 + fr, col0 = u.pn * BM + wc * 32 + 4 * fq;
;         f32x4 gv[2], bv[2];
;         load_gb<LN, 0>(col0, gv, bv);
;         batch<LN, 0, 0, 4>(acc, row0, col0, gv, bv);
;         batch<LN, 0, 4, 8>(acc, row0, col0, gv, bv);
;         batch<LN, 0, 8, 12>(acc, row0, col0, gv, bv);
;         batch<LN, 0, 12, 16>(acc, row0, col0, gv, bv);
;         load_gb<LN, 1>(col0, gv, bv);
;         batch<LN, 1, 0, 8>(acc, row0, col0, gv, bv);
;         batch<LN, 1, 8, 16>(acc, row0, col0, gv, bv);
	v_pk_mul_f32 v[96:97], v[66:67], s[78:79] op_sel_hi:[1,0]
	v_pk_mul_f32 v[98:99], v[64:65], s[78:79] op_sel_hi:[1,0]
	global_load_dwordx4 v[68:71], v[152:153], off offset:512
	global_load_dwordx4 v[64:67], v[150:151], off offset:576
	global_load_dwordx2 v[138:139], v[154:155], off
	global_load_dwordx4 v[126:129], v[72:73], off
	v_lshl_add_u64 v[72:73], v[158:159], 2, s[90:91]
	v_add_u32_e32 v158, v149, v119
	s_waitcnt vmcnt(0)
	v_pk_mul_f32 v[92:93], v[66:67], s[78:79] op_sel_hi:[1,0]
	v_pk_mul_f32 v[94:95], v[64:65], s[78:79] op_sel_hi:[1,0]
	global_load_dwordx4 v[64:67], v[152:153], off offset:576
	global_load_dwordx4 v[130:133], v[72:73], off
	global_load_dwordx2 v[112:113], v[186:187], off
	v_lshl_add_u64 v[72:73], v[158:159], 2, s[90:91]
	global_load_dwordx4 v[134:137], v[72:73], off
	v_add_u32_e32 v158, v149, v118
	v_lshl_add_u64 v[72:73], v[158:159], 2, s[90:91]
	global_load_dwordx4 v[88:91], v[72:73], off
	global_load_dwordx2 v[102:103], v[120:121], off
	v_add_u32_e32 v158, v124, v119
	v_lshl_add_u64 v[72:73], v[158:159], 2, s[90:91]
	global_load_dwordx4 v[84:87], v[72:73], off
	v_add_u32_e32 v158, v124, v118
	v_lshl_add_u64 v[72:73], v[158:159], 2, s[90:91]
	global_load_dwordx4 v[80:83], v[72:73], off
	global_load_dwordx2 v[100:101], v[122:123], off
	v_add_u32_e32 v158, v125, v119
	v_lshl_add_u64 v[72:73], v[158:159], 2, s[90:91]
	global_load_dwordx4 v[76:79], v[72:73], off
	v_add_u32_e32 v158, v125, v118
	v_lshl_add_u64 v[72:73], v[158:159], 2, s[90:91]
	global_load_dwordx4 v[72:75], v[72:73], off
	v_sub_f32_e32 v121, v127, v138
	v_sub_f32_e32 v120, v126, v138
	v_sub_f32_e32 v123, v129, v138
	v_sub_f32_e32 v122, v128, v138
	v_pk_mul_f32 v[122:123], v[138:139], v[122:123] op_sel:[1,0]
	v_pk_mul_f32 v[120:121], v[138:139], v[120:121] op_sel:[1,0]
	v_or_b32_e32 v158, 0x80, v148
	v_pk_fma_f32 v[60:61], v[98:99], v[120:121], v[60:61]
	v_pk_fma_f32 v[62:63], v[96:97], v[122:123], v[62:63]
	v_pk_fma_f32 v[60:61], v[68:69], s[78:79], v[60:61] op_sel_hi:[1,0,1]
	v_pk_fma_f32 v[62:63], v[70:71], s[78:79], v[62:63] op_sel_hi:[1,0,1]
	v_lshl_add_u64 v[120:121], v[158:159], 2, s[88:89]
	global_store_dwordx4 v[120:121], v[60:63], off
	v_or_b32_e32 v158, 0x90, v148
	s_waitcnt vmcnt(0)
	v_sub_f32_e32 v61, v131, v138
	v_sub_f32_e32 v60, v130, v138
	v_sub_f32_e32 v63, v133, v138
	v_sub_f32_e32 v62, v132, v138
	v_pk_mul_f32 v[62:63], v[138:139], v[62:63] op_sel:[1,0]
	v_pk_mul_f32 v[60:61], v[138:139], v[60:61] op_sel:[1,0]
	v_pk_fma_f32 v[58:59], v[92:93], v[62:63], v[58:59]
	v_pk_fma_f32 v[56:57], v[94:95], v[60:61], v[56:57]
	v_pk_fma_f32 v[58:59], v[66:67], s[78:79], v[58:59] op_sel_hi:[1,0,1]
	v_pk_fma_f32 v[56:57], v[64:65], s[78:79], v[56:57] op_sel_hi:[1,0,1]
	v_lshl_add_u64 v[60:61], v[158:159], 2, s[88:89]
	global_store_dwordx4 v[60:61], v[56:59], off
	v_add_u32_e32 v158, 0x8080, v148
	s_nop 0
	v_sub_f32_e32 v57, v135, v112
	v_sub_f32_e32 v56, v134, v112
	v_sub_f32_e32 v59, v137, v112
	v_sub_f32_e32 v58, v136, v112
	v_pk_mul_f32 v[58:59], v[112:113], v[58:59] op_sel:[1,0]
	v_pk_mul_f32 v[56:57], v[112:113], v[56:57] op_sel:[1,0]
	v_pk_fma_f32 v[54:55], v[96:97], v[58:59], v[54:55]
	v_pk_fma_f32 v[52:53], v[98:99], v[56:57], v[52:53]
	v_pk_fma_f32 v[54:55], v[70:71], s[78:79], v[54:55] op_sel_hi:[1,0,1]
	v_pk_fma_f32 v[52:53], v[68:69], s[78:79], v[52:53] op_sel_hi:[1,0,1]
	v_lshl_add_u64 v[56:57], v[158:159], 2, s[88:89]
	global_store_dwordx4 v[56:57], v[52:55], off
	v_add_u32_e32 v158, 0x8090, v148
	s_nop 0
	v_sub_f32_e32 v53, v89, v112
	v_sub_f32_e32 v52, v88, v112
	v_sub_f32_e32 v55, v91, v112
	v_sub_f32_e32 v54, v90, v112
	v_pk_mul_f32 v[54:55], v[112:113], v[54:55] op_sel:[1,0]
	v_pk_mul_f32 v[52:53], v[112:113], v[52:53] op_sel:[1,0]
	v_pk_fma_f32 v[50:51], v[92:93], v[54:55], v[50:51]
	v_pk_fma_f32 v[48:49], v[94:95], v[52:53], v[48:49]
	v_pk_fma_f32 v[50:51], v[66:67], s[78:79], v[50:51] op_sel_hi:[1,0,1]
	v_pk_fma_f32 v[48:49], v[64:65], s[78:79], v[48:49] op_sel_hi:[1,0,1]
	v_lshl_add_u64 v[52:53], v[158:159], 2, s[88:89]
	global_store_dwordx4 v[52:53], v[48:51], off
	v_add_u32_e32 v158, 0x10080, v148
	s_nop 0
	v_sub_f32_e32 v49, v85, v102
	v_sub_f32_e32 v48, v84, v102
	v_sub_f32_e32 v51, v87, v102
	v_sub_f32_e32 v50, v86, v102
	v_pk_mul_f32 v[50:51], v[102:103], v[50:51] op_sel:[1,0]
	v_pk_mul_f32 v[48:49], v[102:103], v[48:49] op_sel:[1,0]
	v_pk_fma_f32 v[46:47], v[96:97], v[50:51], v[46:47]
	v_pk_fma_f32 v[44:45], v[98:99], v[48:49], v[44:45]
	v_pk_fma_f32 v[46:47], v[70:71], s[78:79], v[46:47] op_sel_hi:[1,0,1]
	v_pk_fma_f32 v[44:45], v[68:69], s[78:79], v[44:45] op_sel_hi:[1,0,1]
	v_lshl_add_u64 v[48:49], v[158:159], 2, s[88:89]
	global_store_dwordx4 v[48:49], v[44:47], off
	v_add_u32_e32 v158, 0x10090, v148
	s_nop 0
	v_sub_f32_e32 v45, v81, v102
	v_sub_f32_e32 v44, v80, v102
	v_sub_f32_e32 v47, v83, v102
	v_sub_f32_e32 v46, v82, v102
	v_pk_mul_f32 v[46:47], v[102:103], v[46:47] op_sel:[1,0]
	v_pk_mul_f32 v[44:45], v[102:103], v[44:45] op_sel:[1,0]
	v_pk_fma_f32 v[42:43], v[92:93], v[46:47], v[42:43]
	v_pk_fma_f32 v[40:41], v[94:95], v[44:45], v[40:41]
	v_pk_fma_f32 v[42:43], v[66:67], s[78:79], v[42:43] op_sel_hi:[1,0,1]
	v_pk_fma_f32 v[40:41], v[64:65], s[78:79], v[40:41] op_sel_hi:[1,0,1]
	v_lshl_add_u64 v[44:45], v[158:159], 2, s[88:89]
	global_store_dwordx4 v[44:45], v[40:43], off
	v_add_u32_e32 v158, 0x18080, v148
	s_nop 0
	v_sub_f32_e32 v41, v77, v100
	v_sub_f32_e32 v40, v76, v100
	v_sub_f32_e32 v43, v79, v100
	v_sub_f32_e32 v42, v78, v100
	v_pk_mul_f32 v[42:43], v[100:101], v[42:43] op_sel:[1,0]
	v_pk_mul_f32 v[40:41], v[100:101], v[40:41] op_sel:[1,0]
	v_pk_fma_f32 v[38:39], v[96:97], v[42:43], v[38:39]
;     template <bool LN, int BJ, int LO, int HI> DI void batch(const f32x4 (&acc)[2][2][4][2], unsigned row0, unsigned col0, const f32x4 (&gv)[2], const f32x4 (&bv)[2]) const {
;         f32x4 r[HI - LO]; float mean[(HI - LO) / 2], rstd[(HI - LO) / 2];
; #pragma unroll
;         for (int i = LO; i < HI; ++i) { const int ai = i >> 3, m = (i >> 1) & 3, n = i & 1; const unsigned row = row0 + ai * HALF + m * 16;
;             if (n == 0) { mean[(i - LO) >> 1] = 0.f; rstd[(i - LO) >> 1] = 1.f;
;                 if (LN) { const float2 st = *(const float2*)(stats + row * 2u); mean[(i - LO) >> 1] = st.x; rstd[(i - LO) >> 1] = st.y; } }
;             r[i - LO] = *(const f32x4*)(src + (row * (unsigned)DM + col0 + BJ * HALF + n * 16)); }
; #pragma unroll
;         for (int i = LO; i < HI; ++i) { const int ai = i >> 3, m = (i >> 1) & 3, n = i & 1; const unsigned row = row0 + ai * HALF + m * 16;
;             *(f32x4*)(Y + (row * (unsigned)DM + col0 + BJ * HALF + n * 16)) = acc[ai][BJ][m][n] + ((r[i - LO] - mean[(i - LO) >> 1]) * rstd[(i - LO) >> 1]) * gv[n] + bv[n]; }
;         __builtin_amdgcn_sched_barrier(0);
;     }
;     template <bool LN, int BJ> DI void load_gb(unsigned col0, f32x4 (&gv)[2], f32x4 (&bv)[2]) const {
; #pragma unroll
;         for (int n = 0; n < 2; ++n) {
;             if (LN) { gv[n] = *(const f32x4*)(gam + col0 + BJ * HALF + n * 16) * ALPHA; bv[n] = *(const f32x4*)(bet + col0 + BJ * HALF + n * 16) * ALPHA; }
;             else { gv[n] = (f32x4){ALPHA, ALPHA, ALPHA, ALPHA}; bv[n] = (f32x4){0.f, 0.f, 0.f, 0.f}; }
;         }
;     }
;     template <bool LN> DI void run(const f32x4 (&acc)[2][2][4][2], const Unit& u, int wr, int wc, int fr, int fq) const {
;         const unsigned row0 = u.pm * BM + wr * 64 + fr, col0 = u.pn * BM + wc * 32 + 4 * fq;
;         f32x4 gv[2], bv[2];
;         load_gb<LN, 0>(col0, gv, bv);
;         batch<LN, 0, 0, 4>(acc, row0, col0, gv, bv);
;         batch<LN, 0, 4, 8>(acc, row0, col0, gv, bv);
;         batch<LN, 0, 8, 12>(acc, row0, col0, gv, bv);
;         batch<LN, 0, 12, 16>(acc, row0, col0, gv, bv);
;         load_gb<LN, 1>(col0, gv, bv);
;         batch<LN, 1, 0, 8>(acc, row0, col0, gv, bv);
;         batch<LN, 1, 8, 16>(acc, row0, col0, gv, bv);
	v_pk_fma_f32 v[36:37], v[98:99], v[40:41], v[36:37]
	v_pk_fma_f32 v[38:39], v[70:71], s[78:79], v[38:39] op_sel_hi:[1,0,1]
	v_pk_fma_f32 v[36:37], v[68:69], s[78:79], v[36:37] op_sel_hi:[1,0,1]
	v_lshl_add_u64 v[40:41], v[158:159], 2, s[88:89]
	global_store_dwordx4 v[40:41], v[36:39], off
	v_add_u32_e32 v158, 0x18090, v148
	s_nop 0
	v_sub_f32_e32 v37, v73, v100
	v_sub_f32_e32 v36, v72, v100
	v_sub_f32_e32 v39, v75, v100
	v_sub_f32_e32 v38, v74, v100
	v_pk_mul_f32 v[38:39], v[100:101], v[38:39] op_sel:[1,0]
	v_pk_mul_f32 v[36:37], v[100:101], v[36:37] op_sel:[1,0]
	v_pk_fma_f32 v[34:35], v[92:93], v[38:39], v[34:35]
	v_pk_fma_f32 v[32:33], v[94:95], v[36:37], v[32:33]
	v_pk_fma_f32 v[34:35], v[66:67], s[78:79], v[34:35] op_sel_hi:[1,0,1]
	v_pk_fma_f32 v[32:33], v[64:65], s[78:79], v[32:33] op_sel_hi:[1,0,1]
	v_lshl_add_u64 v[36:37], v[158:159], 2, s[88:89]
	global_store_dwordx4 v[36:37], v[32:35], off
	v_add_u32_e32 v158, v114, v119
	s_nop 0
	v_lshl_add_u64 v[32:33], v[158:159], 2, s[90:91]
	global_load_dwordx2 v[62:63], v[104:105], off
	global_load_dwordx4 v[54:57], v[32:33], off
	v_add_u32_e32 v158, v114, v118
	v_lshl_add_u64 v[32:33], v[158:159], 2, s[90:91]
	global_load_dwordx4 v[58:61], v[32:33], off
	global_load_dwordx2 v[52:53], v[106:107], off
	v_add_u32_e32 v158, v115, v119
	v_lshl_add_u64 v[32:33], v[158:159], 2, s[90:91]
	global_load_dwordx4 v[72:75], v[32:33], off
	v_add_u32_e32 v158, v115, v118
	v_lshl_add_u64 v[32:33], v[158:159], 2, s[90:91]
	global_load_dwordx4 v[76:79], v[32:33], off
	global_load_dwordx2 v[50:51], v[108:109], off
	v_add_u32_e32 v158, v116, v119
	v_lshl_add_u64 v[32:33], v[158:159], 2, s[90:91]
	global_load_dwordx4 v[44:47], v[32:33], off
	v_add_u32_e32 v158, v116, v118
	v_lshl_add_u64 v[32:33], v[158:159], 2, s[90:91]
	global_load_dwordx4 v[40:43], v[32:33], off
	global_load_dwordx2 v[48:49], v[110:111], off
	v_add_u32_e32 v158, v117, v119
	v_lshl_add_u64 v[32:33], v[158:159], 2, s[90:91]
	global_load_dwordx4 v[36:39], v[32:33], off
	v_add_u32_e32 v158, v117, v118
	v_lshl_add_u64 v[32:33], v[158:159], 2, s[90:91]
	global_load_dwordx4 v[32:35], v[32:33], off
	v_add_u32_e32 v158, 0x40080, v148
	s_waitcnt vmcnt(0)
; template <class Epi>
; DI void gemm_phase(LAS unsigned char* lds, const Gemm g, const StaticOrder& S, const Epi& E) {
;     ...
;         if (!has_next) break;
;     template <bool LN, int BJ, int LO, int HI> DI void batch(const f32x4 (&acc)[2][2][4][2], unsigned row0, unsigned col0, const f32x4 (&gv)[2], const f32x4 (&bv)[2]) const {
;         f32x4 r[HI - LO]; float mean[(HI - LO) / 2], rstd[(HI - LO) / 2];
; #pragma unroll
;         for (int i = LO; i < HI; ++i) { const int ai = i >> 3, m = (i >> 1) & 3, n = i & 1; const unsigned row = row0 + ai * HALF + m * 16;
;             if (n == 0) { mean[(i - LO) >> 1] = 0.f; rstd[(i - LO) >> 1] = 1.f;
;                 if (LN) { const float2 st = *(const float2*)(stats + row * 2u); mean[(i - LO) >> 1] = st.x; rstd[(i - LO) >> 1] = st.y; } }
;             r[i - LO] = *(const f32x4*)(src + (row * (unsigned)DM + col0 + BJ * HALF + n * 16)); }
; #pragma unroll
;         for (int i = LO; i < HI; ++i) { const int ai = i >> 3, m = (i >> 1) & 3, n = i & 1; const unsigned row = row0 + ai * HALF + m * 16;
;             *(f32x4*)(Y + (row * (unsigned)DM + col0 + BJ * HALF + n * 16)) = acc[ai][BJ][m][n] + ((r[i - LO] - mean[(i - LO) >> 1]) * rstd[(i - LO) >> 1]) * gv[n] + bv[n]; }
;         __builtin_amdgcn_sched_barrier(0);
;     }
;     template <bool LN, int BJ> DI void load_gb(unsigned col0, f32x4 (&gv)[2], f32x4 (&bv)[2]) const {
; #pragma unroll
;         for (int n = 0; n < 2; ++n) {
;             if (LN) { gv[n] = *(const f32x4*)(gam + col0 + BJ * HALF + n * 16) * ALPHA; bv[n] = *(const f32x4*)(bet + col0 + BJ * HALF + n * 16) * ALPHA; }
;             else { gv[n] = (f32x4){ALPHA, ALPHA, ALPHA, ALPHA}; bv[n] = (f32x4){0.f, 0.f, 0.f, 0.f}; }
;         }
;     }
;     template <bool LN> DI void run(const f32x4 (&acc)[2][2][4][2], const Unit& u, int wr, int wc, int fr, int fq) const {
;         const unsigned row0 = u.pm * BM + wr * 64 + fr, col0 = u.pn * BM + wc * 32 + 4 * fq;
;         f32x4 gv[2], bv[2];
;         load_gb<LN, 0>(col0, gv, bv);
;         batch<LN, 0, 0, 4>(acc, row0, col0, gv, bv);
;         batch<LN, 0, 4, 8>(acc, row0, col0, gv, bv);
;         batch<LN, 0, 8, 12>(acc, row0, col0, gv, bv);
;         batch<LN, 0, 12, 16>(acc, row0, col0, gv, bv);
;         load_gb<LN, 1>(col0, gv, bv);
;         batch<LN, 1, 0, 8>(acc, row0, col0, gv, bv);
;         batch<LN, 1, 8, 16>(acc, row0, col0, gv, bv);
	v_sub_f32_e32 v55, v55, v62
	v_sub_f32_e32 v54, v54, v62
	v_sub_f32_e32 v57, v57, v62
	v_sub_f32_e32 v56, v56, v62
	v_pk_mul_f32 v[56:57], v[62:63], v[56:57] op_sel:[1,0]
	v_pk_mul_f32 v[54:55], v[62:63], v[54:55] op_sel:[1,0]
	v_pk_fma_f32 v[30:31], v[96:97], v[56:57], v[30:31]
	v_pk_fma_f32 v[28:29], v[98:99], v[54:55], v[28:29]
	v_pk_fma_f32 v[30:31], v[70:71], s[78:79], v[30:31] op_sel_hi:[1,0,1]
	v_pk_fma_f32 v[28:29], v[68:69], s[78:79], v[28:29] op_sel_hi:[1,0,1]
	v_lshl_add_u64 v[54:55], v[158:159], 2, s[88:89]
	global_store_dwordx4 v[54:55], v[28:31], off
	v_add_u32_e32 v158, 0x40090, v148
	s_nop 0
	v_sub_f32_e32 v29, v59, v62
	v_sub_f32_e32 v28, v58, v62
	v_sub_f32_e32 v31, v61, v62
	v_sub_f32_e32 v30, v60, v62
	v_pk_mul_f32 v[30:31], v[62:63], v[30:31] op_sel:[1,0]
	v_pk_mul_f32 v[28:29], v[62:63], v[28:29] op_sel:[1,0]
	v_pk_fma_f32 v[26:27], v[92:93], v[30:31], v[26:27]
	v_pk_fma_f32 v[24:25], v[94:95], v[28:29], v[24:25]
	v_pk_fma_f32 v[26:27], v[66:67], s[78:79], v[26:27] op_sel_hi:[1,0,1]
	v_pk_fma_f32 v[24:25], v[64:65], s[78:79], v[24:25] op_sel_hi:[1,0,1]
	v_lshl_add_u64 v[28:29], v[158:159], 2, s[88:89]
	global_store_dwordx4 v[28:29], v[24:27], off
	v_add_u32_e32 v158, 0x48080, v148
	s_nop 0
	v_sub_f32_e32 v25, v73, v52
	v_sub_f32_e32 v24, v72, v52
	v_sub_f32_e32 v27, v75, v52
	v_sub_f32_e32 v26, v74, v52
	v_pk_mul_f32 v[26:27], v[52:53], v[26:27] op_sel:[1,0]
	v_pk_mul_f32 v[24:25], v[52:53], v[24:25] op_sel:[1,0]
	v_pk_fma_f32 v[22:23], v[96:97], v[26:27], v[22:23]
	v_pk_fma_f32 v[20:21], v[98:99], v[24:25], v[20:21]
	v_pk_fma_f32 v[22:23], v[70:71], s[78:79], v[22:23] op_sel_hi:[1,0,1]
	v_pk_fma_f32 v[20:21], v[68:69], s[78:79], v[20:21] op_sel_hi:[1,0,1]
	v_lshl_add_u64 v[24:25], v[158:159], 2, s[88:89]
	global_store_dwordx4 v[24:25], v[20:23], off
	v_add_u32_e32 v158, 0x48090, v148
	s_nop 0
	v_sub_f32_e32 v21, v77, v52
	v_sub_f32_e32 v20, v76, v52
	v_sub_f32_e32 v23, v79, v52
	v_sub_f32_e32 v22, v78, v52
	v_pk_mul_f32 v[22:23], v[52:53], v[22:23] op_sel:[1,0]
	v_pk_mul_f32 v[20:21], v[52:53], v[20:21] op_sel:[1,0]
	v_pk_fma_f32 v[18:19], v[92:93], v[22:23], v[18:19]
	v_pk_fma_f32 v[16:17], v[94:95], v[20:21], v[16:17]
	v_pk_fma_f32 v[18:19], v[66:67], s[78:79], v[18:19] op_sel_hi:[1,0,1]
	v_pk_fma_f32 v[16:17], v[64:65], s[78:79], v[16:17] op_sel_hi:[1,0,1]
	v_lshl_add_u64 v[20:21], v[158:159], 2, s[88:89]
	global_store_dwordx4 v[20:21], v[16:19], off
	v_add_u32_e32 v158, 0x50080, v148
	s_nop 0
	v_sub_f32_e32 v17, v45, v50
	v_sub_f32_e32 v16, v44, v50
	v_sub_f32_e32 v19, v47, v50
	v_sub_f32_e32 v18, v46, v50
	v_pk_mul_f32 v[18:19], v[50:51], v[18:19] op_sel:[1,0]
	v_pk_mul_f32 v[16:17], v[50:51], v[16:17] op_sel:[1,0]
	v_pk_fma_f32 v[14:15], v[96:97], v[18:19], v[14:15]
	v_pk_fma_f32 v[12:13], v[98:99], v[16:17], v[12:13]
	v_pk_fma_f32 v[14:15], v[70:71], s[78:79], v[14:15] op_sel_hi:[1,0,1]
	v_pk_fma_f32 v[12:13], v[68:69], s[78:79], v[12:13] op_sel_hi:[1,0,1]
	v_lshl_add_u64 v[16:17], v[158:159], 2, s[88:89]
	global_store_dwordx4 v[16:17], v[12:15], off
	v_add_u32_e32 v158, 0x50090, v148
	s_nop 0
	v_sub_f32_e32 v13, v41, v50
	v_sub_f32_e32 v12, v40, v50
	v_sub_f32_e32 v15, v43, v50
	v_sub_f32_e32 v14, v42, v50
	v_pk_mul_f32 v[14:15], v[50:51], v[14:15] op_sel:[1,0]
	v_pk_mul_f32 v[12:13], v[50:51], v[12:13] op_sel:[1,0]
	v_pk_fma_f32 v[10:11], v[92:93], v[14:15], v[10:11]
	v_pk_fma_f32 v[8:9], v[94:95], v[12:13], v[8:9]
	v_pk_fma_f32 v[10:11], v[66:67], s[78:79], v[10:11] op_sel_hi:[1,0,1]
	v_pk_fma_f32 v[8:9], v[64:65], s[78:79], v[8:9] op_sel_hi:[1,0,1]
	v_lshl_add_u64 v[12:13], v[158:159], 2, s[88:89]
	global_store_dwordx4 v[12:13], v[8:11], off
	v_add_u32_e32 v158, 0x58080, v148
	s_nop 0
	v_sub_f32_e32 v9, v37, v48
	v_sub_f32_e32 v8, v36, v48
	v_sub_f32_e32 v11, v39, v48
	v_sub_f32_e32 v10, v38, v48
	v_pk_mul_f32 v[10:11], v[48:49], v[10:11] op_sel:[1,0]
	v_pk_mul_f32 v[8:9], v[48:49], v[8:9] op_sel:[1,0]
	v_pk_fma_f32 v[6:7], v[96:97], v[10:11], v[6:7]
	v_pk_fma_f32 v[4:5], v[98:99], v[8:9], v[4:5]
	v_pk_fma_f32 v[6:7], v[70:71], s[78:79], v[6:7] op_sel_hi:[1,0,1]
	v_pk_fma_f32 v[4:5], v[68:69], s[78:79], v[4:5] op_sel_hi:[1,0,1]
	v_lshl_add_u64 v[8:9], v[158:159], 2, s[88:89]
	global_store_dwordx4 v[8:9], v[4:7], off
	v_add_u32_e32 v158, 0x58090, v148
	s_nop 0
	v_sub_f32_e32 v5, v33, v48
	v_sub_f32_e32 v4, v32, v48
	v_sub_f32_e32 v7, v35, v48
	v_sub_f32_e32 v6, v34, v48
	v_pk_mul_f32 v[6:7], v[48:49], v[6:7] op_sel:[1,0]
	v_pk_mul_f32 v[4:5], v[48:49], v[4:5] op_sel:[1,0]
	v_pk_fma_f32 v[2:3], v[92:93], v[6:7], v[2:3]
	v_pk_fma_f32 v[0:1], v[94:95], v[4:5], v[0:1]
	v_pk_fma_f32 v[2:3], v[66:67], s[78:79], v[2:3] op_sel_hi:[1,0,1]
	v_pk_fma_f32 v[0:1], v[64:65], s[78:79], v[0:1] op_sel_hi:[1,0,1]
	v_lshl_add_u64 v[4:5], v[158:159], 2, s[88:89]
	global_store_dwordx4 v[4:5], v[0:3], off
	s_and_b64 vcc, exec, s[6:7]
	s_mov_b32 s2, s37
	s_mov_b32 s3, s38
	s_mov_b64 s[18:19], s[10:11]
	s_mov_b64 s[16:17], s[8:9]
	v_readlane_b32 s33, v255, 39
	s_cbranch_vccz .LBB0_123
	s_waitcnt vmcnt(0)
	s_cmpk_gt_u32 s24, 0xff
	s_cbranch_scc1 .LBB0_138
	s_barrier

; #define PG8_STAGE(bufoff, gbase) do { _Pragma("unroll") for (int _i = 0; _i < 2; ++_i) \
;         __builtin_amdgcn_global_load_lds((const unsigned*)((const char*)(gbase) + voff[_i]), (LAS unsigned*)(lds + (bufoff) + ldsw + _i * 8192), 16, 0, 0); } while (0)
; #define PG8_LDA(dst, b, h) do { _Pragma("unroll") for (int m = 0; m < 4; ++m) _Pragma("unroll") for (int k = 0; k < 2; ++k) dst[m][k] = *(const LAS bf16x8*)(lds + PG8_SA(b, h) + aoff + m * 2048 + k * 1024); } while (0)
; #define PG8_LDB(dst, b, h) do { _Pragma("unroll") for (int n = 0; n < 2; ++n) _Pragma("unroll") for (int k = 0; k < 2; ++k) dst[n][k] = *(const LAS bf16x8*)(lds + PG8_SB(b, h) + boff + n * 2048 + k * 1024); } while (0)
; #define PG8_MMA(ai, bj, At, Bt) do { __builtin_amdgcn_s_setprio(1); _Pragma("unroll") for (int m = 0; m < 4; ++m) _Pragma("unroll") for (int n = 0; n < 2; ++n) _Pragma("unroll") for (int k = 0; k < 2; ++k) \
;         acc[ai][bj][m][n] = __builtin_amdgcn_mfma_f32_16x16x32_bf16(Bt[n][k], At[m][k], acc[ai][bj][m][n], 0, 0, 0); __builtin_amdgcn_s_setprio(0); } while (0)
; #define PG8_WAIT_L(n) asm volatile("s_waitcnt lgkmcnt(" #n ")" ::: "memory")
; #define PG8_BAR __builtin_amdgcn_s_barrier()
; #define PG8_SCHED __builtin_amdgcn_sched_barrier(0)
; template <class Epi>
; DI void gemm_phase(LAS unsigned char* lds, const Gemm g, const StaticOrder& S, const Epi& E) {
;     ...
;         for (int t = 0; t < nt; t += 2) {
;             const bool last = (t == nt - 2);
;             const char* a1 = cA + (size_t)(t + 1) * kstep;
;             const char* a2 = last ? nA : cA + (size_t)(t + 2) * kstep; const char* b2 = last ? nB : cB + (size_t)(t + 2) * kstep;
;             const char* a3 = a2 + kstep; const char* b3 = b2 + kstep;
;             PG8_LDB(B0, 0, 0); PG8_SCHED; PG8_LDA(At, 0, 0); PG8_STAGE(PG8_SA(1, 1), a1 + hstep);
;             PG8_WAIT_L(8); PG8_BAR; PG8_WAIT_L(0); PG8_MMA(0, 0, At, B0); PG8_BAR; PG8_SCHED;
;             PG8_LDB(B1, 0, 1); PG8_STAGE(PG8_SB(0, 0), b2);
;             PG8_BAR; PG8_WAIT_L(0); PG8_MMA(0, 1, At, B1); PG8_BAR;
;             PG8_LDA(At, 0, 1); PG8_STAGE(PG8_SA(0, 0), a2);
;             PG8_BAR; PG8_WAIT_L(0); PG8_MMA(1, 0, At, B0); PG8_BAR; PG8_SCHED;
.LBB0_202:
	s_add_u32 s18, s8, 0xfff80080
	s_addc_u32 s19, s9, -1
	s_add_i32 s37, 0, 0x10000
	v_add_u32_e32 v140, s37, v187
	s_waitcnt lgkmcnt(0)
	ds_read_b128 v[128:131], v140
	ds_read_b128 v[132:135], v140 offset:1024
	ds_read_b128 v[136:139], v140 offset:2048
	ds_read_b128 v[190:193], v140 offset:3072
	s_cmp_eq_u32 s36, 28
	s_cselect_b32 s21, s4, s19
	s_cselect_b32 s20, s5, s18
	s_cselect_b32 s19, s11, s35
	s_cselect_b32 s18, s13, s33
	v_lshl_add_u64 v[140:141], s[8:9], 0, v[150:151]
	s_add_i32 m0, s26, 0xc000
	ds_read_b128 v[194:197], v189
	ds_read_b128 v[198:201], v189 offset:1024
	ds_read_b128 v[202:205], v189 offset:2048
	ds_read_b128 v[206:209], v189 offset:3072
	ds_read_b128 v[210:213], v189 offset:4096
	ds_read_b128 v[214:217], v189 offset:5120
	ds_read_b128 v[226:229], v189 offset:6144
	ds_read_b128 v[230:233], v189 offset:7168
	global_load_lds_dwordx4 v[140:141], off
	v_lshl_add_u64 v[140:141], s[8:9], 0, v[152:153]
	s_add_i32 m0, s26, 0xe000
	s_nop 0
	global_load_lds_dwordx4 v[140:141], off
	s_waitcnt lgkmcnt(8)
	s_setprio 1
	s_barrier
	s_waitcnt lgkmcnt(0)
	v_mfma_f32_16x16x32_bf16 v[124:127], v[128:131], v[194:197], v[124:127]
	v_mfma_f32_16x16x32_bf16 v[120:123], v[136:139], v[194:197], v[120:123]
	v_mfma_f32_16x16x32_bf16 v[108:111], v[128:131], v[202:205], v[108:111]
	v_mfma_f32_16x16x32_bf16 v[104:107], v[136:139], v[202:205], v[104:107]
	v_mfma_f32_16x16x32_bf16 v[92:95], v[128:131], v[210:213], v[92:95]
	v_mfma_f32_16x16x32_bf16 v[88:91], v[136:139], v[210:213], v[88:91]
	v_mfma_f32_16x16x32_bf16 v[76:79], v[128:131], v[226:229], v[76:79]
	v_mfma_f32_16x16x32_bf16 v[72:75], v[136:139], v[226:229], v[72:75]
	v_mfma_f32_16x16x32_bf16 v[124:127], v[132:135], v[198:201], v[124:127]
	v_mfma_f32_16x16x32_bf16 v[120:123], v[190:193], v[198:201], v[120:123]
	v_mfma_f32_16x16x32_bf16 v[108:111], v[132:135], v[206:209], v[108:111]
	v_mfma_f32_16x16x32_bf16 v[104:107], v[190:193], v[206:209], v[104:107]
	v_mfma_f32_16x16x32_bf16 v[92:95], v[132:135], v[214:217], v[92:95]
	v_mfma_f32_16x16x32_bf16 v[88:91], v[190:193], v[214:217], v[88:91]
	v_mfma_f32_16x16x32_bf16 v[76:79], v[132:135], v[230:233], v[76:79]
	v_mfma_f32_16x16x32_bf16 v[72:75], v[190:193], v[230:233], v[72:75]
	s_setprio 0
	s_barrier
	s_add_i32 s40, 0, 0x14000
	v_add_u32_e32 v140, s40, v187
	s_add_i32 s37, s37, s25
	ds_read_b128 v[234:237], v140
	ds_read_b128 v[238:241], v140 offset:1024
	ds_read_b128 v[242:245], v140 offset:2048
	ds_read_b128 v[246:249], v140 offset:3072
	v_lshl_add_u64 v[140:141], s[18:19], 0, v[144:145]
	s_mov_b32 m0, s37
	v_lshl_add_u64 v[154:155], s[18:19], 0, v[142:143]
	global_load_lds_dwordx4 v[140:141], off
	s_add_i32 m0, s37, 0x2000
	s_nop 0
	global_load_lds_dwordx4 v[154:155], off
	s_waitcnt lgkmcnt(0)
	s_setprio 1
	s_barrier
	v_mfma_f32_16x16x32_bf16 v[116:119], v[234:237], v[194:197], v[116:119]
	v_mfma_f32_16x16x32_bf16 v[112:115], v[242:245], v[194:197], v[112:115]
	v_mfma_f32_16x16x32_bf16 v[100:103], v[234:237], v[202:205], v[100:103]
	v_mfma_f32_16x16x32_bf16 v[96:99], v[242:245], v[202:205], v[96:99]
	v_mfma_f32_16x16x32_bf16 v[84:87], v[234:237], v[210:213], v[84:87]
	v_mfma_f32_16x16x32_bf16 v[80:83], v[242:245], v[210:213], v[80:83]
	v_mfma_f32_16x16x32_bf16 v[68:71], v[234:237], v[226:229], v[68:71]
	v_mfma_f32_16x16x32_bf16 v[64:67], v[242:245], v[226:229], v[64:67]
	v_mfma_f32_16x16x32_bf16 v[116:119], v[238:241], v[198:201], v[116:119]
	v_mfma_f32_16x16x32_bf16 v[112:115], v[246:249], v[198:201], v[112:115]
	v_mfma_f32_16x16x32_bf16 v[100:103], v[238:241], v[206:209], v[100:103]
	v_mfma_f32_16x16x32_bf16 v[96:99], v[246:249], v[206:209], v[96:99]
	s_mov_b32 m0, s26
	v_lshl_add_u64 v[218:219], s[20:21], 0, v[144:145]
	v_mfma_f32_16x16x32_bf16 v[84:87], v[238:241], v[214:217], v[84:87]
	v_mfma_f32_16x16x32_bf16 v[80:83], v[246:249], v[214:217], v[80:83]
	v_mfma_f32_16x16x32_bf16 v[68:71], v[238:241], v[230:233], v[68:71]
	v_mfma_f32_16x16x32_bf16 v[64:67], v[246:249], v[230:233], v[64:67]
	s_setprio 0
	s_barrier
	ds_read_b128 v[194:197], v189 offset:16384
	ds_read_b128 v[198:201], v189 offset:17408
	ds_read_b128 v[202:205], v189 offset:18432
	ds_read_b128 v[206:209], v189 offset:19456
	ds_read_b128 v[210:213], v189 offset:20480
	ds_read_b128 v[214:217], v189 offset:21504
	ds_read_b128 v[226:229], v189 offset:22528
	ds_read_b128 v[230:233], v189 offset:23552
	global_load_lds_dwordx4 v[218:219], off
	v_lshl_add_u64 v[250:251], s[20:21], 0, v[142:143]
	s_mov_b32 m0, s27
	s_nop 0
	global_load_lds_dwordx4 v[250:251], off
	s_waitcnt lgkmcnt(0)
	s_setprio 1
	s_barrier
	v_mfma_f32_16x16x32_bf16 v[60:63], v[128:131], v[194:197], v[60:63]
	v_mfma_f32_16x16x32_bf16 v[56:59], v[136:139], v[194:197], v[56:59]
	v_mfma_f32_16x16x32_bf16 v[44:47], v[128:131], v[202:205], v[44:47]
	v_mfma_f32_16x16x32_bf16 v[40:43], v[136:139], v[202:205], v[40:43]
	v_mfma_f32_16x16x32_bf16 v[28:31], v[128:131], v[210:213], v[28:31]
	v_mfma_f32_16x16x32_bf16 v[24:27], v[136:139], v[210:213], v[24:27]
	v_mfma_f32_16x16x32_bf16 v[12:15], v[128:131], v[226:229], v[12:15]
	v_mfma_f32_16x16x32_bf16 v[8:11], v[136:139], v[226:229], v[8:11]
	v_mfma_f32_16x16x32_bf16 v[60:63], v[132:135], v[198:201], v[60:63]
	v_mfma_f32_16x16x32_bf16 v[56:59], v[190:193], v[198:201], v[56:59]
	v_mfma_f32_16x16x32_bf16 v[44:47], v[132:135], v[206:209], v[44:47]
	v_mfma_f32_16x16x32_bf16 v[40:43], v[190:193], v[206:209], v[40:43]
	v_mfma_f32_16x16x32_bf16 v[28:31], v[132:135], v[214:217], v[28:31]
	v_mfma_f32_16x16x32_bf16 v[24:27], v[190:193], v[214:217], v[24:27]
	v_mfma_f32_16x16x32_bf16 v[12:15], v[132:135], v[230:233], v[12:15]
	v_mfma_f32_16x16x32_bf16 v[8:11], v[190:193], v[230:233], v[8:11]
	s_setprio 0
	s_barrier
; #define PG8_STAGE(bufoff, gbase) do { _Pragma("unroll") for (int _i = 0; _i < 2; ++_i) \
;         __builtin_amdgcn_global_load_lds((const unsigned*)((const char*)(gbase) + voff[_i]), (LAS unsigned*)(lds + (bufoff) + ldsw + _i * 8192), 16, 0, 0); } while (0)
; #define PG8_LDA(dst, b, h) do { _Pragma("unroll") for (int m = 0; m < 4; ++m) _Pragma("unroll") for (int k = 0; k < 2; ++k) dst[m][k] = *(const LAS bf16x8*)(lds + PG8_SA(b, h) + aoff + m * 2048 + k * 1024); } while (0)
; #define PG8_LDB(dst, b, h) do { _Pragma("unroll") for (int n = 0; n < 2; ++n) _Pragma("unroll") for (int k = 0; k < 2; ++k) dst[n][k] = *(const LAS bf16x8*)(lds + PG8_SB(b, h) + boff + n * 2048 + k * 1024); } while (0)
; #define PG8_MMA(ai, bj, At, Bt) do { __builtin_amdgcn_s_setprio(1); _Pragma("unroll") for (int m = 0; m < 4; ++m) _Pragma("unroll") for (int n = 0; n < 2; ++n) _Pragma("unroll") for (int k = 0; k < 2; ++k) \
;         acc[ai][bj][m][n] = __builtin_amdgcn_mfma_f32_16x16x32_bf16(Bt[n][k], At[m][k], acc[ai][bj][m][n], 0, 0, 0); __builtin_amdgcn_s_setprio(0); } while (0)
; #define PG8_WAIT_V(n) asm volatile("s_waitcnt vmcnt(" #n ")" ::: "memory")
; #define PG8_WAIT_L(n) asm volatile("s_waitcnt lgkmcnt(" #n ")" ::: "memory")
; #define PG8_BAR __builtin_amdgcn_s_barrier()
; #define PG8_SCHED __builtin_amdgcn_sched_barrier(0)
; template <class Epi>
; DI void gemm_phase(LAS unsigned char* lds, const Gemm g, const StaticOrder& S, const Epi& E) {
;     ...
;             PG8_STAGE(PG8_SB(0, 1), b2 + hstep);
;             PG8_WAIT_V(6); PG8_BAR; PG8_MMA(1, 1, At, B1); PG8_BAR;
;             PG8_LDB(B0, 1, 0); PG8_SCHED; PG8_LDA(At, 1, 0); PG8_STAGE(PG8_SA(0, 1), a2 + hstep);
;             PG8_WAIT_L(8); PG8_BAR; PG8_WAIT_L(0); PG8_MMA(0, 0, At, B0); PG8_BAR; PG8_SCHED;
;             PG8_LDB(B1, 1, 1); PG8_STAGE(PG8_SB(1, 0), b3);
;             PG8_BAR; PG8_WAIT_L(0); PG8_MMA(0, 1, At, B1); PG8_BAR;
;             PG8_LDA(At, 1, 1); PG8_STAGE(PG8_SA(1, 0), a3);
;             PG8_BAR; PG8_WAIT_L(0); PG8_MMA(1, 0, At, B0); PG8_BAR; PG8_SCHED;
	s_add_u32 s38, s18, 0x80000
	s_addc_u32 s39, s19, 0
	s_add_i32 s37, s40, s25
	v_lshl_add_u64 v[128:129], s[38:39], 0, v[144:145]
	s_mov_b32 m0, s37
	s_nop 0
	global_load_lds_dwordx4 v[128:129], off
	v_lshl_add_u64 v[128:129], s[38:39], 0, v[142:143]
	s_add_i32 m0, s37, 0x2000
	s_nop 0
	global_load_lds_dwordx4 v[128:129], off
	s_waitcnt vmcnt(6)
	s_setprio 1
	s_barrier
	v_mfma_f32_16x16x32_bf16 v[52:55], v[234:237], v[194:197], v[52:55]
	v_mfma_f32_16x16x32_bf16 v[48:51], v[242:245], v[194:197], v[48:51]
	v_mfma_f32_16x16x32_bf16 v[36:39], v[234:237], v[202:205], v[36:39]
	v_mfma_f32_16x16x32_bf16 v[32:35], v[242:245], v[202:205], v[32:35]
	v_mfma_f32_16x16x32_bf16 v[20:23], v[234:237], v[210:213], v[20:23]
	v_mfma_f32_16x16x32_bf16 v[16:19], v[242:245], v[210:213], v[16:19]
	v_mfma_f32_16x16x32_bf16 v[4:7], v[234:237], v[226:229], v[4:7]
	v_mfma_f32_16x16x32_bf16 v[0:3], v[242:245], v[226:229], v[0:3]
	v_mfma_f32_16x16x32_bf16 v[52:55], v[238:241], v[198:201], v[52:55]
	v_mfma_f32_16x16x32_bf16 v[48:51], v[246:249], v[198:201], v[48:51]
	v_mfma_f32_16x16x32_bf16 v[36:39], v[238:241], v[206:209], v[36:39]
	v_mfma_f32_16x16x32_bf16 v[32:35], v[246:249], v[206:209], v[32:35]
	s_add_i32 s37, 0, 0x18000
	v_add_u32_e32 v158, s37, v187
	v_mfma_f32_16x16x32_bf16 v[20:23], v[238:241], v[214:217], v[20:23]
	v_mfma_f32_16x16x32_bf16 v[16:19], v[246:249], v[214:217], v[16:19]
	v_mfma_f32_16x16x32_bf16 v[4:7], v[238:241], v[230:233], v[4:7]
	v_mfma_f32_16x16x32_bf16 v[0:3], v[246:249], v[230:233], v[0:3]
	s_setprio 0
	s_barrier
	ds_read_b128 v[128:131], v158
	ds_read_b128 v[132:135], v158 offset:1024
	ds_read_b128 v[136:139], v158 offset:2048
	ds_read_b128 v[190:193], v158 offset:3072
	s_add_u32 s20, s20, 0x80000
	s_addc_u32 s21, s21, 0
	s_mov_b32 m0, s28
	v_lshl_add_u64 v[234:235], s[20:21], 0, v[144:145]
	ds_read_b128 v[194:197], v189 offset:32768
	ds_read_b128 v[198:201], v189 offset:33792
	ds_read_b128 v[202:205], v189 offset:34816
	ds_read_b128 v[206:209], v189 offset:35840
	ds_read_b128 v[210:213], v189 offset:36864
	ds_read_b128 v[214:217], v189 offset:37888
	ds_read_b128 v[226:229], v189 offset:38912
	ds_read_b128 v[230:233], v189 offset:39936
	global_load_lds_dwordx4 v[234:235], off
	v_lshl_add_u64 v[234:235], s[20:21], 0, v[142:143]
	s_mov_b32 m0, s29
	s_nop 0
	global_load_lds_dwordx4 v[234:235], off
	s_waitcnt lgkmcnt(8)
	s_setprio 1
	s_barrier
	s_waitcnt lgkmcnt(0)
	v_mfma_f32_16x16x32_bf16 v[124:127], v[128:131], v[194:197], v[124:127]
	v_mfma_f32_16x16x32_bf16 v[120:123], v[136:139], v[194:197], v[120:123]
	v_mfma_f32_16x16x32_bf16 v[108:111], v[128:131], v[202:205], v[108:111]
	v_mfma_f32_16x16x32_bf16 v[104:107], v[136:139], v[202:205], v[104:107]
	v_mfma_f32_16x16x32_bf16 v[92:95], v[128:131], v[210:213], v[92:95]
	v_mfma_f32_16x16x32_bf16 v[88:91], v[136:139], v[210:213], v[88:91]
	v_mfma_f32_16x16x32_bf16 v[76:79], v[128:131], v[226:229], v[76:79]
	v_mfma_f32_16x16x32_bf16 v[72:75], v[136:139], v[226:229], v[72:75]
	v_mfma_f32_16x16x32_bf16 v[124:127], v[132:135], v[198:201], v[124:127]
	v_mfma_f32_16x16x32_bf16 v[120:123], v[190:193], v[198:201], v[120:123]
	v_mfma_f32_16x16x32_bf16 v[108:111], v[132:135], v[206:209], v[108:111]
	v_mfma_f32_16x16x32_bf16 v[104:107], v[190:193], v[206:209], v[104:107]
	v_mfma_f32_16x16x32_bf16 v[92:95], v[132:135], v[214:217], v[92:95]
	v_mfma_f32_16x16x32_bf16 v[88:91], v[190:193], v[214:217], v[88:91]
	v_mfma_f32_16x16x32_bf16 v[76:79], v[132:135], v[230:233], v[76:79]
	v_mfma_f32_16x16x32_bf16 v[72:75], v[190:193], v[230:233], v[72:75]
	s_setprio 0
	s_barrier
	s_add_i32 s20, 0, 0x1c000
	s_add_i32 s21, s37, s25
	v_add_u32_e32 v158, s20, v187
	v_lshl_add_u64 v[140:141], v[140:141], 0, s[94:95]
	s_mov_b32 m0, s21
	ds_read_b128 v[234:237], v158
	ds_read_b128 v[238:241], v158 offset:1024
	ds_read_b128 v[242:245], v158 offset:2048
	ds_read_b128 v[246:249], v158 offset:3072
	global_load_lds_dwordx4 v[140:141], off
	v_lshl_add_u64 v[140:141], v[154:155], 0, s[94:95]
	s_add_i32 m0, s21, 0x2000
	s_nop 0
	global_load_lds_dwordx4 v[140:141], off
	s_waitcnt lgkmcnt(0)
	s_setprio 1
	s_barrier
; #define PG8_STAGE(bufoff, gbase) do { _Pragma("unroll") for (int _i = 0; _i < 2; ++_i) \
;         __builtin_amdgcn_global_load_lds((const unsigned*)((const char*)(gbase) + voff[_i]), (LAS unsigned*)(lds + (bufoff) + ldsw + _i * 8192), 16, 0, 0); } while (0)
; #define PG8_MMA(ai, bj, At, Bt) do { __builtin_amdgcn_s_setprio(1); _Pragma("unroll") for (int m = 0; m < 4; ++m) _Pragma("unroll") for (int n = 0; n < 2; ++n) _Pragma("unroll") for (int k = 0; k < 2; ++k) \
;         acc[ai][bj][m][n] = __builtin_amdgcn_mfma_f32_16x16x32_bf16(Bt[n][k], At[m][k], acc[ai][bj][m][n], 0, 0, 0); __builtin_amdgcn_s_setprio(0); } while (0)
; #define PG8_WAIT_V(n) asm volatile("s_waitcnt vmcnt(" #n ")" ::: "memory")
; #define PG8_WAIT_L(n) asm volatile("s_waitcnt lgkmcnt(" #n ")" ::: "memory")
; #define PG8_BAR __builtin_amdgcn_s_barrier()
; #define PG8_SCHED __builtin_amdgcn_sched_barrier(0)
; template <class Epi>
; DI void gemm_phase(LAS unsigned char* lds, const Gemm g, const StaticOrder& S, const Epi& E) {
;     ...
;             PG8_BAR; PG8_WAIT_L(0); PG8_MMA(1, 0, At, B0); PG8_BAR; PG8_SCHED;
;             PG8_STAGE(PG8_SB(1, 1), b3 + hstep);
;             PG8_WAIT_V(6); PG8_BAR; PG8_MMA(1, 1, At, B1); PG8_BAR;
;         }
;         E(acc, cur, wr, wc, fr, fq);
;     DI void operator()(const f32x4 (&acc)[2][2][4][2], const Unit& u, int wr, int wc, int fr, int fq) const {
;         const int row0 = u.pm * BM + wr * 64 + fr, col0 = u.pn * BM + wc * 16 + 4 * fq;
;         const bool rot = u.pn < 18;
; #pragma unroll
;         for (int ai = 0; ai < 2; ++ai)
; #pragma unroll
;             for (int m = 0; m < 4; ++m) { const int row = row0 + ai * HALF + m * 16; u16* rowp = O + (size_t)row * NQKV_DIL + col0;
;                 f32x4 c4 = (f32x4){1.f, 1.f, 1.f, 1.f}, s4 = (f32x4){0.f, 0.f, 0.f, 0.f};
;                 if (rot) { const int pos = row & (SEQ - 1); c4 = *(const f32x4*)(cs + pos * 64 + wc * 16 + 4 * fq); s4 = *(const f32x4*)(sn + pos * 64 + wc * 16 + 4 * fq); }
	v_mfma_f32_16x16x32_bf16 v[116:119], v[234:237], v[194:197], v[116:119]
	v_mfma_f32_16x16x32_bf16 v[112:115], v[242:245], v[194:197], v[112:115]
	v_mfma_f32_16x16x32_bf16 v[100:103], v[234:237], v[202:205], v[100:103]
	v_mfma_f32_16x16x32_bf16 v[96:99], v[242:245], v[202:205], v[96:99]
	v_mfma_f32_16x16x32_bf16 v[84:87], v[234:237], v[210:213], v[84:87]
	v_mfma_f32_16x16x32_bf16 v[80:83], v[242:245], v[210:213], v[80:83]
	v_mfma_f32_16x16x32_bf16 v[68:71], v[234:237], v[226:229], v[68:71]
	v_mfma_f32_16x16x32_bf16 v[64:67], v[242:245], v[226:229], v[64:67]
	v_mfma_f32_16x16x32_bf16 v[116:119], v[238:241], v[198:201], v[116:119]
	v_mfma_f32_16x16x32_bf16 v[112:115], v[246:249], v[198:201], v[112:115]
	v_mfma_f32_16x16x32_bf16 v[100:103], v[238:241], v[206:209], v[100:103]
	v_mfma_f32_16x16x32_bf16 v[96:99], v[246:249], v[206:209], v[96:99]
	s_mov_b32 m0, s30
	v_lshl_add_u64 v[140:141], v[218:219], 0, s[94:95]
	v_mfma_f32_16x16x32_bf16 v[84:87], v[238:241], v[214:217], v[84:87]
	v_mfma_f32_16x16x32_bf16 v[80:83], v[246:249], v[214:217], v[80:83]
	v_mfma_f32_16x16x32_bf16 v[68:71], v[238:241], v[230:233], v[68:71]
	v_mfma_f32_16x16x32_bf16 v[64:67], v[246:249], v[230:233], v[64:67]
	s_setprio 0
	s_barrier
	ds_read_b128 v[194:197], v189 offset:49152
	ds_read_b128 v[198:201], v189 offset:50176
	ds_read_b128 v[202:205], v189 offset:51200
	ds_read_b128 v[206:209], v189 offset:52224
	ds_read_b128 v[210:213], v189 offset:53248
	ds_read_b128 v[214:217], v189 offset:54272
	ds_read_b128 v[226:229], v189 offset:55296
	ds_read_b128 v[230:233], v189 offset:56320
	global_load_lds_dwordx4 v[140:141], off
	v_lshl_add_u64 v[140:141], v[250:251], 0, s[94:95]
	s_mov_b32 m0, s31
	s_nop 0
	global_load_lds_dwordx4 v[140:141], off
	s_waitcnt lgkmcnt(0)
	s_setprio 1
	s_barrier
	v_mfma_f32_16x16x32_bf16 v[60:63], v[128:131], v[194:197], v[60:63]
	v_mfma_f32_16x16x32_bf16 v[56:59], v[136:139], v[194:197], v[56:59]
	v_mfma_f32_16x16x32_bf16 v[44:47], v[128:131], v[202:205], v[44:47]
	v_mfma_f32_16x16x32_bf16 v[40:43], v[136:139], v[202:205], v[40:43]
	v_mfma_f32_16x16x32_bf16 v[28:31], v[128:131], v[210:213], v[28:31]
	v_mfma_f32_16x16x32_bf16 v[24:27], v[136:139], v[210:213], v[24:27]
	v_mfma_f32_16x16x32_bf16 v[12:15], v[128:131], v[226:229], v[12:15]
	v_mfma_f32_16x16x32_bf16 v[8:11], v[136:139], v[226:229], v[8:11]
	v_mfma_f32_16x16x32_bf16 v[60:63], v[132:135], v[198:201], v[60:63]
	v_mfma_f32_16x16x32_bf16 v[56:59], v[190:193], v[198:201], v[56:59]
	v_mfma_f32_16x16x32_bf16 v[44:47], v[132:135], v[206:209], v[44:47]
	v_mfma_f32_16x16x32_bf16 v[40:43], v[190:193], v[206:209], v[40:43]
	v_mfma_f32_16x16x32_bf16 v[28:31], v[132:135], v[214:217], v[28:31]
	v_mfma_f32_16x16x32_bf16 v[24:27], v[190:193], v[214:217], v[24:27]
	v_mfma_f32_16x16x32_bf16 v[12:15], v[132:135], v[230:233], v[12:15]
	v_mfma_f32_16x16x32_bf16 v[8:11], v[190:193], v[230:233], v[8:11]
	s_setprio 0
	s_barrier
	s_add_u32 s18, s18, 0x80080
	s_addc_u32 s19, s19, 0
	s_add_i32 s20, s20, s25
	v_lshl_add_u64 v[128:129], s[18:19], 0, v[144:145]
	s_mov_b32 m0, s20
	s_nop 0
	global_load_lds_dwordx4 v[128:129], off
	v_lshl_add_u64 v[128:129], s[18:19], 0, v[142:143]
	s_add_i32 m0, s20, 0x2000
	s_nop 0
	global_load_lds_dwordx4 v[128:129], off
	s_waitcnt vmcnt(6)
	s_setprio 1
	s_barrier
	v_mfma_f32_16x16x32_bf16 v[52:55], v[234:237], v[194:197], v[52:55]
	v_mfma_f32_16x16x32_bf16 v[48:51], v[242:245], v[194:197], v[48:51]
	v_mfma_f32_16x16x32_bf16 v[36:39], v[234:237], v[202:205], v[36:39]
	v_mfma_f32_16x16x32_bf16 v[32:35], v[242:245], v[202:205], v[32:35]
	v_mfma_f32_16x16x32_bf16 v[20:23], v[234:237], v[210:213], v[20:23]
	v_mfma_f32_16x16x32_bf16 v[16:19], v[242:245], v[210:213], v[16:19]
	v_mfma_f32_16x16x32_bf16 v[4:7], v[234:237], v[226:229], v[4:7]
	v_mfma_f32_16x16x32_bf16 v[0:3], v[242:245], v[226:229], v[0:3]
	v_mfma_f32_16x16x32_bf16 v[52:55], v[238:241], v[198:201], v[52:55]
	v_mfma_f32_16x16x32_bf16 v[48:51], v[246:249], v[198:201], v[48:51]
	v_mfma_f32_16x16x32_bf16 v[36:39], v[238:241], v[206:209], v[36:39]
	v_mfma_f32_16x16x32_bf16 v[32:35], v[246:249], v[206:209], v[32:35]
	s_add_i32 s36, s36, 2
	s_add_u32 s8, s8, 0x100
	s_addc_u32 s9, s9, 0
	s_add_u32 s33, s33, 0x100
	s_addc_u32 s35, s35, 0
	s_cmp_gt_u32 s36, 29
	v_mfma_f32_16x16x32_bf16 v[20:23], v[238:241], v[214:217], v[20:23]
	v_mfma_f32_16x16x32_bf16 v[16:19], v[246:249], v[214:217], v[16:19]
	v_mfma_f32_16x16x32_bf16 v[4:7], v[238:241], v[230:233], v[4:7]
	v_mfma_f32_16x16x32_bf16 v[0:3], v[246:249], v[230:233], v[0:3]
	s_setprio 0
	s_barrier
	s_cbranch_scc0 .LBB0_202
	s_cmp_lt_i32 s2, 18
	v_lshl_add_u32 v190, s3, 8, v186
	v_mov_b32_e32 v128, 1.0
	v_mov_b32_e32 v132, 0
	s_cselect_b64 s[18:19], -1, 0
	s_cmp_gt_i32 s2, 17
	v_mov_b32_e32 v134, 0
	v_mov_b32_e32 v135, 0
	v_mov_b32_e32 v136, 0
	v_mov_b32_e32 v137, 0
	v_mov_b32_e32 v138, 1.0
	v_mov_b32_e32 v139, 1.0
	v_mov_b32_e32 v140, 1.0
	v_mov_b32_e32 v141, 1.0
	s_cbranch_scc1 .LBB0_205
	v_lshlrev_b32_e32 v129, 8, v190
	v_and_b32_e32 v158, 0xfcf00, v129
	v_lshl_add_u64 v[130:131], v[146:147], 0, v[158:159]
	v_lshl_add_u64 v[134:135], v[148:149], 0, v[158:159]
	global_load_dwordx4 v[138:141], v[130:131], off
	s_nop 0
	global_load_dwordx4 v[134:137], v[134:135], off

; #define PG8_STAGE(bufoff, gbase) do { _Pragma("unroll") for (int _i = 0; _i < 2; ++_i) \
;         __builtin_amdgcn_global_load_lds((const unsigned*)((const char*)(gbase) + voff[_i]), (LAS unsigned*)(lds + (bufoff) + ldsw + _i * 8192), 16, 0, 0); } while (0)
; #define PG8_LDA(dst, b, h) do { _Pragma("unroll") for (int m = 0; m < 4; ++m) _Pragma("unroll") for (int k = 0; k < 2; ++k) dst[m][k] = *(const LAS bf16x8*)(lds + PG8_SA(b, h) + aoff + m * 2048 + k * 1024); } while (0)
; #define PG8_LDB(dst, b, h) do { _Pragma("unroll") for (int n = 0; n < 2; ++n) _Pragma("unroll") for (int k = 0; k < 2; ++k) dst[n][k] = *(const LAS bf16x8*)(lds + PG8_SB(b, h) + boff + n * 2048 + k * 1024); } while (0)
; #define PG8_MMA(ai, bj, At, Bt) do { __builtin_amdgcn_s_setprio(1); _Pragma("unroll") for (int m = 0; m < 4; ++m) _Pragma("unroll") for (int n = 0; n < 2; ++n) _Pragma("unroll") for (int k = 0; k < 2; ++k) \
;         acc[ai][bj][m][n] = __builtin_amdgcn_mfma_f32_16x16x32_bf16(Bt[n][k], At[m][k], acc[ai][bj][m][n], 0, 0, 0); __builtin_amdgcn_s_setprio(0); } while (0)
; #define PG8_WAIT_L(n) asm volatile("s_waitcnt lgkmcnt(" #n ")" ::: "memory")
; #define PG8_BAR __builtin_amdgcn_s_barrier()
; #define PG8_SCHED __builtin_amdgcn_sched_barrier(0)
; template <class Epi>
; DI void gemm_phase(LAS unsigned char* lds, const Gemm g, const StaticOrder& S, const Epi& E) {
;     ...
;         for (int t = 0; t < nt; t += 2) {
;             const bool last = (t == nt - 2);
;             const char* a1 = cA + (size_t)(t + 1) * kstep;
;             const char* a2 = last ? nA : cA + (size_t)(t + 2) * kstep; const char* b2 = last ? nB : cB + (size_t)(t + 2) * kstep;
;             const char* a3 = a2 + kstep; const char* b3 = b2 + kstep;
;             PG8_LDB(B0, 0, 0); PG8_SCHED; PG8_LDA(At, 0, 0); PG8_STAGE(PG8_SA(1, 1), a1 + hstep);
;             PG8_WAIT_L(8); PG8_BAR; PG8_WAIT_L(0); PG8_MMA(0, 0, At, B0); PG8_BAR; PG8_SCHED;
;             PG8_LDB(B1, 0, 1); PG8_STAGE(PG8_SB(0, 0), b2);
;             PG8_BAR; PG8_WAIT_L(0); PG8_MMA(0, 1, At, B1); PG8_BAR;
;             PG8_LDA(At, 0, 1); PG8_STAGE(PG8_SA(0, 0), a2);
;             PG8_BAR; PG8_WAIT_L(0); PG8_MMA(1, 0, At, B0); PG8_BAR; PG8_SCHED;
.LBB0_231:
	s_add_u32 s18, s16, 0xfff80080
	s_addc_u32 s19, s17, -1
	s_add_i32 s37, 0, 0x10000
	v_add_u32_e32 v150, s37, v135
	ds_read_b128 v[138:141], v150
	ds_read_b128 v[142:145], v150 offset:1024
	ds_read_b128 v[146:149], v150 offset:2048
	ds_read_b128 v[150:153], v150 offset:3072
	s_cmp_eq_u32 s36, 28
	s_cselect_b32 s21, s4, s19
	s_cselect_b32 s20, s5, s18
	s_cselect_b32 s19, s9, s35
	s_cselect_b32 s18, s11, s34
	v_lshl_add_u64 v[154:155], s[16:17], 0, v[130:131]
	s_add_i32 m0, s24, 0xc000
	ds_read_b128 v[186:189], v137
	ds_read_b128 v[190:193], v137 offset:1024
	ds_read_b128 v[194:197], v137 offset:2048
	ds_read_b128 v[198:201], v137 offset:3072
	ds_read_b128 v[202:205], v137 offset:4096
	ds_read_b128 v[206:209], v137 offset:5120
	ds_read_b128 v[210:213], v137 offset:6144
	ds_read_b128 v[214:217], v137 offset:7168
	global_load_lds_dwordx4 v[154:155], off
	v_lshl_add_u64 v[154:155], s[16:17], 0, v[132:133]
	s_add_i32 m0, s24, 0xe000
	s_nop 0
	global_load_lds_dwordx4 v[154:155], off
	s_waitcnt lgkmcnt(8)
	s_setprio 1
	s_barrier
	s_waitcnt lgkmcnt(0)
	v_mfma_f32_16x16x32_bf16 v[124:127], v[138:141], v[186:189], v[124:127]
	v_mfma_f32_16x16x32_bf16 v[120:123], v[146:149], v[186:189], v[120:123]
	v_mfma_f32_16x16x32_bf16 v[116:119], v[138:141], v[194:197], v[116:119]
	v_mfma_f32_16x16x32_bf16 v[112:115], v[146:149], v[194:197], v[112:115]
	v_mfma_f32_16x16x32_bf16 v[100:103], v[138:141], v[202:205], v[100:103]
	v_mfma_f32_16x16x32_bf16 v[96:99], v[146:149], v[202:205], v[96:99]
	v_mfma_f32_16x16x32_bf16 v[84:87], v[138:141], v[210:213], v[84:87]
	v_mfma_f32_16x16x32_bf16 v[80:83], v[146:149], v[210:213], v[80:83]
	v_mfma_f32_16x16x32_bf16 v[124:127], v[142:145], v[190:193], v[124:127]
	v_mfma_f32_16x16x32_bf16 v[120:123], v[150:153], v[190:193], v[120:123]
	v_mfma_f32_16x16x32_bf16 v[116:119], v[142:145], v[198:201], v[116:119]
	v_mfma_f32_16x16x32_bf16 v[112:115], v[150:153], v[198:201], v[112:115]
	v_mfma_f32_16x16x32_bf16 v[100:103], v[142:145], v[206:209], v[100:103]
	v_mfma_f32_16x16x32_bf16 v[96:99], v[150:153], v[206:209], v[96:99]
	v_mfma_f32_16x16x32_bf16 v[84:87], v[142:145], v[214:217], v[84:87]
	v_mfma_f32_16x16x32_bf16 v[80:83], v[150:153], v[214:217], v[80:83]
	s_setprio 0
	s_barrier
	s_add_i32 s40, 0, 0x14000
	v_add_u32_e32 v154, s40, v135
	s_add_i32 s37, s37, s23
	ds_read_b128 v[226:229], v154
	ds_read_b128 v[230:233], v154 offset:1024
	ds_read_b128 v[234:237], v154 offset:2048
	ds_read_b128 v[238:241], v154 offset:3072
	v_lshl_add_u64 v[154:155], s[18:19], 0, v[158:159]
	s_mov_b32 m0, s37
	v_lshl_add_u64 v[218:219], s[18:19], 0, v[128:129]
	global_load_lds_dwordx4 v[154:155], off
	s_add_i32 m0, s37, 0x2000
	s_nop 0
	global_load_lds_dwordx4 v[218:219], off
	s_waitcnt lgkmcnt(0)
	s_setprio 1
	s_barrier
	v_mfma_f32_16x16x32_bf16 v[108:111], v[226:229], v[186:189], v[108:111]
	v_mfma_f32_16x16x32_bf16 v[104:107], v[234:237], v[186:189], v[104:107]
	v_mfma_f32_16x16x32_bf16 v[92:95], v[226:229], v[194:197], v[92:95]
	v_mfma_f32_16x16x32_bf16 v[88:91], v[234:237], v[194:197], v[88:91]
	v_mfma_f32_16x16x32_bf16 v[76:79], v[226:229], v[202:205], v[76:79]
	v_mfma_f32_16x16x32_bf16 v[72:75], v[234:237], v[202:205], v[72:75]
	v_mfma_f32_16x16x32_bf16 v[68:71], v[226:229], v[210:213], v[68:71]
	v_mfma_f32_16x16x32_bf16 v[64:67], v[234:237], v[210:213], v[64:67]
	v_mfma_f32_16x16x32_bf16 v[108:111], v[230:233], v[190:193], v[108:111]
	v_mfma_f32_16x16x32_bf16 v[104:107], v[238:241], v[190:193], v[104:107]
	v_mfma_f32_16x16x32_bf16 v[92:95], v[230:233], v[198:201], v[92:95]
	v_mfma_f32_16x16x32_bf16 v[88:91], v[238:241], v[198:201], v[88:91]
	s_mov_b32 m0, s24
	v_lshl_add_u64 v[242:243], s[20:21], 0, v[158:159]
	v_mfma_f32_16x16x32_bf16 v[76:79], v[230:233], v[206:209], v[76:79]
	v_mfma_f32_16x16x32_bf16 v[72:75], v[238:241], v[206:209], v[72:75]
	v_mfma_f32_16x16x32_bf16 v[68:71], v[230:233], v[214:217], v[68:71]
	v_mfma_f32_16x16x32_bf16 v[64:67], v[238:241], v[214:217], v[64:67]
	s_setprio 0
	s_barrier
	ds_read_b128 v[186:189], v137 offset:16384
	ds_read_b128 v[190:193], v137 offset:17408
	ds_read_b128 v[194:197], v137 offset:18432
	ds_read_b128 v[198:201], v137 offset:19456
	ds_read_b128 v[202:205], v137 offset:20480
	ds_read_b128 v[206:209], v137 offset:21504
	ds_read_b128 v[210:213], v137 offset:22528
	ds_read_b128 v[214:217], v137 offset:23552
	global_load_lds_dwordx4 v[242:243], off
	v_lshl_add_u64 v[244:245], s[20:21], 0, v[128:129]
	s_mov_b32 m0, s25
	s_nop 0
	global_load_lds_dwordx4 v[244:245], off
	s_waitcnt lgkmcnt(0)
	s_setprio 1
	s_barrier
	v_mfma_f32_16x16x32_bf16 v[60:63], v[138:141], v[186:189], v[60:63]
	v_mfma_f32_16x16x32_bf16 v[56:59], v[146:149], v[186:189], v[56:59]
	v_mfma_f32_16x16x32_bf16 v[52:55], v[138:141], v[194:197], v[52:55]
	v_mfma_f32_16x16x32_bf16 v[48:51], v[146:149], v[194:197], v[48:51]
	v_mfma_f32_16x16x32_bf16 v[36:39], v[138:141], v[202:205], v[36:39]
	v_mfma_f32_16x16x32_bf16 v[32:35], v[146:149], v[202:205], v[32:35]
	v_mfma_f32_16x16x32_bf16 v[20:23], v[138:141], v[210:213], v[20:23]
	v_mfma_f32_16x16x32_bf16 v[16:19], v[146:149], v[210:213], v[16:19]
	v_mfma_f32_16x16x32_bf16 v[60:63], v[142:145], v[190:193], v[60:63]
	v_mfma_f32_16x16x32_bf16 v[56:59], v[150:153], v[190:193], v[56:59]
	v_mfma_f32_16x16x32_bf16 v[52:55], v[142:145], v[198:201], v[52:55]
	v_mfma_f32_16x16x32_bf16 v[48:51], v[150:153], v[198:201], v[48:51]
	v_mfma_f32_16x16x32_bf16 v[36:39], v[142:145], v[206:209], v[36:39]
	v_mfma_f32_16x16x32_bf16 v[32:35], v[150:153], v[206:209], v[32:35]
	v_mfma_f32_16x16x32_bf16 v[20:23], v[142:145], v[214:217], v[20:23]
	v_mfma_f32_16x16x32_bf16 v[16:19], v[150:153], v[214:217], v[16:19]
	s_setprio 0
	s_barrier
; #define PG8_STAGE(bufoff, gbase) do { _Pragma("unroll") for (int _i = 0; _i < 2; ++_i) \
;         __builtin_amdgcn_global_load_lds((const unsigned*)((const char*)(gbase) + voff[_i]), (LAS unsigned*)(lds + (bufoff) + ldsw + _i * 8192), 16, 0, 0); } while (0)
; #define PG8_LDA(dst, b, h) do { _Pragma("unroll") for (int m = 0; m < 4; ++m) _Pragma("unroll") for (int k = 0; k < 2; ++k) dst[m][k] = *(const LAS bf16x8*)(lds + PG8_SA(b, h) + aoff + m * 2048 + k * 1024); } while (0)
; #define PG8_LDB(dst, b, h) do { _Pragma("unroll") for (int n = 0; n < 2; ++n) _Pragma("unroll") for (int k = 0; k < 2; ++k) dst[n][k] = *(const LAS bf16x8*)(lds + PG8_SB(b, h) + boff + n * 2048 + k * 1024); } while (0)
; #define PG8_MMA(ai, bj, At, Bt) do { __builtin_amdgcn_s_setprio(1); _Pragma("unroll") for (int m = 0; m < 4; ++m) _Pragma("unroll") for (int n = 0; n < 2; ++n) _Pragma("unroll") for (int k = 0; k < 2; ++k) \
;         acc[ai][bj][m][n] = __builtin_amdgcn_mfma_f32_16x16x32_bf16(Bt[n][k], At[m][k], acc[ai][bj][m][n], 0, 0, 0); __builtin_amdgcn_s_setprio(0); } while (0)
; #define PG8_WAIT_V(n) asm volatile("s_waitcnt vmcnt(" #n ")" ::: "memory")
; #define PG8_WAIT_L(n) asm volatile("s_waitcnt lgkmcnt(" #n ")" ::: "memory")
; #define PG8_BAR __builtin_amdgcn_s_barrier()
; #define PG8_SCHED __builtin_amdgcn_sched_barrier(0)
; template <class Epi>
; DI void gemm_phase(LAS unsigned char* lds, const Gemm g, const StaticOrder& S, const Epi& E) {
;     ...
;             PG8_STAGE(PG8_SB(0, 1), b2 + hstep);
;             PG8_WAIT_V(6); PG8_BAR; PG8_MMA(1, 1, At, B1); PG8_BAR;
;             PG8_LDB(B0, 1, 0); PG8_SCHED; PG8_LDA(At, 1, 0); PG8_STAGE(PG8_SA(0, 1), a2 + hstep);
;             PG8_WAIT_L(8); PG8_BAR; PG8_WAIT_L(0); PG8_MMA(0, 0, At, B0); PG8_BAR; PG8_SCHED;
;             PG8_LDB(B1, 1, 1); PG8_STAGE(PG8_SB(1, 0), b3);
;             PG8_BAR; PG8_WAIT_L(0); PG8_MMA(0, 1, At, B1); PG8_BAR;
;             PG8_LDA(At, 1, 1); PG8_STAGE(PG8_SA(1, 0), a3);
;             PG8_BAR; PG8_WAIT_L(0); PG8_MMA(1, 0, At, B0); PG8_BAR; PG8_SCHED;
;             PG8_STAGE(PG8_SB(1, 1), b3 + hstep);
	s_add_u32 s38, s18, 0x80000
	s_addc_u32 s39, s19, 0
	s_add_i32 s37, s40, s23
	v_lshl_add_u64 v[138:139], s[38:39], 0, v[158:159]
	s_mov_b32 m0, s37
	s_nop 0
	global_load_lds_dwordx4 v[138:139], off
	v_lshl_add_u64 v[138:139], s[38:39], 0, v[128:129]
	s_add_i32 m0, s37, 0x2000
	s_nop 0
	global_load_lds_dwordx4 v[138:139], off
	s_waitcnt vmcnt(6)
	s_setprio 1
	s_barrier
	v_mfma_f32_16x16x32_bf16 v[44:47], v[226:229], v[186:189], v[44:47]
	v_mfma_f32_16x16x32_bf16 v[40:43], v[234:237], v[186:189], v[40:43]
	v_mfma_f32_16x16x32_bf16 v[28:31], v[226:229], v[194:197], v[28:31]
	v_mfma_f32_16x16x32_bf16 v[24:27], v[234:237], v[194:197], v[24:27]
	v_mfma_f32_16x16x32_bf16 v[12:15], v[226:229], v[202:205], v[12:15]
	v_mfma_f32_16x16x32_bf16 v[8:11], v[234:237], v[202:205], v[8:11]
	v_mfma_f32_16x16x32_bf16 v[4:7], v[226:229], v[210:213], v[4:7]
	v_mfma_f32_16x16x32_bf16 v[0:3], v[234:237], v[210:213], v[0:3]
	v_mfma_f32_16x16x32_bf16 v[44:47], v[230:233], v[190:193], v[44:47]
	v_mfma_f32_16x16x32_bf16 v[40:43], v[238:241], v[190:193], v[40:43]
	v_mfma_f32_16x16x32_bf16 v[28:31], v[230:233], v[198:201], v[28:31]
	v_mfma_f32_16x16x32_bf16 v[24:27], v[238:241], v[198:201], v[24:27]
	s_add_i32 s37, 0, 0x18000
	v_add_u32_e32 v150, s37, v135
	v_mfma_f32_16x16x32_bf16 v[12:15], v[230:233], v[206:209], v[12:15]
	v_mfma_f32_16x16x32_bf16 v[8:11], v[238:241], v[206:209], v[8:11]
	v_mfma_f32_16x16x32_bf16 v[4:7], v[230:233], v[214:217], v[4:7]
	v_mfma_f32_16x16x32_bf16 v[0:3], v[238:241], v[214:217], v[0:3]
	s_setprio 0
	s_barrier
	ds_read_b128 v[138:141], v150
	ds_read_b128 v[142:145], v150 offset:1024
	ds_read_b128 v[146:149], v150 offset:2048
	ds_read_b128 v[150:153], v150 offset:3072
	s_add_u32 s20, s20, 0x80000
	s_addc_u32 s21, s21, 0
	s_mov_b32 m0, s26
	v_lshl_add_u64 v[226:227], s[20:21], 0, v[158:159]
	ds_read_b128 v[186:189], v137 offset:32768
	ds_read_b128 v[190:193], v137 offset:33792
	ds_read_b128 v[194:197], v137 offset:34816
	ds_read_b128 v[198:201], v137 offset:35840
	ds_read_b128 v[202:205], v137 offset:36864
	ds_read_b128 v[206:209], v137 offset:37888
	ds_read_b128 v[210:213], v137 offset:38912
	ds_read_b128 v[214:217], v137 offset:39936
	global_load_lds_dwordx4 v[226:227], off
	v_lshl_add_u64 v[226:227], s[20:21], 0, v[128:129]
	s_mov_b32 m0, s27
	s_nop 0
	global_load_lds_dwordx4 v[226:227], off
	s_waitcnt lgkmcnt(8)
	s_setprio 1
	s_barrier
	s_waitcnt lgkmcnt(0)
	v_mfma_f32_16x16x32_bf16 v[124:127], v[138:141], v[186:189], v[124:127]
	v_mfma_f32_16x16x32_bf16 v[120:123], v[146:149], v[186:189], v[120:123]
	v_mfma_f32_16x16x32_bf16 v[116:119], v[138:141], v[194:197], v[116:119]
	v_mfma_f32_16x16x32_bf16 v[112:115], v[146:149], v[194:197], v[112:115]
	v_mfma_f32_16x16x32_bf16 v[100:103], v[138:141], v[202:205], v[100:103]
	v_mfma_f32_16x16x32_bf16 v[96:99], v[146:149], v[202:205], v[96:99]
	v_mfma_f32_16x16x32_bf16 v[84:87], v[138:141], v[210:213], v[84:87]
	v_mfma_f32_16x16x32_bf16 v[80:83], v[146:149], v[210:213], v[80:83]
	v_mfma_f32_16x16x32_bf16 v[124:127], v[142:145], v[190:193], v[124:127]
	v_mfma_f32_16x16x32_bf16 v[120:123], v[150:153], v[190:193], v[120:123]
	v_mfma_f32_16x16x32_bf16 v[116:119], v[142:145], v[198:201], v[116:119]
	v_mfma_f32_16x16x32_bf16 v[112:115], v[150:153], v[198:201], v[112:115]
	v_mfma_f32_16x16x32_bf16 v[100:103], v[142:145], v[206:209], v[100:103]
	v_mfma_f32_16x16x32_bf16 v[96:99], v[150:153], v[206:209], v[96:99]
	v_mfma_f32_16x16x32_bf16 v[84:87], v[142:145], v[214:217], v[84:87]
	v_mfma_f32_16x16x32_bf16 v[80:83], v[150:153], v[214:217], v[80:83]
	s_setprio 0
	s_barrier
	s_add_i32 s20, 0, 0x1c000
	s_add_i32 s21, s37, s23
	v_add_u32_e32 v220, s20, v135
	v_lshl_add_u64 v[154:155], v[154:155], 0, s[94:95]
	s_mov_b32 m0, s21
	ds_read_b128 v[226:229], v220
	ds_read_b128 v[230:233], v220 offset:1024
	ds_read_b128 v[234:237], v220 offset:2048
	ds_read_b128 v[238:241], v220 offset:3072
	global_load_lds_dwordx4 v[154:155], off
	v_lshl_add_u64 v[154:155], v[218:219], 0, s[94:95]
	s_add_i32 m0, s21, 0x2000
	s_nop 0
	global_load_lds_dwordx4 v[154:155], off
	s_waitcnt lgkmcnt(0)
	s_setprio 1
	s_barrier
	v_mfma_f32_16x16x32_bf16 v[108:111], v[226:229], v[186:189], v[108:111]
	v_mfma_f32_16x16x32_bf16 v[104:107], v[234:237], v[186:189], v[104:107]
	v_mfma_f32_16x16x32_bf16 v[92:95], v[226:229], v[194:197], v[92:95]
	v_mfma_f32_16x16x32_bf16 v[88:91], v[234:237], v[194:197], v[88:91]
	v_mfma_f32_16x16x32_bf16 v[76:79], v[226:229], v[202:205], v[76:79]
	v_mfma_f32_16x16x32_bf16 v[72:75], v[234:237], v[202:205], v[72:75]
	v_mfma_f32_16x16x32_bf16 v[68:71], v[226:229], v[210:213], v[68:71]
	v_mfma_f32_16x16x32_bf16 v[64:67], v[234:237], v[210:213], v[64:67]
	v_mfma_f32_16x16x32_bf16 v[108:111], v[230:233], v[190:193], v[108:111]
	v_mfma_f32_16x16x32_bf16 v[104:107], v[238:241], v[190:193], v[104:107]
	v_mfma_f32_16x16x32_bf16 v[92:95], v[230:233], v[198:201], v[92:95]
	v_mfma_f32_16x16x32_bf16 v[88:91], v[238:241], v[198:201], v[88:91]
	s_mov_b32 m0, s28
	v_lshl_add_u64 v[154:155], v[242:243], 0, s[94:95]
	v_mfma_f32_16x16x32_bf16 v[76:79], v[230:233], v[206:209], v[76:79]
	v_mfma_f32_16x16x32_bf16 v[72:75], v[238:241], v[206:209], v[72:75]
	v_mfma_f32_16x16x32_bf16 v[68:71], v[230:233], v[214:217], v[68:71]
	v_mfma_f32_16x16x32_bf16 v[64:67], v[238:241], v[214:217], v[64:67]
	s_setprio 0
	s_barrier
	ds_read_b128 v[186:189], v137 offset:49152
	ds_read_b128 v[190:193], v137 offset:50176
	ds_read_b128 v[194:197], v137 offset:51200
	ds_read_b128 v[198:201], v137 offset:52224
	ds_read_b128 v[202:205], v137 offset:53248
	ds_read_b128 v[206:209], v137 offset:54272
	ds_read_b128 v[210:213], v137 offset:55296
	ds_read_b128 v[214:217], v137 offset:56320
	global_load_lds_dwordx4 v[154:155], off
	v_lshl_add_u64 v[154:155], v[244:245], 0, s[94:95]
	s_mov_b32 m0, s29
	s_nop 0
	global_load_lds_dwordx4 v[154:155], off
	s_waitcnt lgkmcnt(0)
	s_setprio 1
	s_barrier
; #define PG8_STAGE(bufoff, gbase) do { _Pragma("unroll") for (int _i = 0; _i < 2; ++_i) \
;         __builtin_amdgcn_global_load_lds((const unsigned*)((const char*)(gbase) + voff[_i]), (LAS unsigned*)(lds + (bufoff) + ldsw + _i * 8192), 16, 0, 0); } while (0)
; #define PG8_MMA(ai, bj, At, Bt) do { __builtin_amdgcn_s_setprio(1); _Pragma("unroll") for (int m = 0; m < 4; ++m) _Pragma("unroll") for (int n = 0; n < 2; ++n) _Pragma("unroll") for (int k = 0; k < 2; ++k) \
;         acc[ai][bj][m][n] = __builtin_amdgcn_mfma_f32_16x16x32_bf16(Bt[n][k], At[m][k], acc[ai][bj][m][n], 0, 0, 0); __builtin_amdgcn_s_setprio(0); } while (0)
; #define PG8_WAIT_V(n) asm volatile("s_waitcnt vmcnt(" #n ")" ::: "memory")
; #define PG8_WAIT_L(n) asm volatile("s_waitcnt lgkmcnt(" #n ")" ::: "memory")
; #define PG8_BAR __builtin_amdgcn_s_barrier()
; #define PG8_SCHED __builtin_amdgcn_sched_barrier(0)
; template <class Epi>
; DI void gemm_phase(LAS unsigned char* lds, const Gemm g, const StaticOrder& S, const Epi& E) {
;     ...
;             PG8_BAR; PG8_WAIT_L(0); PG8_MMA(1, 0, At, B0); PG8_BAR; PG8_SCHED;
;             PG8_STAGE(PG8_SB(1, 1), b3 + hstep);
;             PG8_WAIT_V(6); PG8_BAR; PG8_MMA(1, 1, At, B1); PG8_BAR;
	v_mfma_f32_16x16x32_bf16 v[60:63], v[138:141], v[186:189], v[60:63]
	v_mfma_f32_16x16x32_bf16 v[56:59], v[146:149], v[186:189], v[56:59]
	v_mfma_f32_16x16x32_bf16 v[52:55], v[138:141], v[194:197], v[52:55]
	v_mfma_f32_16x16x32_bf16 v[48:51], v[146:149], v[194:197], v[48:51]
	v_mfma_f32_16x16x32_bf16 v[36:39], v[138:141], v[202:205], v[36:39]
	v_mfma_f32_16x16x32_bf16 v[32:35], v[146:149], v[202:205], v[32:35]
	v_mfma_f32_16x16x32_bf16 v[20:23], v[138:141], v[210:213], v[20:23]
	v_mfma_f32_16x16x32_bf16 v[16:19], v[146:149], v[210:213], v[16:19]
	v_mfma_f32_16x16x32_bf16 v[60:63], v[142:145], v[190:193], v[60:63]
	v_mfma_f32_16x16x32_bf16 v[56:59], v[150:153], v[190:193], v[56:59]
	v_mfma_f32_16x16x32_bf16 v[52:55], v[142:145], v[198:201], v[52:55]
	v_mfma_f32_16x16x32_bf16 v[48:51], v[150:153], v[198:201], v[48:51]
	v_mfma_f32_16x16x32_bf16 v[36:39], v[142:145], v[206:209], v[36:39]
	v_mfma_f32_16x16x32_bf16 v[32:35], v[150:153], v[206:209], v[32:35]
	v_mfma_f32_16x16x32_bf16 v[20:23], v[142:145], v[214:217], v[20:23]
	v_mfma_f32_16x16x32_bf16 v[16:19], v[150:153], v[214:217], v[16:19]
	s_setprio 0
	s_barrier
	s_add_u32 s18, s18, 0x80080
	s_addc_u32 s19, s19, 0
	s_add_i32 s20, s20, s23
	v_lshl_add_u64 v[138:139], s[18:19], 0, v[158:159]
	s_mov_b32 m0, s20
	s_nop 0
	global_load_lds_dwordx4 v[138:139], off
	v_lshl_add_u64 v[138:139], s[18:19], 0, v[128:129]
	s_add_i32 m0, s20, 0x2000
	s_nop 0
	global_load_lds_dwordx4 v[138:139], off
	s_waitcnt vmcnt(6)
	s_setprio 1
	s_barrier
	v_mfma_f32_16x16x32_bf16 v[44:47], v[226:229], v[186:189], v[44:47]
	v_mfma_f32_16x16x32_bf16 v[40:43], v[234:237], v[186:189], v[40:43]
	v_mfma_f32_16x16x32_bf16 v[28:31], v[226:229], v[194:197], v[28:31]
	v_mfma_f32_16x16x32_bf16 v[24:27], v[234:237], v[194:197], v[24:27]
	v_mfma_f32_16x16x32_bf16 v[12:15], v[226:229], v[202:205], v[12:15]
	v_mfma_f32_16x16x32_bf16 v[8:11], v[234:237], v[202:205], v[8:11]
	v_mfma_f32_16x16x32_bf16 v[4:7], v[226:229], v[210:213], v[4:7]
	v_mfma_f32_16x16x32_bf16 v[0:3], v[234:237], v[210:213], v[0:3]
	v_mfma_f32_16x16x32_bf16 v[44:47], v[230:233], v[190:193], v[44:47]
	v_mfma_f32_16x16x32_bf16 v[40:43], v[238:241], v[190:193], v[40:43]
	v_mfma_f32_16x16x32_bf16 v[28:31], v[230:233], v[198:201], v[28:31]
	v_mfma_f32_16x16x32_bf16 v[24:27], v[238:241], v[198:201], v[24:27]
	s_add_i32 s36, s36, 2
	s_add_u32 s16, s16, 0x100
	s_addc_u32 s17, s17, 0
	s_add_u32 s34, s34, 0x100
	s_addc_u32 s35, s35, 0
	s_cmp_gt_u32 s36, 29
	v_mfma_f32_16x16x32_bf16 v[12:15], v[230:233], v[206:209], v[12:15]
	v_mfma_f32_16x16x32_bf16 v[8:11], v[238:241], v[206:209], v[8:11]
	v_mfma_f32_16x16x32_bf16 v[4:7], v[230:233], v[214:217], v[4:7]
	v_mfma_f32_16x16x32_bf16 v[0:3], v[238:241], v[214:217], v[0:3]
	s_setprio 0
	s_barrier
	s_cbranch_scc0 .LBB0_231
; #define PG8_WAIT_V(n) asm volatile("s_waitcnt vmcnt(" #n ")" ::: "memory")
; #define PG8_BAR __builtin_amdgcn_s_barrier()
; template <class Epi>
; DI void gemm_phase(LAS unsigned char* lds, const Gemm g, const StaticOrder& S, const Epi& E) {
;     ...
;         E(acc, cur, wr, wc, fr, fq);
;         if (!has_next) break;
; #pragma unroll
;         for (int a = 0; a < 2; ++a)
; #pragma unroll
;             for (int b = 0; b < 2; ++b)
; #pragma unroll
;                 for (int m = 0; m < 4; ++m)
; #pragma unroll
;                     for (int n = 0; n < 2; ++n) acc[a][b][m][n] = (f32x4){0.f, 0.f, 0.f, 0.f};
;         cur = nxt; cA = nA; cB = nB; ++ui;
;     }
;     PG8_WAIT_V(0);
;     if (wr == 0) PG8_BAR;
;     DI void operator()(const f32x4 (&acc)[2][2][4][2], const Unit& u, int wr, int wc, int fr, int fq) const {
;         const int row0 = u.pm * BM + wr * 64 + fr, col0 = u.pn * BM + wc * 32 + 8 * fq;
; #pragma unroll
;         for (int ai = 0; ai < 2; ++ai)
; #pragma unroll
;             for (int m = 0; m < 4; ++m) { u16* rowp = O + (size_t)(row0 + ai * HALF + m * 16) * ldc + col0;
; #pragma unroll
;                 for (int bj = 0; bj < 2; ++bj) { const f32x4 v0 = acc[ai][bj][m][0], v1 = acc[ai][bj][m][1];
;                     *(u32x4*)(rowp + bj * HALF) = (u32x4){pk(v0[0], v0[1]), pk(v0[2], v0[3]), pk(v1[0], v1[1]), pk(v1[2], v1[3])}; } }
;     }
	v_lshl_add_u32 v144, s33, 8, v134
	v_lshl_or_b32 v138, s31, 8, v136
	v_ashrrev_i32_e32 v139, 31, v138
	v_mov_b64_e32 v[140:141], s[50:51]
	s_movk_i32 s9, 0x3000
	v_cvt_pk_bf16_f32 v68, v68, v69
	v_cvt_pk_bf16_f32 v69, v70, v71
	v_cvt_pk_bf16_f32 v70, v64, v65
	v_add_u32_e32 v64, 0x80, v144
	v_mad_i64_i32 v[142:143], s[4:5], v144, s9, v[140:141]
	v_lshlrev_b64 v[138:139], 1, v[138:139]
	v_cvt_pk_bf16_f32 v108, v108, v109
	v_cvt_pk_bf16_f32 v109, v110, v111
	v_cvt_pk_bf16_f32 v110, v104, v105
	v_or_b32_e32 v104, 16, v144
	v_mad_i64_i32 v[64:65], s[4:5], v64, s9, v[140:141]
	v_cvt_pk_bf16_f32 v44, v44, v45
	v_cvt_pk_bf16_f32 v45, v46, v47
	v_cvt_pk_bf16_f32 v46, v40, v41
	v_add_u32_e32 v40, 0x90, v144
	v_lshl_add_u64 v[142:143], v[142:143], 0, v[138:139]
	v_cvt_pk_bf16_f32 v111, v106, v107
	v_mad_i64_i32 v[104:105], s[4:5], v104, s9, v[140:141]
	v_cvt_pk_bf16_f32 v92, v92, v93
	v_cvt_pk_bf16_f32 v93, v94, v95
	v_cvt_pk_bf16_f32 v94, v88, v89
	v_or_b32_e32 v88, 32, v144
	v_lshl_add_u64 v[64:65], v[64:65], 0, v[138:139]
	v_cvt_pk_bf16_f32 v47, v42, v43
	v_mad_i64_i32 v[40:41], s[4:5], v40, s9, v[140:141]
	v_cvt_pk_bf16_f32 v28, v28, v29
	v_cvt_pk_bf16_f32 v29, v30, v31
	v_cvt_pk_bf16_f32 v30, v24, v25
	v_add_u32_e32 v24, 0xa0, v144
	global_store_dwordx4 v[142:143], v[108:111], off offset:256
	v_cvt_pk_bf16_f32 v95, v90, v91
	v_mad_i64_i32 v[88:89], s[4:5], v88, s9, v[140:141]
	v_lshl_add_u64 v[108:109], v[104:105], 0, v[138:139]
	v_cvt_pk_bf16_f32 v76, v76, v77
	v_cvt_pk_bf16_f32 v77, v78, v79
	v_cvt_pk_bf16_f32 v78, v72, v73
	v_or_b32_e32 v72, 48, v144
	global_store_dwordx4 v[64:65], v[44:47], off offset:256
	v_cvt_pk_bf16_f32 v31, v26, v27
	v_mad_i64_i32 v[24:25], s[4:5], v24, s9, v[140:141]
	v_lshl_add_u64 v[44:45], v[40:41], 0, v[138:139]
	v_cvt_pk_bf16_f32 v12, v12, v13
	v_cvt_pk_bf16_f32 v13, v14, v15
	v_cvt_pk_bf16_f32 v14, v8, v9
	v_add_u32_e32 v8, 0xb0, v144
	global_store_dwordx4 v[108:109], v[92:95], off offset:256
	v_cvt_pk_bf16_f32 v79, v74, v75
	v_mad_i64_i32 v[72:73], s[4:5], v72, s9, v[140:141]
	v_lshl_add_u64 v[92:93], v[88:89], 0, v[138:139]
	global_store_dwordx4 v[44:45], v[28:31], off offset:256
	v_cvt_pk_bf16_f32 v15, v10, v11
	v_mad_i64_i32 v[8:9], s[4:5], v8, s9, v[140:141]
	v_lshl_add_u64 v[28:29], v[24:25], 0, v[138:139]
	v_cvt_pk_bf16_f32 v124, v124, v125
	v_cvt_pk_bf16_f32 v125, v126, v127
	v_cvt_pk_bf16_f32 v126, v120, v121
	v_cvt_pk_bf16_f32 v127, v122, v123
	v_cvt_pk_bf16_f32 v104, v116, v117
	v_cvt_pk_bf16_f32 v105, v118, v119
	v_cvt_pk_bf16_f32 v106, v112, v113
	v_cvt_pk_bf16_f32 v107, v114, v115
	v_cvt_pk_bf16_f32 v88, v100, v101
	v_cvt_pk_bf16_f32 v89, v102, v103
	v_cvt_pk_bf16_f32 v90, v96, v97
	v_cvt_pk_bf16_f32 v91, v98, v99
	global_store_dwordx4 v[92:93], v[76:79], off offset:256
	v_cvt_pk_bf16_f32 v74, v80, v81
	v_cvt_pk_bf16_f32 v75, v82, v83
	v_lshl_add_u64 v[76:77], v[72:73], 0, v[138:139]
	v_cvt_pk_bf16_f32 v72, v84, v85
	v_cvt_pk_bf16_f32 v73, v86, v87
	v_cvt_pk_bf16_f32 v71, v66, v67
	v_cvt_pk_bf16_f32 v60, v60, v61
	v_cvt_pk_bf16_f32 v61, v62, v63
	v_cvt_pk_bf16_f32 v62, v56, v57
	v_cvt_pk_bf16_f32 v63, v58, v59
	v_cvt_pk_bf16_f32 v40, v52, v53
	v_cvt_pk_bf16_f32 v41, v54, v55
	v_cvt_pk_bf16_f32 v42, v48, v49
	v_cvt_pk_bf16_f32 v43, v50, v51
	v_cvt_pk_bf16_f32 v24, v36, v37
	v_cvt_pk_bf16_f32 v25, v38, v39
	v_cvt_pk_bf16_f32 v26, v32, v33
	v_cvt_pk_bf16_f32 v27, v34, v35
	global_store_dwordx4 v[28:29], v[12:15], off offset:256
	v_cvt_pk_bf16_f32 v10, v16, v17
	v_cvt_pk_bf16_f32 v11, v18, v19
	v_lshl_add_u64 v[12:13], v[8:9], 0, v[138:139]
	v_cvt_pk_bf16_f32 v8, v20, v21
	v_cvt_pk_bf16_f32 v9, v22, v23
	v_cvt_pk_bf16_f32 v4, v4, v5
	v_cvt_pk_bf16_f32 v5, v6, v7
	v_cvt_pk_bf16_f32 v6, v0, v1
	v_cvt_pk_bf16_f32 v7, v2, v3
	s_and_b64 vcc, exec, s[6:7]
	s_mov_b32 s31, s8
	s_mov_b32 s33, s10
	s_mov_b64 s[18:19], s[14:15]
	s_mov_b64 s[16:17], s[12:13]
	global_store_dwordx4 v[142:143], v[124:127], off
	global_store_dwordx4 v[108:109], v[104:107], off
	global_store_dwordx4 v[92:93], v[88:91], off
	global_store_dwordx4 v[76:77], v[72:75], off
	global_store_dwordx4 v[76:77], v[68:71], off offset:256
	global_store_dwordx4 v[64:65], v[60:63], off
	global_store_dwordx4 v[44:45], v[40:43], off
	global_store_dwordx4 v[28:29], v[24:27], off
	global_store_dwordx4 v[12:13], v[8:11], off
	global_store_dwordx4 v[12:13], v[4:7], off offset:256
	s_cbranch_vccz .LBB0_228
	s_waitcnt vmcnt(0)
	s_cmpk_gt_u32 s2, 0xff
	s_cbranch_scc1 .LBB0_235
	s_barrier

; #define PG8_STAGE(bufoff, gbase) do { _Pragma("unroll") for (int _i = 0; _i < 2; ++_i) \
;         __builtin_amdgcn_global_load_lds((const unsigned*)((const char*)(gbase) + voff[_i]), (LAS unsigned*)(lds + (bufoff) + ldsw + _i * 8192), 16, 0, 0); } while (0)
; #define PG8_LDA(dst, b, h) do { _Pragma("unroll") for (int m = 0; m < 4; ++m) _Pragma("unroll") for (int k = 0; k < 2; ++k) dst[m][k] = *(const LAS bf16x8*)(lds + PG8_SA(b, h) + aoff + m * 2048 + k * 1024); } while (0)
; #define PG8_LDB(dst, b, h) do { _Pragma("unroll") for (int n = 0; n < 2; ++n) _Pragma("unroll") for (int k = 0; k < 2; ++k) dst[n][k] = *(const LAS bf16x8*)(lds + PG8_SB(b, h) + boff + n * 2048 + k * 1024); } while (0)
; #define PG8_MMA(ai, bj, At, Bt) do { __builtin_amdgcn_s_setprio(1); _Pragma("unroll") for (int m = 0; m < 4; ++m) _Pragma("unroll") for (int n = 0; n < 2; ++n) _Pragma("unroll") for (int k = 0; k < 2; ++k) \
;         acc[ai][bj][m][n] = __builtin_amdgcn_mfma_f32_16x16x32_bf16(Bt[n][k], At[m][k], acc[ai][bj][m][n], 0, 0, 0); __builtin_amdgcn_s_setprio(0); } while (0)
; #define PG8_WAIT_L(n) asm volatile("s_waitcnt lgkmcnt(" #n ")" ::: "memory")
; #define PG8_BAR __builtin_amdgcn_s_barrier()
; #define PG8_SCHED __builtin_amdgcn_sched_barrier(0)
; template <class Epi>
; DI void gemm_phase(LAS unsigned char* lds, const Gemm g, const StaticOrder& S, const Epi& E) {
;     ...
;         for (int t = 0; t < nt; t += 2) {
;             const bool last = (t == nt - 2);
;             const char* a1 = cA + (size_t)(t + 1) * kstep;
;             const char* a2 = last ? nA : cA + (size_t)(t + 2) * kstep; const char* b2 = last ? nB : cB + (size_t)(t + 2) * kstep;
;             const char* a3 = a2 + kstep; const char* b3 = b2 + kstep;
;             PG8_LDB(B0, 0, 0); PG8_SCHED; PG8_LDA(At, 0, 0); PG8_STAGE(PG8_SA(1, 1), a1 + hstep);
;             PG8_WAIT_L(8); PG8_BAR; PG8_WAIT_L(0); PG8_MMA(0, 0, At, B0); PG8_BAR; PG8_SCHED;
;             PG8_LDB(B1, 0, 1); PG8_STAGE(PG8_SB(0, 0), b2);
;             PG8_BAR; PG8_WAIT_L(0); PG8_MMA(0, 1, At, B1); PG8_BAR;
;             PG8_LDA(At, 0, 1); PG8_STAGE(PG8_SA(0, 0), a2);
;             PG8_BAR; PG8_WAIT_L(0); PG8_MMA(1, 0, At, B0); PG8_BAR; PG8_SCHED;
.LBB0_320:
	s_add_u32 s26, s24, 0x100
	s_addc_u32 s27, s25, 0
	s_add_i32 s47, 0, 0x10000
	v_add_u32_e32 v140, s47, v226
	ds_read_b128 v[128:131], v140
	ds_read_b128 v[132:135], v140 offset:1024
	ds_read_b128 v[136:139], v140 offset:2048
	ds_read_b128 v[140:143], v140 offset:3072
	s_cmp_eq_u32 s46, 28
	s_cselect_b32 s31, s4, s27
	s_cselect_b32 s30, s5, s26
	s_cselect_b32 s29, s9, s45
	s_cselect_b32 s28, s11, s33
	v_lshl_add_u64 v[214:215], s[24:25], 0, v[190:191]
	s_add_i32 m0, s38, 0xc000
	ds_read_b128 v[144:147], v228
	ds_read_b128 v[148:151], v228 offset:1024
	ds_read_b128 v[152:155], v228 offset:2048
	ds_read_b128 v[194:197], v228 offset:3072
	ds_read_b128 v[198:201], v228 offset:4096
	ds_read_b128 v[202:205], v228 offset:5120
	ds_read_b128 v[206:209], v228 offset:6144
	ds_read_b128 v[210:213], v228 offset:7168
	global_load_lds_dwordx4 v[214:215], off
	v_lshl_add_u64 v[214:215], s[24:25], 0, v[192:193]
	s_add_i32 m0, s38, 0xe000
	s_nop 0
	global_load_lds_dwordx4 v[214:215], off
	s_waitcnt lgkmcnt(8)
	s_setprio 1
	s_barrier
	s_waitcnt lgkmcnt(0)
	v_mfma_f32_16x16x32_bf16 v[124:127], v[128:131], v[144:147], v[124:127]
	v_mfma_f32_16x16x32_bf16 v[120:123], v[136:139], v[144:147], v[120:123]
	v_mfma_f32_16x16x32_bf16 v[116:119], v[128:131], v[152:155], v[116:119]
	v_mfma_f32_16x16x32_bf16 v[112:115], v[136:139], v[152:155], v[112:115]
	v_mfma_f32_16x16x32_bf16 v[108:111], v[128:131], v[198:201], v[108:111]
	v_mfma_f32_16x16x32_bf16 v[104:107], v[136:139], v[198:201], v[104:107]
	v_mfma_f32_16x16x32_bf16 v[100:103], v[128:131], v[206:209], v[100:103]
	v_mfma_f32_16x16x32_bf16 v[96:99], v[136:139], v[206:209], v[96:99]
	v_mfma_f32_16x16x32_bf16 v[124:127], v[132:135], v[148:151], v[124:127]
	v_mfma_f32_16x16x32_bf16 v[120:123], v[140:143], v[148:151], v[120:123]
	v_mfma_f32_16x16x32_bf16 v[116:119], v[132:135], v[194:197], v[116:119]
	v_mfma_f32_16x16x32_bf16 v[112:115], v[140:143], v[194:197], v[112:115]
	v_mfma_f32_16x16x32_bf16 v[108:111], v[132:135], v[202:205], v[108:111]
	v_mfma_f32_16x16x32_bf16 v[104:107], v[140:143], v[202:205], v[104:107]
	v_mfma_f32_16x16x32_bf16 v[100:103], v[132:135], v[210:213], v[100:103]
	v_mfma_f32_16x16x32_bf16 v[96:99], v[140:143], v[210:213], v[96:99]
	s_setprio 0
	s_barrier
	s_add_i32 s48, 0, 0x14000
	s_add_i32 s24, s47, s37
	v_add_u32_e32 v158, s48, v226
	v_lshl_add_u64 v[218:219], s[28:29], 0, v[188:189]
	s_mov_b32 m0, s24
	ds_read_b128 v[214:217], v158
	ds_read_b128 v[230:233], v158 offset:1024
	ds_read_b128 v[234:237], v158 offset:2048
	ds_read_b128 v[238:241], v158 offset:3072
	global_load_lds_dwordx4 v[218:219], off
	v_lshl_add_u64 v[220:221], s[28:29], 0, v[186:187]
	s_add_i32 m0, s24, 0x2000
	s_nop 0
	global_load_lds_dwordx4 v[220:221], off
	s_waitcnt lgkmcnt(0)
	s_setprio 1
	s_barrier
	v_mfma_f32_16x16x32_bf16 v[60:63], v[214:217], v[144:147], v[60:63]
	v_mfma_f32_16x16x32_bf16 v[56:59], v[234:237], v[144:147], v[56:59]
	v_mfma_f32_16x16x32_bf16 v[52:55], v[214:217], v[152:155], v[52:55]
	v_mfma_f32_16x16x32_bf16 v[48:51], v[234:237], v[152:155], v[48:51]
	v_mfma_f32_16x16x32_bf16 v[44:47], v[214:217], v[198:201], v[44:47]
	v_mfma_f32_16x16x32_bf16 v[40:43], v[234:237], v[198:201], v[40:43]
	v_mfma_f32_16x16x32_bf16 v[36:39], v[214:217], v[206:209], v[36:39]
	v_mfma_f32_16x16x32_bf16 v[32:35], v[234:237], v[206:209], v[32:35]
	v_mfma_f32_16x16x32_bf16 v[60:63], v[230:233], v[148:151], v[60:63]
	v_mfma_f32_16x16x32_bf16 v[56:59], v[238:241], v[148:151], v[56:59]
	v_mfma_f32_16x16x32_bf16 v[52:55], v[230:233], v[194:197], v[52:55]
	v_mfma_f32_16x16x32_bf16 v[48:51], v[238:241], v[194:197], v[48:51]
	s_mov_b32 m0, s38
	v_lshl_add_u64 v[242:243], s[30:31], 0, v[188:189]
	v_mfma_f32_16x16x32_bf16 v[44:47], v[230:233], v[202:205], v[44:47]
	v_mfma_f32_16x16x32_bf16 v[40:43], v[238:241], v[202:205], v[40:43]
	v_mfma_f32_16x16x32_bf16 v[36:39], v[230:233], v[210:213], v[36:39]
	v_mfma_f32_16x16x32_bf16 v[32:35], v[238:241], v[210:213], v[32:35]
	s_setprio 0
	s_barrier
	ds_read_b128 v[144:147], v228 offset:16384
	ds_read_b128 v[148:151], v228 offset:17408
	ds_read_b128 v[152:155], v228 offset:18432
	ds_read_b128 v[194:197], v228 offset:19456
	ds_read_b128 v[198:201], v228 offset:20480
	ds_read_b128 v[202:205], v228 offset:21504
	ds_read_b128 v[206:209], v228 offset:22528
	ds_read_b128 v[210:213], v228 offset:23552
	global_load_lds_dwordx4 v[242:243], off
	v_lshl_add_u64 v[244:245], s[30:31], 0, v[186:187]
	s_mov_b32 m0, s39
	s_nop 0
	global_load_lds_dwordx4 v[244:245], off
	s_waitcnt lgkmcnt(0)
	s_setprio 1
	s_barrier
	v_mfma_f32_16x16x32_bf16 v[92:95], v[128:131], v[144:147], v[92:95]
	v_mfma_f32_16x16x32_bf16 v[88:91], v[136:139], v[144:147], v[88:91]
	v_mfma_f32_16x16x32_bf16 v[84:87], v[128:131], v[152:155], v[84:87]
	v_mfma_f32_16x16x32_bf16 v[80:83], v[136:139], v[152:155], v[80:83]
	v_mfma_f32_16x16x32_bf16 v[76:79], v[128:131], v[198:201], v[76:79]
	v_mfma_f32_16x16x32_bf16 v[72:75], v[136:139], v[198:201], v[72:75]
	v_mfma_f32_16x16x32_bf16 v[68:71], v[128:131], v[206:209], v[68:71]
	v_mfma_f32_16x16x32_bf16 v[64:67], v[136:139], v[206:209], v[64:67]
	v_mfma_f32_16x16x32_bf16 v[92:95], v[132:135], v[148:151], v[92:95]
	v_mfma_f32_16x16x32_bf16 v[88:91], v[140:143], v[148:151], v[88:91]
	v_mfma_f32_16x16x32_bf16 v[84:87], v[132:135], v[194:197], v[84:87]
	v_mfma_f32_16x16x32_bf16 v[80:83], v[140:143], v[194:197], v[80:83]
	v_mfma_f32_16x16x32_bf16 v[76:79], v[132:135], v[202:205], v[76:79]
	v_mfma_f32_16x16x32_bf16 v[72:75], v[140:143], v[202:205], v[72:75]
	v_mfma_f32_16x16x32_bf16 v[68:71], v[132:135], v[210:213], v[68:71]
	v_mfma_f32_16x16x32_bf16 v[64:67], v[140:143], v[210:213], v[64:67]
	s_setprio 0
	s_barrier
; #define PG8_STAGE(bufoff, gbase) do { _Pragma("unroll") for (int _i = 0; _i < 2; ++_i) \
;         __builtin_amdgcn_global_load_lds((const unsigned*)((const char*)(gbase) + voff[_i]), (LAS unsigned*)(lds + (bufoff) + ldsw + _i * 8192), 16, 0, 0); } while (0)
; #define PG8_LDA(dst, b, h) do { _Pragma("unroll") for (int m = 0; m < 4; ++m) _Pragma("unroll") for (int k = 0; k < 2; ++k) dst[m][k] = *(const LAS bf16x8*)(lds + PG8_SA(b, h) + aoff + m * 2048 + k * 1024); } while (0)
; #define PG8_LDB(dst, b, h) do { _Pragma("unroll") for (int n = 0; n < 2; ++n) _Pragma("unroll") for (int k = 0; k < 2; ++k) dst[n][k] = *(const LAS bf16x8*)(lds + PG8_SB(b, h) + boff + n * 2048 + k * 1024); } while (0)
; #define PG8_MMA(ai, bj, At, Bt) do { __builtin_amdgcn_s_setprio(1); _Pragma("unroll") for (int m = 0; m < 4; ++m) _Pragma("unroll") for (int n = 0; n < 2; ++n) _Pragma("unroll") for (int k = 0; k < 2; ++k) \
;         acc[ai][bj][m][n] = __builtin_amdgcn_mfma_f32_16x16x32_bf16(Bt[n][k], At[m][k], acc[ai][bj][m][n], 0, 0, 0); __builtin_amdgcn_s_setprio(0); } while (0)
; #define PG8_WAIT_V(n) asm volatile("s_waitcnt vmcnt(" #n ")" ::: "memory")
; #define PG8_WAIT_L(n) asm volatile("s_waitcnt lgkmcnt(" #n ")" ::: "memory")
; #define PG8_BAR __builtin_amdgcn_s_barrier()
; #define PG8_SCHED __builtin_amdgcn_sched_barrier(0)
; template <class Epi>
; DI void gemm_phase(LAS unsigned char* lds, const Gemm g, const StaticOrder& S, const Epi& E) {
;     ...
;             PG8_STAGE(PG8_SB(0, 1), b2 + hstep);
;             PG8_WAIT_V(6); PG8_BAR; PG8_MMA(1, 1, At, B1); PG8_BAR;
;             PG8_LDB(B0, 1, 0); PG8_SCHED; PG8_LDA(At, 1, 0); PG8_STAGE(PG8_SA(0, 1), a2 + hstep);
;             PG8_WAIT_L(8); PG8_BAR; PG8_WAIT_L(0); PG8_MMA(0, 0, At, B0); PG8_BAR; PG8_SCHED;
;             PG8_LDB(B1, 1, 1); PG8_STAGE(PG8_SB(1, 0), b3);
;             PG8_BAR; PG8_WAIT_L(0); PG8_MMA(0, 1, At, B1); PG8_BAR;
;             PG8_LDA(At, 1, 1); PG8_STAGE(PG8_SA(1, 0), a3);
;             PG8_BAR; PG8_WAIT_L(0); PG8_MMA(1, 0, At, B0); PG8_BAR; PG8_SCHED;
;             PG8_STAGE(PG8_SB(1, 1), b3 + hstep);
	s_add_u32 s24, s28, 0x80000
	s_addc_u32 s25, s29, 0
	s_add_i32 s47, s48, s37
	v_lshl_add_u64 v[128:129], s[24:25], 0, v[188:189]
	s_mov_b32 m0, s47
	s_nop 0
	global_load_lds_dwordx4 v[128:129], off
	v_lshl_add_u64 v[128:129], s[24:25], 0, v[186:187]
	s_add_i32 m0, s47, 0x2000
	s_nop 0
	global_load_lds_dwordx4 v[128:129], off
	s_waitcnt vmcnt(6)
	s_setprio 1
	s_barrier
	v_mfma_f32_16x16x32_bf16 v[28:31], v[214:217], v[144:147], v[28:31]
	v_mfma_f32_16x16x32_bf16 v[24:27], v[234:237], v[144:147], v[24:27]
	v_mfma_f32_16x16x32_bf16 v[20:23], v[214:217], v[152:155], v[20:23]
	v_mfma_f32_16x16x32_bf16 v[16:19], v[234:237], v[152:155], v[16:19]
	v_mfma_f32_16x16x32_bf16 v[12:15], v[214:217], v[198:201], v[12:15]
	v_mfma_f32_16x16x32_bf16 v[8:11], v[234:237], v[198:201], v[8:11]
	v_mfma_f32_16x16x32_bf16 v[4:7], v[214:217], v[206:209], v[4:7]
	v_mfma_f32_16x16x32_bf16 v[0:3], v[234:237], v[206:209], v[0:3]
	v_mfma_f32_16x16x32_bf16 v[28:31], v[230:233], v[148:151], v[28:31]
	v_mfma_f32_16x16x32_bf16 v[24:27], v[238:241], v[148:151], v[24:27]
	v_mfma_f32_16x16x32_bf16 v[20:23], v[230:233], v[194:197], v[20:23]
	v_mfma_f32_16x16x32_bf16 v[16:19], v[238:241], v[194:197], v[16:19]
	s_add_i32 s47, 0, 0x18000
	v_add_u32_e32 v140, s47, v226
	v_mfma_f32_16x16x32_bf16 v[12:15], v[230:233], v[202:205], v[12:15]
	v_mfma_f32_16x16x32_bf16 v[8:11], v[238:241], v[202:205], v[8:11]
	v_mfma_f32_16x16x32_bf16 v[4:7], v[230:233], v[210:213], v[4:7]
	v_mfma_f32_16x16x32_bf16 v[0:3], v[238:241], v[210:213], v[0:3]
	s_setprio 0
	s_barrier
	ds_read_b128 v[128:131], v140
	ds_read_b128 v[132:135], v140 offset:1024
	ds_read_b128 v[136:139], v140 offset:2048
	ds_read_b128 v[140:143], v140 offset:3072
	s_add_u32 s24, s30, 0x80000
	s_addc_u32 s25, s31, 0
	s_mov_b32 m0, s40
	v_lshl_add_u64 v[214:215], s[24:25], 0, v[188:189]
	ds_read_b128 v[144:147], v228 offset:32768
	ds_read_b128 v[148:151], v228 offset:33792
	ds_read_b128 v[152:155], v228 offset:34816
	ds_read_b128 v[194:197], v228 offset:35840
	ds_read_b128 v[198:201], v228 offset:36864
	ds_read_b128 v[202:205], v228 offset:37888
	ds_read_b128 v[206:209], v228 offset:38912
	ds_read_b128 v[210:213], v228 offset:39936
	global_load_lds_dwordx4 v[214:215], off
	v_lshl_add_u64 v[214:215], s[24:25], 0, v[186:187]
	s_mov_b32 m0, s41
	s_nop 0
	global_load_lds_dwordx4 v[214:215], off
	s_waitcnt lgkmcnt(8)
	s_setprio 1
	s_barrier
	s_waitcnt lgkmcnt(0)
	v_mfma_f32_16x16x32_bf16 v[124:127], v[128:131], v[144:147], v[124:127]
	v_mfma_f32_16x16x32_bf16 v[120:123], v[136:139], v[144:147], v[120:123]
	v_mfma_f32_16x16x32_bf16 v[116:119], v[128:131], v[152:155], v[116:119]
	v_mfma_f32_16x16x32_bf16 v[112:115], v[136:139], v[152:155], v[112:115]
	v_mfma_f32_16x16x32_bf16 v[108:111], v[128:131], v[198:201], v[108:111]
	v_mfma_f32_16x16x32_bf16 v[104:107], v[136:139], v[198:201], v[104:107]
	v_mfma_f32_16x16x32_bf16 v[100:103], v[128:131], v[206:209], v[100:103]
	v_mfma_f32_16x16x32_bf16 v[96:99], v[136:139], v[206:209], v[96:99]
	v_mfma_f32_16x16x32_bf16 v[124:127], v[132:135], v[148:151], v[124:127]
	v_mfma_f32_16x16x32_bf16 v[120:123], v[140:143], v[148:151], v[120:123]
	v_mfma_f32_16x16x32_bf16 v[116:119], v[132:135], v[194:197], v[116:119]
	v_mfma_f32_16x16x32_bf16 v[112:115], v[140:143], v[194:197], v[112:115]
	v_mfma_f32_16x16x32_bf16 v[108:111], v[132:135], v[202:205], v[108:111]
	v_mfma_f32_16x16x32_bf16 v[104:107], v[140:143], v[202:205], v[104:107]
	v_mfma_f32_16x16x32_bf16 v[100:103], v[132:135], v[210:213], v[100:103]
	v_mfma_f32_16x16x32_bf16 v[96:99], v[140:143], v[210:213], v[96:99]
	s_setprio 0
	s_barrier
	s_add_i32 s30, 0, 0x1c000
	s_add_i32 s24, s47, s37
	v_add_u32_e32 v158, s30, v226
	v_lshl_add_u64 v[218:219], v[218:219], 0, s[94:95]
	s_mov_b32 m0, s24
	ds_read_b128 v[214:217], v158
	ds_read_b128 v[230:233], v158 offset:1024
	ds_read_b128 v[234:237], v158 offset:2048
	ds_read_b128 v[238:241], v158 offset:3072
	global_load_lds_dwordx4 v[218:219], off
	v_lshl_add_u64 v[218:219], v[220:221], 0, s[94:95]
	s_add_i32 m0, s24, 0x2000
	s_nop 0
	global_load_lds_dwordx4 v[218:219], off
	s_waitcnt lgkmcnt(0)
	s_setprio 1
	s_barrier
	v_mfma_f32_16x16x32_bf16 v[60:63], v[214:217], v[144:147], v[60:63]
	v_mfma_f32_16x16x32_bf16 v[56:59], v[234:237], v[144:147], v[56:59]
	v_mfma_f32_16x16x32_bf16 v[52:55], v[214:217], v[152:155], v[52:55]
	v_mfma_f32_16x16x32_bf16 v[48:51], v[234:237], v[152:155], v[48:51]
	v_mfma_f32_16x16x32_bf16 v[44:47], v[214:217], v[198:201], v[44:47]
	v_mfma_f32_16x16x32_bf16 v[40:43], v[234:237], v[198:201], v[40:43]
	v_mfma_f32_16x16x32_bf16 v[36:39], v[214:217], v[206:209], v[36:39]
	v_mfma_f32_16x16x32_bf16 v[32:35], v[234:237], v[206:209], v[32:35]
	v_mfma_f32_16x16x32_bf16 v[60:63], v[230:233], v[148:151], v[60:63]
	v_mfma_f32_16x16x32_bf16 v[56:59], v[238:241], v[148:151], v[56:59]
	v_mfma_f32_16x16x32_bf16 v[52:55], v[230:233], v[194:197], v[52:55]
	v_mfma_f32_16x16x32_bf16 v[48:51], v[238:241], v[194:197], v[48:51]
	s_mov_b32 m0, s42
	v_lshl_add_u64 v[218:219], v[242:243], 0, s[94:95]
	v_mfma_f32_16x16x32_bf16 v[44:47], v[230:233], v[202:205], v[44:47]
	v_mfma_f32_16x16x32_bf16 v[40:43], v[238:241], v[202:205], v[40:43]
	v_mfma_f32_16x16x32_bf16 v[36:39], v[230:233], v[210:213], v[36:39]
	v_mfma_f32_16x16x32_bf16 v[32:35], v[238:241], v[210:213], v[32:35]
	s_setprio 0
	s_barrier
	ds_read_b128 v[144:147], v228 offset:49152
	ds_read_b128 v[148:151], v228 offset:50176
	ds_read_b128 v[152:155], v228 offset:51200
	ds_read_b128 v[194:197], v228 offset:52224
	ds_read_b128 v[198:201], v228 offset:53248
	ds_read_b128 v[202:205], v228 offset:54272
	ds_read_b128 v[206:209], v228 offset:55296
	ds_read_b128 v[210:213], v228 offset:56320
	global_load_lds_dwordx4 v[218:219], off
	v_lshl_add_u64 v[218:219], v[244:245], 0, s[94:95]
	s_mov_b32 m0, s43
	s_nop 0
	global_load_lds_dwordx4 v[218:219], off
	s_waitcnt lgkmcnt(0)
	s_setprio 1
	s_barrier
; #define PG8_WAIT_V(n) asm volatile("s_waitcnt vmcnt(" #n ")" ::: "memory")
; template <class Epi>
; DI void gemm_phase(LAS unsigned char* lds, const Gemm g, const StaticOrder& S, const Epi& E) {
;     ...
;             PG8_BAR; PG8_WAIT_L(0); PG8_MMA(1, 0, At, B0); PG8_BAR; PG8_SCHED;
;             PG8_STAGE(PG8_SB(1, 1), b3 + hstep);
;             PG8_WAIT_V(6); PG8_BAR; PG8_MMA(1, 1, At, B1); PG8_BAR;
;         }
;     template <bool LN, int BJ, int LO, int HI> DI void batch(const f32x4 (&acc)[2][2][4][2], unsigned row0, unsigned col0, const f32x4 (&gv)[2], const f32x4 (&bv)[2]) const {
;         f32x4 r[HI - LO]; float mean[(HI - LO) / 2], rstd[(HI - LO) / 2];
; #pragma unroll
;         for (int i = LO; i < HI; ++i) { const int ai = i >> 3, m = (i >> 1) & 3, n = i & 1; const unsigned row = row0 + ai * HALF + m * 16;
;             if (n == 0) { mean[(i - LO) >> 1] = 0.f; rstd[(i - LO) >> 1] = 1.f;
;                 if (LN) { const float2 st = *(const float2*)(stats + row * 2u); mean[(i - LO) >> 1] = st.x; rstd[(i - LO) >> 1] = st.y; } }
;             r[i - LO] = *(const f32x4*)(src + (row * (unsigned)DM + col0 + BJ * HALF + n * 16)); }
; #pragma unroll
;         for (int i = LO; i < HI; ++i) { const int ai = i >> 3, m = (i >> 1) & 3, n = i & 1; const unsigned row = row0 + ai * HALF + m * 16;
;             *(f32x4*)(Y + (row * (unsigned)DM + col0 + BJ * HALF + n * 16)) = acc[ai][BJ][m][n] + ((r[i - LO] - mean[(i - LO) >> 1]) * rstd[(i - LO) >> 1]) * gv[n] + bv[n]; }
;         __builtin_amdgcn_sched_barrier(0);
;     }
;     template <bool LN, int BJ> DI void load_gb(unsigned col0, f32x4 (&gv)[2], f32x4 (&bv)[2]) const {
; #pragma unroll
;         for (int n = 0; n < 2; ++n) {
;             if (LN) { gv[n] = *(const f32x4*)(gam + col0 + BJ * HALF + n * 16) * ALPHA; bv[n] = *(const f32x4*)(bet + col0 + BJ * HALF + n * 16) * ALPHA; }
;             else { gv[n] = (f32x4){ALPHA, ALPHA, ALPHA, ALPHA}; bv[n] = (f32x4){0.f, 0.f, 0.f, 0.f}; }
;         }
;     }
;     template <bool LN> DI void run(const f32x4 (&acc)[2][2][4][2], const Unit& u, int wr, int wc, int fr, int fq) const {
;         const unsigned row0 = u.pm * BM + wr * 64 + fr, col0 = u.pn * BM + wc * 32 + 4 * fq;
;         f32x4 gv[2], bv[2];
;         load_gb<LN, 0>(col0, gv, bv);
;         batch<LN, 0, 0, 4>(acc, row0, col0, gv, bv);
;         batch<LN, 0, 4, 8>(acc, row0, col0, gv, bv);
	v_mfma_f32_16x16x32_bf16 v[92:95], v[128:131], v[144:147], v[92:95]
	v_mfma_f32_16x16x32_bf16 v[88:91], v[136:139], v[144:147], v[88:91]
	v_mfma_f32_16x16x32_bf16 v[84:87], v[128:131], v[152:155], v[84:87]
	v_mfma_f32_16x16x32_bf16 v[80:83], v[136:139], v[152:155], v[80:83]
	v_mfma_f32_16x16x32_bf16 v[76:79], v[128:131], v[198:201], v[76:79]
	v_mfma_f32_16x16x32_bf16 v[72:75], v[136:139], v[198:201], v[72:75]
	v_mfma_f32_16x16x32_bf16 v[68:71], v[128:131], v[206:209], v[68:71]
	v_mfma_f32_16x16x32_bf16 v[64:67], v[136:139], v[206:209], v[64:67]
	v_mfma_f32_16x16x32_bf16 v[92:95], v[132:135], v[148:151], v[92:95]
	v_mfma_f32_16x16x32_bf16 v[88:91], v[140:143], v[148:151], v[88:91]
	v_mfma_f32_16x16x32_bf16 v[84:87], v[132:135], v[194:197], v[84:87]
	v_mfma_f32_16x16x32_bf16 v[80:83], v[140:143], v[194:197], v[80:83]
	v_mfma_f32_16x16x32_bf16 v[76:79], v[132:135], v[202:205], v[76:79]
	v_mfma_f32_16x16x32_bf16 v[72:75], v[140:143], v[202:205], v[72:75]
	v_mfma_f32_16x16x32_bf16 v[68:71], v[132:135], v[210:213], v[68:71]
	v_mfma_f32_16x16x32_bf16 v[64:67], v[140:143], v[210:213], v[64:67]
	s_setprio 0
	s_barrier
	s_add_u32 s24, s28, 0x80080
	s_addc_u32 s25, s29, 0
	s_add_i32 s28, s30, s37
	v_lshl_add_u64 v[128:129], s[24:25], 0, v[188:189]
	s_mov_b32 m0, s28
	s_nop 0
	global_load_lds_dwordx4 v[128:129], off
	v_lshl_add_u64 v[128:129], s[24:25], 0, v[186:187]
	s_add_i32 m0, s28, 0x2000
	s_nop 0
	global_load_lds_dwordx4 v[128:129], off
	s_waitcnt vmcnt(6)
	s_setprio 1
	s_barrier
	v_mfma_f32_16x16x32_bf16 v[28:31], v[214:217], v[144:147], v[28:31]
	v_mfma_f32_16x16x32_bf16 v[24:27], v[234:237], v[144:147], v[24:27]
	v_mfma_f32_16x16x32_bf16 v[20:23], v[214:217], v[152:155], v[20:23]
	v_mfma_f32_16x16x32_bf16 v[16:19], v[234:237], v[152:155], v[16:19]
	v_mfma_f32_16x16x32_bf16 v[12:15], v[214:217], v[198:201], v[12:15]
	v_mfma_f32_16x16x32_bf16 v[8:11], v[234:237], v[198:201], v[8:11]
	v_mfma_f32_16x16x32_bf16 v[4:7], v[214:217], v[206:209], v[4:7]
	v_mfma_f32_16x16x32_bf16 v[0:3], v[234:237], v[206:209], v[0:3]
	v_mfma_f32_16x16x32_bf16 v[28:31], v[230:233], v[148:151], v[28:31]
	v_mfma_f32_16x16x32_bf16 v[24:27], v[238:241], v[148:151], v[24:27]
	v_mfma_f32_16x16x32_bf16 v[20:23], v[230:233], v[194:197], v[20:23]
	v_mfma_f32_16x16x32_bf16 v[16:19], v[238:241], v[194:197], v[16:19]
	s_add_i32 s46, s46, 2
	s_add_u32 s33, s33, 0x100
	s_addc_u32 s45, s45, 0
	s_cmp_gt_u32 s46, 29
	s_mov_b64 s[24:25], s[26:27]
	v_mfma_f32_16x16x32_bf16 v[12:15], v[230:233], v[202:205], v[12:15]
	v_mfma_f32_16x16x32_bf16 v[8:11], v[238:241], v[202:205], v[8:11]
	v_mfma_f32_16x16x32_bf16 v[4:7], v[230:233], v[210:213], v[4:7]
	v_mfma_f32_16x16x32_bf16 v[0:3], v[238:241], v[210:213], v[0:3]
	s_setprio 0
	s_barrier
	s_cbranch_scc0 .LBB0_320
	v_lshl_add_u32 v206, s3, 8, v225
	v_lshl_or_b32 v158, s2, 8, v227
	v_lshlrev_b32_e32 v232, 11, v206
	s_andn2_b64 vcc, exec, s[14:15]
	v_or_b32_e32 v231, 16, v158
	v_add_u32_e32 v194, v232, v158
	v_or_b32_e32 v230, 0x80, v158
	v_or_b32_e32 v229, 0x90, v158
	s_cbranch_vccnz .LBB0_323
	v_lshlrev_b64 v[132:133], 2, v[158:159]
	v_lshl_add_u64 v[140:141], s[16:17], 0, v[132:133]
	global_load_dwordx4 v[128:131], v[140:141], off
	v_lshl_add_u64 v[142:143], s[18:19], 0, v[132:133]
	v_readlane_b32 s2, v253, 8
	v_mov_b32_e32 v195, v159
	v_lshlrev_b32_e32 v136, 1, v206
	v_mov_b32_e32 v137, v159
	v_readlane_b32 s3, v253, 9
	v_lshlrev_b64 v[212:213], 2, v[194:195]
	v_add_u32_e32 v146, v232, v231
	v_lshl_add_u64 v[144:145], v[136:137], 2, s[2:3]
	v_lshl_add_u64 v[136:137], s[88:89], 0, v[212:213]
	v_mov_b32_e32 v147, v159
	v_lshl_add_u64 v[146:147], v[146:147], 2, s[88:89]
	v_or_b32_e32 v195, 16, v206
	v_mov_b32_e32 v201, v159
	v_mov_b32_e32 v209, v159
	v_lshl_add_u64 v[212:213], s[90:91], 0, v[212:213]
	s_waitcnt vmcnt(0)
	v_pk_mul_f32 v[152:153], v[130:131], s[78:79] op_sel_hi:[1,0]
	v_pk_mul_f32 v[154:155], v[128:129], s[78:79] op_sel_hi:[1,0]
	global_load_dwordx4 v[132:135], v[142:143], off
	global_load_dwordx4 v[128:131], v[140:141], off offset:64
	global_load_dwordx2 v[204:205], v[144:145], off
	global_load_dwordx4 v[196:199], v[146:147], off
	v_lshlrev_b32_e32 v146, 1, v195
	global_load_dwordx4 v[136:139], v[136:137], off
	v_lshlrev_b32_e32 v195, 11, v195
	v_mov_b32_e32 v147, v159
	v_add_u32_e32 v200, v195, v158
	v_lshl_add_u64 v[146:147], v[146:147], 2, s[2:3]
	v_lshl_add_u64 v[200:201], v[200:201], 2, s[88:89]
	global_load_dwordx2 v[214:215], v[146:147], off
	v_add_u32_e32 v208, v195, v231
	global_load_dwordx4 v[200:203], v[200:201], off
	v_lshl_add_u64 v[208:209], v[208:209], 2, s[88:89]
	global_load_dwordx4 v[208:211], v[208:209], off
	s_waitcnt vmcnt(0)
	v_pk_mul_f32 v[148:149], v[130:131], s[78:79] op_sel_hi:[1,0]
	v_pk_mul_f32 v[150:151], v[128:129], s[78:79] op_sel_hi:[1,0]
	global_load_dwordx4 v[128:131], v[142:143], off offset:64
	v_sub_f32_e32 v137, v137, v204
	v_sub_f32_e32 v136, v136, v204
	v_sub_f32_e32 v139, v139, v204
	v_sub_f32_e32 v138, v138, v204
	v_pk_mul_f32 v[138:139], v[204:205], v[138:139] op_sel:[1,0]
	v_pk_mul_f32 v[136:137], v[204:205], v[136:137] op_sel:[1,0]
	v_pk_fma_f32 v[138:139], v[152:153], v[138:139], v[126:127]
	v_pk_fma_f32 v[136:137], v[154:155], v[136:137], v[124:125]
	v_pk_fma_f32 v[138:139], v[134:135], s[78:79], v[138:139] op_sel_hi:[1,0,1]
	v_pk_fma_f32 v[136:137], v[132:133], s[78:79], v[136:137] op_sel_hi:[1,0,1]
	global_store_dwordx4 v[212:213], v[136:139], off
	s_nop 1
	v_sub_f32_e32 v137, v197, v204
	v_sub_f32_e32 v136, v196, v204
	v_sub_f32_e32 v139, v199, v204
	v_sub_f32_e32 v138, v198, v204
	v_pk_mul_f32 v[138:139], v[204:205], v[138:139] op_sel:[1,0]
	v_pk_mul_f32 v[136:137], v[204:205], v[136:137] op_sel:[1,0]
	v_pk_fma_f32 v[138:139], v[148:149], v[138:139], v[122:123]
	v_pk_fma_f32 v[136:137], v[150:151], v[136:137], v[120:121]
	v_or_b32_e32 v196, 16, v194
	v_mov_b32_e32 v197, v159
	v_lshl_add_u64 v[196:197], v[196:197], 2, s[90:91]
	s_waitcnt vmcnt(0)
;     template <bool LN, int BJ, int LO, int HI> DI void batch(const f32x4 (&acc)[2][2][4][2], unsigned row0, unsigned col0, const f32x4 (&gv)[2], const f32x4 (&bv)[2]) const {
;         f32x4 r[HI - LO]; float mean[(HI - LO) / 2], rstd[(HI - LO) / 2];
; #pragma unroll
;         for (int i = LO; i < HI; ++i) { const int ai = i >> 3, m = (i >> 1) & 3, n = i & 1; const unsigned row = row0 + ai * HALF + m * 16;
;             if (n == 0) { mean[(i - LO) >> 1] = 0.f; rstd[(i - LO) >> 1] = 1.f;
;                 if (LN) { const float2 st = *(const float2*)(stats + row * 2u); mean[(i - LO) >> 1] = st.x; rstd[(i - LO) >> 1] = st.y; } }
;             r[i - LO] = *(const f32x4*)(src + (row * (unsigned)DM + col0 + BJ * HALF + n * 16)); }
; #pragma unroll
;         for (int i = LO; i < HI; ++i) { const int ai = i >> 3, m = (i >> 1) & 3, n = i & 1; const unsigned row = row0 + ai * HALF + m * 16;
;             *(f32x4*)(Y + (row * (unsigned)DM + col0 + BJ * HALF + n * 16)) = acc[ai][BJ][m][n] + ((r[i - LO] - mean[(i - LO) >> 1]) * rstd[(i - LO) >> 1]) * gv[n] + bv[n]; }
	v_pk_fma_f32 v[138:139], v[130:131], s[78:79], v[138:139] op_sel_hi:[1,0,1]
	v_pk_fma_f32 v[136:137], v[128:129], s[78:79], v[136:137] op_sel_hi:[1,0,1]
	global_store_dwordx4 v[196:197], v[136:139], off
	v_add_u32_e32 v196, 0x8000, v194
	v_mov_b32_e32 v197, v159
	v_sub_f32_e32 v137, v201, v214
	v_sub_f32_e32 v136, v200, v214
	v_sub_f32_e32 v139, v203, v214
	v_sub_f32_e32 v138, v202, v214
	v_pk_mul_f32 v[138:139], v[214:215], v[138:139] op_sel:[1,0]
	v_pk_mul_f32 v[136:137], v[214:215], v[136:137] op_sel:[1,0]
	v_pk_fma_f32 v[138:139], v[152:153], v[138:139], v[118:119]
	v_pk_fma_f32 v[136:137], v[154:155], v[136:137], v[116:117]
	v_pk_fma_f32 v[138:139], v[134:135], s[78:79], v[138:139] op_sel_hi:[1,0,1]
	v_pk_fma_f32 v[136:137], v[132:133], s[78:79], v[136:137] op_sel_hi:[1,0,1]
	v_lshl_add_u64 v[196:197], v[196:197], 2, s[90:91]
	global_store_dwordx4 v[196:197], v[136:139], off
	v_add_u32_e32 v196, 0x8010, v194
	v_mov_b32_e32 v197, v159
	v_sub_f32_e32 v137, v209, v214
	v_sub_f32_e32 v136, v208, v214
	v_sub_f32_e32 v139, v211, v214
	v_sub_f32_e32 v138, v210, v214
	v_pk_mul_f32 v[138:139], v[214:215], v[138:139] op_sel:[1,0]
	v_pk_mul_f32 v[136:137], v[214:215], v[136:137] op_sel:[1,0]
	v_pk_fma_f32 v[138:139], v[148:149], v[138:139], v[114:115]
	v_pk_fma_f32 v[136:137], v[150:151], v[136:137], v[112:113]
	v_pk_fma_f32 v[138:139], v[130:131], s[78:79], v[138:139] op_sel_hi:[1,0,1]
	v_pk_fma_f32 v[136:137], v[128:129], s[78:79], v[136:137] op_sel_hi:[1,0,1]
	v_lshl_add_u64 v[196:197], v[196:197], 2, s[90:91]
	global_store_dwordx4 v[196:197], v[136:139], off
	s_nop 1
	v_or_b32_e32 v138, 32, v206
	v_lshlrev_b32_e32 v136, 1, v138
	v_mov_b32_e32 v137, v159
	v_lshlrev_b32_e32 v236, 11, v138
	v_lshl_add_u64 v[200:201], v[136:137], 2, s[2:3]
	v_add_u32_e32 v136, v236, v158
	v_lshl_add_u64 v[136:137], v[136:137], 2, s[88:89]
	global_load_dwordx2 v[204:205], v[200:201], off
	v_add_u32_e32 v196, v236, v231
	global_load_dwordx4 v[136:139], v[136:137], off
	v_mov_b32_e32 v197, v159
	v_lshl_add_u64 v[196:197], v[196:197], 2, s[88:89]
	global_load_dwordx4 v[196:199], v[196:197], off
	v_or_b32_e32 v207, 48, v206
	v_lshlrev_b32_e32 v235, 11, v207
	v_lshlrev_b32_e32 v202, 1, v207
	v_mov_b32_e32 v203, v159
	v_add_u32_e32 v208, v235, v158
	v_mov_b32_e32 v209, v159
	v_lshl_add_u64 v[202:203], v[202:203], 2, s[2:3]
	v_lshl_add_u64 v[208:209], v[208:209], 2, s[88:89]
	global_load_dwordx2 v[216:217], v[202:203], off
	v_add_u32_e32 v212, v235, v231
	global_load_dwordx4 v[208:211], v[208:209], off
	v_mov_b32_e32 v213, v159
	v_lshl_add_u64 v[212:213], v[212:213], 2, s[88:89]
	global_load_dwordx4 v[212:215], v[212:213], off
	v_add_u32_e32 v218, 0x10000, v194
	v_mov_b32_e32 v219, v159
	v_lshl_add_u64 v[218:219], v[218:219], 2, s[90:91]
	s_waitcnt vmcnt(0)
	v_sub_f32_e32 v137, v137, v204
	v_sub_f32_e32 v136, v136, v204
	v_sub_f32_e32 v139, v139, v204
	v_sub_f32_e32 v138, v138, v204
	v_pk_mul_f32 v[138:139], v[204:205], v[138:139] op_sel:[1,0]
	v_pk_mul_f32 v[136:137], v[204:205], v[136:137] op_sel:[1,0]
	v_pk_fma_f32 v[138:139], v[152:153], v[138:139], v[110:111]
	v_pk_fma_f32 v[136:137], v[154:155], v[136:137], v[108:109]
	v_pk_fma_f32 v[138:139], v[134:135], s[78:79], v[138:139] op_sel_hi:[1,0,1]
	v_pk_fma_f32 v[136:137], v[132:133], s[78:79], v[136:137] op_sel_hi:[1,0,1]
	global_store_dwordx4 v[218:219], v[136:139], off
	s_nop 1
	v_sub_f32_e32 v137, v197, v204
	v_sub_f32_e32 v136, v196, v204
	v_sub_f32_e32 v139, v199, v204
	v_sub_f32_e32 v138, v198, v204
	v_pk_mul_f32 v[138:139], v[204:205], v[138:139] op_sel:[1,0]
	v_pk_mul_f32 v[136:137], v[204:205], v[136:137] op_sel:[1,0]
	v_pk_fma_f32 v[138:139], v[148:149], v[138:139], v[106:107]
	v_pk_fma_f32 v[136:137], v[150:151], v[136:137], v[104:105]
	v_add_u32_e32 v196, 0x10010, v194
	v_mov_b32_e32 v197, v159
	v_pk_fma_f32 v[138:139], v[130:131], s[78:79], v[138:139] op_sel_hi:[1,0,1]
	v_pk_fma_f32 v[136:137], v[128:129], s[78:79], v[136:137] op_sel_hi:[1,0,1]
	v_lshl_add_u64 v[196:197], v[196:197], 2, s[90:91]
	global_store_dwordx4 v[196:197], v[136:139], off
	v_add_u32_e32 v196, 0x18000, v194
	v_mov_b32_e32 v197, v159
	v_sub_f32_e32 v137, v209, v216
	v_sub_f32_e32 v136, v208, v216
	v_sub_f32_e32 v139, v211, v216
	v_sub_f32_e32 v138, v210, v216
	v_pk_mul_f32 v[138:139], v[216:217], v[138:139] op_sel:[1,0]
	v_pk_mul_f32 v[136:137], v[216:217], v[136:137] op_sel:[1,0]
	v_pk_fma_f32 v[138:139], v[152:153], v[138:139], v[102:103]
	v_pk_fma_f32 v[136:137], v[154:155], v[136:137], v[100:101]
	v_pk_fma_f32 v[138:139], v[134:135], s[78:79], v[138:139] op_sel_hi:[1,0,1]
	v_pk_fma_f32 v[136:137], v[132:133], s[78:79], v[136:137] op_sel_hi:[1,0,1]
	v_lshl_add_u64 v[196:197], v[196:197], 2, s[90:91]
	global_store_dwordx4 v[196:197], v[136:139], off
	v_add_u32_e32 v196, 0x18010, v194
	v_mov_b32_e32 v197, v159
	v_sub_f32_e32 v137, v213, v216
	v_sub_f32_e32 v136, v212, v216
	v_sub_f32_e32 v139, v215, v216
	v_sub_f32_e32 v138, v214, v216
	v_pk_mul_f32 v[138:139], v[216:217], v[138:139] op_sel:[1,0]
	v_pk_mul_f32 v[136:137], v[216:217], v[136:137] op_sel:[1,0]
	v_pk_fma_f32 v[138:139], v[148:149], v[138:139], v[98:99]
	v_pk_fma_f32 v[136:137], v[150:151], v[136:137], v[96:97]
	v_pk_fma_f32 v[138:139], v[130:131], s[78:79], v[138:139] op_sel_hi:[1,0,1]
	v_pk_fma_f32 v[136:137], v[128:129], s[78:79], v[136:137] op_sel_hi:[1,0,1]
	v_lshl_add_u64 v[196:197], v[196:197], 2, s[90:91]
	global_store_dwordx4 v[196:197], v[136:139], off
	s_nop 1
	v_add_u32_e32 v138, 0x80, v206
	v_lshlrev_b32_e32 v136, 1, v138
	v_mov_b32_e32 v137, v159
	v_lshlrev_b32_e32 v233, 11, v138
	v_lshl_add_u64 v[196:197], v[136:137], 2, s[2:3]
	v_add_u32_e32 v136, v233, v158
	v_lshl_add_u64 v[136:137], v[136:137], 2, s[88:89]
	global_load_dwordx2 v[204:205], v[196:197], off
	v_add_u32_e32 v198, v233, v231
	global_load_dwordx4 v[136:139], v[136:137], off
	v_mov_b32_e32 v199, v159
	v_add_u32_e32 v207, 0x90, v206
	v_lshl_add_u64 v[198:199], v[198:199], 2, s[88:89]
	v_lshlrev_b32_e32 v234, 11, v207
	global_load_dwordx4 v[208:211], v[198:199], off
	v_add_u32_e32 v212, v234, v158
	v_mov_b32_e32 v213, v159
	v_lshl_add_u64 v[212:213], v[212:213], 2, s[88:89]
	global_load_dwordx4 v[212:215], v[212:213], off
	v_lshlrev_b32_e32 v198, 1, v207
	v_mov_b32_e32 v199, v159
	v_lshl_add_u64 v[198:199], v[198:199], 2, s[2:3]
	global_load_dwordx2 v[238:239], v[198:199], off
	v_add_u32_e32 v216, v234, v231
	v_mov_b32_e32 v217, v159
	v_lshl_add_u64 v[216:217], v[216:217], 2, s[88:89]
	global_load_dwordx4 v[216:219], v[216:217], off
	v_add_u32_e32 v240, 0x40000, v194
	v_mov_b32_e32 v241, v159
	v_lshl_add_u64 v[240:241], v[240:241], 2, s[90:91]
	s_waitcnt vmcnt(0)
;     template <bool LN, int BJ, int LO, int HI> DI void batch(const f32x4 (&acc)[2][2][4][2], unsigned row0, unsigned col0, const f32x4 (&gv)[2], const f32x4 (&bv)[2]) const {
;         f32x4 r[HI - LO]; float mean[(HI - LO) / 2], rstd[(HI - LO) / 2];
; #pragma unroll
;         for (int i = LO; i < HI; ++i) { const int ai = i >> 3, m = (i >> 1) & 3, n = i & 1; const unsigned row = row0 + ai * HALF + m * 16;
;             if (n == 0) { mean[(i - LO) >> 1] = 0.f; rstd[(i - LO) >> 1] = 1.f;
;                 if (LN) { const float2 st = *(const float2*)(stats + row * 2u); mean[(i - LO) >> 1] = st.x; rstd[(i - LO) >> 1] = st.y; } }
;             r[i - LO] = *(const f32x4*)(src + (row * (unsigned)DM + col0 + BJ * HALF + n * 16)); }
; #pragma unroll
;         for (int i = LO; i < HI; ++i) { const int ai = i >> 3, m = (i >> 1) & 3, n = i & 1; const unsigned row = row0 + ai * HALF + m * 16;
;             *(f32x4*)(Y + (row * (unsigned)DM + col0 + BJ * HALF + n * 16)) = acc[ai][BJ][m][n] + ((r[i - LO] - mean[(i - LO) >> 1]) * rstd[(i - LO) >> 1]) * gv[n] + bv[n]; }
;         __builtin_amdgcn_sched_barrier(0);
;     }
;     template <bool LN, int BJ> DI void load_gb(unsigned col0, f32x4 (&gv)[2], f32x4 (&bv)[2]) const {
; #pragma unroll
;         for (int n = 0; n < 2; ++n) {
;             if (LN) { gv[n] = *(const f32x4*)(gam + col0 + BJ * HALF + n * 16) * ALPHA; bv[n] = *(const f32x4*)(bet + col0 + BJ * HALF + n * 16) * ALPHA; }
;             else { gv[n] = (f32x4){ALPHA, ALPHA, ALPHA, ALPHA}; bv[n] = (f32x4){0.f, 0.f, 0.f, 0.f}; }
;         }
;     }
;     template <bool LN> DI void run(const f32x4 (&acc)[2][2][4][2], const Unit& u, int wr, int wc, int fr, int fq) const {
;         const unsigned row0 = u.pm * BM + wr * 64 + fr, col0 = u.pn * BM + wc * 32 + 4 * fq;
;         f32x4 gv[2], bv[2];
;         load_gb<LN, 0>(col0, gv, bv);
;         batch<LN, 0, 0, 4>(acc, row0, col0, gv, bv);
;         batch<LN, 0, 4, 8>(acc, row0, col0, gv, bv);
;         batch<LN, 0, 8, 12>(acc, row0, col0, gv, bv);
;         batch<LN, 0, 12, 16>(acc, row0, col0, gv, bv);
;         load_gb<LN, 1>(col0, gv, bv);
	v_sub_f32_e32 v137, v137, v204
	v_sub_f32_e32 v136, v136, v204
	v_sub_f32_e32 v139, v139, v204
	v_sub_f32_e32 v138, v138, v204
	v_pk_mul_f32 v[138:139], v[204:205], v[138:139] op_sel:[1,0]
	v_pk_mul_f32 v[136:137], v[204:205], v[136:137] op_sel:[1,0]
	v_pk_fma_f32 v[138:139], v[152:153], v[138:139], v[94:95]
	v_pk_fma_f32 v[136:137], v[154:155], v[136:137], v[92:93]
	v_pk_fma_f32 v[138:139], v[134:135], s[78:79], v[138:139] op_sel_hi:[1,0,1]
	v_pk_fma_f32 v[136:137], v[132:133], s[78:79], v[136:137] op_sel_hi:[1,0,1]
	global_store_dwordx4 v[240:241], v[136:139], off
	s_nop 1
	v_sub_f32_e32 v137, v209, v204
	v_sub_f32_e32 v136, v208, v204
	v_sub_f32_e32 v139, v211, v204
	v_sub_f32_e32 v138, v210, v204
	v_pk_mul_f32 v[138:139], v[204:205], v[138:139] op_sel:[1,0]
	v_pk_mul_f32 v[136:137], v[204:205], v[136:137] op_sel:[1,0]
	v_pk_fma_f32 v[138:139], v[148:149], v[138:139], v[90:91]
	v_pk_fma_f32 v[136:137], v[150:151], v[136:137], v[88:89]
	v_add_u32_e32 v204, 0x40010, v194
	v_mov_b32_e32 v205, v159
	v_pk_fma_f32 v[138:139], v[130:131], s[78:79], v[138:139] op_sel_hi:[1,0,1]
	v_pk_fma_f32 v[136:137], v[128:129], s[78:79], v[136:137] op_sel_hi:[1,0,1]
	v_lshl_add_u64 v[204:205], v[204:205], 2, s[90:91]
	global_store_dwordx4 v[204:205], v[136:139], off
	v_add_u32_e32 v204, 0x48000, v194
	v_mov_b32_e32 v205, v159
	v_sub_f32_e32 v137, v213, v238
	v_sub_f32_e32 v136, v212, v238
	v_sub_f32_e32 v139, v215, v238
	v_sub_f32_e32 v138, v214, v238
	v_pk_mul_f32 v[138:139], v[238:239], v[138:139] op_sel:[1,0]
	v_pk_mul_f32 v[136:137], v[238:239], v[136:137] op_sel:[1,0]
	v_pk_fma_f32 v[138:139], v[152:153], v[138:139], v[86:87]
	v_pk_fma_f32 v[136:137], v[154:155], v[136:137], v[84:85]
	v_pk_fma_f32 v[138:139], v[134:135], s[78:79], v[138:139] op_sel_hi:[1,0,1]
	v_pk_fma_f32 v[136:137], v[132:133], s[78:79], v[136:137] op_sel_hi:[1,0,1]
	v_lshl_add_u64 v[204:205], v[204:205], 2, s[90:91]
	global_store_dwordx4 v[204:205], v[136:139], off
	v_add_u32_e32 v204, 0x48010, v194
	v_mov_b32_e32 v205, v159
	v_sub_f32_e32 v137, v217, v238
	v_sub_f32_e32 v136, v216, v238
	v_sub_f32_e32 v139, v219, v238
	v_sub_f32_e32 v138, v218, v238
	v_pk_mul_f32 v[138:139], v[238:239], v[138:139] op_sel:[1,0]
	v_pk_mul_f32 v[136:137], v[238:239], v[136:137] op_sel:[1,0]
	v_pk_fma_f32 v[138:139], v[148:149], v[138:139], v[82:83]
	v_pk_fma_f32 v[136:137], v[150:151], v[136:137], v[80:81]
	v_pk_fma_f32 v[138:139], v[130:131], s[78:79], v[138:139] op_sel_hi:[1,0,1]
	v_pk_fma_f32 v[136:137], v[128:129], s[78:79], v[136:137] op_sel_hi:[1,0,1]
	v_lshl_add_u64 v[204:205], v[204:205], 2, s[90:91]
	global_store_dwordx4 v[204:205], v[136:139], off
	s_nop 1
	v_add_u32_e32 v138, 0xa0, v206
	v_lshlrev_b32_e32 v136, 1, v138
	v_mov_b32_e32 v137, v159
	v_lshlrev_b32_e32 v237, 11, v138
	v_lshl_add_u64 v[204:205], v[136:137], 2, s[2:3]
	v_add_u32_e32 v136, v237, v158
	v_lshl_add_u64 v[136:137], v[136:137], 2, s[88:89]
	global_load_dwordx2 v[240:241], v[204:205], off
	v_add_u32_e32 v208, v237, v231
	global_load_dwordx4 v[136:139], v[136:137], off
	v_mov_b32_e32 v209, v159
	v_lshl_add_u64 v[208:209], v[208:209], 2, s[88:89]
	global_load_dwordx4 v[212:215], v[208:209], off
	v_add_u32_e32 v208, 0xb0, v206
	v_lshlrev_b32_e32 v206, 1, v208
	v_mov_b32_e32 v207, v159
	v_lshlrev_b32_e32 v238, 11, v208
	v_lshl_add_u64 v[210:211], v[206:207], 2, s[2:3]
	v_add_u32_e32 v206, v238, v158
	v_lshl_add_u64 v[206:207], v[206:207], 2, s[88:89]
	global_load_dwordx2 v[242:243], v[210:211], off
	v_add_u32_e32 v216, v238, v231
	global_load_dwordx4 v[206:209], v[206:207], off
	v_mov_b32_e32 v217, v159
	v_lshl_add_u64 v[216:217], v[216:217], 2, s[88:89]
	global_load_dwordx4 v[216:219], v[216:217], off
	v_add_u32_e32 v244, 0x50000, v194
	v_mov_b32_e32 v245, v159
	v_lshl_add_u64 v[244:245], v[244:245], 2, s[90:91]
	s_waitcnt vmcnt(0)
	v_sub_f32_e32 v137, v137, v240
	v_sub_f32_e32 v136, v136, v240
	v_sub_f32_e32 v139, v139, v240
	v_sub_f32_e32 v138, v138, v240
	v_pk_mul_f32 v[138:139], v[240:241], v[138:139] op_sel:[1,0]
	v_pk_mul_f32 v[136:137], v[240:241], v[136:137] op_sel:[1,0]
	v_pk_fma_f32 v[138:139], v[152:153], v[138:139], v[78:79]
	v_pk_fma_f32 v[136:137], v[154:155], v[136:137], v[76:77]
	v_pk_fma_f32 v[138:139], v[134:135], s[78:79], v[138:139] op_sel_hi:[1,0,1]
	v_pk_fma_f32 v[136:137], v[132:133], s[78:79], v[136:137] op_sel_hi:[1,0,1]
	global_store_dwordx4 v[244:245], v[136:139], off
	s_nop 1
	v_sub_f32_e32 v137, v213, v240
	v_sub_f32_e32 v136, v212, v240
	v_sub_f32_e32 v139, v215, v240
	v_sub_f32_e32 v138, v214, v240
	v_pk_mul_f32 v[138:139], v[240:241], v[138:139] op_sel:[1,0]
	v_pk_mul_f32 v[136:137], v[240:241], v[136:137] op_sel:[1,0]
	v_pk_fma_f32 v[138:139], v[148:149], v[138:139], v[74:75]
	v_pk_fma_f32 v[136:137], v[150:151], v[136:137], v[72:73]
	v_add_u32_e32 v212, 0x50010, v194
	v_mov_b32_e32 v213, v159
	v_pk_fma_f32 v[138:139], v[130:131], s[78:79], v[138:139] op_sel_hi:[1,0,1]
	v_pk_fma_f32 v[136:137], v[128:129], s[78:79], v[136:137] op_sel_hi:[1,0,1]
	v_lshl_add_u64 v[212:213], v[212:213], 2, s[90:91]
	global_store_dwordx4 v[212:213], v[136:139], off
	s_nop 1
	v_sub_f32_e32 v137, v207, v242
	v_sub_f32_e32 v136, v206, v242
	v_sub_f32_e32 v139, v209, v242
	v_sub_f32_e32 v138, v208, v242
	v_pk_mul_f32 v[136:137], v[242:243], v[136:137] op_sel:[1,0]
	v_pk_mul_f32 v[138:139], v[242:243], v[138:139] op_sel:[1,0]
	v_pk_fma_f32 v[136:137], v[154:155], v[136:137], v[68:69]
	v_pk_fma_f32 v[138:139], v[152:153], v[138:139], v[70:71]
	v_pk_fma_f32 v[132:133], v[132:133], s[78:79], v[136:137] op_sel_hi:[1,0,1]
	v_add_u32_e32 v136, 0x58000, v194
	v_mov_b32_e32 v137, v159
	v_pk_fma_f32 v[134:135], v[134:135], s[78:79], v[138:139] op_sel_hi:[1,0,1]
	v_lshl_add_u64 v[136:137], v[136:137], 2, s[90:91]
	global_store_dwordx4 v[136:137], v[132:135], off
	s_nop 1
	v_sub_f32_e32 v133, v217, v242
	v_sub_f32_e32 v132, v216, v242
	v_sub_f32_e32 v135, v219, v242
	v_sub_f32_e32 v134, v218, v242
	v_pk_mul_f32 v[132:133], v[242:243], v[132:133] op_sel:[1,0]
	v_pk_mul_f32 v[134:135], v[242:243], v[134:135] op_sel:[1,0]
	v_pk_fma_f32 v[132:133], v[150:151], v[132:133], v[64:65]
	v_pk_fma_f32 v[134:135], v[148:149], v[134:135], v[66:67]
	v_pk_fma_f32 v[128:129], v[128:129], s[78:79], v[132:133] op_sel_hi:[1,0,1]
	v_add_u32_e32 v132, 0x58010, v194
	v_mov_b32_e32 v133, v159
	v_pk_fma_f32 v[130:131], v[130:131], s[78:79], v[134:135] op_sel_hi:[1,0,1]
	v_lshl_add_u64 v[132:133], v[132:133], 2, s[90:91]
	global_store_dwordx4 v[132:133], v[128:131], off
	global_load_dwordx4 v[128:131], v[140:141], off offset:512
	v_add_u32_e32 v136, v232, v230
	v_mov_b32_e32 v137, v159
	v_lshl_add_u64 v[136:137], v[136:137], 2, s[88:89]
	s_waitcnt vmcnt(0)
;     template <bool LN, int BJ> DI void load_gb(unsigned col0, f32x4 (&gv)[2], f32x4 (&bv)[2]) const {
; #pragma unroll
;         for (int n = 0; n < 2; ++n) {
;             if (LN) { gv[n] = *(const f32x4*)(gam + col0 + BJ * HALF + n * 16) * ALPHA; bv[n] = *(const f32x4*)(bet + col0 + BJ * HALF + n * 16) * ALPHA; }
;             else { gv[n] = (f32x4){ALPHA, ALPHA, ALPHA, ALPHA}; bv[n] = (f32x4){0.f, 0.f, 0.f, 0.f}; }
;         }
;     }
;     template <bool LN> DI void run(const f32x4 (&acc)[2][2][4][2], const Unit& u, int wr, int wc, int fr, int fq) const {
;         const unsigned row0 = u.pm * BM + wr * 64 + fr, col0 = u.pn * BM + wc * 32 + 4 * fq;
;         f32x4 gv[2], bv[2];
;         load_gb<LN, 0>(col0, gv, bv);
;         batch<LN, 0, 0, 4>(acc, row0, col0, gv, bv);
;         batch<LN, 0, 4, 8>(acc, row0, col0, gv, bv);
;         batch<LN, 0, 8, 12>(acc, row0, col0, gv, bv);
;         batch<LN, 0, 12, 16>(acc, row0, col0, gv, bv);
;         load_gb<LN, 1>(col0, gv, bv);
;         batch<LN, 1, 0, 8>(acc, row0, col0, gv, bv);
	v_pk_mul_f32 v[212:213], v[130:131], s[78:79] op_sel_hi:[1,0]
	v_pk_mul_f32 v[214:215], v[128:129], s[78:79] op_sel_hi:[1,0]
	global_load_dwordx4 v[132:135], v[142:143], off offset:512
	global_load_dwordx4 v[128:131], v[140:141], off offset:576
	s_waitcnt vmcnt(0)
	v_pk_mul_f32 v[206:207], v[130:131], s[78:79] op_sel_hi:[1,0]
	v_pk_mul_f32 v[208:209], v[128:129], s[78:79] op_sel_hi:[1,0]
	global_load_dwordx4 v[128:131], v[142:143], off offset:576
	global_load_dwordx2 v[220:221], v[144:145], off
	global_load_dwordx4 v[240:243], v[136:137], off
	v_add_u32_e32 v136, v232, v229
	v_mov_b32_e32 v137, v159
	v_lshl_add_u64 v[136:137], v[136:137], 2, s[88:89]
	global_load_dwordx4 v[244:247], v[136:137], off
	global_load_dwordx2 v[218:219], v[146:147], off
	v_add_u32_e32 v136, v195, v230
	v_mov_b32_e32 v137, v159
	v_lshl_add_u64 v[136:137], v[136:137], 2, s[88:89]
	global_load_dwordx4 v[248:251], v[136:137], off
	v_add_u32_e32 v136, v195, v229
	v_mov_b32_e32 v137, v159
	v_lshl_add_u64 v[136:137], v[136:137], 2, s[88:89]
	global_load_dwordx4 v[152:155], v[136:137], off
	global_load_dwordx2 v[216:217], v[200:201], off
	v_add_u32_e32 v136, v236, v230
	v_mov_b32_e32 v137, v159
	v_lshl_add_u64 v[136:137], v[136:137], 2, s[88:89]
	global_load_dwordx4 v[148:151], v[136:137], off
	v_add_u32_e32 v136, v236, v229
	v_mov_b32_e32 v137, v159
	v_lshl_add_u64 v[136:137], v[136:137], 2, s[88:89]
	global_load_dwordx4 v[144:147], v[136:137], off
	global_load_dwordx2 v[200:201], v[202:203], off
	v_add_u32_e32 v136, v235, v230
	v_mov_b32_e32 v137, v159
	v_lshl_add_u64 v[136:137], v[136:137], 2, s[88:89]
	global_load_dwordx4 v[140:143], v[136:137], off
	v_add_u32_e32 v136, v235, v229
	v_mov_b32_e32 v137, v159
	v_lshl_add_u64 v[136:137], v[136:137], 2, s[88:89]
	global_load_dwordx4 v[136:139], v[136:137], off
	v_add_u32_e32 v202, 0x80, v194
	v_mov_b32_e32 v203, v159
	v_lshl_add_u64 v[202:203], v[202:203], 2, s[90:91]
	s_waitcnt vmcnt(0)
	v_sub_f32_e32 v241, v241, v220
	v_sub_f32_e32 v240, v240, v220
	v_sub_f32_e32 v243, v243, v220
	v_sub_f32_e32 v242, v242, v220
	v_pk_mul_f32 v[242:243], v[220:221], v[242:243] op_sel:[1,0]
	v_pk_mul_f32 v[240:241], v[220:221], v[240:241] op_sel:[1,0]
	v_pk_fma_f32 v[242:243], v[212:213], v[242:243], v[62:63]
	v_pk_fma_f32 v[240:241], v[214:215], v[240:241], v[60:61]
	v_pk_fma_f32 v[242:243], v[134:135], s[78:79], v[242:243] op_sel_hi:[1,0,1]
	v_pk_fma_f32 v[240:241], v[132:133], s[78:79], v[240:241] op_sel_hi:[1,0,1]
	global_store_dwordx4 v[202:203], v[240:243], off
	v_sub_f32_e32 v203, v245, v220
	v_sub_f32_e32 v202, v244, v220
	v_sub_f32_e32 v241, v247, v220
	v_sub_f32_e32 v240, v246, v220
	v_pk_mul_f32 v[202:203], v[220:221], v[202:203] op_sel:[1,0]
	v_pk_mul_f32 v[240:241], v[220:221], v[240:241] op_sel:[1,0]
	v_pk_fma_f32 v[202:203], v[208:209], v[202:203], v[56:57]
	v_pk_fma_f32 v[220:221], v[206:207], v[240:241], v[58:59]
	v_pk_fma_f32 v[240:241], v[128:129], s[78:79], v[202:203] op_sel_hi:[1,0,1]
	v_add_u32_e32 v202, 0x90, v194
	v_mov_b32_e32 v203, v159
	v_pk_fma_f32 v[242:243], v[130:131], s[78:79], v[220:221] op_sel_hi:[1,0,1]
	v_lshl_add_u64 v[202:203], v[202:203], 2, s[90:91]
	global_store_dwordx4 v[202:203], v[240:243], off
	v_sub_f32_e32 v203, v249, v218
	v_sub_f32_e32 v202, v248, v218
	v_sub_f32_e32 v221, v251, v218
	v_sub_f32_e32 v220, v250, v218
	v_pk_mul_f32 v[202:203], v[218:219], v[202:203] op_sel:[1,0]
	v_pk_mul_f32 v[220:221], v[218:219], v[220:221] op_sel:[1,0]
	v_pk_fma_f32 v[202:203], v[214:215], v[202:203], v[52:53]
	v_pk_fma_f32 v[220:221], v[212:213], v[220:221], v[54:55]
	v_pk_fma_f32 v[240:241], v[132:133], s[78:79], v[202:203] op_sel_hi:[1,0,1]
	v_add_u32_e32 v202, 0x8080, v194
	v_mov_b32_e32 v203, v159
	v_sub_f32_e32 v153, v153, v218
	v_sub_f32_e32 v152, v152, v218
	v_sub_f32_e32 v155, v155, v218
	v_sub_f32_e32 v154, v154, v218
	v_pk_fma_f32 v[242:243], v[134:135], s[78:79], v[220:221] op_sel_hi:[1,0,1]
	v_lshl_add_u64 v[202:203], v[202:203], 2, s[90:91]
	v_pk_mul_f32 v[154:155], v[218:219], v[154:155] op_sel:[1,0]
	v_pk_mul_f32 v[152:153], v[218:219], v[152:153] op_sel:[1,0]
	global_store_dwordx4 v[202:203], v[240:243], off
	v_pk_fma_f32 v[152:153], v[208:209], v[152:153], v[48:49]
	v_pk_fma_f32 v[154:155], v[206:207], v[154:155], v[50:51]
	v_add_u32_e32 v202, 0x8090, v194
	v_mov_b32_e32 v203, v159
	v_sub_f32_e32 v149, v149, v216
	v_sub_f32_e32 v148, v148, v216
	v_sub_f32_e32 v151, v151, v216
	v_sub_f32_e32 v150, v150, v216
	v_pk_fma_f32 v[154:155], v[130:131], s[78:79], v[154:155] op_sel_hi:[1,0,1]
	v_pk_fma_f32 v[152:153], v[128:129], s[78:79], v[152:153] op_sel_hi:[1,0,1]
	v_lshl_add_u64 v[202:203], v[202:203], 2, s[90:91]
	v_pk_mul_f32 v[150:151], v[216:217], v[150:151] op_sel:[1,0]
	v_pk_mul_f32 v[148:149], v[216:217], v[148:149] op_sel:[1,0]
	global_store_dwordx4 v[202:203], v[152:155], off
	v_pk_fma_f32 v[148:149], v[214:215], v[148:149], v[44:45]
	v_pk_fma_f32 v[150:151], v[212:213], v[150:151], v[46:47]
	v_add_u32_e32 v152, 0x10080, v194
	v_mov_b32_e32 v153, v159
	v_sub_f32_e32 v145, v145, v216
	v_sub_f32_e32 v144, v144, v216
	v_sub_f32_e32 v147, v147, v216
	v_sub_f32_e32 v146, v146, v216
	v_pk_fma_f32 v[150:151], v[134:135], s[78:79], v[150:151] op_sel_hi:[1,0,1]
	v_pk_fma_f32 v[148:149], v[132:133], s[78:79], v[148:149] op_sel_hi:[1,0,1]
	v_lshl_add_u64 v[152:153], v[152:153], 2, s[90:91]
	v_pk_mul_f32 v[146:147], v[216:217], v[146:147] op_sel:[1,0]
	v_pk_mul_f32 v[144:145], v[216:217], v[144:145] op_sel:[1,0]
	global_store_dwordx4 v[152:153], v[148:151], off
	v_pk_fma_f32 v[144:145], v[208:209], v[144:145], v[40:41]
	v_pk_fma_f32 v[146:147], v[206:207], v[146:147], v[42:43]
;     template <bool LN, int BJ, int LO, int HI> DI void batch(const f32x4 (&acc)[2][2][4][2], unsigned row0, unsigned col0, const f32x4 (&gv)[2], const f32x4 (&bv)[2]) const {
;         f32x4 r[HI - LO]; float mean[(HI - LO) / 2], rstd[(HI - LO) / 2];
; #pragma unroll
;         for (int i = LO; i < HI; ++i) { const int ai = i >> 3, m = (i >> 1) & 3, n = i & 1; const unsigned row = row0 + ai * HALF + m * 16;
;             if (n == 0) { mean[(i - LO) >> 1] = 0.f; rstd[(i - LO) >> 1] = 1.f;
;                 if (LN) { const float2 st = *(const float2*)(stats + row * 2u); mean[(i - LO) >> 1] = st.x; rstd[(i - LO) >> 1] = st.y; } }
;             r[i - LO] = *(const f32x4*)(src + (row * (unsigned)DM + col0 + BJ * HALF + n * 16)); }
; #pragma unroll
;         for (int i = LO; i < HI; ++i) { const int ai = i >> 3, m = (i >> 1) & 3, n = i & 1; const unsigned row = row0 + ai * HALF + m * 16;
;             *(f32x4*)(Y + (row * (unsigned)DM + col0 + BJ * HALF + n * 16)) = acc[ai][BJ][m][n] + ((r[i - LO] - mean[(i - LO) >> 1]) * rstd[(i - LO) >> 1]) * gv[n] + bv[n]; }
;         __builtin_amdgcn_sched_barrier(0);
;     }
;     template <bool LN, int BJ> DI void load_gb(unsigned col0, f32x4 (&gv)[2], f32x4 (&bv)[2]) const {
; #pragma unroll
;         for (int n = 0; n < 2; ++n) {
;             if (LN) { gv[n] = *(const f32x4*)(gam + col0 + BJ * HALF + n * 16) * ALPHA; bv[n] = *(const f32x4*)(bet + col0 + BJ * HALF + n * 16) * ALPHA; }
;             else { gv[n] = (f32x4){ALPHA, ALPHA, ALPHA, ALPHA}; bv[n] = (f32x4){0.f, 0.f, 0.f, 0.f}; }
;         }
;     }
;     template <bool LN> DI void run(const f32x4 (&acc)[2][2][4][2], const Unit& u, int wr, int wc, int fr, int fq) const {
;         const unsigned row0 = u.pm * BM + wr * 64 + fr, col0 = u.pn * BM + wc * 32 + 4 * fq;
;         f32x4 gv[2], bv[2];
;         load_gb<LN, 0>(col0, gv, bv);
;         batch<LN, 0, 0, 4>(acc, row0, col0, gv, bv);
;         batch<LN, 0, 4, 8>(acc, row0, col0, gv, bv);
;         batch<LN, 0, 8, 12>(acc, row0, col0, gv, bv);
;         batch<LN, 0, 12, 16>(acc, row0, col0, gv, bv);
;         load_gb<LN, 1>(col0, gv, bv);
;         batch<LN, 1, 0, 8>(acc, row0, col0, gv, bv);
;         batch<LN, 1, 8, 16>(acc, row0, col0, gv, bv);
	v_add_u32_e32 v148, 0x10090, v194
	v_mov_b32_e32 v149, v159
	v_sub_f32_e32 v141, v141, v200
	v_sub_f32_e32 v140, v140, v200
	v_sub_f32_e32 v143, v143, v200
	v_sub_f32_e32 v142, v142, v200
	v_pk_fma_f32 v[146:147], v[130:131], s[78:79], v[146:147] op_sel_hi:[1,0,1]
	v_pk_fma_f32 v[144:145], v[128:129], s[78:79], v[144:145] op_sel_hi:[1,0,1]
	v_lshl_add_u64 v[148:149], v[148:149], 2, s[90:91]
	v_pk_mul_f32 v[142:143], v[200:201], v[142:143] op_sel:[1,0]
	v_pk_mul_f32 v[140:141], v[200:201], v[140:141] op_sel:[1,0]
	global_store_dwordx4 v[148:149], v[144:147], off
	v_pk_fma_f32 v[140:141], v[214:215], v[140:141], v[36:37]
	v_pk_fma_f32 v[142:143], v[212:213], v[142:143], v[38:39]
	v_add_u32_e32 v144, 0x18080, v194
	v_mov_b32_e32 v145, v159
	v_sub_f32_e32 v137, v137, v200
	v_sub_f32_e32 v136, v136, v200
	v_sub_f32_e32 v139, v139, v200
	v_sub_f32_e32 v138, v138, v200
	v_pk_fma_f32 v[142:143], v[134:135], s[78:79], v[142:143] op_sel_hi:[1,0,1]
	v_pk_fma_f32 v[140:141], v[132:133], s[78:79], v[140:141] op_sel_hi:[1,0,1]
	v_lshl_add_u64 v[144:145], v[144:145], 2, s[90:91]
	v_pk_mul_f32 v[138:139], v[200:201], v[138:139] op_sel:[1,0]
	v_pk_mul_f32 v[136:137], v[200:201], v[136:137] op_sel:[1,0]
	global_store_dwordx4 v[144:145], v[140:143], off
	v_pk_fma_f32 v[136:137], v[208:209], v[136:137], v[32:33]
	v_pk_fma_f32 v[138:139], v[206:207], v[138:139], v[34:35]
	v_add_u32_e32 v140, 0x18090, v194
	v_mov_b32_e32 v141, v159
	v_pk_fma_f32 v[138:139], v[130:131], s[78:79], v[138:139] op_sel_hi:[1,0,1]
	v_pk_fma_f32 v[136:137], v[128:129], s[78:79], v[136:137] op_sel_hi:[1,0,1]
	v_lshl_add_u64 v[140:141], v[140:141], 2, s[90:91]
	global_store_dwordx4 v[140:141], v[136:139], off
	s_nop 1
	v_add_u32_e32 v136, v233, v230
	v_mov_b32_e32 v137, v159
	v_lshl_add_u64 v[136:137], v[136:137], 2, s[88:89]
	global_load_dwordx2 v[220:221], v[196:197], off
	global_load_dwordx4 v[216:219], v[136:137], off
	v_add_u32_e32 v136, v233, v229
	v_mov_b32_e32 v137, v159
	v_lshl_add_u64 v[136:137], v[136:137], 2, s[88:89]
	global_load_dwordx4 v[240:243], v[136:137], off
	global_load_dwordx2 v[200:201], v[198:199], off
	v_add_u32_e32 v136, v234, v230
	v_mov_b32_e32 v137, v159
	v_lshl_add_u64 v[136:137], v[136:137], 2, s[88:89]
	global_load_dwordx4 v[244:247], v[136:137], off
	v_add_u32_e32 v136, v234, v229
	v_mov_b32_e32 v137, v159
	v_lshl_add_u64 v[136:137], v[136:137], 2, s[88:89]
	global_load_dwordx4 v[152:155], v[136:137], off
	global_load_dwordx2 v[198:199], v[204:205], off
	v_add_u32_e32 v136, v237, v230
	v_mov_b32_e32 v137, v159
	v_lshl_add_u64 v[136:137], v[136:137], 2, s[88:89]
	global_load_dwordx4 v[148:151], v[136:137], off
	v_add_u32_e32 v136, v237, v229
	v_mov_b32_e32 v137, v159
	v_lshl_add_u64 v[136:137], v[136:137], 2, s[88:89]
	global_load_dwordx4 v[144:147], v[136:137], off
	global_load_dwordx2 v[196:197], v[210:211], off
	v_add_u32_e32 v136, v238, v230
	v_mov_b32_e32 v137, v159
	v_lshl_add_u64 v[136:137], v[136:137], 2, s[88:89]
	global_load_dwordx4 v[140:143], v[136:137], off
	v_add_u32_e32 v136, v238, v229
	v_mov_b32_e32 v137, v159
	v_lshl_add_u64 v[136:137], v[136:137], 2, s[88:89]
	global_load_dwordx4 v[136:139], v[136:137], off
	v_add_u32_e32 v210, 0x40080, v194
	v_mov_b32_e32 v211, v159
	v_lshl_add_u64 v[210:211], v[210:211], 2, s[90:91]
	s_waitcnt vmcnt(0)
;     template <bool LN, int BJ, int LO, int HI> DI void batch(const f32x4 (&acc)[2][2][4][2], unsigned row0, unsigned col0, const f32x4 (&gv)[2], const f32x4 (&bv)[2]) const {
;         f32x4 r[HI - LO]; float mean[(HI - LO) / 2], rstd[(HI - LO) / 2];
; #pragma unroll
;         for (int i = LO; i < HI; ++i) { const int ai = i >> 3, m = (i >> 1) & 3, n = i & 1; const unsigned row = row0 + ai * HALF + m * 16;
;             if (n == 0) { mean[(i - LO) >> 1] = 0.f; rstd[(i - LO) >> 1] = 1.f;
;                 if (LN) { const float2 st = *(const float2*)(stats + row * 2u); mean[(i - LO) >> 1] = st.x; rstd[(i - LO) >> 1] = st.y; } }
;             r[i - LO] = *(const f32x4*)(src + (row * (unsigned)DM + col0 + BJ * HALF + n * 16)); }
; #pragma unroll
;         for (int i = LO; i < HI; ++i) { const int ai = i >> 3, m = (i >> 1) & 3, n = i & 1; const unsigned row = row0 + ai * HALF + m * 16;
;             *(f32x4*)(Y + (row * (unsigned)DM + col0 + BJ * HALF + n * 16)) = acc[ai][BJ][m][n] + ((r[i - LO] - mean[(i - LO) >> 1]) * rstd[(i - LO) >> 1]) * gv[n] + bv[n]; }
;         __builtin_amdgcn_sched_barrier(0);
;     }
;     template <bool LN, int BJ> DI void load_gb(unsigned col0, f32x4 (&gv)[2], f32x4 (&bv)[2]) const {
; #pragma unroll
;         for (int n = 0; n < 2; ++n) {
;             if (LN) { gv[n] = *(const f32x4*)(gam + col0 + BJ * HALF + n * 16) * ALPHA; bv[n] = *(const f32x4*)(bet + col0 + BJ * HALF + n * 16) * ALPHA; }
;             else { gv[n] = (f32x4){ALPHA, ALPHA, ALPHA, ALPHA}; bv[n] = (f32x4){0.f, 0.f, 0.f, 0.f}; }
;         }
;     }
;     template <bool LN> DI void run(const f32x4 (&acc)[2][2][4][2], const Unit& u, int wr, int wc, int fr, int fq) const {
;         const unsigned row0 = u.pm * BM + wr * 64 + fr, col0 = u.pn * BM + wc * 32 + 4 * fq;
;         f32x4 gv[2], bv[2];
;         load_gb<LN, 0>(col0, gv, bv);
;         batch<LN, 0, 0, 4>(acc, row0, col0, gv, bv);
;         batch<LN, 0, 4, 8>(acc, row0, col0, gv, bv);
;         batch<LN, 0, 8, 12>(acc, row0, col0, gv, bv);
;         batch<LN, 0, 12, 16>(acc, row0, col0, gv, bv);
;         load_gb<LN, 1>(col0, gv, bv);
;         batch<LN, 1, 0, 8>(acc, row0, col0, gv, bv);
;         batch<LN, 1, 8, 16>(acc, row0, col0, gv, bv);
	v_sub_f32_e32 v203, v217, v220
	v_sub_f32_e32 v202, v216, v220
	v_sub_f32_e32 v205, v219, v220
	v_sub_f32_e32 v204, v218, v220
	v_pk_mul_f32 v[204:205], v[220:221], v[204:205] op_sel:[1,0]
	v_pk_mul_f32 v[202:203], v[220:221], v[202:203] op_sel:[1,0]
	v_pk_fma_f32 v[204:205], v[212:213], v[204:205], v[30:31]
	v_pk_fma_f32 v[202:203], v[214:215], v[202:203], v[28:29]
	v_pk_fma_f32 v[204:205], v[134:135], s[78:79], v[204:205] op_sel_hi:[1,0,1]
	v_pk_fma_f32 v[202:203], v[132:133], s[78:79], v[202:203] op_sel_hi:[1,0,1]
	global_store_dwordx4 v[210:211], v[202:205], off
	v_add_u32_e32 v210, 0x40090, v194
	v_mov_b32_e32 v211, v159
	v_sub_f32_e32 v203, v241, v220
	v_sub_f32_e32 v202, v240, v220
	v_sub_f32_e32 v205, v243, v220
	v_sub_f32_e32 v204, v242, v220
	v_pk_mul_f32 v[204:205], v[220:221], v[204:205] op_sel:[1,0]
	v_pk_mul_f32 v[202:203], v[220:221], v[202:203] op_sel:[1,0]
	v_pk_fma_f32 v[204:205], v[206:207], v[204:205], v[26:27]
	v_pk_fma_f32 v[202:203], v[208:209], v[202:203], v[24:25]
	v_pk_fma_f32 v[204:205], v[130:131], s[78:79], v[204:205] op_sel_hi:[1,0,1]
	v_pk_fma_f32 v[202:203], v[128:129], s[78:79], v[202:203] op_sel_hi:[1,0,1]
	v_lshl_add_u64 v[210:211], v[210:211], 2, s[90:91]
	global_store_dwordx4 v[210:211], v[202:205], off
	v_sub_f32_e32 v149, v149, v198
	v_sub_f32_e32 v148, v148, v198
	v_sub_f32_e32 v203, v245, v200
	v_sub_f32_e32 v202, v244, v200
	v_sub_f32_e32 v141, v141, v196
	v_sub_f32_e32 v140, v140, v196
	v_sub_f32_e32 v205, v247, v200
	v_sub_f32_e32 v204, v246, v200
	v_pk_mul_f32 v[202:203], v[200:201], v[202:203] op_sel:[1,0]
	v_sub_f32_e32 v151, v151, v198
	v_sub_f32_e32 v150, v150, v198
	v_pk_mul_f32 v[148:149], v[198:199], v[148:149] op_sel:[1,0]
	v_sub_f32_e32 v143, v143, v196
	v_sub_f32_e32 v142, v142, v196
	v_pk_mul_f32 v[140:141], v[196:197], v[140:141] op_sel:[1,0]
	v_pk_mul_f32 v[204:205], v[200:201], v[204:205] op_sel:[1,0]
	v_pk_fma_f32 v[202:203], v[214:215], v[202:203], v[20:21]
	v_sub_f32_e32 v153, v153, v200
	v_sub_f32_e32 v152, v152, v200
	v_sub_f32_e32 v155, v155, v200
	v_sub_f32_e32 v154, v154, v200
	v_pk_mul_f32 v[150:151], v[198:199], v[150:151] op_sel:[1,0]
	v_pk_fma_f32 v[148:149], v[214:215], v[148:149], v[12:13]
	v_pk_mul_f32 v[142:143], v[196:197], v[142:143] op_sel:[1,0]
	v_pk_fma_f32 v[140:141], v[214:215], v[140:141], v[4:5]
	v_pk_fma_f32 v[204:205], v[212:213], v[204:205], v[22:23]
	v_pk_fma_f32 v[202:203], v[132:133], s[78:79], v[202:203] op_sel_hi:[1,0,1]
	v_pk_mul_f32 v[154:155], v[200:201], v[154:155] op_sel:[1,0]
	v_pk_mul_f32 v[152:153], v[200:201], v[152:153] op_sel:[1,0]
	v_pk_fma_f32 v[150:151], v[212:213], v[150:151], v[14:15]
	v_pk_fma_f32 v[148:149], v[132:133], s[78:79], v[148:149] op_sel_hi:[1,0,1]
	v_pk_fma_f32 v[142:143], v[212:213], v[142:143], v[6:7]
	v_pk_fma_f32 v[132:133], v[132:133], s[78:79], v[140:141] op_sel_hi:[1,0,1]
	v_add_u32_e32 v140, 0x58080, v194
	v_mov_b32_e32 v141, v159
	v_pk_fma_f32 v[204:205], v[134:135], s[78:79], v[204:205] op_sel_hi:[1,0,1]
	v_pk_fma_f32 v[152:153], v[208:209], v[152:153], v[16:17]
	v_pk_fma_f32 v[154:155], v[206:207], v[154:155], v[18:19]
	v_add_u32_e32 v200, 0x48090, v194
	v_mov_b32_e32 v201, v159
	v_pk_fma_f32 v[150:151], v[134:135], s[78:79], v[150:151] op_sel_hi:[1,0,1]
	v_pk_fma_f32 v[134:135], v[134:135], s[78:79], v[142:143] op_sel_hi:[1,0,1]
	v_lshl_add_u64 v[140:141], v[140:141], 2, s[90:91]
	v_pk_fma_f32 v[154:155], v[130:131], s[78:79], v[154:155] op_sel_hi:[1,0,1]
	v_pk_fma_f32 v[152:153], v[128:129], s[78:79], v[152:153] op_sel_hi:[1,0,1]
	v_lshl_add_u64 v[200:201], v[200:201], 2, s[90:91]
	v_sub_f32_e32 v145, v145, v198
	v_sub_f32_e32 v144, v144, v198
	global_store_dwordx4 v[140:141], v[132:135], off
	global_store_dwordx4 v[200:201], v[152:155], off
	v_sub_f32_e32 v147, v147, v198
	v_sub_f32_e32 v133, v137, v196
	v_sub_f32_e32 v132, v136, v196
	v_add_u32_e32 v152, 0x50080, v194
	v_mov_b32_e32 v153, v159
	v_sub_f32_e32 v146, v146, v198
	v_pk_mul_f32 v[144:145], v[198:199], v[144:145] op_sel:[1,0]
	v_sub_f32_e32 v135, v139, v196
	v_sub_f32_e32 v134, v138, v196
	v_pk_mul_f32 v[132:133], v[196:197], v[132:133] op_sel:[1,0]
	v_lshl_add_u64 v[152:153], v[152:153], 2, s[90:91]
	v_pk_mul_f32 v[146:147], v[198:199], v[146:147] op_sel:[1,0]
	v_pk_fma_f32 v[144:145], v[208:209], v[144:145], v[8:9]
	v_pk_mul_f32 v[134:135], v[196:197], v[134:135] op_sel:[1,0]
	v_pk_fma_f32 v[132:133], v[208:209], v[132:133], v[0:1]
	v_add_u32_e32 v210, 0x48080, v194
	v_mov_b32_e32 v211, v159
	global_store_dwordx4 v[152:153], v[148:151], off
	v_pk_fma_f32 v[146:147], v[206:207], v[146:147], v[10:11]
	v_pk_fma_f32 v[144:145], v[128:129], s[78:79], v[144:145] op_sel_hi:[1,0,1]
	v_add_u32_e32 v148, 0x50090, v194
	v_mov_b32_e32 v149, v159
	v_pk_fma_f32 v[134:135], v[206:207], v[134:135], v[2:3]
	v_pk_fma_f32 v[128:129], v[128:129], s[78:79], v[132:133] op_sel_hi:[1,0,1]
	v_add_u32_e32 v132, 0x58090, v194
	v_mov_b32_e32 v133, v159
	v_lshl_add_u64 v[210:211], v[210:211], 2, s[90:91]
	v_pk_fma_f32 v[146:147], v[130:131], s[78:79], v[146:147] op_sel_hi:[1,0,1]
	v_lshl_add_u64 v[148:149], v[148:149], 2, s[90:91]
	v_pk_fma_f32 v[130:131], v[130:131], s[78:79], v[134:135] op_sel_hi:[1,0,1]
	v_lshl_add_u64 v[132:133], v[132:133], 2, s[90:91]
	global_store_dwordx4 v[210:211], v[202:205], off
	global_store_dwordx4 v[148:149], v[144:147], off
	global_store_dwordx4 v[132:133], v[128:131], off
	s_mov_b64 s[24:25], 0
	s_branch .LBB0_324
